# gather dot phase: per-pair row offsets from a wave-private LDS row of expert ids (one prefetched ds_read + one v_mad) instead of two readlanes, two scalar multiplies and two exec-masked adds
# speedup vs baseline: 1.0010x; 1.0010x over previous
; __device__ void peer_gather_phase(const Params& P, int l, bool do_store) {
;     ...
;       for (int pr = 0; pr < 4; ++pr) {
;         const int ea = __builtin_amdgcn_readlane(evs, kb + 2 * pr), eb = __builtin_amdgcn_readlane(evs, kb + 2 * pr + 1);
;         const uint2* up = (const uint2*)(U + (size_t)(uphi ? eb : ea) * 768);
;         u6[3 * pr] = up[0]; u6[3 * pr + 1] = up[1]; u6[3 * pr + 2] = up[2];
;     ...
;       for (int pr = 0; pr < 4; ++pr) {
;         v6u_t qv; qv[0] = u6[3 * pr].x; qv[1] = u6[3 * pr].y; qv[2] = u6[3 * pr + 1].x; qv[3] = u6[3 * pr + 1].y; qv[4] = u6[3 * pr + 2].x; qv[5] = u6[3 * pr + 2].y;
;         const v32f_t wv = __builtin_amdgcn_cvt_scalef32_pk32_f32_fp6(qv, 1.0f);
;         f32x2 a2 = f32x2{0.f, 0.f};
; #pragma unroll
;         for (int i = 0; i < 16; ++i) a2 += f32x2{wv[2 * i], wv[2 * i + 1]} * xu[i];
;         float hs = a2.x + a2.y;
;         hs += dpp_row_shr(hs, 1); hs += dpp_row_shr(hs, 2); hs += dpp_row_shr(hs, 4); hs += dpp_row_shr(hs, 8);
;         hs += __builtin_bit_cast(float, __builtin_amdgcn_update_dpp(0, __builtin_bit_cast(int, hs), 0x142, 0xa, 0xf, false));
;         const float da = __builtin_bit_cast(float, __builtin_amdgcn_readlane(__builtin_bit_cast(int, hs), 31));
;         const float db = __builtin_bit_cast(float, __builtin_amdgcn_readlane(__builtin_bit_cast(int, hs), 63));
;         dvec = (lane == kb + 2 * pr) ? da : dvec;
;         dvec = (lane == kb + 2 * pr + 1) ? db : dvec;
;       }
.LBB0_22:
	ds_write_b32 v75, v92 offset:256
	ds_read_b32 v76, v74 offset:320
	s_waitcnt lgkmcnt(0)
	v_mad_u32_u24 v167, v76, s33, v195
	ds_read_b32 v77, v74 offset:328
	s_waitcnt vmcnt(32)
	v_cvt_scalef32_pk32_f32_fp6 v[0:31], v[50:55], 1.0
	global_load_dwordx2 v[54:55], v167, s[62:63] offset:16
	global_load_dwordx4 v[50:53], v167, s[62:63]
	v_pk_mul_f32 v[246:247], v[0:1], v[96:97]
	v_pk_mul_f32 v[254:255], v[2:3], v[98:99]
	v_pk_mul_f32 v[160:161], v[4:5], v[100:101]
	v_pk_fma_f32 v[246:247], v[6:7], v[102:103], v[246:247]
	v_pk_fma_f32 v[254:255], v[8:9], v[104:105], v[254:255]
	v_pk_fma_f32 v[160:161], v[10:11], v[106:107], v[160:161]
	v_pk_fma_f32 v[246:247], v[12:13], v[108:109], v[246:247]
	v_pk_fma_f32 v[254:255], v[14:15], v[110:111], v[254:255]
	v_pk_fma_f32 v[160:161], v[16:17], v[112:113], v[160:161]
	v_pk_fma_f32 v[246:247], v[18:19], v[114:115], v[246:247]
	v_pk_fma_f32 v[254:255], v[20:21], v[116:117], v[254:255]
	v_pk_fma_f32 v[160:161], v[22:23], v[118:119], v[160:161]
	v_pk_fma_f32 v[246:247], v[24:25], v[120:121], v[246:247]
	v_pk_fma_f32 v[254:255], v[26:27], v[122:123], v[254:255]
	v_pk_fma_f32 v[160:161], v[28:29], v[124:125], v[160:161]
	v_pk_fma_f32 v[246:247], v[30:31], v[126:127], v[246:247]
	v_pk_add_f32 v[254:255], v[254:255], v[160:161]
	s_nop 0
	v_pk_add_f32 v[246:247], v[246:247], v[254:255]
	s_nop 0
	v_add_f32_e32 v162, v246, v247
	s_waitcnt lgkmcnt(0)
	v_mad_u32_u24 v167, v77, s33, v195
	ds_read_b32 v76, v74 offset:336
	s_waitcnt vmcnt(32)
	v_cvt_scalef32_pk32_f32_fp6 v[0:31], v[44:49], 1.0
	global_load_dwordx2 v[48:49], v167, s[62:63] offset:16
	global_load_dwordx4 v[44:47], v167, s[62:63]
	v_pk_mul_f32 v[246:247], v[0:1], v[96:97]
	v_pk_mul_f32 v[254:255], v[2:3], v[98:99]
	v_pk_mul_f32 v[160:161], v[4:5], v[100:101]
	v_pk_fma_f32 v[246:247], v[6:7], v[102:103], v[246:247]
	v_pk_fma_f32 v[254:255], v[8:9], v[104:105], v[254:255]
	v_pk_fma_f32 v[160:161], v[10:11], v[106:107], v[160:161]
	v_pk_fma_f32 v[246:247], v[12:13], v[108:109], v[246:247]
	v_pk_fma_f32 v[254:255], v[14:15], v[110:111], v[254:255]
	v_pk_fma_f32 v[160:161], v[16:17], v[112:113], v[160:161]
	v_pk_fma_f32 v[246:247], v[18:19], v[114:115], v[246:247]
	v_pk_fma_f32 v[254:255], v[20:21], v[116:117], v[254:255]
	v_pk_fma_f32 v[160:161], v[22:23], v[118:119], v[160:161]
	v_pk_fma_f32 v[246:247], v[24:25], v[120:121], v[246:247]
	v_pk_fma_f32 v[254:255], v[26:27], v[122:123], v[254:255]
	v_pk_fma_f32 v[160:161], v[28:29], v[124:125], v[160:161]
	v_pk_fma_f32 v[246:247], v[30:31], v[126:127], v[246:247]
	v_pk_add_f32 v[254:255], v[254:255], v[160:161]
	s_nop 0
	v_pk_add_f32 v[246:247], v[246:247], v[254:255]
	s_nop 0
	v_add_f32_e32 v163, v246, v247
	s_waitcnt lgkmcnt(0)
	v_mad_u32_u24 v167, v76, s33, v195
	ds_read_b32 v77, v74 offset:344
	s_waitcnt vmcnt(32)
	v_cvt_scalef32_pk32_f32_fp6 v[0:31], v[38:43], 1.0
	global_load_dwordx2 v[42:43], v167, s[62:63] offset:16
	global_load_dwordx4 v[38:41], v167, s[62:63]
	v_pk_mul_f32 v[246:247], v[0:1], v[96:97]
	v_pk_mul_f32 v[254:255], v[2:3], v[98:99]
	v_pk_mul_f32 v[160:161], v[4:5], v[100:101]
	v_pk_fma_f32 v[246:247], v[6:7], v[102:103], v[246:247]
	v_pk_fma_f32 v[254:255], v[8:9], v[104:105], v[254:255]
	v_pk_fma_f32 v[160:161], v[10:11], v[106:107], v[160:161]
	v_pk_fma_f32 v[246:247], v[12:13], v[108:109], v[246:247]
	v_pk_fma_f32 v[254:255], v[14:15], v[110:111], v[254:255]
	v_pk_fma_f32 v[160:161], v[16:17], v[112:113], v[160:161]
	v_pk_fma_f32 v[246:247], v[18:19], v[114:115], v[246:247]
	v_pk_fma_f32 v[254:255], v[20:21], v[116:117], v[254:255]
	v_pk_fma_f32 v[160:161], v[22:23], v[118:119], v[160:161]
	v_pk_fma_f32 v[246:247], v[24:25], v[120:121], v[246:247]
	v_pk_fma_f32 v[254:255], v[26:27], v[122:123], v[254:255]
	v_pk_fma_f32 v[160:161], v[28:29], v[124:125], v[160:161]
	v_pk_fma_f32 v[246:247], v[30:31], v[126:127], v[246:247]
	v_pk_add_f32 v[254:255], v[254:255], v[160:161]
	s_nop 0
	v_pk_add_f32 v[246:247], v[246:247], v[254:255]
	s_nop 0
	v_add_f32_e32 v164, v246, v247
	s_waitcnt lgkmcnt(0)
	v_mad_u32_u24 v167, v77, s33, v195
	ds_read_b32 v76, v74 offset:352
	s_waitcnt vmcnt(32)
	v_cvt_scalef32_pk32_f32_fp6 v[0:31], v[32:37], 1.0
	global_load_dwordx2 v[36:37], v167, s[62:63] offset:16
	global_load_dwordx4 v[32:35], v167, s[62:63]
	v_pk_mul_f32 v[246:247], v[0:1], v[96:97]
	v_pk_mul_f32 v[254:255], v[2:3], v[98:99]
	v_pk_mul_f32 v[160:161], v[4:5], v[100:101]
	v_pk_fma_f32 v[246:247], v[6:7], v[102:103], v[246:247]
	v_pk_fma_f32 v[254:255], v[8:9], v[104:105], v[254:255]
	v_pk_fma_f32 v[160:161], v[10:11], v[106:107], v[160:161]
	v_pk_fma_f32 v[246:247], v[12:13], v[108:109], v[246:247]
	v_pk_fma_f32 v[254:255], v[14:15], v[110:111], v[254:255]
	v_pk_fma_f32 v[160:161], v[16:17], v[112:113], v[160:161]
	v_pk_fma_f32 v[246:247], v[18:19], v[114:115], v[246:247]
	v_pk_fma_f32 v[254:255], v[20:21], v[116:117], v[254:255]
	v_pk_fma_f32 v[160:161], v[22:23], v[118:119], v[160:161]
	v_pk_fma_f32 v[246:247], v[24:25], v[120:121], v[246:247]
	v_pk_fma_f32 v[254:255], v[26:27], v[122:123], v[254:255]
	v_pk_fma_f32 v[160:161], v[28:29], v[124:125], v[160:161]
	v_pk_fma_f32 v[246:247], v[30:31], v[126:127], v[246:247]
	v_pk_add_f32 v[254:255], v[254:255], v[160:161]
	s_nop 0
	v_pk_add_f32 v[246:247], v[246:247], v[254:255]
	s_nop 0
	v_add_f32_e32 v165, v246, v247
	v_add_f32_dpp v162, v162, v162 row_shr:1 row_mask:0xf bank_mask:0xf bound_ctrl:1
	v_add_f32_dpp v163, v163, v163 row_shr:1 row_mask:0xf bank_mask:0xf bound_ctrl:1
	v_add_f32_dpp v164, v164, v164 row_shr:1 row_mask:0xf bank_mask:0xf bound_ctrl:1
	v_add_f32_dpp v165, v165, v165 row_shr:1 row_mask:0xf bank_mask:0xf bound_ctrl:1
; __device__ void peer_gather_phase(const Params& P, int l, bool do_store) {
;     ...
;       for (int pr = 0; pr < 4; ++pr) {
;         const int ea = __builtin_amdgcn_readlane(evs, kb + 2 * pr), eb = __builtin_amdgcn_readlane(evs, kb + 2 * pr + 1);
;         const uint2* up = (const uint2*)(U + (size_t)(uphi ? eb : ea) * 768);
;         u6[3 * pr] = up[0]; u6[3 * pr + 1] = up[1]; u6[3 * pr + 2] = up[2];
;     ...
;       for (int pr = 0; pr < 4; ++pr) {
;         v6u_t qv; qv[0] = u6[3 * pr].x; qv[1] = u6[3 * pr].y; qv[2] = u6[3 * pr + 1].x; qv[3] = u6[3 * pr + 1].y; qv[4] = u6[3 * pr + 2].x; qv[5] = u6[3 * pr + 2].y;
;         const v32f_t wv = __builtin_amdgcn_cvt_scalef32_pk32_f32_fp6(qv, 1.0f);
;         f32x2 a2 = f32x2{0.f, 0.f};
; #pragma unroll
;         for (int i = 0; i < 16; ++i) a2 += f32x2{wv[2 * i], wv[2 * i + 1]} * xu[i];
;         float hs = a2.x + a2.y;
;         hs += dpp_row_shr(hs, 1); hs += dpp_row_shr(hs, 2); hs += dpp_row_shr(hs, 4); hs += dpp_row_shr(hs, 8);
;         hs += __builtin_bit_cast(float, __builtin_amdgcn_update_dpp(0, __builtin_bit_cast(int, hs), 0x142, 0xa, 0xf, false));
;         const float da = __builtin_bit_cast(float, __builtin_amdgcn_readlane(__builtin_bit_cast(int, hs), 31));
;         const float db = __builtin_bit_cast(float, __builtin_amdgcn_readlane(__builtin_bit_cast(int, hs), 63));
;         dvec = (lane == kb + 2 * pr) ? da : dvec;
;         dvec = (lane == kb + 2 * pr + 1) ? db : dvec;
;       }
	v_add_f32_dpp v162, v162, v162 row_shr:2 row_mask:0xf bank_mask:0xf bound_ctrl:1
	v_add_f32_dpp v163, v163, v163 row_shr:2 row_mask:0xf bank_mask:0xf bound_ctrl:1
	v_add_f32_dpp v164, v164, v164 row_shr:2 row_mask:0xf bank_mask:0xf bound_ctrl:1
	v_add_f32_dpp v165, v165, v165 row_shr:2 row_mask:0xf bank_mask:0xf bound_ctrl:1
	v_add_f32_dpp v162, v162, v162 row_shr:4 row_mask:0xf bank_mask:0xf bound_ctrl:1
	v_add_f32_dpp v163, v163, v163 row_shr:4 row_mask:0xf bank_mask:0xf bound_ctrl:1
	v_add_f32_dpp v164, v164, v164 row_shr:4 row_mask:0xf bank_mask:0xf bound_ctrl:1
	v_add_f32_dpp v165, v165, v165 row_shr:4 row_mask:0xf bank_mask:0xf bound_ctrl:1
	v_add_f32_dpp v162, v162, v162 row_shr:8 row_mask:0xf bank_mask:0xf bound_ctrl:1
	v_add_f32_dpp v163, v163, v163 row_shr:8 row_mask:0xf bank_mask:0xf bound_ctrl:1
	v_add_f32_dpp v164, v164, v164 row_shr:8 row_mask:0xf bank_mask:0xf bound_ctrl:1
	v_add_f32_dpp v165, v165, v165 row_shr:8 row_mask:0xf bank_mask:0xf bound_ctrl:1
	v_add_f32_dpp v162, v162, v162 row_bcast:15 row_mask:0xa bank_mask:0xf
	v_add_f32_dpp v163, v163, v163 row_bcast:15 row_mask:0xa bank_mask:0xf
	v_add_f32_dpp v164, v164, v164 row_bcast:15 row_mask:0xa bank_mask:0xf
	v_add_f32_dpp v165, v165, v165 row_bcast:15 row_mask:0xa bank_mask:0xf
	s_mov_b64 s[98:99], exec
	s_mov_b32 exec_lo, 0x80000000
	s_mov_b32 exec_hi, 0x80000000
	ds_write_b32 v74, v162
	ds_write_b32 v74, v163 offset:8
	ds_write_b32 v74, v164 offset:16
	ds_write_b32 v74, v165 offset:24
	s_mov_b64 exec, s[98:99]
	s_waitcnt lgkmcnt(0)
	v_mad_u32_u24 v167, v76, s33, v195
	ds_read_b32 v77, v74 offset:360
	s_waitcnt vmcnt(32)
	v_cvt_scalef32_pk32_f32_fp6 v[0:31], v[196:201], 1.0
	global_load_dwordx2 v[200:201], v167, s[62:63] offset:16
	global_load_dwordx4 v[196:199], v167, s[62:63]
	v_pk_mul_f32 v[246:247], v[0:1], v[96:97]
	v_pk_mul_f32 v[254:255], v[2:3], v[98:99]
	v_pk_mul_f32 v[160:161], v[4:5], v[100:101]
	v_pk_fma_f32 v[246:247], v[6:7], v[102:103], v[246:247]
	v_pk_fma_f32 v[254:255], v[8:9], v[104:105], v[254:255]
	v_pk_fma_f32 v[160:161], v[10:11], v[106:107], v[160:161]
	v_pk_fma_f32 v[246:247], v[12:13], v[108:109], v[246:247]
	v_pk_fma_f32 v[254:255], v[14:15], v[110:111], v[254:255]
	v_pk_fma_f32 v[160:161], v[16:17], v[112:113], v[160:161]
	v_pk_fma_f32 v[246:247], v[18:19], v[114:115], v[246:247]
	v_pk_fma_f32 v[254:255], v[20:21], v[116:117], v[254:255]
	v_pk_fma_f32 v[160:161], v[22:23], v[118:119], v[160:161]
	v_pk_fma_f32 v[246:247], v[24:25], v[120:121], v[246:247]
	v_pk_fma_f32 v[254:255], v[26:27], v[122:123], v[254:255]
	v_pk_fma_f32 v[160:161], v[28:29], v[124:125], v[160:161]
	v_pk_fma_f32 v[246:247], v[30:31], v[126:127], v[246:247]
	v_pk_add_f32 v[254:255], v[254:255], v[160:161]
	s_nop 0
	v_pk_add_f32 v[246:247], v[246:247], v[254:255]
	s_nop 0
	v_add_f32_e32 v162, v246, v247
	s_waitcnt lgkmcnt(0)
	v_mad_u32_u24 v167, v77, s33, v195
	ds_read_b32 v76, v74 offset:368
	s_waitcnt vmcnt(32)
	v_cvt_scalef32_pk32_f32_fp6 v[0:31], v[228:233], 1.0
	global_load_dwordx2 v[232:233], v167, s[62:63] offset:16
	global_load_dwordx4 v[228:231], v167, s[62:63]
	v_pk_mul_f32 v[246:247], v[0:1], v[96:97]
	v_pk_mul_f32 v[254:255], v[2:3], v[98:99]
	v_pk_mul_f32 v[160:161], v[4:5], v[100:101]
	v_pk_fma_f32 v[246:247], v[6:7], v[102:103], v[246:247]
	v_pk_fma_f32 v[254:255], v[8:9], v[104:105], v[254:255]
	v_pk_fma_f32 v[160:161], v[10:11], v[106:107], v[160:161]
	v_pk_fma_f32 v[246:247], v[12:13], v[108:109], v[246:247]
	v_pk_fma_f32 v[254:255], v[14:15], v[110:111], v[254:255]
	v_pk_fma_f32 v[160:161], v[16:17], v[112:113], v[160:161]
	v_pk_fma_f32 v[246:247], v[18:19], v[114:115], v[246:247]
	v_pk_fma_f32 v[254:255], v[20:21], v[116:117], v[254:255]
	v_pk_fma_f32 v[160:161], v[22:23], v[118:119], v[160:161]
	v_pk_fma_f32 v[246:247], v[24:25], v[120:121], v[246:247]
	v_pk_fma_f32 v[254:255], v[26:27], v[122:123], v[254:255]
	v_pk_fma_f32 v[160:161], v[28:29], v[124:125], v[160:161]
	v_pk_fma_f32 v[246:247], v[30:31], v[126:127], v[246:247]
	v_pk_add_f32 v[254:255], v[254:255], v[160:161]
	s_nop 0
	v_pk_add_f32 v[246:247], v[246:247], v[254:255]
	s_nop 0
	v_add_f32_e32 v163, v246, v247
	s_waitcnt lgkmcnt(0)
	v_mad_u32_u24 v167, v76, s33, v195
	ds_read_b32 v77, v74 offset:376
	s_waitcnt vmcnt(32)
	v_cvt_scalef32_pk32_f32_fp6 v[0:31], v[234:239], 1.0
	global_load_dwordx2 v[238:239], v167, s[62:63] offset:16
	global_load_dwordx4 v[234:237], v167, s[62:63]
	v_pk_mul_f32 v[246:247], v[0:1], v[96:97]
	v_pk_mul_f32 v[254:255], v[2:3], v[98:99]
	v_pk_mul_f32 v[160:161], v[4:5], v[100:101]
	v_pk_fma_f32 v[246:247], v[6:7], v[102:103], v[246:247]
	v_pk_fma_f32 v[254:255], v[8:9], v[104:105], v[254:255]
	v_pk_fma_f32 v[160:161], v[10:11], v[106:107], v[160:161]
	v_pk_fma_f32 v[246:247], v[12:13], v[108:109], v[246:247]
	v_pk_fma_f32 v[254:255], v[14:15], v[110:111], v[254:255]
	v_pk_fma_f32 v[160:161], v[16:17], v[112:113], v[160:161]
	v_pk_fma_f32 v[246:247], v[18:19], v[114:115], v[246:247]
	v_pk_fma_f32 v[254:255], v[20:21], v[116:117], v[254:255]
	v_pk_fma_f32 v[160:161], v[22:23], v[118:119], v[160:161]
	v_pk_fma_f32 v[246:247], v[24:25], v[120:121], v[246:247]
	v_pk_fma_f32 v[254:255], v[26:27], v[122:123], v[254:255]
	v_pk_fma_f32 v[160:161], v[28:29], v[124:125], v[160:161]
	v_pk_fma_f32 v[246:247], v[30:31], v[126:127], v[246:247]
	v_pk_add_f32 v[254:255], v[254:255], v[160:161]
	s_nop 0
	v_pk_add_f32 v[246:247], v[246:247], v[254:255]
	s_nop 0
	v_add_f32_e32 v164, v246, v247
	s_waitcnt lgkmcnt(0)
	v_mad_u32_u24 v167, v77, s33, v195
	ds_read_b32 v76, v74 offset:384
	s_waitcnt vmcnt(32)
; __device__ void peer_gather_phase(const Params& P, int l, bool do_store) {
;     ...
;       for (int pr = 0; pr < 4; ++pr) {
;         const int ea = __builtin_amdgcn_readlane(evs, kb + 2 * pr), eb = __builtin_amdgcn_readlane(evs, kb + 2 * pr + 1);
;         const uint2* up = (const uint2*)(U + (size_t)(uphi ? eb : ea) * 768);
;         u6[3 * pr] = up[0]; u6[3 * pr + 1] = up[1]; u6[3 * pr + 2] = up[2];
;     ...
;       for (int pr = 0; pr < 4; ++pr) {
;         v6u_t qv; qv[0] = u6[3 * pr].x; qv[1] = u6[3 * pr].y; qv[2] = u6[3 * pr + 1].x; qv[3] = u6[3 * pr + 1].y; qv[4] = u6[3 * pr + 2].x; qv[5] = u6[3 * pr + 2].y;
;         const v32f_t wv = __builtin_amdgcn_cvt_scalef32_pk32_f32_fp6(qv, 1.0f);
;         f32x2 a2 = f32x2{0.f, 0.f};
; #pragma unroll
;         for (int i = 0; i < 16; ++i) a2 += f32x2{wv[2 * i], wv[2 * i + 1]} * xu[i];
;         float hs = a2.x + a2.y;
;         hs += dpp_row_shr(hs, 1); hs += dpp_row_shr(hs, 2); hs += dpp_row_shr(hs, 4); hs += dpp_row_shr(hs, 8);
;         hs += __builtin_bit_cast(float, __builtin_amdgcn_update_dpp(0, __builtin_bit_cast(int, hs), 0x142, 0xa, 0xf, false));
;         const float da = __builtin_bit_cast(float, __builtin_amdgcn_readlane(__builtin_bit_cast(int, hs), 31));
;         const float db = __builtin_bit_cast(float, __builtin_amdgcn_readlane(__builtin_bit_cast(int, hs), 63));
;         dvec = (lane == kb + 2 * pr) ? da : dvec;
;         dvec = (lane == kb + 2 * pr + 1) ? db : dvec;
;       }
	v_cvt_scalef32_pk32_f32_fp6 v[0:31], v[240:245], 1.0
	global_load_dwordx2 v[244:245], v167, s[62:63] offset:16
	global_load_dwordx4 v[240:243], v167, s[62:63]
	v_pk_mul_f32 v[246:247], v[0:1], v[96:97]
	v_pk_mul_f32 v[254:255], v[2:3], v[98:99]
	v_pk_mul_f32 v[160:161], v[4:5], v[100:101]
	v_pk_fma_f32 v[246:247], v[6:7], v[102:103], v[246:247]
	v_pk_fma_f32 v[254:255], v[8:9], v[104:105], v[254:255]
	v_pk_fma_f32 v[160:161], v[10:11], v[106:107], v[160:161]
	v_pk_fma_f32 v[246:247], v[12:13], v[108:109], v[246:247]
	v_pk_fma_f32 v[254:255], v[14:15], v[110:111], v[254:255]
	v_pk_fma_f32 v[160:161], v[16:17], v[112:113], v[160:161]
	v_pk_fma_f32 v[246:247], v[18:19], v[114:115], v[246:247]
	v_pk_fma_f32 v[254:255], v[20:21], v[116:117], v[254:255]
	v_pk_fma_f32 v[160:161], v[22:23], v[118:119], v[160:161]
	v_pk_fma_f32 v[246:247], v[24:25], v[120:121], v[246:247]
	v_pk_fma_f32 v[254:255], v[26:27], v[122:123], v[254:255]
	v_pk_fma_f32 v[160:161], v[28:29], v[124:125], v[160:161]
	v_pk_fma_f32 v[246:247], v[30:31], v[126:127], v[246:247]
	v_pk_add_f32 v[254:255], v[254:255], v[160:161]
	s_nop 0
	v_pk_add_f32 v[246:247], v[246:247], v[254:255]
	s_nop 0
	v_add_f32_e32 v165, v246, v247
	v_add_f32_dpp v162, v162, v162 row_shr:1 row_mask:0xf bank_mask:0xf bound_ctrl:1
	v_add_f32_dpp v163, v163, v163 row_shr:1 row_mask:0xf bank_mask:0xf bound_ctrl:1
	v_add_f32_dpp v164, v164, v164 row_shr:1 row_mask:0xf bank_mask:0xf bound_ctrl:1
	v_add_f32_dpp v165, v165, v165 row_shr:1 row_mask:0xf bank_mask:0xf bound_ctrl:1
	v_add_f32_dpp v162, v162, v162 row_shr:2 row_mask:0xf bank_mask:0xf bound_ctrl:1
	v_add_f32_dpp v163, v163, v163 row_shr:2 row_mask:0xf bank_mask:0xf bound_ctrl:1
	v_add_f32_dpp v164, v164, v164 row_shr:2 row_mask:0xf bank_mask:0xf bound_ctrl:1
	v_add_f32_dpp v165, v165, v165 row_shr:2 row_mask:0xf bank_mask:0xf bound_ctrl:1
	v_add_f32_dpp v162, v162, v162 row_shr:4 row_mask:0xf bank_mask:0xf bound_ctrl:1
	v_add_f32_dpp v163, v163, v163 row_shr:4 row_mask:0xf bank_mask:0xf bound_ctrl:1
	v_add_f32_dpp v164, v164, v164 row_shr:4 row_mask:0xf bank_mask:0xf bound_ctrl:1
	v_add_f32_dpp v165, v165, v165 row_shr:4 row_mask:0xf bank_mask:0xf bound_ctrl:1
	v_add_f32_dpp v162, v162, v162 row_shr:8 row_mask:0xf bank_mask:0xf bound_ctrl:1
	v_add_f32_dpp v163, v163, v163 row_shr:8 row_mask:0xf bank_mask:0xf bound_ctrl:1
	v_add_f32_dpp v164, v164, v164 row_shr:8 row_mask:0xf bank_mask:0xf bound_ctrl:1
	v_add_f32_dpp v165, v165, v165 row_shr:8 row_mask:0xf bank_mask:0xf bound_ctrl:1
	v_add_f32_dpp v162, v162, v162 row_bcast:15 row_mask:0xa bank_mask:0xf
	v_add_f32_dpp v163, v163, v163 row_bcast:15 row_mask:0xa bank_mask:0xf
	v_add_f32_dpp v164, v164, v164 row_bcast:15 row_mask:0xa bank_mask:0xf
	v_add_f32_dpp v165, v165, v165 row_bcast:15 row_mask:0xa bank_mask:0xf
	s_mov_b64 s[98:99], exec
	s_mov_b32 exec_lo, 0x80000000
	s_mov_b32 exec_hi, 0x80000000
	ds_write_b32 v74, v162 offset:32
	ds_write_b32 v74, v163 offset:40
	ds_write_b32 v74, v164 offset:48
	ds_write_b32 v74, v165 offset:56
	s_mov_b64 exec, s[98:99]
	s_waitcnt lgkmcnt(0)
	v_mad_u32_u24 v167, v76, s33, v195
	ds_read_b32 v77, v74 offset:392
	s_waitcnt vmcnt(14)
	v_cvt_scalef32_pk32_f32_fp6 v[0:31], v[50:55], 1.0
	global_load_dwordx2 v[54:55], v167, s[62:63] offset:16
	global_load_dwordx4 v[50:53], v167, s[62:63]
	v_pk_mul_f32 v[246:247], v[0:1], v[96:97]
	v_pk_mul_f32 v[254:255], v[2:3], v[98:99]
	v_pk_mul_f32 v[160:161], v[4:5], v[100:101]
	v_pk_fma_f32 v[246:247], v[6:7], v[102:103], v[246:247]
	v_pk_fma_f32 v[254:255], v[8:9], v[104:105], v[254:255]
	v_pk_fma_f32 v[160:161], v[10:11], v[106:107], v[160:161]
	v_pk_fma_f32 v[246:247], v[12:13], v[108:109], v[246:247]
	v_pk_fma_f32 v[254:255], v[14:15], v[110:111], v[254:255]
	v_pk_fma_f32 v[160:161], v[16:17], v[112:113], v[160:161]
	v_pk_fma_f32 v[246:247], v[18:19], v[114:115], v[246:247]
	v_pk_fma_f32 v[254:255], v[20:21], v[116:117], v[254:255]
	v_pk_fma_f32 v[160:161], v[22:23], v[118:119], v[160:161]
	v_pk_fma_f32 v[246:247], v[24:25], v[120:121], v[246:247]
	v_pk_fma_f32 v[254:255], v[26:27], v[122:123], v[254:255]
	v_pk_fma_f32 v[160:161], v[28:29], v[124:125], v[160:161]
	v_pk_fma_f32 v[246:247], v[30:31], v[126:127], v[246:247]
	v_pk_add_f32 v[254:255], v[254:255], v[160:161]
	s_nop 0
	v_pk_add_f32 v[246:247], v[246:247], v[254:255]
	s_nop 0
	v_add_f32_e32 v162, v246, v247
	s_waitcnt lgkmcnt(0)
	v_mad_u32_u24 v167, v77, s33, v195
	ds_read_b32 v76, v74 offset:400
	s_waitcnt vmcnt(14)
	v_cvt_scalef32_pk32_f32_fp6 v[0:31], v[44:49], 1.0
	global_load_dwordx2 v[48:49], v167, s[62:63] offset:16
	global_load_dwordx4 v[44:47], v167, s[62:63]
	v_pk_mul_f32 v[246:247], v[0:1], v[96:97]
	v_pk_mul_f32 v[254:255], v[2:3], v[98:99]
	v_pk_mul_f32 v[160:161], v[4:5], v[100:101]
	v_pk_fma_f32 v[246:247], v[6:7], v[102:103], v[246:247]
	v_pk_fma_f32 v[254:255], v[8:9], v[104:105], v[254:255]
	v_pk_fma_f32 v[160:161], v[10:11], v[106:107], v[160:161]
	v_pk_fma_f32 v[246:247], v[12:13], v[108:109], v[246:247]
	v_pk_fma_f32 v[254:255], v[14:15], v[110:111], v[254:255]
	v_pk_fma_f32 v[160:161], v[16:17], v[112:113], v[160:161]
	v_pk_fma_f32 v[246:247], v[18:19], v[114:115], v[246:247]
	v_pk_fma_f32 v[254:255], v[20:21], v[116:117], v[254:255]
	v_pk_fma_f32 v[160:161], v[22:23], v[118:119], v[160:161]
	v_pk_fma_f32 v[246:247], v[24:25], v[120:121], v[246:247]
	v_pk_fma_f32 v[254:255], v[26:27], v[122:123], v[254:255]
	v_pk_fma_f32 v[160:161], v[28:29], v[124:125], v[160:161]
	v_pk_fma_f32 v[246:247], v[30:31], v[126:127], v[246:247]
	v_pk_add_f32 v[254:255], v[254:255], v[160:161]
	s_nop 0
	v_pk_add_f32 v[246:247], v[246:247], v[254:255]
	s_nop 0
	v_add_f32_e32 v163, v246, v247
	s_waitcnt lgkmcnt(0)
; __device__ void peer_gather_phase(const Params& P, int l, bool do_store) {
;     ...
;     auto load_batch = [&](uint2 (&u6)[12], uint2 (&v8)[8], int bt) {
;       const int evs = (bt < 8) ? ev0 : ev1;
;       const int kb = (bt & 7) * 8;
; #pragma unroll
;       for (int pr = 0; pr < 4; ++pr) {
;         const int ea = __builtin_amdgcn_readlane(evs, kb + 2 * pr), eb = __builtin_amdgcn_readlane(evs, kb + 2 * pr + 1);
;         const uint2* up = (const uint2*)(U + (size_t)(uphi ? eb : ea) * 768);
;         u6[3 * pr] = up[0]; u6[3 * pr + 1] = up[1]; u6[3 * pr + 2] = up[2];
;         v8[2 * pr] = *(const uint2*)(V + (size_t)ea * 512);
;         v8[2 * pr + 1] = *(const uint2*)(V + (size_t)eb * 512);
;       }
;     };
;     auto compute_batch = [&](const uint2 (&u6)[12], const uint2 (&v8)[8], int bt) {
;       const int kb = (bt & 7) * 8;
;       float dvec = 0.f;
; #pragma unroll
;       for (int pr = 0; pr < 4; ++pr) {
;         v6u_t qv; qv[0] = u6[3 * pr].x; qv[1] = u6[3 * pr].y; qv[2] = u6[3 * pr + 1].x; qv[3] = u6[3 * pr + 1].y; qv[4] = u6[3 * pr + 2].x; qv[5] = u6[3 * pr + 2].y;
;         const v32f_t wv = __builtin_amdgcn_cvt_scalef32_pk32_f32_fp6(qv, 1.0f);
;         f32x2 a2 = f32x2{0.f, 0.f};
; #pragma unroll
;         for (int i = 0; i < 16; ++i) a2 += f32x2{wv[2 * i], wv[2 * i + 1]} * xu[i];
;         float hs = a2.x + a2.y;
;         hs += dpp_row_shr(hs, 1); hs += dpp_row_shr(hs, 2); hs += dpp_row_shr(hs, 4); hs += dpp_row_shr(hs, 8);
;         hs += __builtin_bit_cast(float, __builtin_amdgcn_update_dpp(0, __builtin_bit_cast(int, hs), 0x142, 0xa, 0xf, false));
;         const float da = __builtin_bit_cast(float, __builtin_amdgcn_readlane(__builtin_bit_cast(int, hs), 31));
;         const float db = __builtin_bit_cast(float, __builtin_amdgcn_readlane(__builtin_bit_cast(int, hs), 63));
;         dvec = (lane == kb + 2 * pr) ? da : dvec;
;         dvec = (lane == kb + 2 * pr + 1) ? db : dvec;
;       }
	v_mad_u32_u24 v167, v76, s33, v195
	ds_read_b32 v77, v74 offset:408
	s_waitcnt vmcnt(14)
	v_cvt_scalef32_pk32_f32_fp6 v[0:31], v[38:43], 1.0
	global_load_dwordx2 v[42:43], v167, s[62:63] offset:16
	global_load_dwordx4 v[38:41], v167, s[62:63]
	v_pk_mul_f32 v[246:247], v[0:1], v[96:97]
	v_pk_mul_f32 v[254:255], v[2:3], v[98:99]
	v_pk_mul_f32 v[160:161], v[4:5], v[100:101]
	v_pk_fma_f32 v[246:247], v[6:7], v[102:103], v[246:247]
	v_pk_fma_f32 v[254:255], v[8:9], v[104:105], v[254:255]
	v_pk_fma_f32 v[160:161], v[10:11], v[106:107], v[160:161]
	v_pk_fma_f32 v[246:247], v[12:13], v[108:109], v[246:247]
	v_pk_fma_f32 v[254:255], v[14:15], v[110:111], v[254:255]
	v_pk_fma_f32 v[160:161], v[16:17], v[112:113], v[160:161]
	v_pk_fma_f32 v[246:247], v[18:19], v[114:115], v[246:247]
	v_pk_fma_f32 v[254:255], v[20:21], v[116:117], v[254:255]
	v_pk_fma_f32 v[160:161], v[22:23], v[118:119], v[160:161]
	v_pk_fma_f32 v[246:247], v[24:25], v[120:121], v[246:247]
	v_pk_fma_f32 v[254:255], v[26:27], v[122:123], v[254:255]
	v_pk_fma_f32 v[160:161], v[28:29], v[124:125], v[160:161]
	v_pk_fma_f32 v[246:247], v[30:31], v[126:127], v[246:247]
	v_pk_add_f32 v[254:255], v[254:255], v[160:161]
	s_nop 0
	v_pk_add_f32 v[246:247], v[246:247], v[254:255]
	s_nop 0
	v_add_f32_e32 v164, v246, v247
	s_waitcnt lgkmcnt(0)
	v_mad_u32_u24 v167, v77, s33, v195
	ds_read_b32 v76, v74 offset:416
	s_waitcnt vmcnt(14)
	v_cvt_scalef32_pk32_f32_fp6 v[0:31], v[32:37], 1.0
	global_load_dwordx2 v[36:37], v167, s[62:63] offset:16
	global_load_dwordx4 v[32:35], v167, s[62:63]
	v_pk_mul_f32 v[246:247], v[0:1], v[96:97]
	v_pk_mul_f32 v[254:255], v[2:3], v[98:99]
	v_pk_mul_f32 v[160:161], v[4:5], v[100:101]
	v_pk_fma_f32 v[246:247], v[6:7], v[102:103], v[246:247]
	v_pk_fma_f32 v[254:255], v[8:9], v[104:105], v[254:255]
	v_pk_fma_f32 v[160:161], v[10:11], v[106:107], v[160:161]
	v_pk_fma_f32 v[246:247], v[12:13], v[108:109], v[246:247]
	v_pk_fma_f32 v[254:255], v[14:15], v[110:111], v[254:255]
	v_pk_fma_f32 v[160:161], v[16:17], v[112:113], v[160:161]
	v_pk_fma_f32 v[246:247], v[18:19], v[114:115], v[246:247]
	v_pk_fma_f32 v[254:255], v[20:21], v[116:117], v[254:255]
	v_pk_fma_f32 v[160:161], v[22:23], v[118:119], v[160:161]
	v_pk_fma_f32 v[246:247], v[24:25], v[120:121], v[246:247]
	v_pk_fma_f32 v[254:255], v[26:27], v[122:123], v[254:255]
	v_pk_fma_f32 v[160:161], v[28:29], v[124:125], v[160:161]
	v_pk_fma_f32 v[246:247], v[30:31], v[126:127], v[246:247]
	v_pk_add_f32 v[254:255], v[254:255], v[160:161]
	s_nop 0
	v_pk_add_f32 v[246:247], v[246:247], v[254:255]
	s_nop 0
	v_add_f32_e32 v165, v246, v247
	v_add_f32_dpp v162, v162, v162 row_shr:1 row_mask:0xf bank_mask:0xf bound_ctrl:1
	v_add_f32_dpp v163, v163, v163 row_shr:1 row_mask:0xf bank_mask:0xf bound_ctrl:1
	v_add_f32_dpp v164, v164, v164 row_shr:1 row_mask:0xf bank_mask:0xf bound_ctrl:1
	v_add_f32_dpp v165, v165, v165 row_shr:1 row_mask:0xf bank_mask:0xf bound_ctrl:1
	v_add_f32_dpp v162, v162, v162 row_shr:2 row_mask:0xf bank_mask:0xf bound_ctrl:1
	v_add_f32_dpp v163, v163, v163 row_shr:2 row_mask:0xf bank_mask:0xf bound_ctrl:1
	v_add_f32_dpp v164, v164, v164 row_shr:2 row_mask:0xf bank_mask:0xf bound_ctrl:1
	v_add_f32_dpp v165, v165, v165 row_shr:2 row_mask:0xf bank_mask:0xf bound_ctrl:1
	v_add_f32_dpp v162, v162, v162 row_shr:4 row_mask:0xf bank_mask:0xf bound_ctrl:1
	v_add_f32_dpp v163, v163, v163 row_shr:4 row_mask:0xf bank_mask:0xf bound_ctrl:1
	v_add_f32_dpp v164, v164, v164 row_shr:4 row_mask:0xf bank_mask:0xf bound_ctrl:1
	v_add_f32_dpp v165, v165, v165 row_shr:4 row_mask:0xf bank_mask:0xf bound_ctrl:1
	v_add_f32_dpp v162, v162, v162 row_shr:8 row_mask:0xf bank_mask:0xf bound_ctrl:1
	v_add_f32_dpp v163, v163, v163 row_shr:8 row_mask:0xf bank_mask:0xf bound_ctrl:1
	v_add_f32_dpp v164, v164, v164 row_shr:8 row_mask:0xf bank_mask:0xf bound_ctrl:1
	v_add_f32_dpp v165, v165, v165 row_shr:8 row_mask:0xf bank_mask:0xf bound_ctrl:1
	v_add_f32_dpp v162, v162, v162 row_bcast:15 row_mask:0xa bank_mask:0xf
	v_add_f32_dpp v163, v163, v163 row_bcast:15 row_mask:0xa bank_mask:0xf
	v_add_f32_dpp v164, v164, v164 row_bcast:15 row_mask:0xa bank_mask:0xf
	v_add_f32_dpp v165, v165, v165 row_bcast:15 row_mask:0xa bank_mask:0xf
	s_mov_b64 s[98:99], exec
	s_mov_b32 exec_lo, 0x80000000
	s_mov_b32 exec_hi, 0x80000000
	ds_write_b32 v74, v162 offset:64
	ds_write_b32 v74, v163 offset:72
	ds_write_b32 v74, v164 offset:80
	ds_write_b32 v74, v165 offset:88
	s_mov_b64 exec, s[98:99]
	s_waitcnt lgkmcnt(0)
	v_mad_u32_u24 v167, v76, s33, v195
	ds_read_b32 v77, v74 offset:424
	s_waitcnt vmcnt(14)
	v_cvt_scalef32_pk32_f32_fp6 v[0:31], v[196:201], 1.0
	global_load_dwordx2 v[200:201], v167, s[62:63] offset:16
	global_load_dwordx4 v[196:199], v167, s[62:63]
	v_pk_mul_f32 v[246:247], v[0:1], v[96:97]
	v_pk_mul_f32 v[254:255], v[2:3], v[98:99]
	v_pk_mul_f32 v[160:161], v[4:5], v[100:101]
	v_pk_fma_f32 v[246:247], v[6:7], v[102:103], v[246:247]
	v_pk_fma_f32 v[254:255], v[8:9], v[104:105], v[254:255]
	v_pk_fma_f32 v[160:161], v[10:11], v[106:107], v[160:161]
	v_pk_fma_f32 v[246:247], v[12:13], v[108:109], v[246:247]
	v_pk_fma_f32 v[254:255], v[14:15], v[110:111], v[254:255]
	v_pk_fma_f32 v[160:161], v[16:17], v[112:113], v[160:161]
	v_pk_fma_f32 v[246:247], v[18:19], v[114:115], v[246:247]
	v_pk_fma_f32 v[254:255], v[20:21], v[116:117], v[254:255]
	v_pk_fma_f32 v[160:161], v[22:23], v[118:119], v[160:161]
	v_pk_fma_f32 v[246:247], v[24:25], v[120:121], v[246:247]
	v_pk_fma_f32 v[254:255], v[26:27], v[122:123], v[254:255]
	v_pk_fma_f32 v[160:161], v[28:29], v[124:125], v[160:161]
	v_pk_fma_f32 v[246:247], v[30:31], v[126:127], v[246:247]
	v_pk_add_f32 v[254:255], v[254:255], v[160:161]
	s_nop 0
	v_pk_add_f32 v[246:247], v[246:247], v[254:255]
	s_nop 0
	v_add_f32_e32 v162, v246, v247
	s_waitcnt lgkmcnt(0)
; __device__ void peer_gather_phase(const Params& P, int l, bool do_store) {
;     ...
;     auto load_batch = [&](uint2 (&u6)[12], uint2 (&v8)[8], int bt) {
;       const int evs = (bt < 8) ? ev0 : ev1;
;       const int kb = (bt & 7) * 8;
; #pragma unroll
;       for (int pr = 0; pr < 4; ++pr) {
;         const int ea = __builtin_amdgcn_readlane(evs, kb + 2 * pr), eb = __builtin_amdgcn_readlane(evs, kb + 2 * pr + 1);
;         const uint2* up = (const uint2*)(U + (size_t)(uphi ? eb : ea) * 768);
;         u6[3 * pr] = up[0]; u6[3 * pr + 1] = up[1]; u6[3 * pr + 2] = up[2];
;         v8[2 * pr] = *(const uint2*)(V + (size_t)ea * 512);
;         v8[2 * pr + 1] = *(const uint2*)(V + (size_t)eb * 512);
;       }
;     };
;     auto compute_batch = [&](const uint2 (&u6)[12], const uint2 (&v8)[8], int bt) {
;       const int kb = (bt & 7) * 8;
;       float dvec = 0.f;
; #pragma unroll
;       for (int pr = 0; pr < 4; ++pr) {
;         v6u_t qv; qv[0] = u6[3 * pr].x; qv[1] = u6[3 * pr].y; qv[2] = u6[3 * pr + 1].x; qv[3] = u6[3 * pr + 1].y; qv[4] = u6[3 * pr + 2].x; qv[5] = u6[3 * pr + 2].y;
;         const v32f_t wv = __builtin_amdgcn_cvt_scalef32_pk32_f32_fp6(qv, 1.0f);
;         f32x2 a2 = f32x2{0.f, 0.f};
; #pragma unroll
;         for (int i = 0; i < 16; ++i) a2 += f32x2{wv[2 * i], wv[2 * i + 1]} * xu[i];
;         float hs = a2.x + a2.y;
;         hs += dpp_row_shr(hs, 1); hs += dpp_row_shr(hs, 2); hs += dpp_row_shr(hs, 4); hs += dpp_row_shr(hs, 8);
;         hs += __builtin_bit_cast(float, __builtin_amdgcn_update_dpp(0, __builtin_bit_cast(int, hs), 0x142, 0xa, 0xf, false));
;         const float da = __builtin_bit_cast(float, __builtin_amdgcn_readlane(__builtin_bit_cast(int, hs), 31));
;         const float db = __builtin_bit_cast(float, __builtin_amdgcn_readlane(__builtin_bit_cast(int, hs), 63));
;         dvec = (lane == kb + 2 * pr) ? da : dvec;
;         dvec = (lane == kb + 2 * pr + 1) ? db : dvec;
;       }
	v_mad_u32_u24 v167, v77, s33, v195
	ds_read_b32 v76, v74 offset:432
	s_waitcnt vmcnt(14)
	v_cvt_scalef32_pk32_f32_fp6 v[0:31], v[228:233], 1.0
	global_load_dwordx2 v[232:233], v167, s[62:63] offset:16
	global_load_dwordx4 v[228:231], v167, s[62:63]
	v_pk_mul_f32 v[246:247], v[0:1], v[96:97]
	v_pk_mul_f32 v[254:255], v[2:3], v[98:99]
	v_pk_mul_f32 v[160:161], v[4:5], v[100:101]
	v_pk_fma_f32 v[246:247], v[6:7], v[102:103], v[246:247]
	v_pk_fma_f32 v[254:255], v[8:9], v[104:105], v[254:255]
	v_pk_fma_f32 v[160:161], v[10:11], v[106:107], v[160:161]
	v_pk_fma_f32 v[246:247], v[12:13], v[108:109], v[246:247]
	v_pk_fma_f32 v[254:255], v[14:15], v[110:111], v[254:255]
	v_pk_fma_f32 v[160:161], v[16:17], v[112:113], v[160:161]
	v_pk_fma_f32 v[246:247], v[18:19], v[114:115], v[246:247]
	v_pk_fma_f32 v[254:255], v[20:21], v[116:117], v[254:255]
	v_pk_fma_f32 v[160:161], v[22:23], v[118:119], v[160:161]
	v_pk_fma_f32 v[246:247], v[24:25], v[120:121], v[246:247]
	v_pk_fma_f32 v[254:255], v[26:27], v[122:123], v[254:255]
	v_pk_fma_f32 v[160:161], v[28:29], v[124:125], v[160:161]
	v_pk_fma_f32 v[246:247], v[30:31], v[126:127], v[246:247]
	v_pk_add_f32 v[254:255], v[254:255], v[160:161]
	s_nop 0
	v_pk_add_f32 v[246:247], v[246:247], v[254:255]
	s_nop 0
	v_add_f32_e32 v163, v246, v247
	s_waitcnt lgkmcnt(0)
	v_mad_u32_u24 v167, v76, s33, v195
	ds_read_b32 v77, v74 offset:440
	s_waitcnt vmcnt(14)
	v_cvt_scalef32_pk32_f32_fp6 v[0:31], v[234:239], 1.0
	global_load_dwordx2 v[238:239], v167, s[62:63] offset:16
	global_load_dwordx4 v[234:237], v167, s[62:63]
	v_pk_mul_f32 v[246:247], v[0:1], v[96:97]
	v_pk_mul_f32 v[254:255], v[2:3], v[98:99]
	v_pk_mul_f32 v[160:161], v[4:5], v[100:101]
	v_pk_fma_f32 v[246:247], v[6:7], v[102:103], v[246:247]
	v_pk_fma_f32 v[254:255], v[8:9], v[104:105], v[254:255]
	v_pk_fma_f32 v[160:161], v[10:11], v[106:107], v[160:161]
	v_pk_fma_f32 v[246:247], v[12:13], v[108:109], v[246:247]
	v_pk_fma_f32 v[254:255], v[14:15], v[110:111], v[254:255]
	v_pk_fma_f32 v[160:161], v[16:17], v[112:113], v[160:161]
	v_pk_fma_f32 v[246:247], v[18:19], v[114:115], v[246:247]
	v_pk_fma_f32 v[254:255], v[20:21], v[116:117], v[254:255]
	v_pk_fma_f32 v[160:161], v[22:23], v[118:119], v[160:161]
	v_pk_fma_f32 v[246:247], v[24:25], v[120:121], v[246:247]
	v_pk_fma_f32 v[254:255], v[26:27], v[122:123], v[254:255]
	v_pk_fma_f32 v[160:161], v[28:29], v[124:125], v[160:161]
	v_pk_fma_f32 v[246:247], v[30:31], v[126:127], v[246:247]
	v_pk_add_f32 v[254:255], v[254:255], v[160:161]
	s_nop 0
	v_pk_add_f32 v[246:247], v[246:247], v[254:255]
	s_nop 0
	v_add_f32_e32 v164, v246, v247
	s_waitcnt lgkmcnt(0)
	v_mad_u32_u24 v167, v77, s33, v195
	ds_read_b32 v76, v74 offset:448
	s_waitcnt vmcnt(14)
	v_cvt_scalef32_pk32_f32_fp6 v[0:31], v[240:245], 1.0
	global_load_dwordx2 v[244:245], v167, s[62:63] offset:16
	global_load_dwordx4 v[240:243], v167, s[62:63]
	v_pk_mul_f32 v[246:247], v[0:1], v[96:97]
	v_pk_mul_f32 v[254:255], v[2:3], v[98:99]
	v_pk_mul_f32 v[160:161], v[4:5], v[100:101]
	v_pk_fma_f32 v[246:247], v[6:7], v[102:103], v[246:247]
	v_pk_fma_f32 v[254:255], v[8:9], v[104:105], v[254:255]
	v_pk_fma_f32 v[160:161], v[10:11], v[106:107], v[160:161]
	v_pk_fma_f32 v[246:247], v[12:13], v[108:109], v[246:247]
	v_pk_fma_f32 v[254:255], v[14:15], v[110:111], v[254:255]
	v_pk_fma_f32 v[160:161], v[16:17], v[112:113], v[160:161]
	v_pk_fma_f32 v[246:247], v[18:19], v[114:115], v[246:247]
	v_pk_fma_f32 v[254:255], v[20:21], v[116:117], v[254:255]
	v_pk_fma_f32 v[160:161], v[22:23], v[118:119], v[160:161]
	v_pk_fma_f32 v[246:247], v[24:25], v[120:121], v[246:247]
	v_pk_fma_f32 v[254:255], v[26:27], v[122:123], v[254:255]
	v_pk_fma_f32 v[160:161], v[28:29], v[124:125], v[160:161]
	v_pk_fma_f32 v[246:247], v[30:31], v[126:127], v[246:247]
	v_pk_add_f32 v[254:255], v[254:255], v[160:161]
	s_nop 0
	v_pk_add_f32 v[246:247], v[246:247], v[254:255]
	s_nop 0
	v_add_f32_e32 v165, v246, v247
	v_add_f32_dpp v162, v162, v162 row_shr:1 row_mask:0xf bank_mask:0xf bound_ctrl:1
	v_add_f32_dpp v163, v163, v163 row_shr:1 row_mask:0xf bank_mask:0xf bound_ctrl:1
	v_add_f32_dpp v164, v164, v164 row_shr:1 row_mask:0xf bank_mask:0xf bound_ctrl:1
	v_add_f32_dpp v165, v165, v165 row_shr:1 row_mask:0xf bank_mask:0xf bound_ctrl:1
	v_add_f32_dpp v162, v162, v162 row_shr:2 row_mask:0xf bank_mask:0xf bound_ctrl:1
	v_add_f32_dpp v163, v163, v163 row_shr:2 row_mask:0xf bank_mask:0xf bound_ctrl:1
	v_add_f32_dpp v164, v164, v164 row_shr:2 row_mask:0xf bank_mask:0xf bound_ctrl:1
	v_add_f32_dpp v165, v165, v165 row_shr:2 row_mask:0xf bank_mask:0xf bound_ctrl:1
	v_add_f32_dpp v162, v162, v162 row_shr:4 row_mask:0xf bank_mask:0xf bound_ctrl:1
	v_add_f32_dpp v163, v163, v163 row_shr:4 row_mask:0xf bank_mask:0xf bound_ctrl:1
	v_add_f32_dpp v164, v164, v164 row_shr:4 row_mask:0xf bank_mask:0xf bound_ctrl:1
	v_add_f32_dpp v165, v165, v165 row_shr:4 row_mask:0xf bank_mask:0xf bound_ctrl:1
	v_add_f32_dpp v162, v162, v162 row_shr:8 row_mask:0xf bank_mask:0xf bound_ctrl:1
	v_add_f32_dpp v163, v163, v163 row_shr:8 row_mask:0xf bank_mask:0xf bound_ctrl:1
	v_add_f32_dpp v164, v164, v164 row_shr:8 row_mask:0xf bank_mask:0xf bound_ctrl:1
	v_add_f32_dpp v165, v165, v165 row_shr:8 row_mask:0xf bank_mask:0xf bound_ctrl:1
	v_add_f32_dpp v162, v162, v162 row_bcast:15 row_mask:0xa bank_mask:0xf
	v_add_f32_dpp v163, v163, v163 row_bcast:15 row_mask:0xa bank_mask:0xf
	v_add_f32_dpp v164, v164, v164 row_bcast:15 row_mask:0xa bank_mask:0xf
	v_add_f32_dpp v165, v165, v165 row_bcast:15 row_mask:0xa bank_mask:0xf
	s_mov_b64 s[98:99], exec
	s_mov_b32 exec_lo, 0x80000000
	s_mov_b32 exec_hi, 0x80000000
	ds_write_b32 v74, v162 offset:96
	ds_write_b32 v74, v163 offset:104
	ds_write_b32 v74, v164 offset:112
	ds_write_b32 v74, v165 offset:120
	s_mov_b64 exec, s[98:99]
	s_waitcnt lgkmcnt(0)
; __device__ void peer_gather_phase(const Params& P, int l, bool do_store) {
;     ...
;     auto load_batch = [&](uint2 (&u6)[12], uint2 (&v8)[8], int bt) {
;       const int evs = (bt < 8) ? ev0 : ev1;
;       const int kb = (bt & 7) * 8;
; #pragma unroll
;       for (int pr = 0; pr < 4; ++pr) {
;         const int ea = __builtin_amdgcn_readlane(evs, kb + 2 * pr), eb = __builtin_amdgcn_readlane(evs, kb + 2 * pr + 1);
;         const uint2* up = (const uint2*)(U + (size_t)(uphi ? eb : ea) * 768);
;         u6[3 * pr] = up[0]; u6[3 * pr + 1] = up[1]; u6[3 * pr + 2] = up[2];
;         v8[2 * pr] = *(const uint2*)(V + (size_t)ea * 512);
;         v8[2 * pr + 1] = *(const uint2*)(V + (size_t)eb * 512);
;       }
;     };
;     auto compute_batch = [&](const uint2 (&u6)[12], const uint2 (&v8)[8], int bt) {
;       const int kb = (bt & 7) * 8;
;       float dvec = 0.f;
; #pragma unroll
;       for (int pr = 0; pr < 4; ++pr) {
;         v6u_t qv; qv[0] = u6[3 * pr].x; qv[1] = u6[3 * pr].y; qv[2] = u6[3 * pr + 1].x; qv[3] = u6[3 * pr + 1].y; qv[4] = u6[3 * pr + 2].x; qv[5] = u6[3 * pr + 2].y;
;         const v32f_t wv = __builtin_amdgcn_cvt_scalef32_pk32_f32_fp6(qv, 1.0f);
;         f32x2 a2 = f32x2{0.f, 0.f};
; #pragma unroll
;         for (int i = 0; i < 16; ++i) a2 += f32x2{wv[2 * i], wv[2 * i + 1]} * xu[i];
;         float hs = a2.x + a2.y;
;         hs += dpp_row_shr(hs, 1); hs += dpp_row_shr(hs, 2); hs += dpp_row_shr(hs, 4); hs += dpp_row_shr(hs, 8);
;         hs += __builtin_bit_cast(float, __builtin_amdgcn_update_dpp(0, __builtin_bit_cast(int, hs), 0x142, 0xa, 0xf, false));
;         const float da = __builtin_bit_cast(float, __builtin_amdgcn_readlane(__builtin_bit_cast(int, hs), 31));
;         const float db = __builtin_bit_cast(float, __builtin_amdgcn_readlane(__builtin_bit_cast(int, hs), 63));
;         dvec = (lane == kb + 2 * pr) ? da : dvec;
;         dvec = (lane == kb + 2 * pr + 1) ? db : dvec;
;       }
	v_mad_u32_u24 v167, v76, s33, v195
	ds_read_b32 v77, v74 offset:456
	s_waitcnt vmcnt(14)
	v_cvt_scalef32_pk32_f32_fp6 v[0:31], v[50:55], 1.0
	global_load_dwordx2 v[54:55], v167, s[62:63] offset:16
	global_load_dwordx4 v[50:53], v167, s[62:63]
	v_pk_mul_f32 v[246:247], v[0:1], v[96:97]
	v_pk_mul_f32 v[254:255], v[2:3], v[98:99]
	v_pk_mul_f32 v[160:161], v[4:5], v[100:101]
	v_pk_fma_f32 v[246:247], v[6:7], v[102:103], v[246:247]
	v_pk_fma_f32 v[254:255], v[8:9], v[104:105], v[254:255]
	v_pk_fma_f32 v[160:161], v[10:11], v[106:107], v[160:161]
	v_pk_fma_f32 v[246:247], v[12:13], v[108:109], v[246:247]
	v_pk_fma_f32 v[254:255], v[14:15], v[110:111], v[254:255]
	v_pk_fma_f32 v[160:161], v[16:17], v[112:113], v[160:161]
	v_pk_fma_f32 v[246:247], v[18:19], v[114:115], v[246:247]
	v_pk_fma_f32 v[254:255], v[20:21], v[116:117], v[254:255]
	v_pk_fma_f32 v[160:161], v[22:23], v[118:119], v[160:161]
	v_pk_fma_f32 v[246:247], v[24:25], v[120:121], v[246:247]
	v_pk_fma_f32 v[254:255], v[26:27], v[122:123], v[254:255]
	v_pk_fma_f32 v[160:161], v[28:29], v[124:125], v[160:161]
	v_pk_fma_f32 v[246:247], v[30:31], v[126:127], v[246:247]
	v_pk_add_f32 v[254:255], v[254:255], v[160:161]
	s_nop 0
	v_pk_add_f32 v[246:247], v[246:247], v[254:255]
	s_nop 0
	v_add_f32_e32 v162, v246, v247
	s_waitcnt lgkmcnt(0)
	v_mad_u32_u24 v167, v77, s33, v195
	ds_read_b32 v76, v74 offset:464
	s_waitcnt vmcnt(14)
	v_cvt_scalef32_pk32_f32_fp6 v[0:31], v[44:49], 1.0
	global_load_dwordx2 v[48:49], v167, s[62:63] offset:16
	global_load_dwordx4 v[44:47], v167, s[62:63]
	v_pk_mul_f32 v[246:247], v[0:1], v[96:97]
	v_pk_mul_f32 v[254:255], v[2:3], v[98:99]
	v_pk_mul_f32 v[160:161], v[4:5], v[100:101]
	v_pk_fma_f32 v[246:247], v[6:7], v[102:103], v[246:247]
	v_pk_fma_f32 v[254:255], v[8:9], v[104:105], v[254:255]
	v_pk_fma_f32 v[160:161], v[10:11], v[106:107], v[160:161]
	v_pk_fma_f32 v[246:247], v[12:13], v[108:109], v[246:247]
	v_pk_fma_f32 v[254:255], v[14:15], v[110:111], v[254:255]
	v_pk_fma_f32 v[160:161], v[16:17], v[112:113], v[160:161]
	v_pk_fma_f32 v[246:247], v[18:19], v[114:115], v[246:247]
	v_pk_fma_f32 v[254:255], v[20:21], v[116:117], v[254:255]
	v_pk_fma_f32 v[160:161], v[22:23], v[118:119], v[160:161]
	v_pk_fma_f32 v[246:247], v[24:25], v[120:121], v[246:247]
	v_pk_fma_f32 v[254:255], v[26:27], v[122:123], v[254:255]
	v_pk_fma_f32 v[160:161], v[28:29], v[124:125], v[160:161]
	v_pk_fma_f32 v[246:247], v[30:31], v[126:127], v[246:247]
	v_pk_add_f32 v[254:255], v[254:255], v[160:161]
	s_nop 0
	v_pk_add_f32 v[246:247], v[246:247], v[254:255]
	s_nop 0
	v_add_f32_e32 v163, v246, v247
	s_waitcnt lgkmcnt(0)
	v_mad_u32_u24 v167, v76, s33, v195
	ds_read_b32 v77, v74 offset:472
	s_waitcnt vmcnt(14)
	v_cvt_scalef32_pk32_f32_fp6 v[0:31], v[38:43], 1.0
	global_load_dwordx2 v[42:43], v167, s[62:63] offset:16
	global_load_dwordx4 v[38:41], v167, s[62:63]
	v_pk_mul_f32 v[246:247], v[0:1], v[96:97]
	v_pk_mul_f32 v[254:255], v[2:3], v[98:99]
	v_pk_mul_f32 v[160:161], v[4:5], v[100:101]
	v_pk_fma_f32 v[246:247], v[6:7], v[102:103], v[246:247]
	v_pk_fma_f32 v[254:255], v[8:9], v[104:105], v[254:255]
	v_pk_fma_f32 v[160:161], v[10:11], v[106:107], v[160:161]
	v_pk_fma_f32 v[246:247], v[12:13], v[108:109], v[246:247]
	v_pk_fma_f32 v[254:255], v[14:15], v[110:111], v[254:255]
	v_pk_fma_f32 v[160:161], v[16:17], v[112:113], v[160:161]
	v_pk_fma_f32 v[246:247], v[18:19], v[114:115], v[246:247]
	v_pk_fma_f32 v[254:255], v[20:21], v[116:117], v[254:255]
	v_pk_fma_f32 v[160:161], v[22:23], v[118:119], v[160:161]
	v_pk_fma_f32 v[246:247], v[24:25], v[120:121], v[246:247]
	v_pk_fma_f32 v[254:255], v[26:27], v[122:123], v[254:255]
	v_pk_fma_f32 v[160:161], v[28:29], v[124:125], v[160:161]
	v_pk_fma_f32 v[246:247], v[30:31], v[126:127], v[246:247]
	v_pk_add_f32 v[254:255], v[254:255], v[160:161]
	s_nop 0
	v_pk_add_f32 v[246:247], v[246:247], v[254:255]
	s_nop 0
	v_add_f32_e32 v164, v246, v247
	s_waitcnt lgkmcnt(0)
	v_mad_u32_u24 v167, v77, s33, v195
	ds_read_b32 v76, v74 offset:480
	s_waitcnt vmcnt(14)
	v_cvt_scalef32_pk32_f32_fp6 v[0:31], v[32:37], 1.0
	global_load_dwordx2 v[36:37], v167, s[62:63] offset:16
	global_load_dwordx4 v[32:35], v167, s[62:63]
	v_pk_mul_f32 v[246:247], v[0:1], v[96:97]
	v_pk_mul_f32 v[254:255], v[2:3], v[98:99]
	v_pk_mul_f32 v[160:161], v[4:5], v[100:101]
	v_pk_fma_f32 v[246:247], v[6:7], v[102:103], v[246:247]
	v_pk_fma_f32 v[254:255], v[8:9], v[104:105], v[254:255]
	v_pk_fma_f32 v[160:161], v[10:11], v[106:107], v[160:161]
	v_pk_fma_f32 v[246:247], v[12:13], v[108:109], v[246:247]
	v_pk_fma_f32 v[254:255], v[14:15], v[110:111], v[254:255]
	v_pk_fma_f32 v[160:161], v[16:17], v[112:113], v[160:161]
	v_pk_fma_f32 v[246:247], v[18:19], v[114:115], v[246:247]
	v_pk_fma_f32 v[254:255], v[20:21], v[116:117], v[254:255]
	v_pk_fma_f32 v[160:161], v[22:23], v[118:119], v[160:161]
	v_pk_fma_f32 v[246:247], v[24:25], v[120:121], v[246:247]
	v_pk_fma_f32 v[254:255], v[26:27], v[122:123], v[254:255]
	v_pk_fma_f32 v[160:161], v[28:29], v[124:125], v[160:161]
	v_pk_fma_f32 v[246:247], v[30:31], v[126:127], v[246:247]
	v_pk_add_f32 v[254:255], v[254:255], v[160:161]
	s_nop 0
	v_pk_add_f32 v[246:247], v[246:247], v[254:255]
	s_nop 0
	v_add_f32_e32 v165, v246, v247
	v_add_f32_dpp v162, v162, v162 row_shr:1 row_mask:0xf bank_mask:0xf bound_ctrl:1
	v_add_f32_dpp v163, v163, v163 row_shr:1 row_mask:0xf bank_mask:0xf bound_ctrl:1
	v_add_f32_dpp v164, v164, v164 row_shr:1 row_mask:0xf bank_mask:0xf bound_ctrl:1
	v_add_f32_dpp v165, v165, v165 row_shr:1 row_mask:0xf bank_mask:0xf bound_ctrl:1
	v_add_f32_dpp v162, v162, v162 row_shr:2 row_mask:0xf bank_mask:0xf bound_ctrl:1
; __device__ void peer_gather_phase(const Params& P, int l, bool do_store) {
;     ...
;     auto load_batch = [&](uint2 (&u6)[12], uint2 (&v8)[8], int bt) {
;       const int evs = (bt < 8) ? ev0 : ev1;
;       const int kb = (bt & 7) * 8;
; #pragma unroll
;       for (int pr = 0; pr < 4; ++pr) {
;         const int ea = __builtin_amdgcn_readlane(evs, kb + 2 * pr), eb = __builtin_amdgcn_readlane(evs, kb + 2 * pr + 1);
;         const uint2* up = (const uint2*)(U + (size_t)(uphi ? eb : ea) * 768);
;         u6[3 * pr] = up[0]; u6[3 * pr + 1] = up[1]; u6[3 * pr + 2] = up[2];
;         v8[2 * pr] = *(const uint2*)(V + (size_t)ea * 512);
;         v8[2 * pr + 1] = *(const uint2*)(V + (size_t)eb * 512);
;       }
;     };
;     auto compute_batch = [&](const uint2 (&u6)[12], const uint2 (&v8)[8], int bt) {
;       const int kb = (bt & 7) * 8;
;       float dvec = 0.f;
; #pragma unroll
;       for (int pr = 0; pr < 4; ++pr) {
;         v6u_t qv; qv[0] = u6[3 * pr].x; qv[1] = u6[3 * pr].y; qv[2] = u6[3 * pr + 1].x; qv[3] = u6[3 * pr + 1].y; qv[4] = u6[3 * pr + 2].x; qv[5] = u6[3 * pr + 2].y;
;         const v32f_t wv = __builtin_amdgcn_cvt_scalef32_pk32_f32_fp6(qv, 1.0f);
;         f32x2 a2 = f32x2{0.f, 0.f};
; #pragma unroll
;         for (int i = 0; i < 16; ++i) a2 += f32x2{wv[2 * i], wv[2 * i + 1]} * xu[i];
;         float hs = a2.x + a2.y;
;         hs += dpp_row_shr(hs, 1); hs += dpp_row_shr(hs, 2); hs += dpp_row_shr(hs, 4); hs += dpp_row_shr(hs, 8);
;         hs += __builtin_bit_cast(float, __builtin_amdgcn_update_dpp(0, __builtin_bit_cast(int, hs), 0x142, 0xa, 0xf, false));
;         const float da = __builtin_bit_cast(float, __builtin_amdgcn_readlane(__builtin_bit_cast(int, hs), 31));
;         const float db = __builtin_bit_cast(float, __builtin_amdgcn_readlane(__builtin_bit_cast(int, hs), 63));
;         dvec = (lane == kb + 2 * pr) ? da : dvec;
;         dvec = (lane == kb + 2 * pr + 1) ? db : dvec;
;       }
	v_add_f32_dpp v163, v163, v163 row_shr:2 row_mask:0xf bank_mask:0xf bound_ctrl:1
	v_add_f32_dpp v164, v164, v164 row_shr:2 row_mask:0xf bank_mask:0xf bound_ctrl:1
	v_add_f32_dpp v165, v165, v165 row_shr:2 row_mask:0xf bank_mask:0xf bound_ctrl:1
	v_add_f32_dpp v162, v162, v162 row_shr:4 row_mask:0xf bank_mask:0xf bound_ctrl:1
	v_add_f32_dpp v163, v163, v163 row_shr:4 row_mask:0xf bank_mask:0xf bound_ctrl:1
	v_add_f32_dpp v164, v164, v164 row_shr:4 row_mask:0xf bank_mask:0xf bound_ctrl:1
	v_add_f32_dpp v165, v165, v165 row_shr:4 row_mask:0xf bank_mask:0xf bound_ctrl:1
	v_add_f32_dpp v162, v162, v162 row_shr:8 row_mask:0xf bank_mask:0xf bound_ctrl:1
	v_add_f32_dpp v163, v163, v163 row_shr:8 row_mask:0xf bank_mask:0xf bound_ctrl:1
	v_add_f32_dpp v164, v164, v164 row_shr:8 row_mask:0xf bank_mask:0xf bound_ctrl:1
	v_add_f32_dpp v165, v165, v165 row_shr:8 row_mask:0xf bank_mask:0xf bound_ctrl:1
	v_add_f32_dpp v162, v162, v162 row_bcast:15 row_mask:0xa bank_mask:0xf
	v_add_f32_dpp v163, v163, v163 row_bcast:15 row_mask:0xa bank_mask:0xf
	v_add_f32_dpp v164, v164, v164 row_bcast:15 row_mask:0xa bank_mask:0xf
	v_add_f32_dpp v165, v165, v165 row_bcast:15 row_mask:0xa bank_mask:0xf
	s_mov_b64 s[98:99], exec
	s_mov_b32 exec_lo, 0x80000000
	s_mov_b32 exec_hi, 0x80000000
	ds_write_b32 v74, v162 offset:128
	ds_write_b32 v74, v163 offset:136
	ds_write_b32 v74, v164 offset:144
	ds_write_b32 v74, v165 offset:152
	s_mov_b64 exec, s[98:99]
	s_waitcnt lgkmcnt(0)
	v_mad_u32_u24 v167, v76, s33, v195
	ds_read_b32 v77, v74 offset:488
	s_waitcnt vmcnt(14)
	v_cvt_scalef32_pk32_f32_fp6 v[0:31], v[196:201], 1.0
	global_load_dwordx2 v[200:201], v167, s[62:63] offset:16
	global_load_dwordx4 v[196:199], v167, s[62:63]
	v_pk_mul_f32 v[246:247], v[0:1], v[96:97]
	v_pk_mul_f32 v[254:255], v[2:3], v[98:99]
	v_pk_mul_f32 v[160:161], v[4:5], v[100:101]
	v_pk_fma_f32 v[246:247], v[6:7], v[102:103], v[246:247]
	v_pk_fma_f32 v[254:255], v[8:9], v[104:105], v[254:255]
	v_pk_fma_f32 v[160:161], v[10:11], v[106:107], v[160:161]
	v_pk_fma_f32 v[246:247], v[12:13], v[108:109], v[246:247]
	v_pk_fma_f32 v[254:255], v[14:15], v[110:111], v[254:255]
	v_pk_fma_f32 v[160:161], v[16:17], v[112:113], v[160:161]
	v_pk_fma_f32 v[246:247], v[18:19], v[114:115], v[246:247]
	v_pk_fma_f32 v[254:255], v[20:21], v[116:117], v[254:255]
	v_pk_fma_f32 v[160:161], v[22:23], v[118:119], v[160:161]
	v_pk_fma_f32 v[246:247], v[24:25], v[120:121], v[246:247]
	v_pk_fma_f32 v[254:255], v[26:27], v[122:123], v[254:255]
	v_pk_fma_f32 v[160:161], v[28:29], v[124:125], v[160:161]
	v_pk_fma_f32 v[246:247], v[30:31], v[126:127], v[246:247]
	v_pk_add_f32 v[254:255], v[254:255], v[160:161]
	s_nop 0
	v_pk_add_f32 v[246:247], v[246:247], v[254:255]
	s_nop 0
	v_add_f32_e32 v162, v246, v247
	s_waitcnt lgkmcnt(0)
	v_mad_u32_u24 v167, v77, s33, v195
	ds_read_b32 v76, v74 offset:496
	s_waitcnt vmcnt(14)
	v_cvt_scalef32_pk32_f32_fp6 v[0:31], v[228:233], 1.0
	global_load_dwordx2 v[232:233], v167, s[62:63] offset:16
	global_load_dwordx4 v[228:231], v167, s[62:63]
	v_pk_mul_f32 v[246:247], v[0:1], v[96:97]
	v_pk_mul_f32 v[254:255], v[2:3], v[98:99]
	v_pk_mul_f32 v[160:161], v[4:5], v[100:101]
	v_pk_fma_f32 v[246:247], v[6:7], v[102:103], v[246:247]
	v_pk_fma_f32 v[254:255], v[8:9], v[104:105], v[254:255]
	v_pk_fma_f32 v[160:161], v[10:11], v[106:107], v[160:161]
	v_pk_fma_f32 v[246:247], v[12:13], v[108:109], v[246:247]
	v_pk_fma_f32 v[254:255], v[14:15], v[110:111], v[254:255]
	v_pk_fma_f32 v[160:161], v[16:17], v[112:113], v[160:161]
	v_pk_fma_f32 v[246:247], v[18:19], v[114:115], v[246:247]
	v_pk_fma_f32 v[254:255], v[20:21], v[116:117], v[254:255]
	v_pk_fma_f32 v[160:161], v[22:23], v[118:119], v[160:161]
	v_pk_fma_f32 v[246:247], v[24:25], v[120:121], v[246:247]
	v_pk_fma_f32 v[254:255], v[26:27], v[122:123], v[254:255]
	v_pk_fma_f32 v[160:161], v[28:29], v[124:125], v[160:161]
	v_pk_fma_f32 v[246:247], v[30:31], v[126:127], v[246:247]
	v_pk_add_f32 v[254:255], v[254:255], v[160:161]
	s_nop 0
	v_pk_add_f32 v[246:247], v[246:247], v[254:255]
	s_nop 0
	v_add_f32_e32 v163, v246, v247
	s_waitcnt lgkmcnt(0)
	v_mad_u32_u24 v167, v76, s33, v195
	ds_read_b32 v77, v74 offset:504
	s_waitcnt vmcnt(14)
	v_cvt_scalef32_pk32_f32_fp6 v[0:31], v[234:239], 1.0
	global_load_dwordx2 v[238:239], v167, s[62:63] offset:16
	global_load_dwordx4 v[234:237], v167, s[62:63]
	v_pk_mul_f32 v[246:247], v[0:1], v[96:97]
	v_pk_mul_f32 v[254:255], v[2:3], v[98:99]
	v_pk_mul_f32 v[160:161], v[4:5], v[100:101]
	v_pk_fma_f32 v[246:247], v[6:7], v[102:103], v[246:247]
	v_pk_fma_f32 v[254:255], v[8:9], v[104:105], v[254:255]
	v_pk_fma_f32 v[160:161], v[10:11], v[106:107], v[160:161]
	v_pk_fma_f32 v[246:247], v[12:13], v[108:109], v[246:247]
	v_pk_fma_f32 v[254:255], v[14:15], v[110:111], v[254:255]
	v_pk_fma_f32 v[160:161], v[16:17], v[112:113], v[160:161]
	v_pk_fma_f32 v[246:247], v[18:19], v[114:115], v[246:247]
	v_pk_fma_f32 v[254:255], v[20:21], v[116:117], v[254:255]
	v_pk_fma_f32 v[160:161], v[22:23], v[118:119], v[160:161]
	v_pk_fma_f32 v[246:247], v[24:25], v[120:121], v[246:247]
	v_pk_fma_f32 v[254:255], v[26:27], v[122:123], v[254:255]
	v_pk_fma_f32 v[160:161], v[28:29], v[124:125], v[160:161]
	v_pk_fma_f32 v[246:247], v[30:31], v[126:127], v[246:247]
	v_pk_add_f32 v[254:255], v[254:255], v[160:161]
	s_nop 0
	v_pk_add_f32 v[246:247], v[246:247], v[254:255]
	s_nop 0
	v_add_f32_e32 v164, v246, v247
	s_waitcnt lgkmcnt(0)
	v_mad_u32_u24 v167, v77, s33, v195
	s_waitcnt vmcnt(14)
; __device__ void peer_gather_phase(const Params& P, int l, bool do_store) {
;     ...
;     auto load_batch = [&](uint2 (&u6)[12], uint2 (&v8)[8], int bt) {
;       const int evs = (bt < 8) ? ev0 : ev1;
;       const int kb = (bt & 7) * 8;
; #pragma unroll
;       for (int pr = 0; pr < 4; ++pr) {
;         const int ea = __builtin_amdgcn_readlane(evs, kb + 2 * pr), eb = __builtin_amdgcn_readlane(evs, kb + 2 * pr + 1);
;         const uint2* up = (const uint2*)(U + (size_t)(uphi ? eb : ea) * 768);
;         u6[3 * pr] = up[0]; u6[3 * pr + 1] = up[1]; u6[3 * pr + 2] = up[2];
;         v8[2 * pr] = *(const uint2*)(V + (size_t)ea * 512);
;         v8[2 * pr + 1] = *(const uint2*)(V + (size_t)eb * 512);
;       }
;     };
;     auto compute_batch = [&](const uint2 (&u6)[12], const uint2 (&v8)[8], int bt) {
;       const int kb = (bt & 7) * 8;
;       float dvec = 0.f;
; #pragma unroll
;       for (int pr = 0; pr < 4; ++pr) {
;         v6u_t qv; qv[0] = u6[3 * pr].x; qv[1] = u6[3 * pr].y; qv[2] = u6[3 * pr + 1].x; qv[3] = u6[3 * pr + 1].y; qv[4] = u6[3 * pr + 2].x; qv[5] = u6[3 * pr + 2].y;
;         const v32f_t wv = __builtin_amdgcn_cvt_scalef32_pk32_f32_fp6(qv, 1.0f);
;         f32x2 a2 = f32x2{0.f, 0.f};
; #pragma unroll
;         for (int i = 0; i < 16; ++i) a2 += f32x2{wv[2 * i], wv[2 * i + 1]} * xu[i];
;         float hs = a2.x + a2.y;
;         hs += dpp_row_shr(hs, 1); hs += dpp_row_shr(hs, 2); hs += dpp_row_shr(hs, 4); hs += dpp_row_shr(hs, 8);
;         hs += __builtin_bit_cast(float, __builtin_amdgcn_update_dpp(0, __builtin_bit_cast(int, hs), 0x142, 0xa, 0xf, false));
;         const float da = __builtin_bit_cast(float, __builtin_amdgcn_readlane(__builtin_bit_cast(int, hs), 31));
;         const float db = __builtin_bit_cast(float, __builtin_amdgcn_readlane(__builtin_bit_cast(int, hs), 63));
;         dvec = (lane == kb + 2 * pr) ? da : dvec;
;         dvec = (lane == kb + 2 * pr + 1) ? db : dvec;
;       }
	v_cvt_scalef32_pk32_f32_fp6 v[0:31], v[240:245], 1.0
	global_load_dwordx2 v[244:245], v167, s[62:63] offset:16
	global_load_dwordx4 v[240:243], v167, s[62:63]
	v_pk_mul_f32 v[246:247], v[0:1], v[96:97]
	v_pk_mul_f32 v[254:255], v[2:3], v[98:99]
	v_pk_mul_f32 v[160:161], v[4:5], v[100:101]
	v_pk_fma_f32 v[246:247], v[6:7], v[102:103], v[246:247]
	v_pk_fma_f32 v[254:255], v[8:9], v[104:105], v[254:255]
	v_pk_fma_f32 v[160:161], v[10:11], v[106:107], v[160:161]
	v_pk_fma_f32 v[246:247], v[12:13], v[108:109], v[246:247]
	v_pk_fma_f32 v[254:255], v[14:15], v[110:111], v[254:255]
	v_pk_fma_f32 v[160:161], v[16:17], v[112:113], v[160:161]
	v_pk_fma_f32 v[246:247], v[18:19], v[114:115], v[246:247]
	v_pk_fma_f32 v[254:255], v[20:21], v[116:117], v[254:255]
	v_pk_fma_f32 v[160:161], v[22:23], v[118:119], v[160:161]
	v_pk_fma_f32 v[246:247], v[24:25], v[120:121], v[246:247]
	v_pk_fma_f32 v[254:255], v[26:27], v[122:123], v[254:255]
	v_pk_fma_f32 v[160:161], v[28:29], v[124:125], v[160:161]
	v_pk_fma_f32 v[246:247], v[30:31], v[126:127], v[246:247]
	v_pk_add_f32 v[254:255], v[254:255], v[160:161]
	s_nop 0
	v_pk_add_f32 v[246:247], v[246:247], v[254:255]
	s_nop 0
	v_add_f32_e32 v165, v246, v247
	v_add_f32_dpp v162, v162, v162 row_shr:1 row_mask:0xf bank_mask:0xf bound_ctrl:1
	v_add_f32_dpp v163, v163, v163 row_shr:1 row_mask:0xf bank_mask:0xf bound_ctrl:1
	v_add_f32_dpp v164, v164, v164 row_shr:1 row_mask:0xf bank_mask:0xf bound_ctrl:1
	v_add_f32_dpp v165, v165, v165 row_shr:1 row_mask:0xf bank_mask:0xf bound_ctrl:1
	v_add_f32_dpp v162, v162, v162 row_shr:2 row_mask:0xf bank_mask:0xf bound_ctrl:1
	v_add_f32_dpp v163, v163, v163 row_shr:2 row_mask:0xf bank_mask:0xf bound_ctrl:1
	v_add_f32_dpp v164, v164, v164 row_shr:2 row_mask:0xf bank_mask:0xf bound_ctrl:1
	v_add_f32_dpp v165, v165, v165 row_shr:2 row_mask:0xf bank_mask:0xf bound_ctrl:1
	v_add_f32_dpp v162, v162, v162 row_shr:4 row_mask:0xf bank_mask:0xf bound_ctrl:1
	v_add_f32_dpp v163, v163, v163 row_shr:4 row_mask:0xf bank_mask:0xf bound_ctrl:1
	v_add_f32_dpp v164, v164, v164 row_shr:4 row_mask:0xf bank_mask:0xf bound_ctrl:1
	v_add_f32_dpp v165, v165, v165 row_shr:4 row_mask:0xf bank_mask:0xf bound_ctrl:1
	v_add_f32_dpp v162, v162, v162 row_shr:8 row_mask:0xf bank_mask:0xf bound_ctrl:1
	v_add_f32_dpp v163, v163, v163 row_shr:8 row_mask:0xf bank_mask:0xf bound_ctrl:1
	v_add_f32_dpp v164, v164, v164 row_shr:8 row_mask:0xf bank_mask:0xf bound_ctrl:1
	v_add_f32_dpp v165, v165, v165 row_shr:8 row_mask:0xf bank_mask:0xf bound_ctrl:1
	v_add_f32_dpp v162, v162, v162 row_bcast:15 row_mask:0xa bank_mask:0xf
	v_add_f32_dpp v163, v163, v163 row_bcast:15 row_mask:0xa bank_mask:0xf
	v_add_f32_dpp v164, v164, v164 row_bcast:15 row_mask:0xa bank_mask:0xf
	v_add_f32_dpp v165, v165, v165 row_bcast:15 row_mask:0xa bank_mask:0xf
	s_mov_b64 s[98:99], exec
	s_mov_b32 exec_lo, 0x80000000
	s_mov_b32 exec_hi, 0x80000000
	ds_write_b32 v74, v162 offset:160
	ds_write_b32 v74, v163 offset:168
	ds_write_b32 v74, v164 offset:176
	ds_write_b32 v74, v165 offset:184
	s_mov_b64 exec, s[98:99]
	ds_write_b32 v75, v90 offset:256
	ds_read_b32 v76, v74 offset:256
	s_waitcnt lgkmcnt(0)
	v_mad_u32_u24 v167, v76, s33, v195
	ds_read_b32 v77, v74 offset:264
	s_waitcnt vmcnt(14)
	v_cvt_scalef32_pk32_f32_fp6 v[0:31], v[50:55], 1.0
	global_load_dwordx2 v[54:55], v167, s[62:63] offset:16
	global_load_dwordx4 v[50:53], v167, s[62:63]
	v_pk_mul_f32 v[246:247], v[0:1], v[96:97]
	v_pk_mul_f32 v[254:255], v[2:3], v[98:99]
	v_pk_mul_f32 v[160:161], v[4:5], v[100:101]
	v_pk_fma_f32 v[246:247], v[6:7], v[102:103], v[246:247]
	v_pk_fma_f32 v[254:255], v[8:9], v[104:105], v[254:255]
	v_pk_fma_f32 v[160:161], v[10:11], v[106:107], v[160:161]
	v_pk_fma_f32 v[246:247], v[12:13], v[108:109], v[246:247]
	v_pk_fma_f32 v[254:255], v[14:15], v[110:111], v[254:255]
	v_pk_fma_f32 v[160:161], v[16:17], v[112:113], v[160:161]
	v_pk_fma_f32 v[246:247], v[18:19], v[114:115], v[246:247]
	v_pk_fma_f32 v[254:255], v[20:21], v[116:117], v[254:255]
	v_pk_fma_f32 v[160:161], v[22:23], v[118:119], v[160:161]
	v_pk_fma_f32 v[246:247], v[24:25], v[120:121], v[246:247]
	v_pk_fma_f32 v[254:255], v[26:27], v[122:123], v[254:255]
	v_pk_fma_f32 v[160:161], v[28:29], v[124:125], v[160:161]
	v_pk_fma_f32 v[246:247], v[30:31], v[126:127], v[246:247]
	v_pk_add_f32 v[254:255], v[254:255], v[160:161]
	s_nop 0
	v_pk_add_f32 v[246:247], v[246:247], v[254:255]
	s_nop 0
	v_add_f32_e32 v162, v246, v247
	s_waitcnt lgkmcnt(0)
	v_mad_u32_u24 v167, v77, s33, v195
	ds_read_b32 v76, v74 offset:272
	s_waitcnt vmcnt(14)
	v_cvt_scalef32_pk32_f32_fp6 v[0:31], v[44:49], 1.0
	global_load_dwordx2 v[48:49], v167, s[62:63] offset:16
	global_load_dwordx4 v[44:47], v167, s[62:63]
	v_pk_mul_f32 v[246:247], v[0:1], v[96:97]
	v_pk_mul_f32 v[254:255], v[2:3], v[98:99]
	v_pk_mul_f32 v[160:161], v[4:5], v[100:101]
	v_pk_fma_f32 v[246:247], v[6:7], v[102:103], v[246:247]
	v_pk_fma_f32 v[254:255], v[8:9], v[104:105], v[254:255]
	v_pk_fma_f32 v[160:161], v[10:11], v[106:107], v[160:161]
	v_pk_fma_f32 v[246:247], v[12:13], v[108:109], v[246:247]
	v_pk_fma_f32 v[254:255], v[14:15], v[110:111], v[254:255]
	v_pk_fma_f32 v[160:161], v[16:17], v[112:113], v[160:161]
	v_pk_fma_f32 v[246:247], v[18:19], v[114:115], v[246:247]
	v_pk_fma_f32 v[254:255], v[20:21], v[116:117], v[254:255]
	v_pk_fma_f32 v[160:161], v[22:23], v[118:119], v[160:161]
	v_pk_fma_f32 v[246:247], v[24:25], v[120:121], v[246:247]
	v_pk_fma_f32 v[254:255], v[26:27], v[122:123], v[254:255]
	v_pk_fma_f32 v[160:161], v[28:29], v[124:125], v[160:161]
	v_pk_fma_f32 v[246:247], v[30:31], v[126:127], v[246:247]
	v_pk_add_f32 v[254:255], v[254:255], v[160:161]
	s_nop 0
	v_pk_add_f32 v[246:247], v[246:247], v[254:255]
	s_nop 0
	v_add_f32_e32 v163, v246, v247
	s_waitcnt lgkmcnt(0)
; __device__ void peer_gather_phase(const Params& P, int l, bool do_store) {
;     ...
;     auto load_batch = [&](uint2 (&u6)[12], uint2 (&v8)[8], int bt) {
;       const int evs = (bt < 8) ? ev0 : ev1;
;       const int kb = (bt & 7) * 8;
; #pragma unroll
;       for (int pr = 0; pr < 4; ++pr) {
;         const int ea = __builtin_amdgcn_readlane(evs, kb + 2 * pr), eb = __builtin_amdgcn_readlane(evs, kb + 2 * pr + 1);
;         const uint2* up = (const uint2*)(U + (size_t)(uphi ? eb : ea) * 768);
;         u6[3 * pr] = up[0]; u6[3 * pr + 1] = up[1]; u6[3 * pr + 2] = up[2];
;         v8[2 * pr] = *(const uint2*)(V + (size_t)ea * 512);
;         v8[2 * pr + 1] = *(const uint2*)(V + (size_t)eb * 512);
;       }
;     };
;     auto compute_batch = [&](const uint2 (&u6)[12], const uint2 (&v8)[8], int bt) {
;       const int kb = (bt & 7) * 8;
;       float dvec = 0.f;
; #pragma unroll
;       for (int pr = 0; pr < 4; ++pr) {
;         v6u_t qv; qv[0] = u6[3 * pr].x; qv[1] = u6[3 * pr].y; qv[2] = u6[3 * pr + 1].x; qv[3] = u6[3 * pr + 1].y; qv[4] = u6[3 * pr + 2].x; qv[5] = u6[3 * pr + 2].y;
;         const v32f_t wv = __builtin_amdgcn_cvt_scalef32_pk32_f32_fp6(qv, 1.0f);
;         f32x2 a2 = f32x2{0.f, 0.f};
; #pragma unroll
;         for (int i = 0; i < 16; ++i) a2 += f32x2{wv[2 * i], wv[2 * i + 1]} * xu[i];
;         float hs = a2.x + a2.y;
;         hs += dpp_row_shr(hs, 1); hs += dpp_row_shr(hs, 2); hs += dpp_row_shr(hs, 4); hs += dpp_row_shr(hs, 8);
;         hs += __builtin_bit_cast(float, __builtin_amdgcn_update_dpp(0, __builtin_bit_cast(int, hs), 0x142, 0xa, 0xf, false));
;         const float da = __builtin_bit_cast(float, __builtin_amdgcn_readlane(__builtin_bit_cast(int, hs), 31));
;         const float db = __builtin_bit_cast(float, __builtin_amdgcn_readlane(__builtin_bit_cast(int, hs), 63));
;         dvec = (lane == kb + 2 * pr) ? da : dvec;
;         dvec = (lane == kb + 2 * pr + 1) ? db : dvec;
;       }
	v_mad_u32_u24 v167, v76, s33, v195
	ds_read_b32 v77, v74 offset:280
	s_waitcnt vmcnt(14)
	v_cvt_scalef32_pk32_f32_fp6 v[0:31], v[38:43], 1.0
	global_load_dwordx2 v[42:43], v167, s[62:63] offset:16
	global_load_dwordx4 v[38:41], v167, s[62:63]
	v_pk_mul_f32 v[246:247], v[0:1], v[96:97]
	v_pk_mul_f32 v[254:255], v[2:3], v[98:99]
	v_pk_mul_f32 v[160:161], v[4:5], v[100:101]
	v_pk_fma_f32 v[246:247], v[6:7], v[102:103], v[246:247]
	v_pk_fma_f32 v[254:255], v[8:9], v[104:105], v[254:255]
	v_pk_fma_f32 v[160:161], v[10:11], v[106:107], v[160:161]
	v_pk_fma_f32 v[246:247], v[12:13], v[108:109], v[246:247]
	v_pk_fma_f32 v[254:255], v[14:15], v[110:111], v[254:255]
	v_pk_fma_f32 v[160:161], v[16:17], v[112:113], v[160:161]
	v_pk_fma_f32 v[246:247], v[18:19], v[114:115], v[246:247]
	v_pk_fma_f32 v[254:255], v[20:21], v[116:117], v[254:255]
	v_pk_fma_f32 v[160:161], v[22:23], v[118:119], v[160:161]
	v_pk_fma_f32 v[246:247], v[24:25], v[120:121], v[246:247]
	v_pk_fma_f32 v[254:255], v[26:27], v[122:123], v[254:255]
	v_pk_fma_f32 v[160:161], v[28:29], v[124:125], v[160:161]
	v_pk_fma_f32 v[246:247], v[30:31], v[126:127], v[246:247]
	v_pk_add_f32 v[254:255], v[254:255], v[160:161]
	s_nop 0
	v_pk_add_f32 v[246:247], v[246:247], v[254:255]
	s_nop 0
	v_add_f32_e32 v164, v246, v247
	s_waitcnt lgkmcnt(0)
	v_mad_u32_u24 v167, v77, s33, v195
	ds_read_b32 v76, v74 offset:288
	s_waitcnt vmcnt(14)
	v_cvt_scalef32_pk32_f32_fp6 v[0:31], v[32:37], 1.0
	global_load_dwordx2 v[36:37], v167, s[62:63] offset:16
	global_load_dwordx4 v[32:35], v167, s[62:63]
	v_pk_mul_f32 v[246:247], v[0:1], v[96:97]
	v_pk_mul_f32 v[254:255], v[2:3], v[98:99]
	v_pk_mul_f32 v[160:161], v[4:5], v[100:101]
	v_pk_fma_f32 v[246:247], v[6:7], v[102:103], v[246:247]
	v_pk_fma_f32 v[254:255], v[8:9], v[104:105], v[254:255]
	v_pk_fma_f32 v[160:161], v[10:11], v[106:107], v[160:161]
	v_pk_fma_f32 v[246:247], v[12:13], v[108:109], v[246:247]
	v_pk_fma_f32 v[254:255], v[14:15], v[110:111], v[254:255]
	v_pk_fma_f32 v[160:161], v[16:17], v[112:113], v[160:161]
	v_pk_fma_f32 v[246:247], v[18:19], v[114:115], v[246:247]
	v_pk_fma_f32 v[254:255], v[20:21], v[116:117], v[254:255]
	v_pk_fma_f32 v[160:161], v[22:23], v[118:119], v[160:161]
	v_pk_fma_f32 v[246:247], v[24:25], v[120:121], v[246:247]
	v_pk_fma_f32 v[254:255], v[26:27], v[122:123], v[254:255]
	v_pk_fma_f32 v[160:161], v[28:29], v[124:125], v[160:161]
	v_pk_fma_f32 v[246:247], v[30:31], v[126:127], v[246:247]
	v_pk_add_f32 v[254:255], v[254:255], v[160:161]
	s_nop 0
	v_pk_add_f32 v[246:247], v[246:247], v[254:255]
	s_nop 0
	v_add_f32_e32 v165, v246, v247
	v_add_f32_dpp v162, v162, v162 row_shr:1 row_mask:0xf bank_mask:0xf bound_ctrl:1
	v_add_f32_dpp v163, v163, v163 row_shr:1 row_mask:0xf bank_mask:0xf bound_ctrl:1
	v_add_f32_dpp v164, v164, v164 row_shr:1 row_mask:0xf bank_mask:0xf bound_ctrl:1
	v_add_f32_dpp v165, v165, v165 row_shr:1 row_mask:0xf bank_mask:0xf bound_ctrl:1
	v_add_f32_dpp v162, v162, v162 row_shr:2 row_mask:0xf bank_mask:0xf bound_ctrl:1
	v_add_f32_dpp v163, v163, v163 row_shr:2 row_mask:0xf bank_mask:0xf bound_ctrl:1
	v_add_f32_dpp v164, v164, v164 row_shr:2 row_mask:0xf bank_mask:0xf bound_ctrl:1
	v_add_f32_dpp v165, v165, v165 row_shr:2 row_mask:0xf bank_mask:0xf bound_ctrl:1
	v_add_f32_dpp v162, v162, v162 row_shr:4 row_mask:0xf bank_mask:0xf bound_ctrl:1
	v_add_f32_dpp v163, v163, v163 row_shr:4 row_mask:0xf bank_mask:0xf bound_ctrl:1
	v_add_f32_dpp v164, v164, v164 row_shr:4 row_mask:0xf bank_mask:0xf bound_ctrl:1
	v_add_f32_dpp v165, v165, v165 row_shr:4 row_mask:0xf bank_mask:0xf bound_ctrl:1
	v_add_f32_dpp v162, v162, v162 row_shr:8 row_mask:0xf bank_mask:0xf bound_ctrl:1
	v_add_f32_dpp v163, v163, v163 row_shr:8 row_mask:0xf bank_mask:0xf bound_ctrl:1
	v_add_f32_dpp v164, v164, v164 row_shr:8 row_mask:0xf bank_mask:0xf bound_ctrl:1
	v_add_f32_dpp v165, v165, v165 row_shr:8 row_mask:0xf bank_mask:0xf bound_ctrl:1
	v_add_f32_dpp v162, v162, v162 row_bcast:15 row_mask:0xa bank_mask:0xf
	v_add_f32_dpp v163, v163, v163 row_bcast:15 row_mask:0xa bank_mask:0xf
	v_add_f32_dpp v164, v164, v164 row_bcast:15 row_mask:0xa bank_mask:0xf
	v_add_f32_dpp v165, v165, v165 row_bcast:15 row_mask:0xa bank_mask:0xf
	s_mov_b64 s[98:99], exec
	s_mov_b32 exec_lo, 0x80000000
	s_mov_b32 exec_hi, 0x80000000
	ds_write_b32 v74, v162 offset:192
	ds_write_b32 v74, v163 offset:200
	ds_write_b32 v74, v164 offset:208
	ds_write_b32 v74, v165 offset:216
	s_mov_b64 exec, s[98:99]
	s_waitcnt lgkmcnt(0)
	v_mad_u32_u24 v167, v76, s33, v195
	ds_read_b32 v77, v74 offset:296
	s_waitcnt vmcnt(14)
	v_cvt_scalef32_pk32_f32_fp6 v[0:31], v[196:201], 1.0
	global_load_dwordx2 v[200:201], v167, s[62:63] offset:16
	global_load_dwordx4 v[196:199], v167, s[62:63]
	v_pk_mul_f32 v[246:247], v[0:1], v[96:97]
	v_pk_mul_f32 v[254:255], v[2:3], v[98:99]
	v_pk_mul_f32 v[160:161], v[4:5], v[100:101]
	v_pk_fma_f32 v[246:247], v[6:7], v[102:103], v[246:247]
	v_pk_fma_f32 v[254:255], v[8:9], v[104:105], v[254:255]
	v_pk_fma_f32 v[160:161], v[10:11], v[106:107], v[160:161]
	v_pk_fma_f32 v[246:247], v[12:13], v[108:109], v[246:247]
	v_pk_fma_f32 v[254:255], v[14:15], v[110:111], v[254:255]
	v_pk_fma_f32 v[160:161], v[16:17], v[112:113], v[160:161]
	v_pk_fma_f32 v[246:247], v[18:19], v[114:115], v[246:247]
	v_pk_fma_f32 v[254:255], v[20:21], v[116:117], v[254:255]
	v_pk_fma_f32 v[160:161], v[22:23], v[118:119], v[160:161]
	v_pk_fma_f32 v[246:247], v[24:25], v[120:121], v[246:247]
	v_pk_fma_f32 v[254:255], v[26:27], v[122:123], v[254:255]
	v_pk_fma_f32 v[160:161], v[28:29], v[124:125], v[160:161]
	v_pk_fma_f32 v[246:247], v[30:31], v[126:127], v[246:247]
	v_pk_add_f32 v[254:255], v[254:255], v[160:161]
	s_nop 0
	v_pk_add_f32 v[246:247], v[246:247], v[254:255]
	s_nop 0
	v_add_f32_e32 v162, v246, v247
	s_waitcnt lgkmcnt(0)
; __device__ void peer_gather_phase(const Params& P, int l, bool do_store) {
;     ...
;     auto load_batch = [&](uint2 (&u6)[12], uint2 (&v8)[8], int bt) {
;       const int evs = (bt < 8) ? ev0 : ev1;
;       const int kb = (bt & 7) * 8;
; #pragma unroll
;       for (int pr = 0; pr < 4; ++pr) {
;         const int ea = __builtin_amdgcn_readlane(evs, kb + 2 * pr), eb = __builtin_amdgcn_readlane(evs, kb + 2 * pr + 1);
;         const uint2* up = (const uint2*)(U + (size_t)(uphi ? eb : ea) * 768);
;         u6[3 * pr] = up[0]; u6[3 * pr + 1] = up[1]; u6[3 * pr + 2] = up[2];
;         v8[2 * pr] = *(const uint2*)(V + (size_t)ea * 512);
;         v8[2 * pr + 1] = *(const uint2*)(V + (size_t)eb * 512);
;       }
;     };
;     auto compute_batch = [&](const uint2 (&u6)[12], const uint2 (&v8)[8], int bt) {
;       const int kb = (bt & 7) * 8;
;       float dvec = 0.f;
; #pragma unroll
;       for (int pr = 0; pr < 4; ++pr) {
;         v6u_t qv; qv[0] = u6[3 * pr].x; qv[1] = u6[3 * pr].y; qv[2] = u6[3 * pr + 1].x; qv[3] = u6[3 * pr + 1].y; qv[4] = u6[3 * pr + 2].x; qv[5] = u6[3 * pr + 2].y;
;         const v32f_t wv = __builtin_amdgcn_cvt_scalef32_pk32_f32_fp6(qv, 1.0f);
;         f32x2 a2 = f32x2{0.f, 0.f};
; #pragma unroll
;         for (int i = 0; i < 16; ++i) a2 += f32x2{wv[2 * i], wv[2 * i + 1]} * xu[i];
;         float hs = a2.x + a2.y;
;         hs += dpp_row_shr(hs, 1); hs += dpp_row_shr(hs, 2); hs += dpp_row_shr(hs, 4); hs += dpp_row_shr(hs, 8);
;         hs += __builtin_bit_cast(float, __builtin_amdgcn_update_dpp(0, __builtin_bit_cast(int, hs), 0x142, 0xa, 0xf, false));
;         const float da = __builtin_bit_cast(float, __builtin_amdgcn_readlane(__builtin_bit_cast(int, hs), 31));
;         const float db = __builtin_bit_cast(float, __builtin_amdgcn_readlane(__builtin_bit_cast(int, hs), 63));
;         dvec = (lane == kb + 2 * pr) ? da : dvec;
;         dvec = (lane == kb + 2 * pr + 1) ? db : dvec;
;       }
	v_mad_u32_u24 v167, v77, s33, v195
	ds_read_b32 v76, v74 offset:304
	s_waitcnt vmcnt(14)
	v_cvt_scalef32_pk32_f32_fp6 v[0:31], v[228:233], 1.0
	global_load_dwordx2 v[232:233], v167, s[62:63] offset:16
	global_load_dwordx4 v[228:231], v167, s[62:63]
	v_pk_mul_f32 v[246:247], v[0:1], v[96:97]
	v_pk_mul_f32 v[254:255], v[2:3], v[98:99]
	v_pk_mul_f32 v[160:161], v[4:5], v[100:101]
	v_pk_fma_f32 v[246:247], v[6:7], v[102:103], v[246:247]
	v_pk_fma_f32 v[254:255], v[8:9], v[104:105], v[254:255]
	v_pk_fma_f32 v[160:161], v[10:11], v[106:107], v[160:161]
	v_pk_fma_f32 v[246:247], v[12:13], v[108:109], v[246:247]
	v_pk_fma_f32 v[254:255], v[14:15], v[110:111], v[254:255]
	v_pk_fma_f32 v[160:161], v[16:17], v[112:113], v[160:161]
	v_pk_fma_f32 v[246:247], v[18:19], v[114:115], v[246:247]
	v_pk_fma_f32 v[254:255], v[20:21], v[116:117], v[254:255]
	v_pk_fma_f32 v[160:161], v[22:23], v[118:119], v[160:161]
	v_pk_fma_f32 v[246:247], v[24:25], v[120:121], v[246:247]
	v_pk_fma_f32 v[254:255], v[26:27], v[122:123], v[254:255]
	v_pk_fma_f32 v[160:161], v[28:29], v[124:125], v[160:161]
	v_pk_fma_f32 v[246:247], v[30:31], v[126:127], v[246:247]
	v_pk_add_f32 v[254:255], v[254:255], v[160:161]
	s_nop 0
	v_pk_add_f32 v[246:247], v[246:247], v[254:255]
	s_nop 0
	v_add_f32_e32 v163, v246, v247
	s_waitcnt lgkmcnt(0)
	v_mad_u32_u24 v167, v76, s33, v195
	ds_read_b32 v77, v74 offset:312
	s_waitcnt vmcnt(14)
	v_cvt_scalef32_pk32_f32_fp6 v[0:31], v[234:239], 1.0
	global_load_dwordx2 v[238:239], v167, s[62:63] offset:16
	global_load_dwordx4 v[234:237], v167, s[62:63]
	v_pk_mul_f32 v[246:247], v[0:1], v[96:97]
	v_pk_mul_f32 v[254:255], v[2:3], v[98:99]
	v_pk_mul_f32 v[160:161], v[4:5], v[100:101]
	v_pk_fma_f32 v[246:247], v[6:7], v[102:103], v[246:247]
	v_pk_fma_f32 v[254:255], v[8:9], v[104:105], v[254:255]
	v_pk_fma_f32 v[160:161], v[10:11], v[106:107], v[160:161]
	v_pk_fma_f32 v[246:247], v[12:13], v[108:109], v[246:247]
	v_pk_fma_f32 v[254:255], v[14:15], v[110:111], v[254:255]
	v_pk_fma_f32 v[160:161], v[16:17], v[112:113], v[160:161]
	v_pk_fma_f32 v[246:247], v[18:19], v[114:115], v[246:247]
	v_pk_fma_f32 v[254:255], v[20:21], v[116:117], v[254:255]
	v_pk_fma_f32 v[160:161], v[22:23], v[118:119], v[160:161]
	v_pk_fma_f32 v[246:247], v[24:25], v[120:121], v[246:247]
	v_pk_fma_f32 v[254:255], v[26:27], v[122:123], v[254:255]
	v_pk_fma_f32 v[160:161], v[28:29], v[124:125], v[160:161]
	v_pk_fma_f32 v[246:247], v[30:31], v[126:127], v[246:247]
	v_pk_add_f32 v[254:255], v[254:255], v[160:161]
	s_nop 0
	v_pk_add_f32 v[246:247], v[246:247], v[254:255]
	s_nop 0
	v_add_f32_e32 v164, v246, v247
	s_waitcnt lgkmcnt(0)
	v_mad_u32_u24 v167, v77, s33, v195
	ds_read_b32 v76, v74 offset:320
	s_waitcnt vmcnt(14)
	v_cvt_scalef32_pk32_f32_fp6 v[0:31], v[240:245], 1.0
	global_load_dwordx2 v[244:245], v167, s[62:63] offset:16
	global_load_dwordx4 v[240:243], v167, s[62:63]
	v_pk_mul_f32 v[246:247], v[0:1], v[96:97]
	v_pk_mul_f32 v[254:255], v[2:3], v[98:99]
	v_pk_mul_f32 v[160:161], v[4:5], v[100:101]
	v_pk_fma_f32 v[246:247], v[6:7], v[102:103], v[246:247]
	v_pk_fma_f32 v[254:255], v[8:9], v[104:105], v[254:255]
	v_pk_fma_f32 v[160:161], v[10:11], v[106:107], v[160:161]
	v_pk_fma_f32 v[246:247], v[12:13], v[108:109], v[246:247]
	v_pk_fma_f32 v[254:255], v[14:15], v[110:111], v[254:255]
	v_pk_fma_f32 v[160:161], v[16:17], v[112:113], v[160:161]
	v_pk_fma_f32 v[246:247], v[18:19], v[114:115], v[246:247]
	v_pk_fma_f32 v[254:255], v[20:21], v[116:117], v[254:255]
	v_pk_fma_f32 v[160:161], v[22:23], v[118:119], v[160:161]
	v_pk_fma_f32 v[246:247], v[24:25], v[120:121], v[246:247]
	v_pk_fma_f32 v[254:255], v[26:27], v[122:123], v[254:255]
	v_pk_fma_f32 v[160:161], v[28:29], v[124:125], v[160:161]
	v_pk_fma_f32 v[246:247], v[30:31], v[126:127], v[246:247]
	v_pk_add_f32 v[254:255], v[254:255], v[160:161]
	s_nop 0
	v_pk_add_f32 v[246:247], v[246:247], v[254:255]
	s_nop 0
	v_add_f32_e32 v165, v246, v247
	v_add_f32_dpp v162, v162, v162 row_shr:1 row_mask:0xf bank_mask:0xf bound_ctrl:1
	v_add_f32_dpp v163, v163, v163 row_shr:1 row_mask:0xf bank_mask:0xf bound_ctrl:1
	v_add_f32_dpp v164, v164, v164 row_shr:1 row_mask:0xf bank_mask:0xf bound_ctrl:1
	v_add_f32_dpp v165, v165, v165 row_shr:1 row_mask:0xf bank_mask:0xf bound_ctrl:1
	v_add_f32_dpp v162, v162, v162 row_shr:2 row_mask:0xf bank_mask:0xf bound_ctrl:1
	v_add_f32_dpp v163, v163, v163 row_shr:2 row_mask:0xf bank_mask:0xf bound_ctrl:1
	v_add_f32_dpp v164, v164, v164 row_shr:2 row_mask:0xf bank_mask:0xf bound_ctrl:1
	v_add_f32_dpp v165, v165, v165 row_shr:2 row_mask:0xf bank_mask:0xf bound_ctrl:1
	v_add_f32_dpp v162, v162, v162 row_shr:4 row_mask:0xf bank_mask:0xf bound_ctrl:1
	v_add_f32_dpp v163, v163, v163 row_shr:4 row_mask:0xf bank_mask:0xf bound_ctrl:1
	v_add_f32_dpp v164, v164, v164 row_shr:4 row_mask:0xf bank_mask:0xf bound_ctrl:1
	v_add_f32_dpp v165, v165, v165 row_shr:4 row_mask:0xf bank_mask:0xf bound_ctrl:1
	v_add_f32_dpp v162, v162, v162 row_shr:8 row_mask:0xf bank_mask:0xf bound_ctrl:1
	v_add_f32_dpp v163, v163, v163 row_shr:8 row_mask:0xf bank_mask:0xf bound_ctrl:1
	v_add_f32_dpp v164, v164, v164 row_shr:8 row_mask:0xf bank_mask:0xf bound_ctrl:1
	v_add_f32_dpp v165, v165, v165 row_shr:8 row_mask:0xf bank_mask:0xf bound_ctrl:1
	v_add_f32_dpp v162, v162, v162 row_bcast:15 row_mask:0xa bank_mask:0xf
	v_add_f32_dpp v163, v163, v163 row_bcast:15 row_mask:0xa bank_mask:0xf
	v_add_f32_dpp v164, v164, v164 row_bcast:15 row_mask:0xa bank_mask:0xf
	v_add_f32_dpp v165, v165, v165 row_bcast:15 row_mask:0xa bank_mask:0xf
	s_mov_b64 s[98:99], exec
	s_mov_b32 exec_lo, 0x80000000
	s_mov_b32 exec_hi, 0x80000000
	ds_write_b32 v74, v162 offset:224
	ds_write_b32 v74, v163 offset:232
	ds_write_b32 v74, v164 offset:240
	ds_write_b32 v74, v165 offset:248
	s_mov_b64 exec, s[98:99]
	ds_read_b32 v166, v75
	s_waitcnt lgkmcnt(0)
; DEV float gelu_t(float x) {
;   float z = 0.7978845608028654f * (x + 0.044715f * x * x * x);
;   float e = __expf(2.f * z);
;   float th = 1.f - 2.f / (e + 1.f);
;   return 0.5f * x * (1.f + th);
; }
; __device__ void peer_gather_phase(const Params& P, int l, bool do_store) {
;     ...
;       const float sux = (bt < 8) ? sux0 : sux1;
;       const float gsx = (bt < 8) ? gsx0 : gsx1;
;       const float avec = gelu_t(dvec * sux) * gsx;
; #pragma unroll
;       for (int j = 0; j < 8; ++j) {
;         const float a = __builtin_bit_cast(float, __builtin_amdgcn_readlane(__builtin_bit_cast(int, avec), kb + j));
;         const f32x2 aa = f32x2{a, a};
;         y[0] += aa * __builtin_amdgcn_cvt_scalef32_pk_f32_fp4(v8[j].x, 1.0f, 0); y[1] += aa * __builtin_amdgcn_cvt_scalef32_pk_f32_fp4(v8[j].x, 1.0f, 1);
;         y[2] += aa * __builtin_amdgcn_cvt_scalef32_pk_f32_fp4(v8[j].x, 1.0f, 2); y[3] += aa * __builtin_amdgcn_cvt_scalef32_pk_f32_fp4(v8[j].x, 1.0f, 3);
;         y[4] += aa * __builtin_amdgcn_cvt_scalef32_pk_f32_fp4(v8[j].y, 1.0f, 0); y[5] += aa * __builtin_amdgcn_cvt_scalef32_pk_f32_fp4(v8[j].y, 1.0f, 1);
;         y[6] += aa * __builtin_amdgcn_cvt_scalef32_pk_f32_fp4(v8[j].y, 1.0f, 2); y[7] += aa * __builtin_amdgcn_cvt_scalef32_pk_f32_fp4(v8[j].y, 1.0f, 3);
;       }
	v_mul_f32_e32 v0, v189, v166
	v_mul_f32_e32 v1, 0x3d372713, v0
	v_mul_f32_e32 v1, v0, v1
	v_fma_f32 v1, v0, v1, v0
	v_mul_f32_e32 v1, 0x3f4c422a, v1
	v_add_f32_e32 v1, v1, v1
	v_mul_f32_e32 v1, 0x3fb8aa3b, v1
	v_exp_f32_e32 v1, v1
	v_mul_f32_e32 v0, 0.5, v0
	v_add_f32_e32 v1, 1.0, v1
	v_div_scale_f32 v2, s[0:1], v1, v1, 2.0
	v_rcp_f32_e32 v3, v2
	s_nop 0
	v_fma_f32 v4, -v2, v3, 1.0
	v_fmac_f32_e32 v3, v4, v3
	v_div_scale_f32 v4, vcc, 2.0, v1, 2.0
	v_mul_f32_e32 v5, v4, v3
	v_fma_f32 v6, -v2, v5, v4
	v_fmac_f32_e32 v5, v6, v3
	v_fma_f32 v2, -v2, v5, v4
	v_div_fmas_f32 v2, v2, v3, v5
	v_div_fixup_f32 v1, v2, v1, 2.0
	v_sub_f32_e32 v1, 1.0, v1
	v_add_f32_e32 v1, 1.0, v1
	v_mul_f32_e32 v0, v0, v1
	v_mul_f32_e32 v167, v191, v0
	s_nop 1
	v_readlane_b32 s0, v167, 0
	s_waitcnt vmcnt(48)
	v_cvt_scalef32_pk_f32_fp4 v[0:1], v144, 1.0
	v_cvt_scalef32_pk_f32_fp4 v[2:3], v144, 1.0 op_sel:[1,0,0]
	v_cvt_scalef32_pk_f32_fp4 v[4:5], v144, 1.0 op_sel:[0,1,0]
	v_cvt_scalef32_pk_f32_fp4 v[6:7], v144, 1.0 op_sel:[1,1,0]
	v_cvt_scalef32_pk_f32_fp4 v[8:9], v145, 1.0
	v_cvt_scalef32_pk_f32_fp4 v[10:11], v145, 1.0 op_sel:[1,0,0]
	v_cvt_scalef32_pk_f32_fp4 v[12:13], v145, 1.0 op_sel:[0,1,0]
	v_cvt_scalef32_pk_f32_fp4 v[14:15], v145, 1.0 op_sel:[1,1,0]
	v_readlane_b32 s54, v92, 16
	s_lshl_b32 s56, s54, 9
	s_add_u32 s56, s64, s56
	s_addc_u32 s57, s65, 0
	global_load_dwordx2 v[144:145], v227, s[56:57]
	v_pk_fma_f32 v[130:131], v[0:1], s[0:1], v[130:131] op_sel_hi:[1,0,1]
	v_pk_fma_f32 v[138:139], v[2:3], s[0:1], v[138:139] op_sel_hi:[1,0,1]
	v_pk_fma_f32 v[140:141], v[4:5], s[0:1], v[140:141] op_sel_hi:[1,0,1]
	v_pk_fma_f32 v[142:143], v[6:7], s[0:1], v[142:143] op_sel_hi:[1,0,1]
	v_pk_fma_f32 v[128:129], v[8:9], s[0:1], v[128:129] op_sel_hi:[1,0,1]
	v_pk_fma_f32 v[132:133], v[10:11], s[0:1], v[132:133] op_sel_hi:[1,0,1]
	v_pk_fma_f32 v[134:135], v[12:13], s[0:1], v[134:135] op_sel_hi:[1,0,1]
	v_pk_fma_f32 v[136:137], v[14:15], s[0:1], v[136:137] op_sel_hi:[1,0,1]
	v_readlane_b32 s0, v167, 1
	s_waitcnt vmcnt(48)
	v_cvt_scalef32_pk_f32_fp4 v[0:1], v146, 1.0
	v_cvt_scalef32_pk_f32_fp4 v[2:3], v146, 1.0 op_sel:[1,0,0]
	v_cvt_scalef32_pk_f32_fp4 v[4:5], v146, 1.0 op_sel:[0,1,0]
	v_cvt_scalef32_pk_f32_fp4 v[6:7], v146, 1.0 op_sel:[1,1,0]
	v_cvt_scalef32_pk_f32_fp4 v[8:9], v147, 1.0
	v_cvt_scalef32_pk_f32_fp4 v[10:11], v147, 1.0 op_sel:[1,0,0]
	v_cvt_scalef32_pk_f32_fp4 v[12:13], v147, 1.0 op_sel:[0,1,0]
	v_cvt_scalef32_pk_f32_fp4 v[14:15], v147, 1.0 op_sel:[1,1,0]
	v_readlane_b32 s54, v92, 17
	s_lshl_b32 s56, s54, 9
	s_add_u32 s56, s64, s56
	s_addc_u32 s57, s65, 0
	global_load_dwordx2 v[146:147], v227, s[56:57]
	v_pk_fma_f32 v[130:131], v[0:1], s[0:1], v[130:131] op_sel_hi:[1,0,1]
	v_pk_fma_f32 v[138:139], v[2:3], s[0:1], v[138:139] op_sel_hi:[1,0,1]
	v_pk_fma_f32 v[140:141], v[4:5], s[0:1], v[140:141] op_sel_hi:[1,0,1]
	v_pk_fma_f32 v[142:143], v[6:7], s[0:1], v[142:143] op_sel_hi:[1,0,1]
	v_pk_fma_f32 v[128:129], v[8:9], s[0:1], v[128:129] op_sel_hi:[1,0,1]
	v_pk_fma_f32 v[132:133], v[10:11], s[0:1], v[132:133] op_sel_hi:[1,0,1]
	v_pk_fma_f32 v[134:135], v[12:13], s[0:1], v[134:135] op_sel_hi:[1,0,1]
	v_pk_fma_f32 v[136:137], v[14:15], s[0:1], v[136:137] op_sel_hi:[1,0,1]
	v_readlane_b32 s0, v167, 2
	s_waitcnt vmcnt(48)
	v_cvt_scalef32_pk_f32_fp4 v[0:1], v148, 1.0
	v_cvt_scalef32_pk_f32_fp4 v[2:3], v148, 1.0 op_sel:[1,0,0]
	v_cvt_scalef32_pk_f32_fp4 v[4:5], v148, 1.0 op_sel:[0,1,0]
	v_cvt_scalef32_pk_f32_fp4 v[6:7], v148, 1.0 op_sel:[1,1,0]
	v_cvt_scalef32_pk_f32_fp4 v[8:9], v149, 1.0
	v_cvt_scalef32_pk_f32_fp4 v[10:11], v149, 1.0 op_sel:[1,0,0]
	v_cvt_scalef32_pk_f32_fp4 v[12:13], v149, 1.0 op_sel:[0,1,0]
	v_cvt_scalef32_pk_f32_fp4 v[14:15], v149, 1.0 op_sel:[1,1,0]
	v_readlane_b32 s54, v92, 18
	s_lshl_b32 s56, s54, 9
	s_add_u32 s56, s64, s56
	s_addc_u32 s57, s65, 0
	global_load_dwordx2 v[148:149], v227, s[56:57]
	v_pk_fma_f32 v[130:131], v[0:1], s[0:1], v[130:131] op_sel_hi:[1,0,1]
	v_pk_fma_f32 v[138:139], v[2:3], s[0:1], v[138:139] op_sel_hi:[1,0,1]
	v_pk_fma_f32 v[140:141], v[4:5], s[0:1], v[140:141] op_sel_hi:[1,0,1]
	v_pk_fma_f32 v[142:143], v[6:7], s[0:1], v[142:143] op_sel_hi:[1,0,1]
	v_pk_fma_f32 v[128:129], v[8:9], s[0:1], v[128:129] op_sel_hi:[1,0,1]
	v_pk_fma_f32 v[132:133], v[10:11], s[0:1], v[132:133] op_sel_hi:[1,0,1]
	v_pk_fma_f32 v[134:135], v[12:13], s[0:1], v[134:135] op_sel_hi:[1,0,1]
	v_pk_fma_f32 v[136:137], v[14:15], s[0:1], v[136:137] op_sel_hi:[1,0,1]
	v_readlane_b32 s0, v167, 3
	s_waitcnt vmcnt(48)
	v_cvt_scalef32_pk_f32_fp4 v[0:1], v150, 1.0
	v_cvt_scalef32_pk_f32_fp4 v[2:3], v150, 1.0 op_sel:[1,0,0]
	v_cvt_scalef32_pk_f32_fp4 v[4:5], v150, 1.0 op_sel:[0,1,0]
	v_cvt_scalef32_pk_f32_fp4 v[6:7], v150, 1.0 op_sel:[1,1,0]
	v_cvt_scalef32_pk_f32_fp4 v[8:9], v151, 1.0
	v_cvt_scalef32_pk_f32_fp4 v[10:11], v151, 1.0 op_sel:[1,0,0]
	v_cvt_scalef32_pk_f32_fp4 v[12:13], v151, 1.0 op_sel:[0,1,0]
	v_cvt_scalef32_pk_f32_fp4 v[14:15], v151, 1.0 op_sel:[1,1,0]
	v_readlane_b32 s54, v92, 19
	s_lshl_b32 s56, s54, 9
	s_add_u32 s56, s64, s56
	s_addc_u32 s57, s65, 0
	global_load_dwordx2 v[150:151], v227, s[56:57]
	v_pk_fma_f32 v[130:131], v[0:1], s[0:1], v[130:131] op_sel_hi:[1,0,1]
	v_pk_fma_f32 v[138:139], v[2:3], s[0:1], v[138:139] op_sel_hi:[1,0,1]
	v_pk_fma_f32 v[140:141], v[4:5], s[0:1], v[140:141] op_sel_hi:[1,0,1]
	v_pk_fma_f32 v[142:143], v[6:7], s[0:1], v[142:143] op_sel_hi:[1,0,1]
	v_pk_fma_f32 v[128:129], v[8:9], s[0:1], v[128:129] op_sel_hi:[1,0,1]
	v_pk_fma_f32 v[132:133], v[10:11], s[0:1], v[132:133] op_sel_hi:[1,0,1]
	v_pk_fma_f32 v[134:135], v[12:13], s[0:1], v[134:135] op_sel_hi:[1,0,1]
	v_pk_fma_f32 v[136:137], v[14:15], s[0:1], v[136:137] op_sel_hi:[1,0,1]
	v_readlane_b32 s0, v167, 4
	s_waitcnt vmcnt(48)
; __device__ void peer_gather_phase(const Params& P, int l, bool do_store) {
;     ...
;     auto load_batch = [&](uint2 (&u6)[12], uint2 (&v8)[8], int bt) {
;       const int evs = (bt < 8) ? ev0 : ev1;
;       const int kb = (bt & 7) * 8;
; #pragma unroll
;       for (int pr = 0; pr < 4; ++pr) {
;         const int ea = __builtin_amdgcn_readlane(evs, kb + 2 * pr), eb = __builtin_amdgcn_readlane(evs, kb + 2 * pr + 1);
;         const uint2* up = (const uint2*)(U + (size_t)(uphi ? eb : ea) * 768);
;         u6[3 * pr] = up[0]; u6[3 * pr + 1] = up[1]; u6[3 * pr + 2] = up[2];
;         v8[2 * pr] = *(const uint2*)(V + (size_t)ea * 512);
;         v8[2 * pr + 1] = *(const uint2*)(V + (size_t)eb * 512);
;       }
;     };
;     auto compute_batch = [&](const uint2 (&u6)[12], const uint2 (&v8)[8], int bt) {
;       const int kb = (bt & 7) * 8;
;       float dvec = 0.f;
; #pragma unroll
;       for (int pr = 0; pr < 4; ++pr) {
;         v6u_t qv; qv[0] = u6[3 * pr].x; qv[1] = u6[3 * pr].y; qv[2] = u6[3 * pr + 1].x; qv[3] = u6[3 * pr + 1].y; qv[4] = u6[3 * pr + 2].x; qv[5] = u6[3 * pr + 2].y;
;         const v32f_t wv = __builtin_amdgcn_cvt_scalef32_pk32_f32_fp6(qv, 1.0f);
;         f32x2 a2 = f32x2{0.f, 0.f};
; #pragma unroll
;         for (int i = 0; i < 16; ++i) a2 += f32x2{wv[2 * i], wv[2 * i + 1]} * xu[i];
;         float hs = a2.x + a2.y;
;         hs += dpp_row_shr(hs, 1); hs += dpp_row_shr(hs, 2); hs += dpp_row_shr(hs, 4); hs += dpp_row_shr(hs, 8);
;         hs += __builtin_bit_cast(float, __builtin_amdgcn_update_dpp(0, __builtin_bit_cast(int, hs), 0x142, 0xa, 0xf, false));
;         const float da = __builtin_bit_cast(float, __builtin_amdgcn_readlane(__builtin_bit_cast(int, hs), 31));
;         const float db = __builtin_bit_cast(float, __builtin_amdgcn_readlane(__builtin_bit_cast(int, hs), 63));
;         dvec = (lane == kb + 2 * pr) ? da : dvec;
;         dvec = (lane == kb + 2 * pr + 1) ? db : dvec;
;       }
;       const float sux = (bt < 8) ? sux0 : sux1;
;       const float gsx = (bt < 8) ? gsx0 : gsx1;
;       const float avec = gelu_t(dvec * sux) * gsx;
; #pragma unroll
;       for (int j = 0; j < 8; ++j) {
;         const float a = __builtin_bit_cast(float, __builtin_amdgcn_readlane(__builtin_bit_cast(int, avec), kb + j));
;         const f32x2 aa = f32x2{a, a};
	v_cvt_scalef32_pk_f32_fp4 v[0:1], v152, 1.0
	v_cvt_scalef32_pk_f32_fp4 v[2:3], v152, 1.0 op_sel:[1,0,0]
	v_cvt_scalef32_pk_f32_fp4 v[4:5], v152, 1.0 op_sel:[0,1,0]
	v_cvt_scalef32_pk_f32_fp4 v[6:7], v152, 1.0 op_sel:[1,1,0]
	v_cvt_scalef32_pk_f32_fp4 v[8:9], v153, 1.0
	v_cvt_scalef32_pk_f32_fp4 v[10:11], v153, 1.0 op_sel:[1,0,0]
	v_cvt_scalef32_pk_f32_fp4 v[12:13], v153, 1.0 op_sel:[0,1,0]
	v_cvt_scalef32_pk_f32_fp4 v[14:15], v153, 1.0 op_sel:[1,1,0]
	v_readlane_b32 s54, v92, 20
	s_lshl_b32 s56, s54, 9
	s_add_u32 s56, s64, s56
	s_addc_u32 s57, s65, 0
	global_load_dwordx2 v[152:153], v227, s[56:57]
	v_pk_fma_f32 v[130:131], v[0:1], s[0:1], v[130:131] op_sel_hi:[1,0,1]
	v_pk_fma_f32 v[138:139], v[2:3], s[0:1], v[138:139] op_sel_hi:[1,0,1]
	v_pk_fma_f32 v[140:141], v[4:5], s[0:1], v[140:141] op_sel_hi:[1,0,1]
	v_pk_fma_f32 v[142:143], v[6:7], s[0:1], v[142:143] op_sel_hi:[1,0,1]
	v_pk_fma_f32 v[128:129], v[8:9], s[0:1], v[128:129] op_sel_hi:[1,0,1]
	v_pk_fma_f32 v[132:133], v[10:11], s[0:1], v[132:133] op_sel_hi:[1,0,1]
	v_pk_fma_f32 v[134:135], v[12:13], s[0:1], v[134:135] op_sel_hi:[1,0,1]
	v_pk_fma_f32 v[136:137], v[14:15], s[0:1], v[136:137] op_sel_hi:[1,0,1]
	v_readlane_b32 s0, v167, 5
	s_waitcnt vmcnt(48)
	v_cvt_scalef32_pk_f32_fp4 v[0:1], v154, 1.0
	v_cvt_scalef32_pk_f32_fp4 v[2:3], v154, 1.0 op_sel:[1,0,0]
	v_cvt_scalef32_pk_f32_fp4 v[4:5], v154, 1.0 op_sel:[0,1,0]
	v_cvt_scalef32_pk_f32_fp4 v[6:7], v154, 1.0 op_sel:[1,1,0]
	v_cvt_scalef32_pk_f32_fp4 v[8:9], v155, 1.0
	v_cvt_scalef32_pk_f32_fp4 v[10:11], v155, 1.0 op_sel:[1,0,0]
	v_cvt_scalef32_pk_f32_fp4 v[12:13], v155, 1.0 op_sel:[0,1,0]
	v_cvt_scalef32_pk_f32_fp4 v[14:15], v155, 1.0 op_sel:[1,1,0]
	v_readlane_b32 s54, v92, 21
	s_lshl_b32 s56, s54, 9
	s_add_u32 s56, s64, s56
	s_addc_u32 s57, s65, 0
	global_load_dwordx2 v[154:155], v227, s[56:57]
	v_pk_fma_f32 v[130:131], v[0:1], s[0:1], v[130:131] op_sel_hi:[1,0,1]
	v_pk_fma_f32 v[138:139], v[2:3], s[0:1], v[138:139] op_sel_hi:[1,0,1]
	v_pk_fma_f32 v[140:141], v[4:5], s[0:1], v[140:141] op_sel_hi:[1,0,1]
	v_pk_fma_f32 v[142:143], v[6:7], s[0:1], v[142:143] op_sel_hi:[1,0,1]
	v_pk_fma_f32 v[128:129], v[8:9], s[0:1], v[128:129] op_sel_hi:[1,0,1]
	v_pk_fma_f32 v[132:133], v[10:11], s[0:1], v[132:133] op_sel_hi:[1,0,1]
	v_pk_fma_f32 v[134:135], v[12:13], s[0:1], v[134:135] op_sel_hi:[1,0,1]
	v_pk_fma_f32 v[136:137], v[14:15], s[0:1], v[136:137] op_sel_hi:[1,0,1]
	v_readlane_b32 s0, v167, 6
	s_waitcnt vmcnt(48)
	v_cvt_scalef32_pk_f32_fp4 v[0:1], v156, 1.0
	v_cvt_scalef32_pk_f32_fp4 v[2:3], v156, 1.0 op_sel:[1,0,0]
	v_cvt_scalef32_pk_f32_fp4 v[4:5], v156, 1.0 op_sel:[0,1,0]
	v_cvt_scalef32_pk_f32_fp4 v[6:7], v156, 1.0 op_sel:[1,1,0]
	v_cvt_scalef32_pk_f32_fp4 v[8:9], v157, 1.0
	v_cvt_scalef32_pk_f32_fp4 v[10:11], v157, 1.0 op_sel:[1,0,0]
	v_cvt_scalef32_pk_f32_fp4 v[12:13], v157, 1.0 op_sel:[0,1,0]
	v_cvt_scalef32_pk_f32_fp4 v[14:15], v157, 1.0 op_sel:[1,1,0]
	v_readlane_b32 s54, v92, 22
	s_lshl_b32 s56, s54, 9
	s_add_u32 s56, s64, s56
	s_addc_u32 s57, s65, 0
	global_load_dwordx2 v[156:157], v227, s[56:57]
	v_pk_fma_f32 v[130:131], v[0:1], s[0:1], v[130:131] op_sel_hi:[1,0,1]
	v_pk_fma_f32 v[138:139], v[2:3], s[0:1], v[138:139] op_sel_hi:[1,0,1]
	v_pk_fma_f32 v[140:141], v[4:5], s[0:1], v[140:141] op_sel_hi:[1,0,1]
	v_pk_fma_f32 v[142:143], v[6:7], s[0:1], v[142:143] op_sel_hi:[1,0,1]
	v_pk_fma_f32 v[128:129], v[8:9], s[0:1], v[128:129] op_sel_hi:[1,0,1]
	v_pk_fma_f32 v[132:133], v[10:11], s[0:1], v[132:133] op_sel_hi:[1,0,1]
	v_pk_fma_f32 v[134:135], v[12:13], s[0:1], v[134:135] op_sel_hi:[1,0,1]
	v_pk_fma_f32 v[136:137], v[14:15], s[0:1], v[136:137] op_sel_hi:[1,0,1]
	v_readlane_b32 s0, v167, 7
	s_waitcnt vmcnt(48)
	v_cvt_scalef32_pk_f32_fp4 v[0:1], v158, 1.0
	v_cvt_scalef32_pk_f32_fp4 v[2:3], v158, 1.0 op_sel:[1,0,0]
	v_cvt_scalef32_pk_f32_fp4 v[4:5], v158, 1.0 op_sel:[0,1,0]
	v_cvt_scalef32_pk_f32_fp4 v[6:7], v158, 1.0 op_sel:[1,1,0]
	v_cvt_scalef32_pk_f32_fp4 v[8:9], v159, 1.0
	v_cvt_scalef32_pk_f32_fp4 v[10:11], v159, 1.0 op_sel:[1,0,0]
	v_cvt_scalef32_pk_f32_fp4 v[12:13], v159, 1.0 op_sel:[0,1,0]
	v_cvt_scalef32_pk_f32_fp4 v[14:15], v159, 1.0 op_sel:[1,1,0]
	v_readlane_b32 s54, v92, 23
	s_lshl_b32 s56, s54, 9
	s_add_u32 s56, s64, s56
	s_addc_u32 s57, s65, 0
	global_load_dwordx2 v[158:159], v227, s[56:57]
	v_pk_fma_f32 v[130:131], v[0:1], s[0:1], v[130:131] op_sel_hi:[1,0,1]
	v_pk_fma_f32 v[138:139], v[2:3], s[0:1], v[138:139] op_sel_hi:[1,0,1]
	v_pk_fma_f32 v[140:141], v[4:5], s[0:1], v[140:141] op_sel_hi:[1,0,1]
	v_pk_fma_f32 v[142:143], v[6:7], s[0:1], v[142:143] op_sel_hi:[1,0,1]
	v_pk_fma_f32 v[128:129], v[8:9], s[0:1], v[128:129] op_sel_hi:[1,0,1]
	v_pk_fma_f32 v[132:133], v[10:11], s[0:1], v[132:133] op_sel_hi:[1,0,1]
	v_pk_fma_f32 v[134:135], v[12:13], s[0:1], v[134:135] op_sel_hi:[1,0,1]
	v_pk_fma_f32 v[136:137], v[14:15], s[0:1], v[136:137] op_sel_hi:[1,0,1]
	v_readlane_b32 s0, v167, 8
	s_waitcnt vmcnt(48)
	v_cvt_scalef32_pk_f32_fp4 v[0:1], v168, 1.0
	v_cvt_scalef32_pk_f32_fp4 v[2:3], v168, 1.0 op_sel:[1,0,0]
	v_cvt_scalef32_pk_f32_fp4 v[4:5], v168, 1.0 op_sel:[0,1,0]
	v_cvt_scalef32_pk_f32_fp4 v[6:7], v168, 1.0 op_sel:[1,1,0]
	v_cvt_scalef32_pk_f32_fp4 v[8:9], v169, 1.0
	v_cvt_scalef32_pk_f32_fp4 v[10:11], v169, 1.0 op_sel:[1,0,0]
	v_cvt_scalef32_pk_f32_fp4 v[12:13], v169, 1.0 op_sel:[0,1,0]
	v_cvt_scalef32_pk_f32_fp4 v[14:15], v169, 1.0 op_sel:[1,1,0]
	v_readlane_b32 s54, v92, 24
	s_lshl_b32 s56, s54, 9
	s_add_u32 s56, s64, s56
	s_addc_u32 s57, s65, 0
	global_load_dwordx2 v[168:169], v227, s[56:57]
	v_pk_fma_f32 v[130:131], v[0:1], s[0:1], v[130:131] op_sel_hi:[1,0,1]
	v_pk_fma_f32 v[138:139], v[2:3], s[0:1], v[138:139] op_sel_hi:[1,0,1]
	v_pk_fma_f32 v[140:141], v[4:5], s[0:1], v[140:141] op_sel_hi:[1,0,1]
	v_pk_fma_f32 v[142:143], v[6:7], s[0:1], v[142:143] op_sel_hi:[1,0,1]
	v_pk_fma_f32 v[128:129], v[8:9], s[0:1], v[128:129] op_sel_hi:[1,0,1]
	v_pk_fma_f32 v[132:133], v[10:11], s[0:1], v[132:133] op_sel_hi:[1,0,1]
	v_pk_fma_f32 v[134:135], v[12:13], s[0:1], v[134:135] op_sel_hi:[1,0,1]
	v_pk_fma_f32 v[136:137], v[14:15], s[0:1], v[136:137] op_sel_hi:[1,0,1]
	v_readlane_b32 s0, v167, 9
	s_waitcnt vmcnt(48)
; __device__ void peer_gather_phase(const Params& P, int l, bool do_store) {
;     ...
;     auto load_batch = [&](uint2 (&u6)[12], uint2 (&v8)[8], int bt) {
;       const int evs = (bt < 8) ? ev0 : ev1;
;       const int kb = (bt & 7) * 8;
; #pragma unroll
;       for (int pr = 0; pr < 4; ++pr) {
;         const int ea = __builtin_amdgcn_readlane(evs, kb + 2 * pr), eb = __builtin_amdgcn_readlane(evs, kb + 2 * pr + 1);
;         const uint2* up = (const uint2*)(U + (size_t)(uphi ? eb : ea) * 768);
;         u6[3 * pr] = up[0]; u6[3 * pr + 1] = up[1]; u6[3 * pr + 2] = up[2];
;         v8[2 * pr] = *(const uint2*)(V + (size_t)ea * 512);
;         v8[2 * pr + 1] = *(const uint2*)(V + (size_t)eb * 512);
;       }
;     };
;     auto compute_batch = [&](const uint2 (&u6)[12], const uint2 (&v8)[8], int bt) {
;       const int kb = (bt & 7) * 8;
;       float dvec = 0.f;
; #pragma unroll
;       for (int pr = 0; pr < 4; ++pr) {
;         v6u_t qv; qv[0] = u6[3 * pr].x; qv[1] = u6[3 * pr].y; qv[2] = u6[3 * pr + 1].x; qv[3] = u6[3 * pr + 1].y; qv[4] = u6[3 * pr + 2].x; qv[5] = u6[3 * pr + 2].y;
;         const v32f_t wv = __builtin_amdgcn_cvt_scalef32_pk32_f32_fp6(qv, 1.0f);
;         f32x2 a2 = f32x2{0.f, 0.f};
; #pragma unroll
;         for (int i = 0; i < 16; ++i) a2 += f32x2{wv[2 * i], wv[2 * i + 1]} * xu[i];
;         float hs = a2.x + a2.y;
;         hs += dpp_row_shr(hs, 1); hs += dpp_row_shr(hs, 2); hs += dpp_row_shr(hs, 4); hs += dpp_row_shr(hs, 8);
;         hs += __builtin_bit_cast(float, __builtin_amdgcn_update_dpp(0, __builtin_bit_cast(int, hs), 0x142, 0xa, 0xf, false));
;         const float da = __builtin_bit_cast(float, __builtin_amdgcn_readlane(__builtin_bit_cast(int, hs), 31));
;         const float db = __builtin_bit_cast(float, __builtin_amdgcn_readlane(__builtin_bit_cast(int, hs), 63));
;         dvec = (lane == kb + 2 * pr) ? da : dvec;
;         dvec = (lane == kb + 2 * pr + 1) ? db : dvec;
;       }
;       const float sux = (bt < 8) ? sux0 : sux1;
;       const float gsx = (bt < 8) ? gsx0 : gsx1;
;       const float avec = gelu_t(dvec * sux) * gsx;
; #pragma unroll
;       for (int j = 0; j < 8; ++j) {
;         const float a = __builtin_bit_cast(float, __builtin_amdgcn_readlane(__builtin_bit_cast(int, avec), kb + j));
;         const f32x2 aa = f32x2{a, a};
	v_cvt_scalef32_pk_f32_fp4 v[0:1], v170, 1.0
	v_cvt_scalef32_pk_f32_fp4 v[2:3], v170, 1.0 op_sel:[1,0,0]
	v_cvt_scalef32_pk_f32_fp4 v[4:5], v170, 1.0 op_sel:[0,1,0]
	v_cvt_scalef32_pk_f32_fp4 v[6:7], v170, 1.0 op_sel:[1,1,0]
	v_cvt_scalef32_pk_f32_fp4 v[8:9], v171, 1.0
	v_cvt_scalef32_pk_f32_fp4 v[10:11], v171, 1.0 op_sel:[1,0,0]
	v_cvt_scalef32_pk_f32_fp4 v[12:13], v171, 1.0 op_sel:[0,1,0]
	v_cvt_scalef32_pk_f32_fp4 v[14:15], v171, 1.0 op_sel:[1,1,0]
	v_readlane_b32 s54, v92, 25
	s_lshl_b32 s56, s54, 9
	s_add_u32 s56, s64, s56
	s_addc_u32 s57, s65, 0
	global_load_dwordx2 v[170:171], v227, s[56:57]
	v_pk_fma_f32 v[130:131], v[0:1], s[0:1], v[130:131] op_sel_hi:[1,0,1]
	v_pk_fma_f32 v[138:139], v[2:3], s[0:1], v[138:139] op_sel_hi:[1,0,1]
	v_pk_fma_f32 v[140:141], v[4:5], s[0:1], v[140:141] op_sel_hi:[1,0,1]
	v_pk_fma_f32 v[142:143], v[6:7], s[0:1], v[142:143] op_sel_hi:[1,0,1]
	v_pk_fma_f32 v[128:129], v[8:9], s[0:1], v[128:129] op_sel_hi:[1,0,1]
	v_pk_fma_f32 v[132:133], v[10:11], s[0:1], v[132:133] op_sel_hi:[1,0,1]
	v_pk_fma_f32 v[134:135], v[12:13], s[0:1], v[134:135] op_sel_hi:[1,0,1]
	v_pk_fma_f32 v[136:137], v[14:15], s[0:1], v[136:137] op_sel_hi:[1,0,1]
	v_readlane_b32 s0, v167, 10
	s_waitcnt vmcnt(48)
	v_cvt_scalef32_pk_f32_fp4 v[0:1], v172, 1.0
	v_cvt_scalef32_pk_f32_fp4 v[2:3], v172, 1.0 op_sel:[1,0,0]
	v_cvt_scalef32_pk_f32_fp4 v[4:5], v172, 1.0 op_sel:[0,1,0]
	v_cvt_scalef32_pk_f32_fp4 v[6:7], v172, 1.0 op_sel:[1,1,0]
	v_cvt_scalef32_pk_f32_fp4 v[8:9], v173, 1.0
	v_cvt_scalef32_pk_f32_fp4 v[10:11], v173, 1.0 op_sel:[1,0,0]
	v_cvt_scalef32_pk_f32_fp4 v[12:13], v173, 1.0 op_sel:[0,1,0]
	v_cvt_scalef32_pk_f32_fp4 v[14:15], v173, 1.0 op_sel:[1,1,0]
	v_readlane_b32 s54, v92, 26
	s_lshl_b32 s56, s54, 9
	s_add_u32 s56, s64, s56
	s_addc_u32 s57, s65, 0
	global_load_dwordx2 v[172:173], v227, s[56:57]
	v_pk_fma_f32 v[130:131], v[0:1], s[0:1], v[130:131] op_sel_hi:[1,0,1]
	v_pk_fma_f32 v[138:139], v[2:3], s[0:1], v[138:139] op_sel_hi:[1,0,1]
	v_pk_fma_f32 v[140:141], v[4:5], s[0:1], v[140:141] op_sel_hi:[1,0,1]
	v_pk_fma_f32 v[142:143], v[6:7], s[0:1], v[142:143] op_sel_hi:[1,0,1]
	v_pk_fma_f32 v[128:129], v[8:9], s[0:1], v[128:129] op_sel_hi:[1,0,1]
	v_pk_fma_f32 v[132:133], v[10:11], s[0:1], v[132:133] op_sel_hi:[1,0,1]
	v_pk_fma_f32 v[134:135], v[12:13], s[0:1], v[134:135] op_sel_hi:[1,0,1]
	v_pk_fma_f32 v[136:137], v[14:15], s[0:1], v[136:137] op_sel_hi:[1,0,1]
	v_readlane_b32 s0, v167, 11
	s_waitcnt vmcnt(48)
	v_cvt_scalef32_pk_f32_fp4 v[0:1], v174, 1.0
	v_cvt_scalef32_pk_f32_fp4 v[2:3], v174, 1.0 op_sel:[1,0,0]
	v_cvt_scalef32_pk_f32_fp4 v[4:5], v174, 1.0 op_sel:[0,1,0]
	v_cvt_scalef32_pk_f32_fp4 v[6:7], v174, 1.0 op_sel:[1,1,0]
	v_cvt_scalef32_pk_f32_fp4 v[8:9], v175, 1.0
	v_cvt_scalef32_pk_f32_fp4 v[10:11], v175, 1.0 op_sel:[1,0,0]
	v_cvt_scalef32_pk_f32_fp4 v[12:13], v175, 1.0 op_sel:[0,1,0]
	v_cvt_scalef32_pk_f32_fp4 v[14:15], v175, 1.0 op_sel:[1,1,0]
	v_readlane_b32 s54, v92, 27
	s_lshl_b32 s56, s54, 9
	s_add_u32 s56, s64, s56
	s_addc_u32 s57, s65, 0
	global_load_dwordx2 v[174:175], v227, s[56:57]
	v_pk_fma_f32 v[130:131], v[0:1], s[0:1], v[130:131] op_sel_hi:[1,0,1]
	v_pk_fma_f32 v[138:139], v[2:3], s[0:1], v[138:139] op_sel_hi:[1,0,1]
	v_pk_fma_f32 v[140:141], v[4:5], s[0:1], v[140:141] op_sel_hi:[1,0,1]
	v_pk_fma_f32 v[142:143], v[6:7], s[0:1], v[142:143] op_sel_hi:[1,0,1]
	v_pk_fma_f32 v[128:129], v[8:9], s[0:1], v[128:129] op_sel_hi:[1,0,1]
	v_pk_fma_f32 v[132:133], v[10:11], s[0:1], v[132:133] op_sel_hi:[1,0,1]
	v_pk_fma_f32 v[134:135], v[12:13], s[0:1], v[134:135] op_sel_hi:[1,0,1]
	v_pk_fma_f32 v[136:137], v[14:15], s[0:1], v[136:137] op_sel_hi:[1,0,1]
	v_readlane_b32 s0, v167, 12
	s_waitcnt vmcnt(48)
	v_cvt_scalef32_pk_f32_fp4 v[0:1], v180, 1.0
	v_cvt_scalef32_pk_f32_fp4 v[2:3], v180, 1.0 op_sel:[1,0,0]
	v_cvt_scalef32_pk_f32_fp4 v[4:5], v180, 1.0 op_sel:[0,1,0]
	v_cvt_scalef32_pk_f32_fp4 v[6:7], v180, 1.0 op_sel:[1,1,0]
	v_cvt_scalef32_pk_f32_fp4 v[8:9], v181, 1.0
	v_cvt_scalef32_pk_f32_fp4 v[10:11], v181, 1.0 op_sel:[1,0,0]
	v_cvt_scalef32_pk_f32_fp4 v[12:13], v181, 1.0 op_sel:[0,1,0]
	v_cvt_scalef32_pk_f32_fp4 v[14:15], v181, 1.0 op_sel:[1,1,0]
	v_readlane_b32 s54, v92, 28
	s_lshl_b32 s56, s54, 9
	s_add_u32 s56, s64, s56
	s_addc_u32 s57, s65, 0
	global_load_dwordx2 v[180:181], v227, s[56:57]
	v_pk_fma_f32 v[130:131], v[0:1], s[0:1], v[130:131] op_sel_hi:[1,0,1]
	v_pk_fma_f32 v[138:139], v[2:3], s[0:1], v[138:139] op_sel_hi:[1,0,1]
	v_pk_fma_f32 v[140:141], v[4:5], s[0:1], v[140:141] op_sel_hi:[1,0,1]
	v_pk_fma_f32 v[142:143], v[6:7], s[0:1], v[142:143] op_sel_hi:[1,0,1]
	v_pk_fma_f32 v[128:129], v[8:9], s[0:1], v[128:129] op_sel_hi:[1,0,1]
	v_pk_fma_f32 v[132:133], v[10:11], s[0:1], v[132:133] op_sel_hi:[1,0,1]
	v_pk_fma_f32 v[134:135], v[12:13], s[0:1], v[134:135] op_sel_hi:[1,0,1]
	v_pk_fma_f32 v[136:137], v[14:15], s[0:1], v[136:137] op_sel_hi:[1,0,1]
	v_readlane_b32 s0, v167, 13
	s_waitcnt vmcnt(48)
	v_cvt_scalef32_pk_f32_fp4 v[0:1], v182, 1.0
	v_cvt_scalef32_pk_f32_fp4 v[2:3], v182, 1.0 op_sel:[1,0,0]
	v_cvt_scalef32_pk_f32_fp4 v[4:5], v182, 1.0 op_sel:[0,1,0]
	v_cvt_scalef32_pk_f32_fp4 v[6:7], v182, 1.0 op_sel:[1,1,0]
	v_cvt_scalef32_pk_f32_fp4 v[8:9], v183, 1.0
	v_cvt_scalef32_pk_f32_fp4 v[10:11], v183, 1.0 op_sel:[1,0,0]
	v_cvt_scalef32_pk_f32_fp4 v[12:13], v183, 1.0 op_sel:[0,1,0]
	v_cvt_scalef32_pk_f32_fp4 v[14:15], v183, 1.0 op_sel:[1,1,0]
	v_readlane_b32 s54, v92, 29
	s_lshl_b32 s56, s54, 9
	s_add_u32 s56, s64, s56
	s_addc_u32 s57, s65, 0
	global_load_dwordx2 v[182:183], v227, s[56:57]
	v_pk_fma_f32 v[130:131], v[0:1], s[0:1], v[130:131] op_sel_hi:[1,0,1]
	v_pk_fma_f32 v[138:139], v[2:3], s[0:1], v[138:139] op_sel_hi:[1,0,1]
	v_pk_fma_f32 v[140:141], v[4:5], s[0:1], v[140:141] op_sel_hi:[1,0,1]
	v_pk_fma_f32 v[142:143], v[6:7], s[0:1], v[142:143] op_sel_hi:[1,0,1]
	v_pk_fma_f32 v[128:129], v[8:9], s[0:1], v[128:129] op_sel_hi:[1,0,1]
	v_pk_fma_f32 v[132:133], v[10:11], s[0:1], v[132:133] op_sel_hi:[1,0,1]
	v_pk_fma_f32 v[134:135], v[12:13], s[0:1], v[134:135] op_sel_hi:[1,0,1]
	v_pk_fma_f32 v[136:137], v[14:15], s[0:1], v[136:137] op_sel_hi:[1,0,1]
	v_readlane_b32 s0, v167, 14
	s_waitcnt vmcnt(48)
; __device__ void peer_gather_phase(const Params& P, int l, bool do_store) {
;     ...
;     auto load_batch = [&](uint2 (&u6)[12], uint2 (&v8)[8], int bt) {
;       const int evs = (bt < 8) ? ev0 : ev1;
;       const int kb = (bt & 7) * 8;
; #pragma unroll
;       for (int pr = 0; pr < 4; ++pr) {
;         const int ea = __builtin_amdgcn_readlane(evs, kb + 2 * pr), eb = __builtin_amdgcn_readlane(evs, kb + 2 * pr + 1);
;         const uint2* up = (const uint2*)(U + (size_t)(uphi ? eb : ea) * 768);
;         u6[3 * pr] = up[0]; u6[3 * pr + 1] = up[1]; u6[3 * pr + 2] = up[2];
;         v8[2 * pr] = *(const uint2*)(V + (size_t)ea * 512);
;         v8[2 * pr + 1] = *(const uint2*)(V + (size_t)eb * 512);
;       }
;     };
;     auto compute_batch = [&](const uint2 (&u6)[12], const uint2 (&v8)[8], int bt) {
;       const int kb = (bt & 7) * 8;
;       float dvec = 0.f;
; #pragma unroll
;       for (int pr = 0; pr < 4; ++pr) {
;         v6u_t qv; qv[0] = u6[3 * pr].x; qv[1] = u6[3 * pr].y; qv[2] = u6[3 * pr + 1].x; qv[3] = u6[3 * pr + 1].y; qv[4] = u6[3 * pr + 2].x; qv[5] = u6[3 * pr + 2].y;
;         const v32f_t wv = __builtin_amdgcn_cvt_scalef32_pk32_f32_fp6(qv, 1.0f);
;         f32x2 a2 = f32x2{0.f, 0.f};
; #pragma unroll
;         for (int i = 0; i < 16; ++i) a2 += f32x2{wv[2 * i], wv[2 * i + 1]} * xu[i];
;         float hs = a2.x + a2.y;
;         hs += dpp_row_shr(hs, 1); hs += dpp_row_shr(hs, 2); hs += dpp_row_shr(hs, 4); hs += dpp_row_shr(hs, 8);
;         hs += __builtin_bit_cast(float, __builtin_amdgcn_update_dpp(0, __builtin_bit_cast(int, hs), 0x142, 0xa, 0xf, false));
;         const float da = __builtin_bit_cast(float, __builtin_amdgcn_readlane(__builtin_bit_cast(int, hs), 31));
;         const float db = __builtin_bit_cast(float, __builtin_amdgcn_readlane(__builtin_bit_cast(int, hs), 63));
;         dvec = (lane == kb + 2 * pr) ? da : dvec;
;         dvec = (lane == kb + 2 * pr + 1) ? db : dvec;
;       }
;       const float sux = (bt < 8) ? sux0 : sux1;
;       const float gsx = (bt < 8) ? gsx0 : gsx1;
;       const float avec = gelu_t(dvec * sux) * gsx;
; #pragma unroll
;       for (int j = 0; j < 8; ++j) {
;         const float a = __builtin_bit_cast(float, __builtin_amdgcn_readlane(__builtin_bit_cast(int, avec), kb + j));
;         const f32x2 aa = f32x2{a, a};
	v_cvt_scalef32_pk_f32_fp4 v[0:1], v184, 1.0
	v_cvt_scalef32_pk_f32_fp4 v[2:3], v184, 1.0 op_sel:[1,0,0]
	v_cvt_scalef32_pk_f32_fp4 v[4:5], v184, 1.0 op_sel:[0,1,0]
	v_cvt_scalef32_pk_f32_fp4 v[6:7], v184, 1.0 op_sel:[1,1,0]
	v_cvt_scalef32_pk_f32_fp4 v[8:9], v185, 1.0
	v_cvt_scalef32_pk_f32_fp4 v[10:11], v185, 1.0 op_sel:[1,0,0]
	v_cvt_scalef32_pk_f32_fp4 v[12:13], v185, 1.0 op_sel:[0,1,0]
	v_cvt_scalef32_pk_f32_fp4 v[14:15], v185, 1.0 op_sel:[1,1,0]
	v_readlane_b32 s54, v92, 30
	s_lshl_b32 s56, s54, 9
	s_add_u32 s56, s64, s56
	s_addc_u32 s57, s65, 0
	global_load_dwordx2 v[184:185], v227, s[56:57]
	v_pk_fma_f32 v[130:131], v[0:1], s[0:1], v[130:131] op_sel_hi:[1,0,1]
	v_pk_fma_f32 v[138:139], v[2:3], s[0:1], v[138:139] op_sel_hi:[1,0,1]
	v_pk_fma_f32 v[140:141], v[4:5], s[0:1], v[140:141] op_sel_hi:[1,0,1]
	v_pk_fma_f32 v[142:143], v[6:7], s[0:1], v[142:143] op_sel_hi:[1,0,1]
	v_pk_fma_f32 v[128:129], v[8:9], s[0:1], v[128:129] op_sel_hi:[1,0,1]
	v_pk_fma_f32 v[132:133], v[10:11], s[0:1], v[132:133] op_sel_hi:[1,0,1]
	v_pk_fma_f32 v[134:135], v[12:13], s[0:1], v[134:135] op_sel_hi:[1,0,1]
	v_pk_fma_f32 v[136:137], v[14:15], s[0:1], v[136:137] op_sel_hi:[1,0,1]
	v_readlane_b32 s0, v167, 15
	s_waitcnt vmcnt(48)
	v_cvt_scalef32_pk_f32_fp4 v[0:1], v186, 1.0
	v_cvt_scalef32_pk_f32_fp4 v[2:3], v186, 1.0 op_sel:[1,0,0]
	v_cvt_scalef32_pk_f32_fp4 v[4:5], v186, 1.0 op_sel:[0,1,0]
	v_cvt_scalef32_pk_f32_fp4 v[6:7], v186, 1.0 op_sel:[1,1,0]
	v_cvt_scalef32_pk_f32_fp4 v[8:9], v187, 1.0
	v_cvt_scalef32_pk_f32_fp4 v[10:11], v187, 1.0 op_sel:[1,0,0]
	v_cvt_scalef32_pk_f32_fp4 v[12:13], v187, 1.0 op_sel:[0,1,0]
	v_cvt_scalef32_pk_f32_fp4 v[14:15], v187, 1.0 op_sel:[1,1,0]
	v_readlane_b32 s54, v92, 31
	s_lshl_b32 s56, s54, 9
	s_add_u32 s56, s64, s56
	s_addc_u32 s57, s65, 0
	global_load_dwordx2 v[186:187], v227, s[56:57]
	v_pk_fma_f32 v[130:131], v[0:1], s[0:1], v[130:131] op_sel_hi:[1,0,1]
	v_pk_fma_f32 v[138:139], v[2:3], s[0:1], v[138:139] op_sel_hi:[1,0,1]
	v_pk_fma_f32 v[140:141], v[4:5], s[0:1], v[140:141] op_sel_hi:[1,0,1]
	v_pk_fma_f32 v[142:143], v[6:7], s[0:1], v[142:143] op_sel_hi:[1,0,1]
	v_pk_fma_f32 v[128:129], v[8:9], s[0:1], v[128:129] op_sel_hi:[1,0,1]
	v_pk_fma_f32 v[132:133], v[10:11], s[0:1], v[132:133] op_sel_hi:[1,0,1]
	v_pk_fma_f32 v[134:135], v[12:13], s[0:1], v[134:135] op_sel_hi:[1,0,1]
	v_pk_fma_f32 v[136:137], v[14:15], s[0:1], v[136:137] op_sel_hi:[1,0,1]
	v_readlane_b32 s0, v167, 16
	s_waitcnt vmcnt(15)
	v_cvt_scalef32_pk_f32_fp4 v[0:1], v144, 1.0
	v_cvt_scalef32_pk_f32_fp4 v[2:3], v144, 1.0 op_sel:[1,0,0]
	v_cvt_scalef32_pk_f32_fp4 v[4:5], v144, 1.0 op_sel:[0,1,0]
	v_cvt_scalef32_pk_f32_fp4 v[6:7], v144, 1.0 op_sel:[1,1,0]
	v_cvt_scalef32_pk_f32_fp4 v[8:9], v145, 1.0
	v_cvt_scalef32_pk_f32_fp4 v[10:11], v145, 1.0 op_sel:[1,0,0]
	v_cvt_scalef32_pk_f32_fp4 v[12:13], v145, 1.0 op_sel:[0,1,0]
	v_cvt_scalef32_pk_f32_fp4 v[14:15], v145, 1.0 op_sel:[1,1,0]
	v_readlane_b32 s54, v92, 32
	s_lshl_b32 s56, s54, 9
	s_add_u32 s56, s64, s56
	s_addc_u32 s57, s65, 0
	global_load_dwordx2 v[144:145], v227, s[56:57]
	v_pk_fma_f32 v[130:131], v[0:1], s[0:1], v[130:131] op_sel_hi:[1,0,1]
	v_pk_fma_f32 v[138:139], v[2:3], s[0:1], v[138:139] op_sel_hi:[1,0,1]
	v_pk_fma_f32 v[140:141], v[4:5], s[0:1], v[140:141] op_sel_hi:[1,0,1]
	v_pk_fma_f32 v[142:143], v[6:7], s[0:1], v[142:143] op_sel_hi:[1,0,1]
	v_pk_fma_f32 v[128:129], v[8:9], s[0:1], v[128:129] op_sel_hi:[1,0,1]
	v_pk_fma_f32 v[132:133], v[10:11], s[0:1], v[132:133] op_sel_hi:[1,0,1]
	v_pk_fma_f32 v[134:135], v[12:13], s[0:1], v[134:135] op_sel_hi:[1,0,1]
	v_pk_fma_f32 v[136:137], v[14:15], s[0:1], v[136:137] op_sel_hi:[1,0,1]
	v_readlane_b32 s0, v167, 17
	s_waitcnt vmcnt(15)
	v_cvt_scalef32_pk_f32_fp4 v[0:1], v146, 1.0
	v_cvt_scalef32_pk_f32_fp4 v[2:3], v146, 1.0 op_sel:[1,0,0]
	v_cvt_scalef32_pk_f32_fp4 v[4:5], v146, 1.0 op_sel:[0,1,0]
	v_cvt_scalef32_pk_f32_fp4 v[6:7], v146, 1.0 op_sel:[1,1,0]
	v_cvt_scalef32_pk_f32_fp4 v[8:9], v147, 1.0
	v_cvt_scalef32_pk_f32_fp4 v[10:11], v147, 1.0 op_sel:[1,0,0]
	v_cvt_scalef32_pk_f32_fp4 v[12:13], v147, 1.0 op_sel:[0,1,0]
	v_cvt_scalef32_pk_f32_fp4 v[14:15], v147, 1.0 op_sel:[1,1,0]
	v_readlane_b32 s54, v92, 33
	s_lshl_b32 s56, s54, 9
	s_add_u32 s56, s64, s56
	s_addc_u32 s57, s65, 0
	global_load_dwordx2 v[146:147], v227, s[56:57]
	v_pk_fma_f32 v[130:131], v[0:1], s[0:1], v[130:131] op_sel_hi:[1,0,1]
	v_pk_fma_f32 v[138:139], v[2:3], s[0:1], v[138:139] op_sel_hi:[1,0,1]
	v_pk_fma_f32 v[140:141], v[4:5], s[0:1], v[140:141] op_sel_hi:[1,0,1]
	v_pk_fma_f32 v[142:143], v[6:7], s[0:1], v[142:143] op_sel_hi:[1,0,1]
	v_pk_fma_f32 v[128:129], v[8:9], s[0:1], v[128:129] op_sel_hi:[1,0,1]
	v_pk_fma_f32 v[132:133], v[10:11], s[0:1], v[132:133] op_sel_hi:[1,0,1]
	v_pk_fma_f32 v[134:135], v[12:13], s[0:1], v[134:135] op_sel_hi:[1,0,1]
	v_pk_fma_f32 v[136:137], v[14:15], s[0:1], v[136:137] op_sel_hi:[1,0,1]
	v_readlane_b32 s0, v167, 18
	s_waitcnt vmcnt(15)
	v_cvt_scalef32_pk_f32_fp4 v[0:1], v148, 1.0
	v_cvt_scalef32_pk_f32_fp4 v[2:3], v148, 1.0 op_sel:[1,0,0]
	v_cvt_scalef32_pk_f32_fp4 v[4:5], v148, 1.0 op_sel:[0,1,0]
	v_cvt_scalef32_pk_f32_fp4 v[6:7], v148, 1.0 op_sel:[1,1,0]
	v_cvt_scalef32_pk_f32_fp4 v[8:9], v149, 1.0
	v_cvt_scalef32_pk_f32_fp4 v[10:11], v149, 1.0 op_sel:[1,0,0]
	v_cvt_scalef32_pk_f32_fp4 v[12:13], v149, 1.0 op_sel:[0,1,0]
	v_cvt_scalef32_pk_f32_fp4 v[14:15], v149, 1.0 op_sel:[1,1,0]
	v_readlane_b32 s54, v92, 34
	s_lshl_b32 s56, s54, 9
	s_add_u32 s56, s64, s56
	s_addc_u32 s57, s65, 0
	global_load_dwordx2 v[148:149], v227, s[56:57]
	v_pk_fma_f32 v[130:131], v[0:1], s[0:1], v[130:131] op_sel_hi:[1,0,1]
	v_pk_fma_f32 v[138:139], v[2:3], s[0:1], v[138:139] op_sel_hi:[1,0,1]
	v_pk_fma_f32 v[140:141], v[4:5], s[0:1], v[140:141] op_sel_hi:[1,0,1]
	v_pk_fma_f32 v[142:143], v[6:7], s[0:1], v[142:143] op_sel_hi:[1,0,1]
	v_pk_fma_f32 v[128:129], v[8:9], s[0:1], v[128:129] op_sel_hi:[1,0,1]
	v_pk_fma_f32 v[132:133], v[10:11], s[0:1], v[132:133] op_sel_hi:[1,0,1]
	v_pk_fma_f32 v[134:135], v[12:13], s[0:1], v[134:135] op_sel_hi:[1,0,1]
	v_pk_fma_f32 v[136:137], v[14:15], s[0:1], v[136:137] op_sel_hi:[1,0,1]
	v_readlane_b32 s0, v167, 19
	s_waitcnt vmcnt(15)
; __device__ void peer_gather_phase(const Params& P, int l, bool do_store) {
;     ...
;     auto load_batch = [&](uint2 (&u6)[12], uint2 (&v8)[8], int bt) {
;       const int evs = (bt < 8) ? ev0 : ev1;
;       const int kb = (bt & 7) * 8;
; #pragma unroll
;       for (int pr = 0; pr < 4; ++pr) {
;         const int ea = __builtin_amdgcn_readlane(evs, kb + 2 * pr), eb = __builtin_amdgcn_readlane(evs, kb + 2 * pr + 1);
;         const uint2* up = (const uint2*)(U + (size_t)(uphi ? eb : ea) * 768);
;         u6[3 * pr] = up[0]; u6[3 * pr + 1] = up[1]; u6[3 * pr + 2] = up[2];
;         v8[2 * pr] = *(const uint2*)(V + (size_t)ea * 512);
;         v8[2 * pr + 1] = *(const uint2*)(V + (size_t)eb * 512);
;       }
;     };
;     auto compute_batch = [&](const uint2 (&u6)[12], const uint2 (&v8)[8], int bt) {
;       const int kb = (bt & 7) * 8;
;       float dvec = 0.f;
; #pragma unroll
;       for (int pr = 0; pr < 4; ++pr) {
;         v6u_t qv; qv[0] = u6[3 * pr].x; qv[1] = u6[3 * pr].y; qv[2] = u6[3 * pr + 1].x; qv[3] = u6[3 * pr + 1].y; qv[4] = u6[3 * pr + 2].x; qv[5] = u6[3 * pr + 2].y;
;         const v32f_t wv = __builtin_amdgcn_cvt_scalef32_pk32_f32_fp6(qv, 1.0f);
;         f32x2 a2 = f32x2{0.f, 0.f};
; #pragma unroll
;         for (int i = 0; i < 16; ++i) a2 += f32x2{wv[2 * i], wv[2 * i + 1]} * xu[i];
;         float hs = a2.x + a2.y;
;         hs += dpp_row_shr(hs, 1); hs += dpp_row_shr(hs, 2); hs += dpp_row_shr(hs, 4); hs += dpp_row_shr(hs, 8);
;         hs += __builtin_bit_cast(float, __builtin_amdgcn_update_dpp(0, __builtin_bit_cast(int, hs), 0x142, 0xa, 0xf, false));
;         const float da = __builtin_bit_cast(float, __builtin_amdgcn_readlane(__builtin_bit_cast(int, hs), 31));
;         const float db = __builtin_bit_cast(float, __builtin_amdgcn_readlane(__builtin_bit_cast(int, hs), 63));
;         dvec = (lane == kb + 2 * pr) ? da : dvec;
;         dvec = (lane == kb + 2 * pr + 1) ? db : dvec;
;       }
;       const float sux = (bt < 8) ? sux0 : sux1;
;       const float gsx = (bt < 8) ? gsx0 : gsx1;
;       const float avec = gelu_t(dvec * sux) * gsx;
; #pragma unroll
;       for (int j = 0; j < 8; ++j) {
;         const float a = __builtin_bit_cast(float, __builtin_amdgcn_readlane(__builtin_bit_cast(int, avec), kb + j));
;         const f32x2 aa = f32x2{a, a};
	v_cvt_scalef32_pk_f32_fp4 v[0:1], v150, 1.0
	v_cvt_scalef32_pk_f32_fp4 v[2:3], v150, 1.0 op_sel:[1,0,0]
	v_cvt_scalef32_pk_f32_fp4 v[4:5], v150, 1.0 op_sel:[0,1,0]
	v_cvt_scalef32_pk_f32_fp4 v[6:7], v150, 1.0 op_sel:[1,1,0]
	v_cvt_scalef32_pk_f32_fp4 v[8:9], v151, 1.0
	v_cvt_scalef32_pk_f32_fp4 v[10:11], v151, 1.0 op_sel:[1,0,0]
	v_cvt_scalef32_pk_f32_fp4 v[12:13], v151, 1.0 op_sel:[0,1,0]
	v_cvt_scalef32_pk_f32_fp4 v[14:15], v151, 1.0 op_sel:[1,1,0]
	v_readlane_b32 s54, v92, 35
	s_lshl_b32 s56, s54, 9
	s_add_u32 s56, s64, s56
	s_addc_u32 s57, s65, 0
	global_load_dwordx2 v[150:151], v227, s[56:57]
	v_pk_fma_f32 v[130:131], v[0:1], s[0:1], v[130:131] op_sel_hi:[1,0,1]
	v_pk_fma_f32 v[138:139], v[2:3], s[0:1], v[138:139] op_sel_hi:[1,0,1]
	v_pk_fma_f32 v[140:141], v[4:5], s[0:1], v[140:141] op_sel_hi:[1,0,1]
	v_pk_fma_f32 v[142:143], v[6:7], s[0:1], v[142:143] op_sel_hi:[1,0,1]
	v_pk_fma_f32 v[128:129], v[8:9], s[0:1], v[128:129] op_sel_hi:[1,0,1]
	v_pk_fma_f32 v[132:133], v[10:11], s[0:1], v[132:133] op_sel_hi:[1,0,1]
	v_pk_fma_f32 v[134:135], v[12:13], s[0:1], v[134:135] op_sel_hi:[1,0,1]
	v_pk_fma_f32 v[136:137], v[14:15], s[0:1], v[136:137] op_sel_hi:[1,0,1]
	v_readlane_b32 s0, v167, 20
	s_waitcnt vmcnt(15)
	v_cvt_scalef32_pk_f32_fp4 v[0:1], v152, 1.0
	v_cvt_scalef32_pk_f32_fp4 v[2:3], v152, 1.0 op_sel:[1,0,0]
	v_cvt_scalef32_pk_f32_fp4 v[4:5], v152, 1.0 op_sel:[0,1,0]
	v_cvt_scalef32_pk_f32_fp4 v[6:7], v152, 1.0 op_sel:[1,1,0]
	v_cvt_scalef32_pk_f32_fp4 v[8:9], v153, 1.0
	v_cvt_scalef32_pk_f32_fp4 v[10:11], v153, 1.0 op_sel:[1,0,0]
	v_cvt_scalef32_pk_f32_fp4 v[12:13], v153, 1.0 op_sel:[0,1,0]
	v_cvt_scalef32_pk_f32_fp4 v[14:15], v153, 1.0 op_sel:[1,1,0]
	v_readlane_b32 s54, v92, 36
	s_lshl_b32 s56, s54, 9
	s_add_u32 s56, s64, s56
	s_addc_u32 s57, s65, 0
	global_load_dwordx2 v[152:153], v227, s[56:57]
	v_pk_fma_f32 v[130:131], v[0:1], s[0:1], v[130:131] op_sel_hi:[1,0,1]
	v_pk_fma_f32 v[138:139], v[2:3], s[0:1], v[138:139] op_sel_hi:[1,0,1]
	v_pk_fma_f32 v[140:141], v[4:5], s[0:1], v[140:141] op_sel_hi:[1,0,1]
	v_pk_fma_f32 v[142:143], v[6:7], s[0:1], v[142:143] op_sel_hi:[1,0,1]
	v_pk_fma_f32 v[128:129], v[8:9], s[0:1], v[128:129] op_sel_hi:[1,0,1]
	v_pk_fma_f32 v[132:133], v[10:11], s[0:1], v[132:133] op_sel_hi:[1,0,1]
	v_pk_fma_f32 v[134:135], v[12:13], s[0:1], v[134:135] op_sel_hi:[1,0,1]
	v_pk_fma_f32 v[136:137], v[14:15], s[0:1], v[136:137] op_sel_hi:[1,0,1]
	v_readlane_b32 s0, v167, 21
	s_waitcnt vmcnt(15)
	v_cvt_scalef32_pk_f32_fp4 v[0:1], v154, 1.0
	v_cvt_scalef32_pk_f32_fp4 v[2:3], v154, 1.0 op_sel:[1,0,0]
	v_cvt_scalef32_pk_f32_fp4 v[4:5], v154, 1.0 op_sel:[0,1,0]
	v_cvt_scalef32_pk_f32_fp4 v[6:7], v154, 1.0 op_sel:[1,1,0]
	v_cvt_scalef32_pk_f32_fp4 v[8:9], v155, 1.0
	v_cvt_scalef32_pk_f32_fp4 v[10:11], v155, 1.0 op_sel:[1,0,0]
	v_cvt_scalef32_pk_f32_fp4 v[12:13], v155, 1.0 op_sel:[0,1,0]
	v_cvt_scalef32_pk_f32_fp4 v[14:15], v155, 1.0 op_sel:[1,1,0]
	v_readlane_b32 s54, v92, 37
	s_lshl_b32 s56, s54, 9
	s_add_u32 s56, s64, s56
	s_addc_u32 s57, s65, 0
	global_load_dwordx2 v[154:155], v227, s[56:57]
	v_pk_fma_f32 v[130:131], v[0:1], s[0:1], v[130:131] op_sel_hi:[1,0,1]
	v_pk_fma_f32 v[138:139], v[2:3], s[0:1], v[138:139] op_sel_hi:[1,0,1]
	v_pk_fma_f32 v[140:141], v[4:5], s[0:1], v[140:141] op_sel_hi:[1,0,1]
	v_pk_fma_f32 v[142:143], v[6:7], s[0:1], v[142:143] op_sel_hi:[1,0,1]
	v_pk_fma_f32 v[128:129], v[8:9], s[0:1], v[128:129] op_sel_hi:[1,0,1]
	v_pk_fma_f32 v[132:133], v[10:11], s[0:1], v[132:133] op_sel_hi:[1,0,1]
	v_pk_fma_f32 v[134:135], v[12:13], s[0:1], v[134:135] op_sel_hi:[1,0,1]
	v_pk_fma_f32 v[136:137], v[14:15], s[0:1], v[136:137] op_sel_hi:[1,0,1]
	v_readlane_b32 s0, v167, 22
	s_waitcnt vmcnt(15)
	v_cvt_scalef32_pk_f32_fp4 v[0:1], v156, 1.0
	v_cvt_scalef32_pk_f32_fp4 v[2:3], v156, 1.0 op_sel:[1,0,0]
	v_cvt_scalef32_pk_f32_fp4 v[4:5], v156, 1.0 op_sel:[0,1,0]
	v_cvt_scalef32_pk_f32_fp4 v[6:7], v156, 1.0 op_sel:[1,1,0]
	v_cvt_scalef32_pk_f32_fp4 v[8:9], v157, 1.0
	v_cvt_scalef32_pk_f32_fp4 v[10:11], v157, 1.0 op_sel:[1,0,0]
	v_cvt_scalef32_pk_f32_fp4 v[12:13], v157, 1.0 op_sel:[0,1,0]
	v_cvt_scalef32_pk_f32_fp4 v[14:15], v157, 1.0 op_sel:[1,1,0]
	v_readlane_b32 s54, v92, 38
	s_lshl_b32 s56, s54, 9
	s_add_u32 s56, s64, s56
	s_addc_u32 s57, s65, 0
	global_load_dwordx2 v[156:157], v227, s[56:57]
	v_pk_fma_f32 v[130:131], v[0:1], s[0:1], v[130:131] op_sel_hi:[1,0,1]
	v_pk_fma_f32 v[138:139], v[2:3], s[0:1], v[138:139] op_sel_hi:[1,0,1]
	v_pk_fma_f32 v[140:141], v[4:5], s[0:1], v[140:141] op_sel_hi:[1,0,1]
	v_pk_fma_f32 v[142:143], v[6:7], s[0:1], v[142:143] op_sel_hi:[1,0,1]
	v_pk_fma_f32 v[128:129], v[8:9], s[0:1], v[128:129] op_sel_hi:[1,0,1]
	v_pk_fma_f32 v[132:133], v[10:11], s[0:1], v[132:133] op_sel_hi:[1,0,1]
	v_pk_fma_f32 v[134:135], v[12:13], s[0:1], v[134:135] op_sel_hi:[1,0,1]
	v_pk_fma_f32 v[136:137], v[14:15], s[0:1], v[136:137] op_sel_hi:[1,0,1]
	v_readlane_b32 s0, v167, 23
	s_waitcnt vmcnt(15)
	v_cvt_scalef32_pk_f32_fp4 v[0:1], v158, 1.0
	v_cvt_scalef32_pk_f32_fp4 v[2:3], v158, 1.0 op_sel:[1,0,0]
	v_cvt_scalef32_pk_f32_fp4 v[4:5], v158, 1.0 op_sel:[0,1,0]
	v_cvt_scalef32_pk_f32_fp4 v[6:7], v158, 1.0 op_sel:[1,1,0]
	v_cvt_scalef32_pk_f32_fp4 v[8:9], v159, 1.0
	v_cvt_scalef32_pk_f32_fp4 v[10:11], v159, 1.0 op_sel:[1,0,0]
	v_cvt_scalef32_pk_f32_fp4 v[12:13], v159, 1.0 op_sel:[0,1,0]
	v_cvt_scalef32_pk_f32_fp4 v[14:15], v159, 1.0 op_sel:[1,1,0]
	v_readlane_b32 s54, v92, 39
	s_lshl_b32 s56, s54, 9
	s_add_u32 s56, s64, s56
	s_addc_u32 s57, s65, 0
	global_load_dwordx2 v[158:159], v227, s[56:57]
	v_pk_fma_f32 v[130:131], v[0:1], s[0:1], v[130:131] op_sel_hi:[1,0,1]
	v_pk_fma_f32 v[138:139], v[2:3], s[0:1], v[138:139] op_sel_hi:[1,0,1]
	v_pk_fma_f32 v[140:141], v[4:5], s[0:1], v[140:141] op_sel_hi:[1,0,1]
	v_pk_fma_f32 v[142:143], v[6:7], s[0:1], v[142:143] op_sel_hi:[1,0,1]
	v_pk_fma_f32 v[128:129], v[8:9], s[0:1], v[128:129] op_sel_hi:[1,0,1]
	v_pk_fma_f32 v[132:133], v[10:11], s[0:1], v[132:133] op_sel_hi:[1,0,1]
	v_pk_fma_f32 v[134:135], v[12:13], s[0:1], v[134:135] op_sel_hi:[1,0,1]
	v_pk_fma_f32 v[136:137], v[14:15], s[0:1], v[136:137] op_sel_hi:[1,0,1]
	v_readlane_b32 s0, v167, 24
	s_waitcnt vmcnt(15)
; __device__ void peer_gather_phase(const Params& P, int l, bool do_store) {
;     ...
;     auto load_batch = [&](uint2 (&u6)[12], uint2 (&v8)[8], int bt) {
;       const int evs = (bt < 8) ? ev0 : ev1;
;       const int kb = (bt & 7) * 8;
; #pragma unroll
;       for (int pr = 0; pr < 4; ++pr) {
;         const int ea = __builtin_amdgcn_readlane(evs, kb + 2 * pr), eb = __builtin_amdgcn_readlane(evs, kb + 2 * pr + 1);
;         const uint2* up = (const uint2*)(U + (size_t)(uphi ? eb : ea) * 768);
;         u6[3 * pr] = up[0]; u6[3 * pr + 1] = up[1]; u6[3 * pr + 2] = up[2];
;         v8[2 * pr] = *(const uint2*)(V + (size_t)ea * 512);
;         v8[2 * pr + 1] = *(const uint2*)(V + (size_t)eb * 512);
;       }
;     };
;     auto compute_batch = [&](const uint2 (&u6)[12], const uint2 (&v8)[8], int bt) {
;       const int kb = (bt & 7) * 8;
;       float dvec = 0.f;
; #pragma unroll
;       for (int pr = 0; pr < 4; ++pr) {
;         v6u_t qv; qv[0] = u6[3 * pr].x; qv[1] = u6[3 * pr].y; qv[2] = u6[3 * pr + 1].x; qv[3] = u6[3 * pr + 1].y; qv[4] = u6[3 * pr + 2].x; qv[5] = u6[3 * pr + 2].y;
;         const v32f_t wv = __builtin_amdgcn_cvt_scalef32_pk32_f32_fp6(qv, 1.0f);
;         f32x2 a2 = f32x2{0.f, 0.f};
; #pragma unroll
;         for (int i = 0; i < 16; ++i) a2 += f32x2{wv[2 * i], wv[2 * i + 1]} * xu[i];
;         float hs = a2.x + a2.y;
;         hs += dpp_row_shr(hs, 1); hs += dpp_row_shr(hs, 2); hs += dpp_row_shr(hs, 4); hs += dpp_row_shr(hs, 8);
;         hs += __builtin_bit_cast(float, __builtin_amdgcn_update_dpp(0, __builtin_bit_cast(int, hs), 0x142, 0xa, 0xf, false));
;         const float da = __builtin_bit_cast(float, __builtin_amdgcn_readlane(__builtin_bit_cast(int, hs), 31));
;         const float db = __builtin_bit_cast(float, __builtin_amdgcn_readlane(__builtin_bit_cast(int, hs), 63));
;         dvec = (lane == kb + 2 * pr) ? da : dvec;
;         dvec = (lane == kb + 2 * pr + 1) ? db : dvec;
;       }
;       const float sux = (bt < 8) ? sux0 : sux1;
;       const float gsx = (bt < 8) ? gsx0 : gsx1;
;       const float avec = gelu_t(dvec * sux) * gsx;
; #pragma unroll
;       for (int j = 0; j < 8; ++j) {
;         const float a = __builtin_bit_cast(float, __builtin_amdgcn_readlane(__builtin_bit_cast(int, avec), kb + j));
;         const f32x2 aa = f32x2{a, a};
	v_cvt_scalef32_pk_f32_fp4 v[0:1], v168, 1.0
	v_cvt_scalef32_pk_f32_fp4 v[2:3], v168, 1.0 op_sel:[1,0,0]
	v_cvt_scalef32_pk_f32_fp4 v[4:5], v168, 1.0 op_sel:[0,1,0]
	v_cvt_scalef32_pk_f32_fp4 v[6:7], v168, 1.0 op_sel:[1,1,0]
	v_cvt_scalef32_pk_f32_fp4 v[8:9], v169, 1.0
	v_cvt_scalef32_pk_f32_fp4 v[10:11], v169, 1.0 op_sel:[1,0,0]
	v_cvt_scalef32_pk_f32_fp4 v[12:13], v169, 1.0 op_sel:[0,1,0]
	v_cvt_scalef32_pk_f32_fp4 v[14:15], v169, 1.0 op_sel:[1,1,0]
	v_readlane_b32 s54, v92, 40
	s_lshl_b32 s56, s54, 9
	s_add_u32 s56, s64, s56
	s_addc_u32 s57, s65, 0
	global_load_dwordx2 v[168:169], v227, s[56:57]
	v_pk_fma_f32 v[130:131], v[0:1], s[0:1], v[130:131] op_sel_hi:[1,0,1]
	v_pk_fma_f32 v[138:139], v[2:3], s[0:1], v[138:139] op_sel_hi:[1,0,1]
	v_pk_fma_f32 v[140:141], v[4:5], s[0:1], v[140:141] op_sel_hi:[1,0,1]
	v_pk_fma_f32 v[142:143], v[6:7], s[0:1], v[142:143] op_sel_hi:[1,0,1]
	v_pk_fma_f32 v[128:129], v[8:9], s[0:1], v[128:129] op_sel_hi:[1,0,1]
	v_pk_fma_f32 v[132:133], v[10:11], s[0:1], v[132:133] op_sel_hi:[1,0,1]
	v_pk_fma_f32 v[134:135], v[12:13], s[0:1], v[134:135] op_sel_hi:[1,0,1]
	v_pk_fma_f32 v[136:137], v[14:15], s[0:1], v[136:137] op_sel_hi:[1,0,1]
	v_readlane_b32 s0, v167, 25
	s_waitcnt vmcnt(15)
	v_cvt_scalef32_pk_f32_fp4 v[0:1], v170, 1.0
	v_cvt_scalef32_pk_f32_fp4 v[2:3], v170, 1.0 op_sel:[1,0,0]
	v_cvt_scalef32_pk_f32_fp4 v[4:5], v170, 1.0 op_sel:[0,1,0]
	v_cvt_scalef32_pk_f32_fp4 v[6:7], v170, 1.0 op_sel:[1,1,0]
	v_cvt_scalef32_pk_f32_fp4 v[8:9], v171, 1.0
	v_cvt_scalef32_pk_f32_fp4 v[10:11], v171, 1.0 op_sel:[1,0,0]
	v_cvt_scalef32_pk_f32_fp4 v[12:13], v171, 1.0 op_sel:[0,1,0]
	v_cvt_scalef32_pk_f32_fp4 v[14:15], v171, 1.0 op_sel:[1,1,0]
	v_readlane_b32 s54, v92, 41
	s_lshl_b32 s56, s54, 9
	s_add_u32 s56, s64, s56
	s_addc_u32 s57, s65, 0
	global_load_dwordx2 v[170:171], v227, s[56:57]
	v_pk_fma_f32 v[130:131], v[0:1], s[0:1], v[130:131] op_sel_hi:[1,0,1]
	v_pk_fma_f32 v[138:139], v[2:3], s[0:1], v[138:139] op_sel_hi:[1,0,1]
	v_pk_fma_f32 v[140:141], v[4:5], s[0:1], v[140:141] op_sel_hi:[1,0,1]
	v_pk_fma_f32 v[142:143], v[6:7], s[0:1], v[142:143] op_sel_hi:[1,0,1]
	v_pk_fma_f32 v[128:129], v[8:9], s[0:1], v[128:129] op_sel_hi:[1,0,1]
	v_pk_fma_f32 v[132:133], v[10:11], s[0:1], v[132:133] op_sel_hi:[1,0,1]
	v_pk_fma_f32 v[134:135], v[12:13], s[0:1], v[134:135] op_sel_hi:[1,0,1]
	v_pk_fma_f32 v[136:137], v[14:15], s[0:1], v[136:137] op_sel_hi:[1,0,1]
	v_readlane_b32 s0, v167, 26
	s_waitcnt vmcnt(15)
	v_cvt_scalef32_pk_f32_fp4 v[0:1], v172, 1.0
	v_cvt_scalef32_pk_f32_fp4 v[2:3], v172, 1.0 op_sel:[1,0,0]
	v_cvt_scalef32_pk_f32_fp4 v[4:5], v172, 1.0 op_sel:[0,1,0]
	v_cvt_scalef32_pk_f32_fp4 v[6:7], v172, 1.0 op_sel:[1,1,0]
	v_cvt_scalef32_pk_f32_fp4 v[8:9], v173, 1.0
	v_cvt_scalef32_pk_f32_fp4 v[10:11], v173, 1.0 op_sel:[1,0,0]
	v_cvt_scalef32_pk_f32_fp4 v[12:13], v173, 1.0 op_sel:[0,1,0]
	v_cvt_scalef32_pk_f32_fp4 v[14:15], v173, 1.0 op_sel:[1,1,0]
	v_readlane_b32 s54, v92, 42
	s_lshl_b32 s56, s54, 9
	s_add_u32 s56, s64, s56
	s_addc_u32 s57, s65, 0
	global_load_dwordx2 v[172:173], v227, s[56:57]
	v_pk_fma_f32 v[130:131], v[0:1], s[0:1], v[130:131] op_sel_hi:[1,0,1]
	v_pk_fma_f32 v[138:139], v[2:3], s[0:1], v[138:139] op_sel_hi:[1,0,1]
	v_pk_fma_f32 v[140:141], v[4:5], s[0:1], v[140:141] op_sel_hi:[1,0,1]
	v_pk_fma_f32 v[142:143], v[6:7], s[0:1], v[142:143] op_sel_hi:[1,0,1]
	v_pk_fma_f32 v[128:129], v[8:9], s[0:1], v[128:129] op_sel_hi:[1,0,1]
	v_pk_fma_f32 v[132:133], v[10:11], s[0:1], v[132:133] op_sel_hi:[1,0,1]
	v_pk_fma_f32 v[134:135], v[12:13], s[0:1], v[134:135] op_sel_hi:[1,0,1]
	v_pk_fma_f32 v[136:137], v[14:15], s[0:1], v[136:137] op_sel_hi:[1,0,1]
	v_readlane_b32 s0, v167, 27
	s_waitcnt vmcnt(15)
	v_cvt_scalef32_pk_f32_fp4 v[0:1], v174, 1.0
	v_cvt_scalef32_pk_f32_fp4 v[2:3], v174, 1.0 op_sel:[1,0,0]
	v_cvt_scalef32_pk_f32_fp4 v[4:5], v174, 1.0 op_sel:[0,1,0]
	v_cvt_scalef32_pk_f32_fp4 v[6:7], v174, 1.0 op_sel:[1,1,0]
	v_cvt_scalef32_pk_f32_fp4 v[8:9], v175, 1.0
	v_cvt_scalef32_pk_f32_fp4 v[10:11], v175, 1.0 op_sel:[1,0,0]
	v_cvt_scalef32_pk_f32_fp4 v[12:13], v175, 1.0 op_sel:[0,1,0]
	v_cvt_scalef32_pk_f32_fp4 v[14:15], v175, 1.0 op_sel:[1,1,0]
	v_readlane_b32 s54, v92, 43
	s_lshl_b32 s56, s54, 9
	s_add_u32 s56, s64, s56
	s_addc_u32 s57, s65, 0
	global_load_dwordx2 v[174:175], v227, s[56:57]
	v_pk_fma_f32 v[130:131], v[0:1], s[0:1], v[130:131] op_sel_hi:[1,0,1]
	v_pk_fma_f32 v[138:139], v[2:3], s[0:1], v[138:139] op_sel_hi:[1,0,1]
	v_pk_fma_f32 v[140:141], v[4:5], s[0:1], v[140:141] op_sel_hi:[1,0,1]
	v_pk_fma_f32 v[142:143], v[6:7], s[0:1], v[142:143] op_sel_hi:[1,0,1]
	v_pk_fma_f32 v[128:129], v[8:9], s[0:1], v[128:129] op_sel_hi:[1,0,1]
	v_pk_fma_f32 v[132:133], v[10:11], s[0:1], v[132:133] op_sel_hi:[1,0,1]
	v_pk_fma_f32 v[134:135], v[12:13], s[0:1], v[134:135] op_sel_hi:[1,0,1]
	v_pk_fma_f32 v[136:137], v[14:15], s[0:1], v[136:137] op_sel_hi:[1,0,1]
	v_readlane_b32 s0, v167, 28
	s_waitcnt vmcnt(15)
	v_cvt_scalef32_pk_f32_fp4 v[0:1], v180, 1.0
	v_cvt_scalef32_pk_f32_fp4 v[2:3], v180, 1.0 op_sel:[1,0,0]
	v_cvt_scalef32_pk_f32_fp4 v[4:5], v180, 1.0 op_sel:[0,1,0]
	v_cvt_scalef32_pk_f32_fp4 v[6:7], v180, 1.0 op_sel:[1,1,0]
	v_cvt_scalef32_pk_f32_fp4 v[8:9], v181, 1.0
	v_cvt_scalef32_pk_f32_fp4 v[10:11], v181, 1.0 op_sel:[1,0,0]
	v_cvt_scalef32_pk_f32_fp4 v[12:13], v181, 1.0 op_sel:[0,1,0]
	v_cvt_scalef32_pk_f32_fp4 v[14:15], v181, 1.0 op_sel:[1,1,0]
	v_readlane_b32 s54, v92, 44
	s_lshl_b32 s56, s54, 9
	s_add_u32 s56, s64, s56
	s_addc_u32 s57, s65, 0
	global_load_dwordx2 v[180:181], v227, s[56:57]
	v_pk_fma_f32 v[130:131], v[0:1], s[0:1], v[130:131] op_sel_hi:[1,0,1]
	v_pk_fma_f32 v[138:139], v[2:3], s[0:1], v[138:139] op_sel_hi:[1,0,1]
	v_pk_fma_f32 v[140:141], v[4:5], s[0:1], v[140:141] op_sel_hi:[1,0,1]
	v_pk_fma_f32 v[142:143], v[6:7], s[0:1], v[142:143] op_sel_hi:[1,0,1]
	v_pk_fma_f32 v[128:129], v[8:9], s[0:1], v[128:129] op_sel_hi:[1,0,1]
	v_pk_fma_f32 v[132:133], v[10:11], s[0:1], v[132:133] op_sel_hi:[1,0,1]
	v_pk_fma_f32 v[134:135], v[12:13], s[0:1], v[134:135] op_sel_hi:[1,0,1]
	v_pk_fma_f32 v[136:137], v[14:15], s[0:1], v[136:137] op_sel_hi:[1,0,1]
	v_readlane_b32 s0, v167, 29
	s_waitcnt vmcnt(15)
; __device__ void peer_gather_phase(const Params& P, int l, bool do_store) {
;     ...
;     auto load_batch = [&](uint2 (&u6)[12], uint2 (&v8)[8], int bt) {
;       const int evs = (bt < 8) ? ev0 : ev1;
;       const int kb = (bt & 7) * 8;
; #pragma unroll
;       for (int pr = 0; pr < 4; ++pr) {
;         const int ea = __builtin_amdgcn_readlane(evs, kb + 2 * pr), eb = __builtin_amdgcn_readlane(evs, kb + 2 * pr + 1);
;         const uint2* up = (const uint2*)(U + (size_t)(uphi ? eb : ea) * 768);
;         u6[3 * pr] = up[0]; u6[3 * pr + 1] = up[1]; u6[3 * pr + 2] = up[2];
;         v8[2 * pr] = *(const uint2*)(V + (size_t)ea * 512);
;         v8[2 * pr + 1] = *(const uint2*)(V + (size_t)eb * 512);
;       }
;     };
;     auto compute_batch = [&](const uint2 (&u6)[12], const uint2 (&v8)[8], int bt) {
;       const int kb = (bt & 7) * 8;
;       float dvec = 0.f;
; #pragma unroll
;       for (int pr = 0; pr < 4; ++pr) {
;         v6u_t qv; qv[0] = u6[3 * pr].x; qv[1] = u6[3 * pr].y; qv[2] = u6[3 * pr + 1].x; qv[3] = u6[3 * pr + 1].y; qv[4] = u6[3 * pr + 2].x; qv[5] = u6[3 * pr + 2].y;
;         const v32f_t wv = __builtin_amdgcn_cvt_scalef32_pk32_f32_fp6(qv, 1.0f);
;         f32x2 a2 = f32x2{0.f, 0.f};
; #pragma unroll
;         for (int i = 0; i < 16; ++i) a2 += f32x2{wv[2 * i], wv[2 * i + 1]} * xu[i];
;         float hs = a2.x + a2.y;
;         hs += dpp_row_shr(hs, 1); hs += dpp_row_shr(hs, 2); hs += dpp_row_shr(hs, 4); hs += dpp_row_shr(hs, 8);
;         hs += __builtin_bit_cast(float, __builtin_amdgcn_update_dpp(0, __builtin_bit_cast(int, hs), 0x142, 0xa, 0xf, false));
;         const float da = __builtin_bit_cast(float, __builtin_amdgcn_readlane(__builtin_bit_cast(int, hs), 31));
;         const float db = __builtin_bit_cast(float, __builtin_amdgcn_readlane(__builtin_bit_cast(int, hs), 63));
;         dvec = (lane == kb + 2 * pr) ? da : dvec;
;         dvec = (lane == kb + 2 * pr + 1) ? db : dvec;
;       }
;       const float sux = (bt < 8) ? sux0 : sux1;
;       const float gsx = (bt < 8) ? gsx0 : gsx1;
;       const float avec = gelu_t(dvec * sux) * gsx;
; #pragma unroll
;       for (int j = 0; j < 8; ++j) {
;         const float a = __builtin_bit_cast(float, __builtin_amdgcn_readlane(__builtin_bit_cast(int, avec), kb + j));
;         const f32x2 aa = f32x2{a, a};
	v_cvt_scalef32_pk_f32_fp4 v[0:1], v182, 1.0
	v_cvt_scalef32_pk_f32_fp4 v[2:3], v182, 1.0 op_sel:[1,0,0]
	v_cvt_scalef32_pk_f32_fp4 v[4:5], v182, 1.0 op_sel:[0,1,0]
	v_cvt_scalef32_pk_f32_fp4 v[6:7], v182, 1.0 op_sel:[1,1,0]
	v_cvt_scalef32_pk_f32_fp4 v[8:9], v183, 1.0
	v_cvt_scalef32_pk_f32_fp4 v[10:11], v183, 1.0 op_sel:[1,0,0]
	v_cvt_scalef32_pk_f32_fp4 v[12:13], v183, 1.0 op_sel:[0,1,0]
	v_cvt_scalef32_pk_f32_fp4 v[14:15], v183, 1.0 op_sel:[1,1,0]
	v_readlane_b32 s54, v92, 45
	s_lshl_b32 s56, s54, 9
	s_add_u32 s56, s64, s56
	s_addc_u32 s57, s65, 0
	global_load_dwordx2 v[182:183], v227, s[56:57]
	v_pk_fma_f32 v[130:131], v[0:1], s[0:1], v[130:131] op_sel_hi:[1,0,1]
	v_pk_fma_f32 v[138:139], v[2:3], s[0:1], v[138:139] op_sel_hi:[1,0,1]
	v_pk_fma_f32 v[140:141], v[4:5], s[0:1], v[140:141] op_sel_hi:[1,0,1]
	v_pk_fma_f32 v[142:143], v[6:7], s[0:1], v[142:143] op_sel_hi:[1,0,1]
	v_pk_fma_f32 v[128:129], v[8:9], s[0:1], v[128:129] op_sel_hi:[1,0,1]
	v_pk_fma_f32 v[132:133], v[10:11], s[0:1], v[132:133] op_sel_hi:[1,0,1]
	v_pk_fma_f32 v[134:135], v[12:13], s[0:1], v[134:135] op_sel_hi:[1,0,1]
	v_pk_fma_f32 v[136:137], v[14:15], s[0:1], v[136:137] op_sel_hi:[1,0,1]
	v_readlane_b32 s0, v167, 30
	s_waitcnt vmcnt(15)
	v_cvt_scalef32_pk_f32_fp4 v[0:1], v184, 1.0
	v_cvt_scalef32_pk_f32_fp4 v[2:3], v184, 1.0 op_sel:[1,0,0]
	v_cvt_scalef32_pk_f32_fp4 v[4:5], v184, 1.0 op_sel:[0,1,0]
	v_cvt_scalef32_pk_f32_fp4 v[6:7], v184, 1.0 op_sel:[1,1,0]
	v_cvt_scalef32_pk_f32_fp4 v[8:9], v185, 1.0
	v_cvt_scalef32_pk_f32_fp4 v[10:11], v185, 1.0 op_sel:[1,0,0]
	v_cvt_scalef32_pk_f32_fp4 v[12:13], v185, 1.0 op_sel:[0,1,0]
	v_cvt_scalef32_pk_f32_fp4 v[14:15], v185, 1.0 op_sel:[1,1,0]
	v_readlane_b32 s54, v92, 46
	s_lshl_b32 s56, s54, 9
	s_add_u32 s56, s64, s56
	s_addc_u32 s57, s65, 0
	global_load_dwordx2 v[184:185], v227, s[56:57]
	v_pk_fma_f32 v[130:131], v[0:1], s[0:1], v[130:131] op_sel_hi:[1,0,1]
	v_pk_fma_f32 v[138:139], v[2:3], s[0:1], v[138:139] op_sel_hi:[1,0,1]
	v_pk_fma_f32 v[140:141], v[4:5], s[0:1], v[140:141] op_sel_hi:[1,0,1]
	v_pk_fma_f32 v[142:143], v[6:7], s[0:1], v[142:143] op_sel_hi:[1,0,1]
	v_pk_fma_f32 v[128:129], v[8:9], s[0:1], v[128:129] op_sel_hi:[1,0,1]
	v_pk_fma_f32 v[132:133], v[10:11], s[0:1], v[132:133] op_sel_hi:[1,0,1]
	v_pk_fma_f32 v[134:135], v[12:13], s[0:1], v[134:135] op_sel_hi:[1,0,1]
	v_pk_fma_f32 v[136:137], v[14:15], s[0:1], v[136:137] op_sel_hi:[1,0,1]
	v_readlane_b32 s0, v167, 31
	s_waitcnt vmcnt(15)
	v_cvt_scalef32_pk_f32_fp4 v[0:1], v186, 1.0
	v_cvt_scalef32_pk_f32_fp4 v[2:3], v186, 1.0 op_sel:[1,0,0]
	v_cvt_scalef32_pk_f32_fp4 v[4:5], v186, 1.0 op_sel:[0,1,0]
	v_cvt_scalef32_pk_f32_fp4 v[6:7], v186, 1.0 op_sel:[1,1,0]
	v_cvt_scalef32_pk_f32_fp4 v[8:9], v187, 1.0
	v_cvt_scalef32_pk_f32_fp4 v[10:11], v187, 1.0 op_sel:[1,0,0]
	v_cvt_scalef32_pk_f32_fp4 v[12:13], v187, 1.0 op_sel:[0,1,0]
	v_cvt_scalef32_pk_f32_fp4 v[14:15], v187, 1.0 op_sel:[1,1,0]
	v_readlane_b32 s54, v92, 47
	s_lshl_b32 s56, s54, 9
	s_add_u32 s56, s64, s56
	s_addc_u32 s57, s65, 0
	global_load_dwordx2 v[186:187], v227, s[56:57]
	v_pk_fma_f32 v[130:131], v[0:1], s[0:1], v[130:131] op_sel_hi:[1,0,1]
	v_pk_fma_f32 v[138:139], v[2:3], s[0:1], v[138:139] op_sel_hi:[1,0,1]
	v_pk_fma_f32 v[140:141], v[4:5], s[0:1], v[140:141] op_sel_hi:[1,0,1]
	v_pk_fma_f32 v[142:143], v[6:7], s[0:1], v[142:143] op_sel_hi:[1,0,1]
	v_pk_fma_f32 v[128:129], v[8:9], s[0:1], v[128:129] op_sel_hi:[1,0,1]
	v_pk_fma_f32 v[132:133], v[10:11], s[0:1], v[132:133] op_sel_hi:[1,0,1]
	v_pk_fma_f32 v[134:135], v[12:13], s[0:1], v[134:135] op_sel_hi:[1,0,1]
	v_pk_fma_f32 v[136:137], v[14:15], s[0:1], v[136:137] op_sel_hi:[1,0,1]
	v_readlane_b32 s0, v167, 32
	s_waitcnt vmcnt(15)
	v_cvt_scalef32_pk_f32_fp4 v[0:1], v144, 1.0
	v_cvt_scalef32_pk_f32_fp4 v[2:3], v144, 1.0 op_sel:[1,0,0]
	v_cvt_scalef32_pk_f32_fp4 v[4:5], v144, 1.0 op_sel:[0,1,0]
	v_cvt_scalef32_pk_f32_fp4 v[6:7], v144, 1.0 op_sel:[1,1,0]
	v_cvt_scalef32_pk_f32_fp4 v[8:9], v145, 1.0
	v_cvt_scalef32_pk_f32_fp4 v[10:11], v145, 1.0 op_sel:[1,0,0]
	v_cvt_scalef32_pk_f32_fp4 v[12:13], v145, 1.0 op_sel:[0,1,0]
	v_cvt_scalef32_pk_f32_fp4 v[14:15], v145, 1.0 op_sel:[1,1,0]
	v_readlane_b32 s54, v92, 48
	s_lshl_b32 s56, s54, 9
	s_add_u32 s56, s64, s56
	s_addc_u32 s57, s65, 0
	global_load_dwordx2 v[144:145], v227, s[56:57]
	v_pk_fma_f32 v[130:131], v[0:1], s[0:1], v[130:131] op_sel_hi:[1,0,1]
	v_pk_fma_f32 v[138:139], v[2:3], s[0:1], v[138:139] op_sel_hi:[1,0,1]
	v_pk_fma_f32 v[140:141], v[4:5], s[0:1], v[140:141] op_sel_hi:[1,0,1]
	v_pk_fma_f32 v[142:143], v[6:7], s[0:1], v[142:143] op_sel_hi:[1,0,1]
	v_pk_fma_f32 v[128:129], v[8:9], s[0:1], v[128:129] op_sel_hi:[1,0,1]
	v_pk_fma_f32 v[132:133], v[10:11], s[0:1], v[132:133] op_sel_hi:[1,0,1]
	v_pk_fma_f32 v[134:135], v[12:13], s[0:1], v[134:135] op_sel_hi:[1,0,1]
	v_pk_fma_f32 v[136:137], v[14:15], s[0:1], v[136:137] op_sel_hi:[1,0,1]
	v_readlane_b32 s0, v167, 33
	s_waitcnt vmcnt(15)
	v_cvt_scalef32_pk_f32_fp4 v[0:1], v146, 1.0
	v_cvt_scalef32_pk_f32_fp4 v[2:3], v146, 1.0 op_sel:[1,0,0]
	v_cvt_scalef32_pk_f32_fp4 v[4:5], v146, 1.0 op_sel:[0,1,0]
	v_cvt_scalef32_pk_f32_fp4 v[6:7], v146, 1.0 op_sel:[1,1,0]
	v_cvt_scalef32_pk_f32_fp4 v[8:9], v147, 1.0
	v_cvt_scalef32_pk_f32_fp4 v[10:11], v147, 1.0 op_sel:[1,0,0]
	v_cvt_scalef32_pk_f32_fp4 v[12:13], v147, 1.0 op_sel:[0,1,0]
	v_cvt_scalef32_pk_f32_fp4 v[14:15], v147, 1.0 op_sel:[1,1,0]
	v_readlane_b32 s54, v92, 49
	s_lshl_b32 s56, s54, 9
	s_add_u32 s56, s64, s56
	s_addc_u32 s57, s65, 0
	global_load_dwordx2 v[146:147], v227, s[56:57]
	v_pk_fma_f32 v[130:131], v[0:1], s[0:1], v[130:131] op_sel_hi:[1,0,1]
	v_pk_fma_f32 v[138:139], v[2:3], s[0:1], v[138:139] op_sel_hi:[1,0,1]
	v_pk_fma_f32 v[140:141], v[4:5], s[0:1], v[140:141] op_sel_hi:[1,0,1]
	v_pk_fma_f32 v[142:143], v[6:7], s[0:1], v[142:143] op_sel_hi:[1,0,1]
	v_pk_fma_f32 v[128:129], v[8:9], s[0:1], v[128:129] op_sel_hi:[1,0,1]
	v_pk_fma_f32 v[132:133], v[10:11], s[0:1], v[132:133] op_sel_hi:[1,0,1]
	v_pk_fma_f32 v[134:135], v[12:13], s[0:1], v[134:135] op_sel_hi:[1,0,1]
	v_pk_fma_f32 v[136:137], v[14:15], s[0:1], v[136:137] op_sel_hi:[1,0,1]
	v_readlane_b32 s0, v167, 34
	s_waitcnt vmcnt(15)
; __device__ void peer_gather_phase(const Params& P, int l, bool do_store) {
;     ...
;     auto load_batch = [&](uint2 (&u6)[12], uint2 (&v8)[8], int bt) {
;       const int evs = (bt < 8) ? ev0 : ev1;
;       const int kb = (bt & 7) * 8;
; #pragma unroll
;       for (int pr = 0; pr < 4; ++pr) {
;         const int ea = __builtin_amdgcn_readlane(evs, kb + 2 * pr), eb = __builtin_amdgcn_readlane(evs, kb + 2 * pr + 1);
;         const uint2* up = (const uint2*)(U + (size_t)(uphi ? eb : ea) * 768);
;         u6[3 * pr] = up[0]; u6[3 * pr + 1] = up[1]; u6[3 * pr + 2] = up[2];
;         v8[2 * pr] = *(const uint2*)(V + (size_t)ea * 512);
;         v8[2 * pr + 1] = *(const uint2*)(V + (size_t)eb * 512);
;       }
;     };
;     auto compute_batch = [&](const uint2 (&u6)[12], const uint2 (&v8)[8], int bt) {
;       const int kb = (bt & 7) * 8;
;       float dvec = 0.f;
; #pragma unroll
;       for (int pr = 0; pr < 4; ++pr) {
;         v6u_t qv; qv[0] = u6[3 * pr].x; qv[1] = u6[3 * pr].y; qv[2] = u6[3 * pr + 1].x; qv[3] = u6[3 * pr + 1].y; qv[4] = u6[3 * pr + 2].x; qv[5] = u6[3 * pr + 2].y;
;         const v32f_t wv = __builtin_amdgcn_cvt_scalef32_pk32_f32_fp6(qv, 1.0f);
;         f32x2 a2 = f32x2{0.f, 0.f};
; #pragma unroll
;         for (int i = 0; i < 16; ++i) a2 += f32x2{wv[2 * i], wv[2 * i + 1]} * xu[i];
;         float hs = a2.x + a2.y;
;         hs += dpp_row_shr(hs, 1); hs += dpp_row_shr(hs, 2); hs += dpp_row_shr(hs, 4); hs += dpp_row_shr(hs, 8);
;         hs += __builtin_bit_cast(float, __builtin_amdgcn_update_dpp(0, __builtin_bit_cast(int, hs), 0x142, 0xa, 0xf, false));
;         const float da = __builtin_bit_cast(float, __builtin_amdgcn_readlane(__builtin_bit_cast(int, hs), 31));
;         const float db = __builtin_bit_cast(float, __builtin_amdgcn_readlane(__builtin_bit_cast(int, hs), 63));
;         dvec = (lane == kb + 2 * pr) ? da : dvec;
;         dvec = (lane == kb + 2 * pr + 1) ? db : dvec;
;       }
;       const float sux = (bt < 8) ? sux0 : sux1;
;       const float gsx = (bt < 8) ? gsx0 : gsx1;
;       const float avec = gelu_t(dvec * sux) * gsx;
; #pragma unroll
;       for (int j = 0; j < 8; ++j) {
;         const float a = __builtin_bit_cast(float, __builtin_amdgcn_readlane(__builtin_bit_cast(int, avec), kb + j));
;         const f32x2 aa = f32x2{a, a};
	v_cvt_scalef32_pk_f32_fp4 v[0:1], v148, 1.0
	v_cvt_scalef32_pk_f32_fp4 v[2:3], v148, 1.0 op_sel:[1,0,0]
	v_cvt_scalef32_pk_f32_fp4 v[4:5], v148, 1.0 op_sel:[0,1,0]
	v_cvt_scalef32_pk_f32_fp4 v[6:7], v148, 1.0 op_sel:[1,1,0]
	v_cvt_scalef32_pk_f32_fp4 v[8:9], v149, 1.0
	v_cvt_scalef32_pk_f32_fp4 v[10:11], v149, 1.0 op_sel:[1,0,0]
	v_cvt_scalef32_pk_f32_fp4 v[12:13], v149, 1.0 op_sel:[0,1,0]
	v_cvt_scalef32_pk_f32_fp4 v[14:15], v149, 1.0 op_sel:[1,1,0]
	v_readlane_b32 s54, v92, 50
	s_lshl_b32 s56, s54, 9
	s_add_u32 s56, s64, s56
	s_addc_u32 s57, s65, 0
	global_load_dwordx2 v[148:149], v227, s[56:57]
	v_pk_fma_f32 v[130:131], v[0:1], s[0:1], v[130:131] op_sel_hi:[1,0,1]
	v_pk_fma_f32 v[138:139], v[2:3], s[0:1], v[138:139] op_sel_hi:[1,0,1]
	v_pk_fma_f32 v[140:141], v[4:5], s[0:1], v[140:141] op_sel_hi:[1,0,1]
	v_pk_fma_f32 v[142:143], v[6:7], s[0:1], v[142:143] op_sel_hi:[1,0,1]
	v_pk_fma_f32 v[128:129], v[8:9], s[0:1], v[128:129] op_sel_hi:[1,0,1]
	v_pk_fma_f32 v[132:133], v[10:11], s[0:1], v[132:133] op_sel_hi:[1,0,1]
	v_pk_fma_f32 v[134:135], v[12:13], s[0:1], v[134:135] op_sel_hi:[1,0,1]
	v_pk_fma_f32 v[136:137], v[14:15], s[0:1], v[136:137] op_sel_hi:[1,0,1]
	v_readlane_b32 s0, v167, 35
	s_waitcnt vmcnt(15)
	v_cvt_scalef32_pk_f32_fp4 v[0:1], v150, 1.0
	v_cvt_scalef32_pk_f32_fp4 v[2:3], v150, 1.0 op_sel:[1,0,0]
	v_cvt_scalef32_pk_f32_fp4 v[4:5], v150, 1.0 op_sel:[0,1,0]
	v_cvt_scalef32_pk_f32_fp4 v[6:7], v150, 1.0 op_sel:[1,1,0]
	v_cvt_scalef32_pk_f32_fp4 v[8:9], v151, 1.0
	v_cvt_scalef32_pk_f32_fp4 v[10:11], v151, 1.0 op_sel:[1,0,0]
	v_cvt_scalef32_pk_f32_fp4 v[12:13], v151, 1.0 op_sel:[0,1,0]
	v_cvt_scalef32_pk_f32_fp4 v[14:15], v151, 1.0 op_sel:[1,1,0]
	v_readlane_b32 s54, v92, 51
	s_lshl_b32 s56, s54, 9
	s_add_u32 s56, s64, s56
	s_addc_u32 s57, s65, 0
	global_load_dwordx2 v[150:151], v227, s[56:57]
	v_pk_fma_f32 v[130:131], v[0:1], s[0:1], v[130:131] op_sel_hi:[1,0,1]
	v_pk_fma_f32 v[138:139], v[2:3], s[0:1], v[138:139] op_sel_hi:[1,0,1]
	v_pk_fma_f32 v[140:141], v[4:5], s[0:1], v[140:141] op_sel_hi:[1,0,1]
	v_pk_fma_f32 v[142:143], v[6:7], s[0:1], v[142:143] op_sel_hi:[1,0,1]
	v_pk_fma_f32 v[128:129], v[8:9], s[0:1], v[128:129] op_sel_hi:[1,0,1]
	v_pk_fma_f32 v[132:133], v[10:11], s[0:1], v[132:133] op_sel_hi:[1,0,1]
	v_pk_fma_f32 v[134:135], v[12:13], s[0:1], v[134:135] op_sel_hi:[1,0,1]
	v_pk_fma_f32 v[136:137], v[14:15], s[0:1], v[136:137] op_sel_hi:[1,0,1]
	v_readlane_b32 s0, v167, 36
	s_waitcnt vmcnt(15)
	v_cvt_scalef32_pk_f32_fp4 v[0:1], v152, 1.0
	v_cvt_scalef32_pk_f32_fp4 v[2:3], v152, 1.0 op_sel:[1,0,0]
	v_cvt_scalef32_pk_f32_fp4 v[4:5], v152, 1.0 op_sel:[0,1,0]
	v_cvt_scalef32_pk_f32_fp4 v[6:7], v152, 1.0 op_sel:[1,1,0]
	v_cvt_scalef32_pk_f32_fp4 v[8:9], v153, 1.0
	v_cvt_scalef32_pk_f32_fp4 v[10:11], v153, 1.0 op_sel:[1,0,0]
	v_cvt_scalef32_pk_f32_fp4 v[12:13], v153, 1.0 op_sel:[0,1,0]
	v_cvt_scalef32_pk_f32_fp4 v[14:15], v153, 1.0 op_sel:[1,1,0]
	v_readlane_b32 s54, v92, 52
	s_lshl_b32 s56, s54, 9
	s_add_u32 s56, s64, s56
	s_addc_u32 s57, s65, 0
	global_load_dwordx2 v[152:153], v227, s[56:57]
	v_pk_fma_f32 v[130:131], v[0:1], s[0:1], v[130:131] op_sel_hi:[1,0,1]
	v_pk_fma_f32 v[138:139], v[2:3], s[0:1], v[138:139] op_sel_hi:[1,0,1]
	v_pk_fma_f32 v[140:141], v[4:5], s[0:1], v[140:141] op_sel_hi:[1,0,1]
	v_pk_fma_f32 v[142:143], v[6:7], s[0:1], v[142:143] op_sel_hi:[1,0,1]
	v_pk_fma_f32 v[128:129], v[8:9], s[0:1], v[128:129] op_sel_hi:[1,0,1]
	v_pk_fma_f32 v[132:133], v[10:11], s[0:1], v[132:133] op_sel_hi:[1,0,1]
	v_pk_fma_f32 v[134:135], v[12:13], s[0:1], v[134:135] op_sel_hi:[1,0,1]
	v_pk_fma_f32 v[136:137], v[14:15], s[0:1], v[136:137] op_sel_hi:[1,0,1]
	v_readlane_b32 s0, v167, 37
	s_waitcnt vmcnt(15)
	v_cvt_scalef32_pk_f32_fp4 v[0:1], v154, 1.0
	v_cvt_scalef32_pk_f32_fp4 v[2:3], v154, 1.0 op_sel:[1,0,0]
	v_cvt_scalef32_pk_f32_fp4 v[4:5], v154, 1.0 op_sel:[0,1,0]
	v_cvt_scalef32_pk_f32_fp4 v[6:7], v154, 1.0 op_sel:[1,1,0]
	v_cvt_scalef32_pk_f32_fp4 v[8:9], v155, 1.0
	v_cvt_scalef32_pk_f32_fp4 v[10:11], v155, 1.0 op_sel:[1,0,0]
	v_cvt_scalef32_pk_f32_fp4 v[12:13], v155, 1.0 op_sel:[0,1,0]
	v_cvt_scalef32_pk_f32_fp4 v[14:15], v155, 1.0 op_sel:[1,1,0]
	v_readlane_b32 s54, v92, 53
	s_lshl_b32 s56, s54, 9
	s_add_u32 s56, s64, s56
	s_addc_u32 s57, s65, 0
	global_load_dwordx2 v[154:155], v227, s[56:57]
	v_pk_fma_f32 v[130:131], v[0:1], s[0:1], v[130:131] op_sel_hi:[1,0,1]
	v_pk_fma_f32 v[138:139], v[2:3], s[0:1], v[138:139] op_sel_hi:[1,0,1]
	v_pk_fma_f32 v[140:141], v[4:5], s[0:1], v[140:141] op_sel_hi:[1,0,1]
	v_pk_fma_f32 v[142:143], v[6:7], s[0:1], v[142:143] op_sel_hi:[1,0,1]
	v_pk_fma_f32 v[128:129], v[8:9], s[0:1], v[128:129] op_sel_hi:[1,0,1]
	v_pk_fma_f32 v[132:133], v[10:11], s[0:1], v[132:133] op_sel_hi:[1,0,1]
	v_pk_fma_f32 v[134:135], v[12:13], s[0:1], v[134:135] op_sel_hi:[1,0,1]
	v_pk_fma_f32 v[136:137], v[14:15], s[0:1], v[136:137] op_sel_hi:[1,0,1]
	v_readlane_b32 s0, v167, 38
	s_waitcnt vmcnt(15)
	v_cvt_scalef32_pk_f32_fp4 v[0:1], v156, 1.0
	v_cvt_scalef32_pk_f32_fp4 v[2:3], v156, 1.0 op_sel:[1,0,0]
	v_cvt_scalef32_pk_f32_fp4 v[4:5], v156, 1.0 op_sel:[0,1,0]
	v_cvt_scalef32_pk_f32_fp4 v[6:7], v156, 1.0 op_sel:[1,1,0]
	v_cvt_scalef32_pk_f32_fp4 v[8:9], v157, 1.0
	v_cvt_scalef32_pk_f32_fp4 v[10:11], v157, 1.0 op_sel:[1,0,0]
	v_cvt_scalef32_pk_f32_fp4 v[12:13], v157, 1.0 op_sel:[0,1,0]
	v_cvt_scalef32_pk_f32_fp4 v[14:15], v157, 1.0 op_sel:[1,1,0]
	v_readlane_b32 s54, v92, 54
	s_lshl_b32 s56, s54, 9
	s_add_u32 s56, s64, s56
	s_addc_u32 s57, s65, 0
	global_load_dwordx2 v[156:157], v227, s[56:57]
	v_pk_fma_f32 v[130:131], v[0:1], s[0:1], v[130:131] op_sel_hi:[1,0,1]
	v_pk_fma_f32 v[138:139], v[2:3], s[0:1], v[138:139] op_sel_hi:[1,0,1]
	v_pk_fma_f32 v[140:141], v[4:5], s[0:1], v[140:141] op_sel_hi:[1,0,1]
	v_pk_fma_f32 v[142:143], v[6:7], s[0:1], v[142:143] op_sel_hi:[1,0,1]
	v_pk_fma_f32 v[128:129], v[8:9], s[0:1], v[128:129] op_sel_hi:[1,0,1]
	v_pk_fma_f32 v[132:133], v[10:11], s[0:1], v[132:133] op_sel_hi:[1,0,1]
	v_pk_fma_f32 v[134:135], v[12:13], s[0:1], v[134:135] op_sel_hi:[1,0,1]
	v_pk_fma_f32 v[136:137], v[14:15], s[0:1], v[136:137] op_sel_hi:[1,0,1]
	v_readlane_b32 s0, v167, 39
	s_waitcnt vmcnt(15)
; __device__ void peer_gather_phase(const Params& P, int l, bool do_store) {
;     ...
;         v8[2 * pr] = *(const uint2*)(V + (size_t)ea * 512);
;         v8[2 * pr + 1] = *(const uint2*)(V + (size_t)eb * 512);
;     ...
; #pragma unroll
;       for (int j = 0; j < 8; ++j) {
;         const float a = __builtin_bit_cast(float, __builtin_amdgcn_readlane(__builtin_bit_cast(int, avec), kb + j));
;         const f32x2 aa = f32x2{a, a};
;         y[0] += aa * __builtin_amdgcn_cvt_scalef32_pk_f32_fp4(v8[j].x, 1.0f, 0); y[1] += aa * __builtin_amdgcn_cvt_scalef32_pk_f32_fp4(v8[j].x, 1.0f, 1);
;         y[2] += aa * __builtin_amdgcn_cvt_scalef32_pk_f32_fp4(v8[j].x, 1.0f, 2); y[3] += aa * __builtin_amdgcn_cvt_scalef32_pk_f32_fp4(v8[j].x, 1.0f, 3);
;         y[4] += aa * __builtin_amdgcn_cvt_scalef32_pk_f32_fp4(v8[j].y, 1.0f, 0); y[5] += aa * __builtin_amdgcn_cvt_scalef32_pk_f32_fp4(v8[j].y, 1.0f, 1);
;         y[6] += aa * __builtin_amdgcn_cvt_scalef32_pk_f32_fp4(v8[j].y, 1.0f, 2); y[7] += aa * __builtin_amdgcn_cvt_scalef32_pk_f32_fp4(v8[j].y, 1.0f, 3);
;       }
	v_cvt_scalef32_pk_f32_fp4 v[0:1], v158, 1.0
	v_cvt_scalef32_pk_f32_fp4 v[2:3], v158, 1.0 op_sel:[1,0,0]
	v_cvt_scalef32_pk_f32_fp4 v[4:5], v158, 1.0 op_sel:[0,1,0]
	v_cvt_scalef32_pk_f32_fp4 v[6:7], v158, 1.0 op_sel:[1,1,0]
	v_cvt_scalef32_pk_f32_fp4 v[8:9], v159, 1.0
	v_cvt_scalef32_pk_f32_fp4 v[10:11], v159, 1.0 op_sel:[1,0,0]
	v_cvt_scalef32_pk_f32_fp4 v[12:13], v159, 1.0 op_sel:[0,1,0]
	v_cvt_scalef32_pk_f32_fp4 v[14:15], v159, 1.0 op_sel:[1,1,0]
	v_readlane_b32 s54, v92, 55
	s_lshl_b32 s56, s54, 9
	s_add_u32 s56, s64, s56
	s_addc_u32 s57, s65, 0
	global_load_dwordx2 v[158:159], v227, s[56:57]
	v_pk_fma_f32 v[130:131], v[0:1], s[0:1], v[130:131] op_sel_hi:[1,0,1]
	v_pk_fma_f32 v[138:139], v[2:3], s[0:1], v[138:139] op_sel_hi:[1,0,1]
	v_pk_fma_f32 v[140:141], v[4:5], s[0:1], v[140:141] op_sel_hi:[1,0,1]
	v_pk_fma_f32 v[142:143], v[6:7], s[0:1], v[142:143] op_sel_hi:[1,0,1]
	v_pk_fma_f32 v[128:129], v[8:9], s[0:1], v[128:129] op_sel_hi:[1,0,1]
	v_pk_fma_f32 v[132:133], v[10:11], s[0:1], v[132:133] op_sel_hi:[1,0,1]
	v_pk_fma_f32 v[134:135], v[12:13], s[0:1], v[134:135] op_sel_hi:[1,0,1]
	v_pk_fma_f32 v[136:137], v[14:15], s[0:1], v[136:137] op_sel_hi:[1,0,1]
	v_readlane_b32 s0, v167, 40
	s_waitcnt vmcnt(15)
	v_cvt_scalef32_pk_f32_fp4 v[0:1], v168, 1.0
	v_cvt_scalef32_pk_f32_fp4 v[2:3], v168, 1.0 op_sel:[1,0,0]
	v_cvt_scalef32_pk_f32_fp4 v[4:5], v168, 1.0 op_sel:[0,1,0]
	v_cvt_scalef32_pk_f32_fp4 v[6:7], v168, 1.0 op_sel:[1,1,0]
	v_cvt_scalef32_pk_f32_fp4 v[8:9], v169, 1.0
	v_cvt_scalef32_pk_f32_fp4 v[10:11], v169, 1.0 op_sel:[1,0,0]
	v_cvt_scalef32_pk_f32_fp4 v[12:13], v169, 1.0 op_sel:[0,1,0]
	v_cvt_scalef32_pk_f32_fp4 v[14:15], v169, 1.0 op_sel:[1,1,0]
	v_readlane_b32 s54, v92, 56
	s_lshl_b32 s56, s54, 9
	s_add_u32 s56, s64, s56
	s_addc_u32 s57, s65, 0
	global_load_dwordx2 v[168:169], v227, s[56:57]
	v_pk_fma_f32 v[130:131], v[0:1], s[0:1], v[130:131] op_sel_hi:[1,0,1]
	v_pk_fma_f32 v[138:139], v[2:3], s[0:1], v[138:139] op_sel_hi:[1,0,1]
	v_pk_fma_f32 v[140:141], v[4:5], s[0:1], v[140:141] op_sel_hi:[1,0,1]
	v_pk_fma_f32 v[142:143], v[6:7], s[0:1], v[142:143] op_sel_hi:[1,0,1]
	v_pk_fma_f32 v[128:129], v[8:9], s[0:1], v[128:129] op_sel_hi:[1,0,1]
	v_pk_fma_f32 v[132:133], v[10:11], s[0:1], v[132:133] op_sel_hi:[1,0,1]
	v_pk_fma_f32 v[134:135], v[12:13], s[0:1], v[134:135] op_sel_hi:[1,0,1]
	v_pk_fma_f32 v[136:137], v[14:15], s[0:1], v[136:137] op_sel_hi:[1,0,1]
	v_readlane_b32 s0, v167, 41
	s_waitcnt vmcnt(15)
	v_cvt_scalef32_pk_f32_fp4 v[0:1], v170, 1.0
	v_cvt_scalef32_pk_f32_fp4 v[2:3], v170, 1.0 op_sel:[1,0,0]
	v_cvt_scalef32_pk_f32_fp4 v[4:5], v170, 1.0 op_sel:[0,1,0]
	v_cvt_scalef32_pk_f32_fp4 v[6:7], v170, 1.0 op_sel:[1,1,0]
	v_cvt_scalef32_pk_f32_fp4 v[8:9], v171, 1.0
	v_cvt_scalef32_pk_f32_fp4 v[10:11], v171, 1.0 op_sel:[1,0,0]
	v_cvt_scalef32_pk_f32_fp4 v[12:13], v171, 1.0 op_sel:[0,1,0]
	v_cvt_scalef32_pk_f32_fp4 v[14:15], v171, 1.0 op_sel:[1,1,0]
	v_readlane_b32 s54, v92, 57
	s_lshl_b32 s56, s54, 9
	s_add_u32 s56, s64, s56
	s_addc_u32 s57, s65, 0
	global_load_dwordx2 v[170:171], v227, s[56:57]
	v_pk_fma_f32 v[130:131], v[0:1], s[0:1], v[130:131] op_sel_hi:[1,0,1]
	v_pk_fma_f32 v[138:139], v[2:3], s[0:1], v[138:139] op_sel_hi:[1,0,1]
	v_pk_fma_f32 v[140:141], v[4:5], s[0:1], v[140:141] op_sel_hi:[1,0,1]
	v_pk_fma_f32 v[142:143], v[6:7], s[0:1], v[142:143] op_sel_hi:[1,0,1]
	v_pk_fma_f32 v[128:129], v[8:9], s[0:1], v[128:129] op_sel_hi:[1,0,1]
	v_pk_fma_f32 v[132:133], v[10:11], s[0:1], v[132:133] op_sel_hi:[1,0,1]
	v_pk_fma_f32 v[134:135], v[12:13], s[0:1], v[134:135] op_sel_hi:[1,0,1]
	v_pk_fma_f32 v[136:137], v[14:15], s[0:1], v[136:137] op_sel_hi:[1,0,1]
	v_readlane_b32 s0, v167, 42
	s_waitcnt vmcnt(15)
	v_cvt_scalef32_pk_f32_fp4 v[0:1], v172, 1.0
	v_cvt_scalef32_pk_f32_fp4 v[2:3], v172, 1.0 op_sel:[1,0,0]
	v_cvt_scalef32_pk_f32_fp4 v[4:5], v172, 1.0 op_sel:[0,1,0]
	v_cvt_scalef32_pk_f32_fp4 v[6:7], v172, 1.0 op_sel:[1,1,0]
	v_cvt_scalef32_pk_f32_fp4 v[8:9], v173, 1.0
	v_cvt_scalef32_pk_f32_fp4 v[10:11], v173, 1.0 op_sel:[1,0,0]
	v_cvt_scalef32_pk_f32_fp4 v[12:13], v173, 1.0 op_sel:[0,1,0]
	v_cvt_scalef32_pk_f32_fp4 v[14:15], v173, 1.0 op_sel:[1,1,0]
	v_readlane_b32 s54, v92, 58
	s_lshl_b32 s56, s54, 9
	s_add_u32 s56, s64, s56
	s_addc_u32 s57, s65, 0
	global_load_dwordx2 v[172:173], v227, s[56:57]
	v_pk_fma_f32 v[130:131], v[0:1], s[0:1], v[130:131] op_sel_hi:[1,0,1]
	v_pk_fma_f32 v[138:139], v[2:3], s[0:1], v[138:139] op_sel_hi:[1,0,1]
	v_pk_fma_f32 v[140:141], v[4:5], s[0:1], v[140:141] op_sel_hi:[1,0,1]
	v_pk_fma_f32 v[142:143], v[6:7], s[0:1], v[142:143] op_sel_hi:[1,0,1]
	v_pk_fma_f32 v[128:129], v[8:9], s[0:1], v[128:129] op_sel_hi:[1,0,1]
	v_pk_fma_f32 v[132:133], v[10:11], s[0:1], v[132:133] op_sel_hi:[1,0,1]
	v_pk_fma_f32 v[134:135], v[12:13], s[0:1], v[134:135] op_sel_hi:[1,0,1]
	v_pk_fma_f32 v[136:137], v[14:15], s[0:1], v[136:137] op_sel_hi:[1,0,1]
	v_readlane_b32 s0, v167, 43
	s_waitcnt vmcnt(15)
	v_cvt_scalef32_pk_f32_fp4 v[0:1], v174, 1.0
	v_cvt_scalef32_pk_f32_fp4 v[2:3], v174, 1.0 op_sel:[1,0,0]
	v_cvt_scalef32_pk_f32_fp4 v[4:5], v174, 1.0 op_sel:[0,1,0]
	v_cvt_scalef32_pk_f32_fp4 v[6:7], v174, 1.0 op_sel:[1,1,0]
	v_cvt_scalef32_pk_f32_fp4 v[8:9], v175, 1.0
	v_cvt_scalef32_pk_f32_fp4 v[10:11], v175, 1.0 op_sel:[1,0,0]
	v_cvt_scalef32_pk_f32_fp4 v[12:13], v175, 1.0 op_sel:[0,1,0]
	v_cvt_scalef32_pk_f32_fp4 v[14:15], v175, 1.0 op_sel:[1,1,0]
	v_readlane_b32 s54, v92, 59
	s_lshl_b32 s56, s54, 9
	s_add_u32 s56, s64, s56
	s_addc_u32 s57, s65, 0
	global_load_dwordx2 v[174:175], v227, s[56:57]
	v_pk_fma_f32 v[130:131], v[0:1], s[0:1], v[130:131] op_sel_hi:[1,0,1]
	v_pk_fma_f32 v[138:139], v[2:3], s[0:1], v[138:139] op_sel_hi:[1,0,1]
	v_pk_fma_f32 v[140:141], v[4:5], s[0:1], v[140:141] op_sel_hi:[1,0,1]
	v_pk_fma_f32 v[142:143], v[6:7], s[0:1], v[142:143] op_sel_hi:[1,0,1]
	v_pk_fma_f32 v[128:129], v[8:9], s[0:1], v[128:129] op_sel_hi:[1,0,1]
	v_pk_fma_f32 v[132:133], v[10:11], s[0:1], v[132:133] op_sel_hi:[1,0,1]
	v_pk_fma_f32 v[134:135], v[12:13], s[0:1], v[134:135] op_sel_hi:[1,0,1]
	v_pk_fma_f32 v[136:137], v[14:15], s[0:1], v[136:137] op_sel_hi:[1,0,1]
	v_readlane_b32 s0, v167, 44
	s_waitcnt vmcnt(15)
; __device__ void peer_gather_phase(const Params& P, int l, bool do_store) {
;     ...
;         v8[2 * pr] = *(const uint2*)(V + (size_t)ea * 512);
;         v8[2 * pr + 1] = *(const uint2*)(V + (size_t)eb * 512);
;     ...
; #pragma unroll
;       for (int j = 0; j < 8; ++j) {
;         const float a = __builtin_bit_cast(float, __builtin_amdgcn_readlane(__builtin_bit_cast(int, avec), kb + j));
;         const f32x2 aa = f32x2{a, a};
;         y[0] += aa * __builtin_amdgcn_cvt_scalef32_pk_f32_fp4(v8[j].x, 1.0f, 0); y[1] += aa * __builtin_amdgcn_cvt_scalef32_pk_f32_fp4(v8[j].x, 1.0f, 1);
;         y[2] += aa * __builtin_amdgcn_cvt_scalef32_pk_f32_fp4(v8[j].x, 1.0f, 2); y[3] += aa * __builtin_amdgcn_cvt_scalef32_pk_f32_fp4(v8[j].x, 1.0f, 3);
;         y[4] += aa * __builtin_amdgcn_cvt_scalef32_pk_f32_fp4(v8[j].y, 1.0f, 0); y[5] += aa * __builtin_amdgcn_cvt_scalef32_pk_f32_fp4(v8[j].y, 1.0f, 1);
;         y[6] += aa * __builtin_amdgcn_cvt_scalef32_pk_f32_fp4(v8[j].y, 1.0f, 2); y[7] += aa * __builtin_amdgcn_cvt_scalef32_pk_f32_fp4(v8[j].y, 1.0f, 3);
;       }
	v_cvt_scalef32_pk_f32_fp4 v[0:1], v180, 1.0
	v_cvt_scalef32_pk_f32_fp4 v[2:3], v180, 1.0 op_sel:[1,0,0]
	v_cvt_scalef32_pk_f32_fp4 v[4:5], v180, 1.0 op_sel:[0,1,0]
	v_cvt_scalef32_pk_f32_fp4 v[6:7], v180, 1.0 op_sel:[1,1,0]
	v_cvt_scalef32_pk_f32_fp4 v[8:9], v181, 1.0
	v_cvt_scalef32_pk_f32_fp4 v[10:11], v181, 1.0 op_sel:[1,0,0]
	v_cvt_scalef32_pk_f32_fp4 v[12:13], v181, 1.0 op_sel:[0,1,0]
	v_cvt_scalef32_pk_f32_fp4 v[14:15], v181, 1.0 op_sel:[1,1,0]
	v_readlane_b32 s54, v92, 60
	s_lshl_b32 s56, s54, 9
	s_add_u32 s56, s64, s56
	s_addc_u32 s57, s65, 0
	global_load_dwordx2 v[180:181], v227, s[56:57]
	v_pk_fma_f32 v[130:131], v[0:1], s[0:1], v[130:131] op_sel_hi:[1,0,1]
	v_pk_fma_f32 v[138:139], v[2:3], s[0:1], v[138:139] op_sel_hi:[1,0,1]
	v_pk_fma_f32 v[140:141], v[4:5], s[0:1], v[140:141] op_sel_hi:[1,0,1]
	v_pk_fma_f32 v[142:143], v[6:7], s[0:1], v[142:143] op_sel_hi:[1,0,1]
	v_pk_fma_f32 v[128:129], v[8:9], s[0:1], v[128:129] op_sel_hi:[1,0,1]
	v_pk_fma_f32 v[132:133], v[10:11], s[0:1], v[132:133] op_sel_hi:[1,0,1]
	v_pk_fma_f32 v[134:135], v[12:13], s[0:1], v[134:135] op_sel_hi:[1,0,1]
	v_pk_fma_f32 v[136:137], v[14:15], s[0:1], v[136:137] op_sel_hi:[1,0,1]
	v_readlane_b32 s0, v167, 45
	s_waitcnt vmcnt(15)
	v_cvt_scalef32_pk_f32_fp4 v[0:1], v182, 1.0
	v_cvt_scalef32_pk_f32_fp4 v[2:3], v182, 1.0 op_sel:[1,0,0]
	v_cvt_scalef32_pk_f32_fp4 v[4:5], v182, 1.0 op_sel:[0,1,0]
	v_cvt_scalef32_pk_f32_fp4 v[6:7], v182, 1.0 op_sel:[1,1,0]
	v_cvt_scalef32_pk_f32_fp4 v[8:9], v183, 1.0
	v_cvt_scalef32_pk_f32_fp4 v[10:11], v183, 1.0 op_sel:[1,0,0]
	v_cvt_scalef32_pk_f32_fp4 v[12:13], v183, 1.0 op_sel:[0,1,0]
	v_cvt_scalef32_pk_f32_fp4 v[14:15], v183, 1.0 op_sel:[1,1,0]
	v_readlane_b32 s54, v92, 61
	s_lshl_b32 s56, s54, 9
	s_add_u32 s56, s64, s56
	s_addc_u32 s57, s65, 0
	global_load_dwordx2 v[182:183], v227, s[56:57]
	v_pk_fma_f32 v[130:131], v[0:1], s[0:1], v[130:131] op_sel_hi:[1,0,1]
	v_pk_fma_f32 v[138:139], v[2:3], s[0:1], v[138:139] op_sel_hi:[1,0,1]
	v_pk_fma_f32 v[140:141], v[4:5], s[0:1], v[140:141] op_sel_hi:[1,0,1]
	v_pk_fma_f32 v[142:143], v[6:7], s[0:1], v[142:143] op_sel_hi:[1,0,1]
	v_pk_fma_f32 v[128:129], v[8:9], s[0:1], v[128:129] op_sel_hi:[1,0,1]
	v_pk_fma_f32 v[132:133], v[10:11], s[0:1], v[132:133] op_sel_hi:[1,0,1]
	v_pk_fma_f32 v[134:135], v[12:13], s[0:1], v[134:135] op_sel_hi:[1,0,1]
	v_pk_fma_f32 v[136:137], v[14:15], s[0:1], v[136:137] op_sel_hi:[1,0,1]
	v_readlane_b32 s0, v167, 46
	s_waitcnt vmcnt(15)
	v_cvt_scalef32_pk_f32_fp4 v[0:1], v184, 1.0
	v_cvt_scalef32_pk_f32_fp4 v[2:3], v184, 1.0 op_sel:[1,0,0]
	v_cvt_scalef32_pk_f32_fp4 v[4:5], v184, 1.0 op_sel:[0,1,0]
	v_cvt_scalef32_pk_f32_fp4 v[6:7], v184, 1.0 op_sel:[1,1,0]
	v_cvt_scalef32_pk_f32_fp4 v[8:9], v185, 1.0
	v_cvt_scalef32_pk_f32_fp4 v[10:11], v185, 1.0 op_sel:[1,0,0]
	v_cvt_scalef32_pk_f32_fp4 v[12:13], v185, 1.0 op_sel:[0,1,0]
	v_cvt_scalef32_pk_f32_fp4 v[14:15], v185, 1.0 op_sel:[1,1,0]
	v_readlane_b32 s54, v92, 62
	s_lshl_b32 s56, s54, 9
	s_add_u32 s56, s64, s56
	s_addc_u32 s57, s65, 0
	global_load_dwordx2 v[184:185], v227, s[56:57]
	v_pk_fma_f32 v[130:131], v[0:1], s[0:1], v[130:131] op_sel_hi:[1,0,1]
	v_pk_fma_f32 v[138:139], v[2:3], s[0:1], v[138:139] op_sel_hi:[1,0,1]
	v_pk_fma_f32 v[140:141], v[4:5], s[0:1], v[140:141] op_sel_hi:[1,0,1]
	v_pk_fma_f32 v[142:143], v[6:7], s[0:1], v[142:143] op_sel_hi:[1,0,1]
	v_pk_fma_f32 v[128:129], v[8:9], s[0:1], v[128:129] op_sel_hi:[1,0,1]
	v_pk_fma_f32 v[132:133], v[10:11], s[0:1], v[132:133] op_sel_hi:[1,0,1]
	v_pk_fma_f32 v[134:135], v[12:13], s[0:1], v[134:135] op_sel_hi:[1,0,1]
	v_pk_fma_f32 v[136:137], v[14:15], s[0:1], v[136:137] op_sel_hi:[1,0,1]
	v_readlane_b32 s0, v167, 47
	s_waitcnt vmcnt(15)
	v_cvt_scalef32_pk_f32_fp4 v[0:1], v186, 1.0
	v_cvt_scalef32_pk_f32_fp4 v[2:3], v186, 1.0 op_sel:[1,0,0]
	v_cvt_scalef32_pk_f32_fp4 v[4:5], v186, 1.0 op_sel:[0,1,0]
	v_cvt_scalef32_pk_f32_fp4 v[6:7], v186, 1.0 op_sel:[1,1,0]
	v_cvt_scalef32_pk_f32_fp4 v[8:9], v187, 1.0
	v_cvt_scalef32_pk_f32_fp4 v[10:11], v187, 1.0 op_sel:[1,0,0]
	v_cvt_scalef32_pk_f32_fp4 v[12:13], v187, 1.0 op_sel:[0,1,0]
	v_cvt_scalef32_pk_f32_fp4 v[14:15], v187, 1.0 op_sel:[1,1,0]
	v_readlane_b32 s54, v92, 63
	s_lshl_b32 s56, s54, 9
	s_add_u32 s56, s64, s56
	s_addc_u32 s57, s65, 0
	global_load_dwordx2 v[186:187], v227, s[56:57]
	v_pk_fma_f32 v[130:131], v[0:1], s[0:1], v[130:131] op_sel_hi:[1,0,1]
	v_pk_fma_f32 v[138:139], v[2:3], s[0:1], v[138:139] op_sel_hi:[1,0,1]
	v_pk_fma_f32 v[140:141], v[4:5], s[0:1], v[140:141] op_sel_hi:[1,0,1]
	v_pk_fma_f32 v[142:143], v[6:7], s[0:1], v[142:143] op_sel_hi:[1,0,1]
	v_pk_fma_f32 v[128:129], v[8:9], s[0:1], v[128:129] op_sel_hi:[1,0,1]
	v_pk_fma_f32 v[132:133], v[10:11], s[0:1], v[132:133] op_sel_hi:[1,0,1]
	v_pk_fma_f32 v[134:135], v[12:13], s[0:1], v[134:135] op_sel_hi:[1,0,1]
	v_pk_fma_f32 v[136:137], v[14:15], s[0:1], v[136:137] op_sel_hi:[1,0,1]
	v_readlane_b32 s0, v167, 48
	s_waitcnt vmcnt(15)
	v_cvt_scalef32_pk_f32_fp4 v[0:1], v144, 1.0
	v_cvt_scalef32_pk_f32_fp4 v[2:3], v144, 1.0 op_sel:[1,0,0]
	v_cvt_scalef32_pk_f32_fp4 v[4:5], v144, 1.0 op_sel:[0,1,0]
	v_cvt_scalef32_pk_f32_fp4 v[6:7], v144, 1.0 op_sel:[1,1,0]
	v_cvt_scalef32_pk_f32_fp4 v[8:9], v145, 1.0
	v_cvt_scalef32_pk_f32_fp4 v[10:11], v145, 1.0 op_sel:[1,0,0]
	v_cvt_scalef32_pk_f32_fp4 v[12:13], v145, 1.0 op_sel:[0,1,0]
	v_cvt_scalef32_pk_f32_fp4 v[14:15], v145, 1.0 op_sel:[1,1,0]
	v_readlane_b32 s54, v90, 0
	s_lshl_b32 s56, s54, 9
	s_add_u32 s56, s64, s56
	s_addc_u32 s57, s65, 0
	global_load_dwordx2 v[144:145], v227, s[56:57]
	v_pk_fma_f32 v[130:131], v[0:1], s[0:1], v[130:131] op_sel_hi:[1,0,1]
	v_pk_fma_f32 v[138:139], v[2:3], s[0:1], v[138:139] op_sel_hi:[1,0,1]
	v_pk_fma_f32 v[140:141], v[4:5], s[0:1], v[140:141] op_sel_hi:[1,0,1]
	v_pk_fma_f32 v[142:143], v[6:7], s[0:1], v[142:143] op_sel_hi:[1,0,1]
	v_pk_fma_f32 v[128:129], v[8:9], s[0:1], v[128:129] op_sel_hi:[1,0,1]
	v_pk_fma_f32 v[132:133], v[10:11], s[0:1], v[132:133] op_sel_hi:[1,0,1]
	v_pk_fma_f32 v[134:135], v[12:13], s[0:1], v[134:135] op_sel_hi:[1,0,1]
	v_pk_fma_f32 v[136:137], v[14:15], s[0:1], v[136:137] op_sel_hi:[1,0,1]
	v_readlane_b32 s0, v167, 49
	s_waitcnt vmcnt(15)
; __device__ void peer_gather_phase(const Params& P, int l, bool do_store) {
;     ...
;         v8[2 * pr] = *(const uint2*)(V + (size_t)ea * 512);
;         v8[2 * pr + 1] = *(const uint2*)(V + (size_t)eb * 512);
;     ...
; #pragma unroll
;       for (int j = 0; j < 8; ++j) {
;         const float a = __builtin_bit_cast(float, __builtin_amdgcn_readlane(__builtin_bit_cast(int, avec), kb + j));
;         const f32x2 aa = f32x2{a, a};
;         y[0] += aa * __builtin_amdgcn_cvt_scalef32_pk_f32_fp4(v8[j].x, 1.0f, 0); y[1] += aa * __builtin_amdgcn_cvt_scalef32_pk_f32_fp4(v8[j].x, 1.0f, 1);
;         y[2] += aa * __builtin_amdgcn_cvt_scalef32_pk_f32_fp4(v8[j].x, 1.0f, 2); y[3] += aa * __builtin_amdgcn_cvt_scalef32_pk_f32_fp4(v8[j].x, 1.0f, 3);
;         y[4] += aa * __builtin_amdgcn_cvt_scalef32_pk_f32_fp4(v8[j].y, 1.0f, 0); y[5] += aa * __builtin_amdgcn_cvt_scalef32_pk_f32_fp4(v8[j].y, 1.0f, 1);
;         y[6] += aa * __builtin_amdgcn_cvt_scalef32_pk_f32_fp4(v8[j].y, 1.0f, 2); y[7] += aa * __builtin_amdgcn_cvt_scalef32_pk_f32_fp4(v8[j].y, 1.0f, 3);
;       }
	v_cvt_scalef32_pk_f32_fp4 v[0:1], v146, 1.0
	v_cvt_scalef32_pk_f32_fp4 v[2:3], v146, 1.0 op_sel:[1,0,0]
	v_cvt_scalef32_pk_f32_fp4 v[4:5], v146, 1.0 op_sel:[0,1,0]
	v_cvt_scalef32_pk_f32_fp4 v[6:7], v146, 1.0 op_sel:[1,1,0]
	v_cvt_scalef32_pk_f32_fp4 v[8:9], v147, 1.0
	v_cvt_scalef32_pk_f32_fp4 v[10:11], v147, 1.0 op_sel:[1,0,0]
	v_cvt_scalef32_pk_f32_fp4 v[12:13], v147, 1.0 op_sel:[0,1,0]
	v_cvt_scalef32_pk_f32_fp4 v[14:15], v147, 1.0 op_sel:[1,1,0]
	v_readlane_b32 s54, v90, 1
	s_lshl_b32 s56, s54, 9
	s_add_u32 s56, s64, s56
	s_addc_u32 s57, s65, 0
	global_load_dwordx2 v[146:147], v227, s[56:57]
	v_pk_fma_f32 v[130:131], v[0:1], s[0:1], v[130:131] op_sel_hi:[1,0,1]
	v_pk_fma_f32 v[138:139], v[2:3], s[0:1], v[138:139] op_sel_hi:[1,0,1]
	v_pk_fma_f32 v[140:141], v[4:5], s[0:1], v[140:141] op_sel_hi:[1,0,1]
	v_pk_fma_f32 v[142:143], v[6:7], s[0:1], v[142:143] op_sel_hi:[1,0,1]
	v_pk_fma_f32 v[128:129], v[8:9], s[0:1], v[128:129] op_sel_hi:[1,0,1]
	v_pk_fma_f32 v[132:133], v[10:11], s[0:1], v[132:133] op_sel_hi:[1,0,1]
	v_pk_fma_f32 v[134:135], v[12:13], s[0:1], v[134:135] op_sel_hi:[1,0,1]
	v_pk_fma_f32 v[136:137], v[14:15], s[0:1], v[136:137] op_sel_hi:[1,0,1]
	v_readlane_b32 s0, v167, 50
	s_waitcnt vmcnt(15)
	v_cvt_scalef32_pk_f32_fp4 v[0:1], v148, 1.0
	v_cvt_scalef32_pk_f32_fp4 v[2:3], v148, 1.0 op_sel:[1,0,0]
	v_cvt_scalef32_pk_f32_fp4 v[4:5], v148, 1.0 op_sel:[0,1,0]
	v_cvt_scalef32_pk_f32_fp4 v[6:7], v148, 1.0 op_sel:[1,1,0]
	v_cvt_scalef32_pk_f32_fp4 v[8:9], v149, 1.0
	v_cvt_scalef32_pk_f32_fp4 v[10:11], v149, 1.0 op_sel:[1,0,0]
	v_cvt_scalef32_pk_f32_fp4 v[12:13], v149, 1.0 op_sel:[0,1,0]
	v_cvt_scalef32_pk_f32_fp4 v[14:15], v149, 1.0 op_sel:[1,1,0]
	v_readlane_b32 s54, v90, 2
	s_lshl_b32 s56, s54, 9
	s_add_u32 s56, s64, s56
	s_addc_u32 s57, s65, 0
	global_load_dwordx2 v[148:149], v227, s[56:57]
	v_pk_fma_f32 v[130:131], v[0:1], s[0:1], v[130:131] op_sel_hi:[1,0,1]
	v_pk_fma_f32 v[138:139], v[2:3], s[0:1], v[138:139] op_sel_hi:[1,0,1]
	v_pk_fma_f32 v[140:141], v[4:5], s[0:1], v[140:141] op_sel_hi:[1,0,1]
	v_pk_fma_f32 v[142:143], v[6:7], s[0:1], v[142:143] op_sel_hi:[1,0,1]
	v_pk_fma_f32 v[128:129], v[8:9], s[0:1], v[128:129] op_sel_hi:[1,0,1]
	v_pk_fma_f32 v[132:133], v[10:11], s[0:1], v[132:133] op_sel_hi:[1,0,1]
	v_pk_fma_f32 v[134:135], v[12:13], s[0:1], v[134:135] op_sel_hi:[1,0,1]
	v_pk_fma_f32 v[136:137], v[14:15], s[0:1], v[136:137] op_sel_hi:[1,0,1]
	v_readlane_b32 s0, v167, 51
	s_waitcnt vmcnt(15)
	v_cvt_scalef32_pk_f32_fp4 v[0:1], v150, 1.0
	v_cvt_scalef32_pk_f32_fp4 v[2:3], v150, 1.0 op_sel:[1,0,0]
	v_cvt_scalef32_pk_f32_fp4 v[4:5], v150, 1.0 op_sel:[0,1,0]
	v_cvt_scalef32_pk_f32_fp4 v[6:7], v150, 1.0 op_sel:[1,1,0]
	v_cvt_scalef32_pk_f32_fp4 v[8:9], v151, 1.0
	v_cvt_scalef32_pk_f32_fp4 v[10:11], v151, 1.0 op_sel:[1,0,0]
	v_cvt_scalef32_pk_f32_fp4 v[12:13], v151, 1.0 op_sel:[0,1,0]
	v_cvt_scalef32_pk_f32_fp4 v[14:15], v151, 1.0 op_sel:[1,1,0]
	v_readlane_b32 s54, v90, 3
	s_lshl_b32 s56, s54, 9
	s_add_u32 s56, s64, s56
	s_addc_u32 s57, s65, 0
	global_load_dwordx2 v[150:151], v227, s[56:57]
	v_pk_fma_f32 v[130:131], v[0:1], s[0:1], v[130:131] op_sel_hi:[1,0,1]
	v_pk_fma_f32 v[138:139], v[2:3], s[0:1], v[138:139] op_sel_hi:[1,0,1]
	v_pk_fma_f32 v[140:141], v[4:5], s[0:1], v[140:141] op_sel_hi:[1,0,1]
	v_pk_fma_f32 v[142:143], v[6:7], s[0:1], v[142:143] op_sel_hi:[1,0,1]
	v_pk_fma_f32 v[128:129], v[8:9], s[0:1], v[128:129] op_sel_hi:[1,0,1]
	v_pk_fma_f32 v[132:133], v[10:11], s[0:1], v[132:133] op_sel_hi:[1,0,1]
	v_pk_fma_f32 v[134:135], v[12:13], s[0:1], v[134:135] op_sel_hi:[1,0,1]
	v_pk_fma_f32 v[136:137], v[14:15], s[0:1], v[136:137] op_sel_hi:[1,0,1]
	v_readlane_b32 s0, v167, 52
	s_waitcnt vmcnt(15)
	v_cvt_scalef32_pk_f32_fp4 v[0:1], v152, 1.0
	v_cvt_scalef32_pk_f32_fp4 v[2:3], v152, 1.0 op_sel:[1,0,0]
	v_cvt_scalef32_pk_f32_fp4 v[4:5], v152, 1.0 op_sel:[0,1,0]
	v_cvt_scalef32_pk_f32_fp4 v[6:7], v152, 1.0 op_sel:[1,1,0]
	v_cvt_scalef32_pk_f32_fp4 v[8:9], v153, 1.0
	v_cvt_scalef32_pk_f32_fp4 v[10:11], v153, 1.0 op_sel:[1,0,0]
	v_cvt_scalef32_pk_f32_fp4 v[12:13], v153, 1.0 op_sel:[0,1,0]
	v_cvt_scalef32_pk_f32_fp4 v[14:15], v153, 1.0 op_sel:[1,1,0]
	v_readlane_b32 s54, v90, 4
	s_lshl_b32 s56, s54, 9
	s_add_u32 s56, s64, s56
	s_addc_u32 s57, s65, 0
	global_load_dwordx2 v[152:153], v227, s[56:57]
	v_pk_fma_f32 v[130:131], v[0:1], s[0:1], v[130:131] op_sel_hi:[1,0,1]
	v_pk_fma_f32 v[138:139], v[2:3], s[0:1], v[138:139] op_sel_hi:[1,0,1]
	v_pk_fma_f32 v[140:141], v[4:5], s[0:1], v[140:141] op_sel_hi:[1,0,1]
	v_pk_fma_f32 v[142:143], v[6:7], s[0:1], v[142:143] op_sel_hi:[1,0,1]
	v_pk_fma_f32 v[128:129], v[8:9], s[0:1], v[128:129] op_sel_hi:[1,0,1]
	v_pk_fma_f32 v[132:133], v[10:11], s[0:1], v[132:133] op_sel_hi:[1,0,1]
	v_pk_fma_f32 v[134:135], v[12:13], s[0:1], v[134:135] op_sel_hi:[1,0,1]
	v_pk_fma_f32 v[136:137], v[14:15], s[0:1], v[136:137] op_sel_hi:[1,0,1]
	v_readlane_b32 s0, v167, 53
	s_waitcnt vmcnt(15)
	v_cvt_scalef32_pk_f32_fp4 v[0:1], v154, 1.0
	v_cvt_scalef32_pk_f32_fp4 v[2:3], v154, 1.0 op_sel:[1,0,0]
	v_cvt_scalef32_pk_f32_fp4 v[4:5], v154, 1.0 op_sel:[0,1,0]
	v_cvt_scalef32_pk_f32_fp4 v[6:7], v154, 1.0 op_sel:[1,1,0]
	v_cvt_scalef32_pk_f32_fp4 v[8:9], v155, 1.0
	v_cvt_scalef32_pk_f32_fp4 v[10:11], v155, 1.0 op_sel:[1,0,0]
	v_cvt_scalef32_pk_f32_fp4 v[12:13], v155, 1.0 op_sel:[0,1,0]
	v_cvt_scalef32_pk_f32_fp4 v[14:15], v155, 1.0 op_sel:[1,1,0]
	v_readlane_b32 s54, v90, 5
	s_lshl_b32 s56, s54, 9
	s_add_u32 s56, s64, s56
	s_addc_u32 s57, s65, 0
	global_load_dwordx2 v[154:155], v227, s[56:57]
	v_pk_fma_f32 v[130:131], v[0:1], s[0:1], v[130:131] op_sel_hi:[1,0,1]
	v_pk_fma_f32 v[138:139], v[2:3], s[0:1], v[138:139] op_sel_hi:[1,0,1]
	v_pk_fma_f32 v[140:141], v[4:5], s[0:1], v[140:141] op_sel_hi:[1,0,1]
	v_pk_fma_f32 v[142:143], v[6:7], s[0:1], v[142:143] op_sel_hi:[1,0,1]
	v_pk_fma_f32 v[128:129], v[8:9], s[0:1], v[128:129] op_sel_hi:[1,0,1]
	v_pk_fma_f32 v[132:133], v[10:11], s[0:1], v[132:133] op_sel_hi:[1,0,1]
	v_pk_fma_f32 v[134:135], v[12:13], s[0:1], v[134:135] op_sel_hi:[1,0,1]
	v_pk_fma_f32 v[136:137], v[14:15], s[0:1], v[136:137] op_sel_hi:[1,0,1]
	v_readlane_b32 s0, v167, 54
	s_waitcnt vmcnt(15)
; __device__ void peer_gather_phase(const Params& P, int l, bool do_store) {
;     ...
;         v8[2 * pr] = *(const uint2*)(V + (size_t)ea * 512);
;         v8[2 * pr + 1] = *(const uint2*)(V + (size_t)eb * 512);
;     ...
; #pragma unroll
;       for (int j = 0; j < 8; ++j) {
;         const float a = __builtin_bit_cast(float, __builtin_amdgcn_readlane(__builtin_bit_cast(int, avec), kb + j));
;         const f32x2 aa = f32x2{a, a};
;         y[0] += aa * __builtin_amdgcn_cvt_scalef32_pk_f32_fp4(v8[j].x, 1.0f, 0); y[1] += aa * __builtin_amdgcn_cvt_scalef32_pk_f32_fp4(v8[j].x, 1.0f, 1);
;         y[2] += aa * __builtin_amdgcn_cvt_scalef32_pk_f32_fp4(v8[j].x, 1.0f, 2); y[3] += aa * __builtin_amdgcn_cvt_scalef32_pk_f32_fp4(v8[j].x, 1.0f, 3);
;         y[4] += aa * __builtin_amdgcn_cvt_scalef32_pk_f32_fp4(v8[j].y, 1.0f, 0); y[5] += aa * __builtin_amdgcn_cvt_scalef32_pk_f32_fp4(v8[j].y, 1.0f, 1);
;         y[6] += aa * __builtin_amdgcn_cvt_scalef32_pk_f32_fp4(v8[j].y, 1.0f, 2); y[7] += aa * __builtin_amdgcn_cvt_scalef32_pk_f32_fp4(v8[j].y, 1.0f, 3);
;       }
	v_cvt_scalef32_pk_f32_fp4 v[0:1], v156, 1.0
	v_cvt_scalef32_pk_f32_fp4 v[2:3], v156, 1.0 op_sel:[1,0,0]
	v_cvt_scalef32_pk_f32_fp4 v[4:5], v156, 1.0 op_sel:[0,1,0]
	v_cvt_scalef32_pk_f32_fp4 v[6:7], v156, 1.0 op_sel:[1,1,0]
	v_cvt_scalef32_pk_f32_fp4 v[8:9], v157, 1.0
	v_cvt_scalef32_pk_f32_fp4 v[10:11], v157, 1.0 op_sel:[1,0,0]
	v_cvt_scalef32_pk_f32_fp4 v[12:13], v157, 1.0 op_sel:[0,1,0]
	v_cvt_scalef32_pk_f32_fp4 v[14:15], v157, 1.0 op_sel:[1,1,0]
	v_readlane_b32 s54, v90, 6
	s_lshl_b32 s56, s54, 9
	s_add_u32 s56, s64, s56
	s_addc_u32 s57, s65, 0
	global_load_dwordx2 v[156:157], v227, s[56:57]
	v_pk_fma_f32 v[130:131], v[0:1], s[0:1], v[130:131] op_sel_hi:[1,0,1]
	v_pk_fma_f32 v[138:139], v[2:3], s[0:1], v[138:139] op_sel_hi:[1,0,1]
	v_pk_fma_f32 v[140:141], v[4:5], s[0:1], v[140:141] op_sel_hi:[1,0,1]
	v_pk_fma_f32 v[142:143], v[6:7], s[0:1], v[142:143] op_sel_hi:[1,0,1]
	v_pk_fma_f32 v[128:129], v[8:9], s[0:1], v[128:129] op_sel_hi:[1,0,1]
	v_pk_fma_f32 v[132:133], v[10:11], s[0:1], v[132:133] op_sel_hi:[1,0,1]
	v_pk_fma_f32 v[134:135], v[12:13], s[0:1], v[134:135] op_sel_hi:[1,0,1]
	v_pk_fma_f32 v[136:137], v[14:15], s[0:1], v[136:137] op_sel_hi:[1,0,1]
	v_readlane_b32 s0, v167, 55
	s_waitcnt vmcnt(15)
	v_cvt_scalef32_pk_f32_fp4 v[0:1], v158, 1.0
	v_cvt_scalef32_pk_f32_fp4 v[2:3], v158, 1.0 op_sel:[1,0,0]
	v_cvt_scalef32_pk_f32_fp4 v[4:5], v158, 1.0 op_sel:[0,1,0]
	v_cvt_scalef32_pk_f32_fp4 v[6:7], v158, 1.0 op_sel:[1,1,0]
	v_cvt_scalef32_pk_f32_fp4 v[8:9], v159, 1.0
	v_cvt_scalef32_pk_f32_fp4 v[10:11], v159, 1.0 op_sel:[1,0,0]
	v_cvt_scalef32_pk_f32_fp4 v[12:13], v159, 1.0 op_sel:[0,1,0]
	v_cvt_scalef32_pk_f32_fp4 v[14:15], v159, 1.0 op_sel:[1,1,0]
	v_readlane_b32 s54, v90, 7
	s_lshl_b32 s56, s54, 9
	s_add_u32 s56, s64, s56
	s_addc_u32 s57, s65, 0
	global_load_dwordx2 v[158:159], v227, s[56:57]
	v_pk_fma_f32 v[130:131], v[0:1], s[0:1], v[130:131] op_sel_hi:[1,0,1]
	v_pk_fma_f32 v[138:139], v[2:3], s[0:1], v[138:139] op_sel_hi:[1,0,1]
	v_pk_fma_f32 v[140:141], v[4:5], s[0:1], v[140:141] op_sel_hi:[1,0,1]
	v_pk_fma_f32 v[142:143], v[6:7], s[0:1], v[142:143] op_sel_hi:[1,0,1]
	v_pk_fma_f32 v[128:129], v[8:9], s[0:1], v[128:129] op_sel_hi:[1,0,1]
	v_pk_fma_f32 v[132:133], v[10:11], s[0:1], v[132:133] op_sel_hi:[1,0,1]
	v_pk_fma_f32 v[134:135], v[12:13], s[0:1], v[134:135] op_sel_hi:[1,0,1]
	v_pk_fma_f32 v[136:137], v[14:15], s[0:1], v[136:137] op_sel_hi:[1,0,1]
	v_readlane_b32 s0, v167, 56
	s_waitcnt vmcnt(15)
	v_cvt_scalef32_pk_f32_fp4 v[0:1], v168, 1.0
	v_cvt_scalef32_pk_f32_fp4 v[2:3], v168, 1.0 op_sel:[1,0,0]
	v_cvt_scalef32_pk_f32_fp4 v[4:5], v168, 1.0 op_sel:[0,1,0]
	v_cvt_scalef32_pk_f32_fp4 v[6:7], v168, 1.0 op_sel:[1,1,0]
	v_cvt_scalef32_pk_f32_fp4 v[8:9], v169, 1.0
	v_cvt_scalef32_pk_f32_fp4 v[10:11], v169, 1.0 op_sel:[1,0,0]
	v_cvt_scalef32_pk_f32_fp4 v[12:13], v169, 1.0 op_sel:[0,1,0]
	v_cvt_scalef32_pk_f32_fp4 v[14:15], v169, 1.0 op_sel:[1,1,0]
	v_readlane_b32 s54, v90, 8
	s_lshl_b32 s56, s54, 9
	s_add_u32 s56, s64, s56
	s_addc_u32 s57, s65, 0
	global_load_dwordx2 v[168:169], v227, s[56:57]
	v_pk_fma_f32 v[130:131], v[0:1], s[0:1], v[130:131] op_sel_hi:[1,0,1]
	v_pk_fma_f32 v[138:139], v[2:3], s[0:1], v[138:139] op_sel_hi:[1,0,1]
	v_pk_fma_f32 v[140:141], v[4:5], s[0:1], v[140:141] op_sel_hi:[1,0,1]
	v_pk_fma_f32 v[142:143], v[6:7], s[0:1], v[142:143] op_sel_hi:[1,0,1]
	v_pk_fma_f32 v[128:129], v[8:9], s[0:1], v[128:129] op_sel_hi:[1,0,1]
	v_pk_fma_f32 v[132:133], v[10:11], s[0:1], v[132:133] op_sel_hi:[1,0,1]
	v_pk_fma_f32 v[134:135], v[12:13], s[0:1], v[134:135] op_sel_hi:[1,0,1]
	v_pk_fma_f32 v[136:137], v[14:15], s[0:1], v[136:137] op_sel_hi:[1,0,1]
	v_readlane_b32 s0, v167, 57
	s_waitcnt vmcnt(15)
	v_cvt_scalef32_pk_f32_fp4 v[0:1], v170, 1.0
	v_cvt_scalef32_pk_f32_fp4 v[2:3], v170, 1.0 op_sel:[1,0,0]
	v_cvt_scalef32_pk_f32_fp4 v[4:5], v170, 1.0 op_sel:[0,1,0]
	v_cvt_scalef32_pk_f32_fp4 v[6:7], v170, 1.0 op_sel:[1,1,0]
	v_cvt_scalef32_pk_f32_fp4 v[8:9], v171, 1.0
	v_cvt_scalef32_pk_f32_fp4 v[10:11], v171, 1.0 op_sel:[1,0,0]
	v_cvt_scalef32_pk_f32_fp4 v[12:13], v171, 1.0 op_sel:[0,1,0]
	v_cvt_scalef32_pk_f32_fp4 v[14:15], v171, 1.0 op_sel:[1,1,0]
	v_readlane_b32 s54, v90, 9
	s_lshl_b32 s56, s54, 9
	s_add_u32 s56, s64, s56
	s_addc_u32 s57, s65, 0
	global_load_dwordx2 v[170:171], v227, s[56:57]
	v_pk_fma_f32 v[130:131], v[0:1], s[0:1], v[130:131] op_sel_hi:[1,0,1]
	v_pk_fma_f32 v[138:139], v[2:3], s[0:1], v[138:139] op_sel_hi:[1,0,1]
	v_pk_fma_f32 v[140:141], v[4:5], s[0:1], v[140:141] op_sel_hi:[1,0,1]
	v_pk_fma_f32 v[142:143], v[6:7], s[0:1], v[142:143] op_sel_hi:[1,0,1]
	v_pk_fma_f32 v[128:129], v[8:9], s[0:1], v[128:129] op_sel_hi:[1,0,1]
	v_pk_fma_f32 v[132:133], v[10:11], s[0:1], v[132:133] op_sel_hi:[1,0,1]
	v_pk_fma_f32 v[134:135], v[12:13], s[0:1], v[134:135] op_sel_hi:[1,0,1]
	v_pk_fma_f32 v[136:137], v[14:15], s[0:1], v[136:137] op_sel_hi:[1,0,1]
	v_readlane_b32 s0, v167, 58
	s_waitcnt vmcnt(15)
	v_cvt_scalef32_pk_f32_fp4 v[0:1], v172, 1.0
	v_cvt_scalef32_pk_f32_fp4 v[2:3], v172, 1.0 op_sel:[1,0,0]
	v_cvt_scalef32_pk_f32_fp4 v[4:5], v172, 1.0 op_sel:[0,1,0]
	v_cvt_scalef32_pk_f32_fp4 v[6:7], v172, 1.0 op_sel:[1,1,0]
	v_cvt_scalef32_pk_f32_fp4 v[8:9], v173, 1.0
	v_cvt_scalef32_pk_f32_fp4 v[10:11], v173, 1.0 op_sel:[1,0,0]
	v_cvt_scalef32_pk_f32_fp4 v[12:13], v173, 1.0 op_sel:[0,1,0]
	v_cvt_scalef32_pk_f32_fp4 v[14:15], v173, 1.0 op_sel:[1,1,0]
	v_readlane_b32 s54, v90, 10
	s_lshl_b32 s56, s54, 9
	s_add_u32 s56, s64, s56
	s_addc_u32 s57, s65, 0
	global_load_dwordx2 v[172:173], v227, s[56:57]
	v_pk_fma_f32 v[130:131], v[0:1], s[0:1], v[130:131] op_sel_hi:[1,0,1]
	v_pk_fma_f32 v[138:139], v[2:3], s[0:1], v[138:139] op_sel_hi:[1,0,1]
	v_pk_fma_f32 v[140:141], v[4:5], s[0:1], v[140:141] op_sel_hi:[1,0,1]
	v_pk_fma_f32 v[142:143], v[6:7], s[0:1], v[142:143] op_sel_hi:[1,0,1]
	v_pk_fma_f32 v[128:129], v[8:9], s[0:1], v[128:129] op_sel_hi:[1,0,1]
	v_pk_fma_f32 v[132:133], v[10:11], s[0:1], v[132:133] op_sel_hi:[1,0,1]
	v_pk_fma_f32 v[134:135], v[12:13], s[0:1], v[134:135] op_sel_hi:[1,0,1]
	v_pk_fma_f32 v[136:137], v[14:15], s[0:1], v[136:137] op_sel_hi:[1,0,1]
	v_readlane_b32 s0, v167, 59
	s_waitcnt vmcnt(15)
; __device__ void peer_gather_phase(const Params& P, int l, bool do_store) {
;     ...
;         v8[2 * pr] = *(const uint2*)(V + (size_t)ea * 512);
;         v8[2 * pr + 1] = *(const uint2*)(V + (size_t)eb * 512);
;     ...
; #pragma unroll
;       for (int j = 0; j < 8; ++j) {
;         const float a = __builtin_bit_cast(float, __builtin_amdgcn_readlane(__builtin_bit_cast(int, avec), kb + j));
;         const f32x2 aa = f32x2{a, a};
;         y[0] += aa * __builtin_amdgcn_cvt_scalef32_pk_f32_fp4(v8[j].x, 1.0f, 0); y[1] += aa * __builtin_amdgcn_cvt_scalef32_pk_f32_fp4(v8[j].x, 1.0f, 1);
;         y[2] += aa * __builtin_amdgcn_cvt_scalef32_pk_f32_fp4(v8[j].x, 1.0f, 2); y[3] += aa * __builtin_amdgcn_cvt_scalef32_pk_f32_fp4(v8[j].x, 1.0f, 3);
;         y[4] += aa * __builtin_amdgcn_cvt_scalef32_pk_f32_fp4(v8[j].y, 1.0f, 0); y[5] += aa * __builtin_amdgcn_cvt_scalef32_pk_f32_fp4(v8[j].y, 1.0f, 1);
;         y[6] += aa * __builtin_amdgcn_cvt_scalef32_pk_f32_fp4(v8[j].y, 1.0f, 2); y[7] += aa * __builtin_amdgcn_cvt_scalef32_pk_f32_fp4(v8[j].y, 1.0f, 3);
;       }
	v_cvt_scalef32_pk_f32_fp4 v[0:1], v174, 1.0
	v_cvt_scalef32_pk_f32_fp4 v[2:3], v174, 1.0 op_sel:[1,0,0]
	v_cvt_scalef32_pk_f32_fp4 v[4:5], v174, 1.0 op_sel:[0,1,0]
	v_cvt_scalef32_pk_f32_fp4 v[6:7], v174, 1.0 op_sel:[1,1,0]
	v_cvt_scalef32_pk_f32_fp4 v[8:9], v175, 1.0
	v_cvt_scalef32_pk_f32_fp4 v[10:11], v175, 1.0 op_sel:[1,0,0]
	v_cvt_scalef32_pk_f32_fp4 v[12:13], v175, 1.0 op_sel:[0,1,0]
	v_cvt_scalef32_pk_f32_fp4 v[14:15], v175, 1.0 op_sel:[1,1,0]
	v_readlane_b32 s54, v90, 11
	s_lshl_b32 s56, s54, 9
	s_add_u32 s56, s64, s56
	s_addc_u32 s57, s65, 0
	global_load_dwordx2 v[174:175], v227, s[56:57]
	v_pk_fma_f32 v[130:131], v[0:1], s[0:1], v[130:131] op_sel_hi:[1,0,1]
	v_pk_fma_f32 v[138:139], v[2:3], s[0:1], v[138:139] op_sel_hi:[1,0,1]
	v_pk_fma_f32 v[140:141], v[4:5], s[0:1], v[140:141] op_sel_hi:[1,0,1]
	v_pk_fma_f32 v[142:143], v[6:7], s[0:1], v[142:143] op_sel_hi:[1,0,1]
	v_pk_fma_f32 v[128:129], v[8:9], s[0:1], v[128:129] op_sel_hi:[1,0,1]
	v_pk_fma_f32 v[132:133], v[10:11], s[0:1], v[132:133] op_sel_hi:[1,0,1]
	v_pk_fma_f32 v[134:135], v[12:13], s[0:1], v[134:135] op_sel_hi:[1,0,1]
	v_pk_fma_f32 v[136:137], v[14:15], s[0:1], v[136:137] op_sel_hi:[1,0,1]
	v_readlane_b32 s0, v167, 60
	s_waitcnt vmcnt(15)
	v_cvt_scalef32_pk_f32_fp4 v[0:1], v180, 1.0
	v_cvt_scalef32_pk_f32_fp4 v[2:3], v180, 1.0 op_sel:[1,0,0]
	v_cvt_scalef32_pk_f32_fp4 v[4:5], v180, 1.0 op_sel:[0,1,0]
	v_cvt_scalef32_pk_f32_fp4 v[6:7], v180, 1.0 op_sel:[1,1,0]
	v_cvt_scalef32_pk_f32_fp4 v[8:9], v181, 1.0
	v_cvt_scalef32_pk_f32_fp4 v[10:11], v181, 1.0 op_sel:[1,0,0]
	v_cvt_scalef32_pk_f32_fp4 v[12:13], v181, 1.0 op_sel:[0,1,0]
	v_cvt_scalef32_pk_f32_fp4 v[14:15], v181, 1.0 op_sel:[1,1,0]
	v_readlane_b32 s54, v90, 12
	s_lshl_b32 s56, s54, 9
	s_add_u32 s56, s64, s56
	s_addc_u32 s57, s65, 0
	global_load_dwordx2 v[180:181], v227, s[56:57]
	v_pk_fma_f32 v[130:131], v[0:1], s[0:1], v[130:131] op_sel_hi:[1,0,1]
	v_pk_fma_f32 v[138:139], v[2:3], s[0:1], v[138:139] op_sel_hi:[1,0,1]
	v_pk_fma_f32 v[140:141], v[4:5], s[0:1], v[140:141] op_sel_hi:[1,0,1]
	v_pk_fma_f32 v[142:143], v[6:7], s[0:1], v[142:143] op_sel_hi:[1,0,1]
	v_pk_fma_f32 v[128:129], v[8:9], s[0:1], v[128:129] op_sel_hi:[1,0,1]
	v_pk_fma_f32 v[132:133], v[10:11], s[0:1], v[132:133] op_sel_hi:[1,0,1]
	v_pk_fma_f32 v[134:135], v[12:13], s[0:1], v[134:135] op_sel_hi:[1,0,1]
	v_pk_fma_f32 v[136:137], v[14:15], s[0:1], v[136:137] op_sel_hi:[1,0,1]
	v_readlane_b32 s0, v167, 61
	s_waitcnt vmcnt(15)
	v_cvt_scalef32_pk_f32_fp4 v[0:1], v182, 1.0
	v_cvt_scalef32_pk_f32_fp4 v[2:3], v182, 1.0 op_sel:[1,0,0]
	v_cvt_scalef32_pk_f32_fp4 v[4:5], v182, 1.0 op_sel:[0,1,0]
	v_cvt_scalef32_pk_f32_fp4 v[6:7], v182, 1.0 op_sel:[1,1,0]
	v_cvt_scalef32_pk_f32_fp4 v[8:9], v183, 1.0
	v_cvt_scalef32_pk_f32_fp4 v[10:11], v183, 1.0 op_sel:[1,0,0]
	v_cvt_scalef32_pk_f32_fp4 v[12:13], v183, 1.0 op_sel:[0,1,0]
	v_cvt_scalef32_pk_f32_fp4 v[14:15], v183, 1.0 op_sel:[1,1,0]
	v_readlane_b32 s54, v90, 13
	s_lshl_b32 s56, s54, 9
	s_add_u32 s56, s64, s56
	s_addc_u32 s57, s65, 0
	global_load_dwordx2 v[182:183], v227, s[56:57]
	v_pk_fma_f32 v[130:131], v[0:1], s[0:1], v[130:131] op_sel_hi:[1,0,1]
	v_pk_fma_f32 v[138:139], v[2:3], s[0:1], v[138:139] op_sel_hi:[1,0,1]
	v_pk_fma_f32 v[140:141], v[4:5], s[0:1], v[140:141] op_sel_hi:[1,0,1]
	v_pk_fma_f32 v[142:143], v[6:7], s[0:1], v[142:143] op_sel_hi:[1,0,1]
	v_pk_fma_f32 v[128:129], v[8:9], s[0:1], v[128:129] op_sel_hi:[1,0,1]
	v_pk_fma_f32 v[132:133], v[10:11], s[0:1], v[132:133] op_sel_hi:[1,0,1]
	v_pk_fma_f32 v[134:135], v[12:13], s[0:1], v[134:135] op_sel_hi:[1,0,1]
	v_pk_fma_f32 v[136:137], v[14:15], s[0:1], v[136:137] op_sel_hi:[1,0,1]
	v_readlane_b32 s0, v167, 62
	s_waitcnt vmcnt(15)
	v_cvt_scalef32_pk_f32_fp4 v[0:1], v184, 1.0
	v_cvt_scalef32_pk_f32_fp4 v[2:3], v184, 1.0 op_sel:[1,0,0]
	v_cvt_scalef32_pk_f32_fp4 v[4:5], v184, 1.0 op_sel:[0,1,0]
	v_cvt_scalef32_pk_f32_fp4 v[6:7], v184, 1.0 op_sel:[1,1,0]
	v_cvt_scalef32_pk_f32_fp4 v[8:9], v185, 1.0
	v_cvt_scalef32_pk_f32_fp4 v[10:11], v185, 1.0 op_sel:[1,0,0]
	v_cvt_scalef32_pk_f32_fp4 v[12:13], v185, 1.0 op_sel:[0,1,0]
	v_cvt_scalef32_pk_f32_fp4 v[14:15], v185, 1.0 op_sel:[1,1,0]
	v_readlane_b32 s54, v90, 14
	s_lshl_b32 s56, s54, 9
	s_add_u32 s56, s64, s56
	s_addc_u32 s57, s65, 0
	global_load_dwordx2 v[184:185], v227, s[56:57]
	v_pk_fma_f32 v[130:131], v[0:1], s[0:1], v[130:131] op_sel_hi:[1,0,1]
	v_pk_fma_f32 v[138:139], v[2:3], s[0:1], v[138:139] op_sel_hi:[1,0,1]
	v_pk_fma_f32 v[140:141], v[4:5], s[0:1], v[140:141] op_sel_hi:[1,0,1]
	v_pk_fma_f32 v[142:143], v[6:7], s[0:1], v[142:143] op_sel_hi:[1,0,1]
	v_pk_fma_f32 v[128:129], v[8:9], s[0:1], v[128:129] op_sel_hi:[1,0,1]
	v_pk_fma_f32 v[132:133], v[10:11], s[0:1], v[132:133] op_sel_hi:[1,0,1]
	v_pk_fma_f32 v[134:135], v[12:13], s[0:1], v[134:135] op_sel_hi:[1,0,1]
	v_pk_fma_f32 v[136:137], v[14:15], s[0:1], v[136:137] op_sel_hi:[1,0,1]
	v_readlane_b32 s0, v167, 63
	s_waitcnt vmcnt(15)
	v_cvt_scalef32_pk_f32_fp4 v[0:1], v186, 1.0
	v_cvt_scalef32_pk_f32_fp4 v[2:3], v186, 1.0 op_sel:[1,0,0]
	v_cvt_scalef32_pk_f32_fp4 v[4:5], v186, 1.0 op_sel:[0,1,0]
	v_cvt_scalef32_pk_f32_fp4 v[6:7], v186, 1.0 op_sel:[1,1,0]
	v_cvt_scalef32_pk_f32_fp4 v[8:9], v187, 1.0
	v_cvt_scalef32_pk_f32_fp4 v[10:11], v187, 1.0 op_sel:[1,0,0]
	v_cvt_scalef32_pk_f32_fp4 v[12:13], v187, 1.0 op_sel:[0,1,0]
	v_cvt_scalef32_pk_f32_fp4 v[14:15], v187, 1.0 op_sel:[1,1,0]
	v_readlane_b32 s54, v90, 15
	s_lshl_b32 s56, s54, 9
	s_add_u32 s56, s64, s56
	s_addc_u32 s57, s65, 0
	global_load_dwordx2 v[186:187], v227, s[56:57]
	v_pk_fma_f32 v[130:131], v[0:1], s[0:1], v[130:131] op_sel_hi:[1,0,1]
	v_pk_fma_f32 v[138:139], v[2:3], s[0:1], v[138:139] op_sel_hi:[1,0,1]
	v_pk_fma_f32 v[140:141], v[4:5], s[0:1], v[140:141] op_sel_hi:[1,0,1]
	v_pk_fma_f32 v[142:143], v[6:7], s[0:1], v[142:143] op_sel_hi:[1,0,1]
	v_pk_fma_f32 v[128:129], v[8:9], s[0:1], v[128:129] op_sel_hi:[1,0,1]
	v_pk_fma_f32 v[132:133], v[10:11], s[0:1], v[132:133] op_sel_hi:[1,0,1]
	v_pk_fma_f32 v[134:135], v[12:13], s[0:1], v[134:135] op_sel_hi:[1,0,1]
	v_pk_fma_f32 v[136:137], v[14:15], s[0:1], v[136:137] op_sel_hi:[1,0,1]
	s_waitcnt lgkmcnt(0)
; __device__ void peer_gather_phase(const Params& P, int l, bool do_store) {
;     ...
;         const int ea = __builtin_amdgcn_readlane(evs, kb + 2 * pr), eb = __builtin_amdgcn_readlane(evs, kb + 2 * pr + 1);
;         const uint2* up = (const uint2*)(U + (size_t)(uphi ? eb : ea) * 768);
;         u6[3 * pr] = up[0]; u6[3 * pr + 1] = up[1]; u6[3 * pr + 2] = up[2];
;     ...
;       for (int pr = 0; pr < 4; ++pr) {
;         v6u_t qv; qv[0] = u6[3 * pr].x; qv[1] = u6[3 * pr].y; qv[2] = u6[3 * pr + 1].x; qv[3] = u6[3 * pr + 1].y; qv[4] = u6[3 * pr + 2].x; qv[5] = u6[3 * pr + 2].y;
;         const v32f_t wv = __builtin_amdgcn_cvt_scalef32_pk32_f32_fp6(qv, 1.0f);
;         f32x2 a2 = f32x2{0.f, 0.f};
; #pragma unroll
;         for (int i = 0; i < 16; ++i) a2 += f32x2{wv[2 * i], wv[2 * i + 1]} * xu[i];
;         float hs = a2.x + a2.y;
;         hs += dpp_row_shr(hs, 1); hs += dpp_row_shr(hs, 2); hs += dpp_row_shr(hs, 4); hs += dpp_row_shr(hs, 8);
;         hs += __builtin_bit_cast(float, __builtin_amdgcn_update_dpp(0, __builtin_bit_cast(int, hs), 0x142, 0xa, 0xf, false));
;         const float da = __builtin_bit_cast(float, __builtin_amdgcn_readlane(__builtin_bit_cast(int, hs), 31));
;         const float db = __builtin_bit_cast(float, __builtin_amdgcn_readlane(__builtin_bit_cast(int, hs), 63));
;         dvec = (lane == kb + 2 * pr) ? da : dvec;
;         dvec = (lane == kb + 2 * pr + 1) ? db : dvec;
;       }
	v_mad_u32_u24 v167, v76, s33, v195
	ds_read_b32 v77, v74 offset:328
	s_waitcnt vmcnt(48)
	v_cvt_scalef32_pk32_f32_fp6 v[0:31], v[50:55], 1.0
	global_load_dwordx2 v[54:55], v167, s[62:63] offset:16
	global_load_dwordx4 v[50:53], v167, s[62:63]
	v_pk_mul_f32 v[246:247], v[0:1], v[96:97]
	v_pk_mul_f32 v[254:255], v[2:3], v[98:99]
	v_pk_mul_f32 v[160:161], v[4:5], v[100:101]
	v_pk_fma_f32 v[246:247], v[6:7], v[102:103], v[246:247]
	v_pk_fma_f32 v[254:255], v[8:9], v[104:105], v[254:255]
	v_pk_fma_f32 v[160:161], v[10:11], v[106:107], v[160:161]
	v_pk_fma_f32 v[246:247], v[12:13], v[108:109], v[246:247]
	v_pk_fma_f32 v[254:255], v[14:15], v[110:111], v[254:255]
	v_pk_fma_f32 v[160:161], v[16:17], v[112:113], v[160:161]
	v_pk_fma_f32 v[246:247], v[18:19], v[114:115], v[246:247]
	v_pk_fma_f32 v[254:255], v[20:21], v[116:117], v[254:255]
	v_pk_fma_f32 v[160:161], v[22:23], v[118:119], v[160:161]
	v_pk_fma_f32 v[246:247], v[24:25], v[120:121], v[246:247]
	v_pk_fma_f32 v[254:255], v[26:27], v[122:123], v[254:255]
	v_pk_fma_f32 v[160:161], v[28:29], v[124:125], v[160:161]
	v_pk_fma_f32 v[246:247], v[30:31], v[126:127], v[246:247]
	v_pk_add_f32 v[254:255], v[254:255], v[160:161]
	s_nop 0
	v_pk_add_f32 v[246:247], v[246:247], v[254:255]
	s_nop 0
	v_add_f32_e32 v162, v246, v247
	s_waitcnt lgkmcnt(0)
	v_mad_u32_u24 v167, v77, s33, v195
	ds_read_b32 v76, v74 offset:336
	s_waitcnt vmcnt(48)
	v_cvt_scalef32_pk32_f32_fp6 v[0:31], v[44:49], 1.0
	global_load_dwordx2 v[48:49], v167, s[62:63] offset:16
	global_load_dwordx4 v[44:47], v167, s[62:63]
	v_pk_mul_f32 v[246:247], v[0:1], v[96:97]
	v_pk_mul_f32 v[254:255], v[2:3], v[98:99]
	v_pk_mul_f32 v[160:161], v[4:5], v[100:101]
	v_pk_fma_f32 v[246:247], v[6:7], v[102:103], v[246:247]
	v_pk_fma_f32 v[254:255], v[8:9], v[104:105], v[254:255]
	v_pk_fma_f32 v[160:161], v[10:11], v[106:107], v[160:161]
	v_pk_fma_f32 v[246:247], v[12:13], v[108:109], v[246:247]
	v_pk_fma_f32 v[254:255], v[14:15], v[110:111], v[254:255]
	v_pk_fma_f32 v[160:161], v[16:17], v[112:113], v[160:161]
	v_pk_fma_f32 v[246:247], v[18:19], v[114:115], v[246:247]
	v_pk_fma_f32 v[254:255], v[20:21], v[116:117], v[254:255]
	v_pk_fma_f32 v[160:161], v[22:23], v[118:119], v[160:161]
	v_pk_fma_f32 v[246:247], v[24:25], v[120:121], v[246:247]
	v_pk_fma_f32 v[254:255], v[26:27], v[122:123], v[254:255]
	v_pk_fma_f32 v[160:161], v[28:29], v[124:125], v[160:161]
	v_pk_fma_f32 v[246:247], v[30:31], v[126:127], v[246:247]
	v_pk_add_f32 v[254:255], v[254:255], v[160:161]
	s_nop 0
	v_pk_add_f32 v[246:247], v[246:247], v[254:255]
	s_nop 0
	v_add_f32_e32 v163, v246, v247
	s_waitcnt lgkmcnt(0)
	v_mad_u32_u24 v167, v76, s33, v195
	ds_read_b32 v77, v74 offset:344
	s_waitcnt vmcnt(48)
	v_cvt_scalef32_pk32_f32_fp6 v[0:31], v[38:43], 1.0
	global_load_dwordx2 v[42:43], v167, s[62:63] offset:16
	global_load_dwordx4 v[38:41], v167, s[62:63]
	v_pk_mul_f32 v[246:247], v[0:1], v[96:97]
	v_pk_mul_f32 v[254:255], v[2:3], v[98:99]
	v_pk_mul_f32 v[160:161], v[4:5], v[100:101]
	v_pk_fma_f32 v[246:247], v[6:7], v[102:103], v[246:247]
	v_pk_fma_f32 v[254:255], v[8:9], v[104:105], v[254:255]
	v_pk_fma_f32 v[160:161], v[10:11], v[106:107], v[160:161]
	v_pk_fma_f32 v[246:247], v[12:13], v[108:109], v[246:247]
	v_pk_fma_f32 v[254:255], v[14:15], v[110:111], v[254:255]
	v_pk_fma_f32 v[160:161], v[16:17], v[112:113], v[160:161]
	v_pk_fma_f32 v[246:247], v[18:19], v[114:115], v[246:247]
	v_pk_fma_f32 v[254:255], v[20:21], v[116:117], v[254:255]
	v_pk_fma_f32 v[160:161], v[22:23], v[118:119], v[160:161]
	v_pk_fma_f32 v[246:247], v[24:25], v[120:121], v[246:247]
	v_pk_fma_f32 v[254:255], v[26:27], v[122:123], v[254:255]
	v_pk_fma_f32 v[160:161], v[28:29], v[124:125], v[160:161]
	v_pk_fma_f32 v[246:247], v[30:31], v[126:127], v[246:247]
	v_pk_add_f32 v[254:255], v[254:255], v[160:161]
	s_nop 0
	v_pk_add_f32 v[246:247], v[246:247], v[254:255]
	s_nop 0
	v_add_f32_e32 v164, v246, v247
	s_waitcnt lgkmcnt(0)
	v_mad_u32_u24 v167, v77, s33, v195
	ds_read_b32 v76, v74 offset:352
	s_waitcnt vmcnt(48)
	v_cvt_scalef32_pk32_f32_fp6 v[0:31], v[32:37], 1.0
	global_load_dwordx2 v[36:37], v167, s[62:63] offset:16
	global_load_dwordx4 v[32:35], v167, s[62:63]
	v_pk_mul_f32 v[246:247], v[0:1], v[96:97]
	v_pk_mul_f32 v[254:255], v[2:3], v[98:99]
	v_pk_mul_f32 v[160:161], v[4:5], v[100:101]
	v_pk_fma_f32 v[246:247], v[6:7], v[102:103], v[246:247]
	v_pk_fma_f32 v[254:255], v[8:9], v[104:105], v[254:255]
	v_pk_fma_f32 v[160:161], v[10:11], v[106:107], v[160:161]
	v_pk_fma_f32 v[246:247], v[12:13], v[108:109], v[246:247]
	v_pk_fma_f32 v[254:255], v[14:15], v[110:111], v[254:255]
	v_pk_fma_f32 v[160:161], v[16:17], v[112:113], v[160:161]
	v_pk_fma_f32 v[246:247], v[18:19], v[114:115], v[246:247]
	v_pk_fma_f32 v[254:255], v[20:21], v[116:117], v[254:255]
	v_pk_fma_f32 v[160:161], v[22:23], v[118:119], v[160:161]
	v_pk_fma_f32 v[246:247], v[24:25], v[120:121], v[246:247]
	v_pk_fma_f32 v[254:255], v[26:27], v[122:123], v[254:255]
	v_pk_fma_f32 v[160:161], v[28:29], v[124:125], v[160:161]
	v_pk_fma_f32 v[246:247], v[30:31], v[126:127], v[246:247]
	v_pk_add_f32 v[254:255], v[254:255], v[160:161]
	s_nop 0
	v_pk_add_f32 v[246:247], v[246:247], v[254:255]
	s_nop 0
	v_add_f32_e32 v165, v246, v247
	v_add_f32_dpp v162, v162, v162 row_shr:1 row_mask:0xf bank_mask:0xf bound_ctrl:1
	v_add_f32_dpp v163, v163, v163 row_shr:1 row_mask:0xf bank_mask:0xf bound_ctrl:1
	v_add_f32_dpp v164, v164, v164 row_shr:1 row_mask:0xf bank_mask:0xf bound_ctrl:1
	v_add_f32_dpp v165, v165, v165 row_shr:1 row_mask:0xf bank_mask:0xf bound_ctrl:1
	v_add_f32_dpp v162, v162, v162 row_shr:2 row_mask:0xf bank_mask:0xf bound_ctrl:1
; __device__ void peer_gather_phase(const Params& P, int l, bool do_store) {
;     ...
;       for (int pr = 0; pr < 4; ++pr) {
;         v6u_t qv; qv[0] = u6[3 * pr].x; qv[1] = u6[3 * pr].y; qv[2] = u6[3 * pr + 1].x; qv[3] = u6[3 * pr + 1].y; qv[4] = u6[3 * pr + 2].x; qv[5] = u6[3 * pr + 2].y;
;         const v32f_t wv = __builtin_amdgcn_cvt_scalef32_pk32_f32_fp6(qv, 1.0f);
;         f32x2 a2 = f32x2{0.f, 0.f};
; #pragma unroll
;         for (int i = 0; i < 16; ++i) a2 += f32x2{wv[2 * i], wv[2 * i + 1]} * xu[i];
;     ...
;         hs += dpp_row_shr(hs, 1); hs += dpp_row_shr(hs, 2); hs += dpp_row_shr(hs, 4); hs += dpp_row_shr(hs, 8);
;         hs += __builtin_bit_cast(float, __builtin_amdgcn_update_dpp(0, __builtin_bit_cast(int, hs), 0x142, 0xa, 0xf, false));
;         const float da = __builtin_bit_cast(float, __builtin_amdgcn_readlane(__builtin_bit_cast(int, hs), 31));
;         const float db = __builtin_bit_cast(float, __builtin_amdgcn_readlane(__builtin_bit_cast(int, hs), 63));
;         dvec = (lane == kb + 2 * pr) ? da : dvec;
;         dvec = (lane == kb + 2 * pr + 1) ? db : dvec;
;       }
	v_add_f32_dpp v163, v163, v163 row_shr:2 row_mask:0xf bank_mask:0xf bound_ctrl:1
	v_add_f32_dpp v164, v164, v164 row_shr:2 row_mask:0xf bank_mask:0xf bound_ctrl:1
	v_add_f32_dpp v165, v165, v165 row_shr:2 row_mask:0xf bank_mask:0xf bound_ctrl:1
	v_add_f32_dpp v162, v162, v162 row_shr:4 row_mask:0xf bank_mask:0xf bound_ctrl:1
	v_add_f32_dpp v163, v163, v163 row_shr:4 row_mask:0xf bank_mask:0xf bound_ctrl:1
	v_add_f32_dpp v164, v164, v164 row_shr:4 row_mask:0xf bank_mask:0xf bound_ctrl:1
	v_add_f32_dpp v165, v165, v165 row_shr:4 row_mask:0xf bank_mask:0xf bound_ctrl:1
	v_add_f32_dpp v162, v162, v162 row_shr:8 row_mask:0xf bank_mask:0xf bound_ctrl:1
	v_add_f32_dpp v163, v163, v163 row_shr:8 row_mask:0xf bank_mask:0xf bound_ctrl:1
	v_add_f32_dpp v164, v164, v164 row_shr:8 row_mask:0xf bank_mask:0xf bound_ctrl:1
	v_add_f32_dpp v165, v165, v165 row_shr:8 row_mask:0xf bank_mask:0xf bound_ctrl:1
	v_add_f32_dpp v162, v162, v162 row_bcast:15 row_mask:0xa bank_mask:0xf
	v_add_f32_dpp v163, v163, v163 row_bcast:15 row_mask:0xa bank_mask:0xf
	v_add_f32_dpp v164, v164, v164 row_bcast:15 row_mask:0xa bank_mask:0xf
	v_add_f32_dpp v165, v165, v165 row_bcast:15 row_mask:0xa bank_mask:0xf
	s_mov_b64 s[98:99], exec
	s_mov_b32 exec_lo, 0x80000000
	s_mov_b32 exec_hi, 0x80000000
	ds_write_b32 v74, v162
	ds_write_b32 v74, v163 offset:8
	ds_write_b32 v74, v164 offset:16
	ds_write_b32 v74, v165 offset:24
	s_mov_b64 exec, s[98:99]
	s_waitcnt lgkmcnt(0)
	v_mad_u32_u24 v167, v76, s33, v195
	ds_read_b32 v77, v74 offset:360
	s_waitcnt vmcnt(48)
	v_cvt_scalef32_pk32_f32_fp6 v[0:31], v[196:201], 1.0
	global_load_dwordx2 v[200:201], v167, s[62:63] offset:16
	global_load_dwordx4 v[196:199], v167, s[62:63]
	v_pk_mul_f32 v[246:247], v[0:1], v[96:97]
	v_pk_mul_f32 v[254:255], v[2:3], v[98:99]
	v_pk_mul_f32 v[160:161], v[4:5], v[100:101]
	v_pk_fma_f32 v[246:247], v[6:7], v[102:103], v[246:247]
	v_pk_fma_f32 v[254:255], v[8:9], v[104:105], v[254:255]
	v_pk_fma_f32 v[160:161], v[10:11], v[106:107], v[160:161]
	v_pk_fma_f32 v[246:247], v[12:13], v[108:109], v[246:247]
	v_pk_fma_f32 v[254:255], v[14:15], v[110:111], v[254:255]
	v_pk_fma_f32 v[160:161], v[16:17], v[112:113], v[160:161]
	v_pk_fma_f32 v[246:247], v[18:19], v[114:115], v[246:247]
	v_pk_fma_f32 v[254:255], v[20:21], v[116:117], v[254:255]
	v_pk_fma_f32 v[160:161], v[22:23], v[118:119], v[160:161]
	v_pk_fma_f32 v[246:247], v[24:25], v[120:121], v[246:247]
	v_pk_fma_f32 v[254:255], v[26:27], v[122:123], v[254:255]
	v_pk_fma_f32 v[160:161], v[28:29], v[124:125], v[160:161]
	v_pk_fma_f32 v[246:247], v[30:31], v[126:127], v[246:247]
	v_pk_add_f32 v[254:255], v[254:255], v[160:161]
	s_nop 0
	v_pk_add_f32 v[246:247], v[246:247], v[254:255]
	s_nop 0
	v_add_f32_e32 v162, v246, v247
	s_waitcnt lgkmcnt(0)
	v_mad_u32_u24 v167, v77, s33, v195
	ds_read_b32 v76, v74 offset:368
	s_waitcnt vmcnt(48)
	v_cvt_scalef32_pk32_f32_fp6 v[0:31], v[228:233], 1.0
	global_load_dwordx2 v[232:233], v167, s[62:63] offset:16
	global_load_dwordx4 v[228:231], v167, s[62:63]
	v_pk_mul_f32 v[246:247], v[0:1], v[96:97]
	v_pk_mul_f32 v[254:255], v[2:3], v[98:99]
	v_pk_mul_f32 v[160:161], v[4:5], v[100:101]
	v_pk_fma_f32 v[246:247], v[6:7], v[102:103], v[246:247]
	v_pk_fma_f32 v[254:255], v[8:9], v[104:105], v[254:255]
	v_pk_fma_f32 v[160:161], v[10:11], v[106:107], v[160:161]
	v_pk_fma_f32 v[246:247], v[12:13], v[108:109], v[246:247]
	v_pk_fma_f32 v[254:255], v[14:15], v[110:111], v[254:255]
	v_pk_fma_f32 v[160:161], v[16:17], v[112:113], v[160:161]
	v_pk_fma_f32 v[246:247], v[18:19], v[114:115], v[246:247]
	v_pk_fma_f32 v[254:255], v[20:21], v[116:117], v[254:255]
	v_pk_fma_f32 v[160:161], v[22:23], v[118:119], v[160:161]
	v_pk_fma_f32 v[246:247], v[24:25], v[120:121], v[246:247]
	v_pk_fma_f32 v[254:255], v[26:27], v[122:123], v[254:255]
	v_pk_fma_f32 v[160:161], v[28:29], v[124:125], v[160:161]
	v_pk_fma_f32 v[246:247], v[30:31], v[126:127], v[246:247]
	v_pk_add_f32 v[254:255], v[254:255], v[160:161]
	s_nop 0
	v_pk_add_f32 v[246:247], v[246:247], v[254:255]
	s_nop 0
	v_add_f32_e32 v163, v246, v247
	s_waitcnt lgkmcnt(0)
	v_mad_u32_u24 v167, v76, s33, v195
	ds_read_b32 v77, v74 offset:376
	s_waitcnt vmcnt(48)
	v_cvt_scalef32_pk32_f32_fp6 v[0:31], v[234:239], 1.0
	global_load_dwordx2 v[238:239], v167, s[62:63] offset:16
	global_load_dwordx4 v[234:237], v167, s[62:63]
	v_pk_mul_f32 v[246:247], v[0:1], v[96:97]
	v_pk_mul_f32 v[254:255], v[2:3], v[98:99]
	v_pk_mul_f32 v[160:161], v[4:5], v[100:101]
	v_pk_fma_f32 v[246:247], v[6:7], v[102:103], v[246:247]
	v_pk_fma_f32 v[254:255], v[8:9], v[104:105], v[254:255]
	v_pk_fma_f32 v[160:161], v[10:11], v[106:107], v[160:161]
	v_pk_fma_f32 v[246:247], v[12:13], v[108:109], v[246:247]
	v_pk_fma_f32 v[254:255], v[14:15], v[110:111], v[254:255]
	v_pk_fma_f32 v[160:161], v[16:17], v[112:113], v[160:161]
	v_pk_fma_f32 v[246:247], v[18:19], v[114:115], v[246:247]
	v_pk_fma_f32 v[254:255], v[20:21], v[116:117], v[254:255]
	v_pk_fma_f32 v[160:161], v[22:23], v[118:119], v[160:161]
	v_pk_fma_f32 v[246:247], v[24:25], v[120:121], v[246:247]
	v_pk_fma_f32 v[254:255], v[26:27], v[122:123], v[254:255]
	v_pk_fma_f32 v[160:161], v[28:29], v[124:125], v[160:161]
	v_pk_fma_f32 v[246:247], v[30:31], v[126:127], v[246:247]
	v_pk_add_f32 v[254:255], v[254:255], v[160:161]
	s_nop 0
	v_pk_add_f32 v[246:247], v[246:247], v[254:255]
	s_nop 0
	v_add_f32_e32 v164, v246, v247
	s_waitcnt lgkmcnt(0)
	v_mad_u32_u24 v167, v77, s33, v195
	ds_read_b32 v76, v74 offset:384
	s_waitcnt vmcnt(48)
; __device__ void peer_gather_phase(const Params& P, int l, bool do_store) {
;     ...
;         const int ea = __builtin_amdgcn_readlane(evs, kb + 2 * pr), eb = __builtin_amdgcn_readlane(evs, kb + 2 * pr + 1);
;         const uint2* up = (const uint2*)(U + (size_t)(uphi ? eb : ea) * 768);
;         u6[3 * pr] = up[0]; u6[3 * pr + 1] = up[1]; u6[3 * pr + 2] = up[2];
;     ...
;       for (int pr = 0; pr < 4; ++pr) {
;         v6u_t qv; qv[0] = u6[3 * pr].x; qv[1] = u6[3 * pr].y; qv[2] = u6[3 * pr + 1].x; qv[3] = u6[3 * pr + 1].y; qv[4] = u6[3 * pr + 2].x; qv[5] = u6[3 * pr + 2].y;
;         const v32f_t wv = __builtin_amdgcn_cvt_scalef32_pk32_f32_fp6(qv, 1.0f);
;         f32x2 a2 = f32x2{0.f, 0.f};
; #pragma unroll
;         for (int i = 0; i < 16; ++i) a2 += f32x2{wv[2 * i], wv[2 * i + 1]} * xu[i];
;         float hs = a2.x + a2.y;
;         hs += dpp_row_shr(hs, 1); hs += dpp_row_shr(hs, 2); hs += dpp_row_shr(hs, 4); hs += dpp_row_shr(hs, 8);
;         hs += __builtin_bit_cast(float, __builtin_amdgcn_update_dpp(0, __builtin_bit_cast(int, hs), 0x142, 0xa, 0xf, false));
;         const float da = __builtin_bit_cast(float, __builtin_amdgcn_readlane(__builtin_bit_cast(int, hs), 31));
;         const float db = __builtin_bit_cast(float, __builtin_amdgcn_readlane(__builtin_bit_cast(int, hs), 63));
;         dvec = (lane == kb + 2 * pr) ? da : dvec;
;         dvec = (lane == kb + 2 * pr + 1) ? db : dvec;
;       }
	v_cvt_scalef32_pk32_f32_fp6 v[0:31], v[240:245], 1.0
	global_load_dwordx2 v[244:245], v167, s[62:63] offset:16
	global_load_dwordx4 v[240:243], v167, s[62:63]
	v_pk_mul_f32 v[246:247], v[0:1], v[96:97]
	v_pk_mul_f32 v[254:255], v[2:3], v[98:99]
	v_pk_mul_f32 v[160:161], v[4:5], v[100:101]
	v_pk_fma_f32 v[246:247], v[6:7], v[102:103], v[246:247]
	v_pk_fma_f32 v[254:255], v[8:9], v[104:105], v[254:255]
	v_pk_fma_f32 v[160:161], v[10:11], v[106:107], v[160:161]
	v_pk_fma_f32 v[246:247], v[12:13], v[108:109], v[246:247]
	v_pk_fma_f32 v[254:255], v[14:15], v[110:111], v[254:255]
	v_pk_fma_f32 v[160:161], v[16:17], v[112:113], v[160:161]
	v_pk_fma_f32 v[246:247], v[18:19], v[114:115], v[246:247]
	v_pk_fma_f32 v[254:255], v[20:21], v[116:117], v[254:255]
	v_pk_fma_f32 v[160:161], v[22:23], v[118:119], v[160:161]
	v_pk_fma_f32 v[246:247], v[24:25], v[120:121], v[246:247]
	v_pk_fma_f32 v[254:255], v[26:27], v[122:123], v[254:255]
	v_pk_fma_f32 v[160:161], v[28:29], v[124:125], v[160:161]
	v_pk_fma_f32 v[246:247], v[30:31], v[126:127], v[246:247]
	v_pk_add_f32 v[254:255], v[254:255], v[160:161]
	s_nop 0
	v_pk_add_f32 v[246:247], v[246:247], v[254:255]
	s_nop 0
	v_add_f32_e32 v165, v246, v247
	v_add_f32_dpp v162, v162, v162 row_shr:1 row_mask:0xf bank_mask:0xf bound_ctrl:1
	v_add_f32_dpp v163, v163, v163 row_shr:1 row_mask:0xf bank_mask:0xf bound_ctrl:1
	v_add_f32_dpp v164, v164, v164 row_shr:1 row_mask:0xf bank_mask:0xf bound_ctrl:1
	v_add_f32_dpp v165, v165, v165 row_shr:1 row_mask:0xf bank_mask:0xf bound_ctrl:1
	v_add_f32_dpp v162, v162, v162 row_shr:2 row_mask:0xf bank_mask:0xf bound_ctrl:1
	v_add_f32_dpp v163, v163, v163 row_shr:2 row_mask:0xf bank_mask:0xf bound_ctrl:1
	v_add_f32_dpp v164, v164, v164 row_shr:2 row_mask:0xf bank_mask:0xf bound_ctrl:1
	v_add_f32_dpp v165, v165, v165 row_shr:2 row_mask:0xf bank_mask:0xf bound_ctrl:1
	v_add_f32_dpp v162, v162, v162 row_shr:4 row_mask:0xf bank_mask:0xf bound_ctrl:1
	v_add_f32_dpp v163, v163, v163 row_shr:4 row_mask:0xf bank_mask:0xf bound_ctrl:1
	v_add_f32_dpp v164, v164, v164 row_shr:4 row_mask:0xf bank_mask:0xf bound_ctrl:1
	v_add_f32_dpp v165, v165, v165 row_shr:4 row_mask:0xf bank_mask:0xf bound_ctrl:1
	v_add_f32_dpp v162, v162, v162 row_shr:8 row_mask:0xf bank_mask:0xf bound_ctrl:1
	v_add_f32_dpp v163, v163, v163 row_shr:8 row_mask:0xf bank_mask:0xf bound_ctrl:1
	v_add_f32_dpp v164, v164, v164 row_shr:8 row_mask:0xf bank_mask:0xf bound_ctrl:1
	v_add_f32_dpp v165, v165, v165 row_shr:8 row_mask:0xf bank_mask:0xf bound_ctrl:1
	v_add_f32_dpp v162, v162, v162 row_bcast:15 row_mask:0xa bank_mask:0xf
	v_add_f32_dpp v163, v163, v163 row_bcast:15 row_mask:0xa bank_mask:0xf
	v_add_f32_dpp v164, v164, v164 row_bcast:15 row_mask:0xa bank_mask:0xf
	v_add_f32_dpp v165, v165, v165 row_bcast:15 row_mask:0xa bank_mask:0xf
	s_mov_b64 s[98:99], exec
	s_mov_b32 exec_lo, 0x80000000
	s_mov_b32 exec_hi, 0x80000000
	ds_write_b32 v74, v162 offset:32
	ds_write_b32 v74, v163 offset:40
	ds_write_b32 v74, v164 offset:48
	ds_write_b32 v74, v165 offset:56
	s_mov_b64 exec, s[98:99]
	s_waitcnt lgkmcnt(0)
	v_mad_u32_u24 v167, v76, s33, v195
	ds_read_b32 v77, v74 offset:392
	s_waitcnt vmcnt(14)
	v_cvt_scalef32_pk32_f32_fp6 v[0:31], v[50:55], 1.0
	global_load_dwordx2 v[54:55], v167, s[62:63] offset:16
	global_load_dwordx4 v[50:53], v167, s[62:63]
	v_pk_mul_f32 v[246:247], v[0:1], v[96:97]
	v_pk_mul_f32 v[254:255], v[2:3], v[98:99]
	v_pk_mul_f32 v[160:161], v[4:5], v[100:101]
	v_pk_fma_f32 v[246:247], v[6:7], v[102:103], v[246:247]
	v_pk_fma_f32 v[254:255], v[8:9], v[104:105], v[254:255]
	v_pk_fma_f32 v[160:161], v[10:11], v[106:107], v[160:161]
	v_pk_fma_f32 v[246:247], v[12:13], v[108:109], v[246:247]
	v_pk_fma_f32 v[254:255], v[14:15], v[110:111], v[254:255]
	v_pk_fma_f32 v[160:161], v[16:17], v[112:113], v[160:161]
	v_pk_fma_f32 v[246:247], v[18:19], v[114:115], v[246:247]
	v_pk_fma_f32 v[254:255], v[20:21], v[116:117], v[254:255]
	v_pk_fma_f32 v[160:161], v[22:23], v[118:119], v[160:161]
	v_pk_fma_f32 v[246:247], v[24:25], v[120:121], v[246:247]
	v_pk_fma_f32 v[254:255], v[26:27], v[122:123], v[254:255]
	v_pk_fma_f32 v[160:161], v[28:29], v[124:125], v[160:161]
	v_pk_fma_f32 v[246:247], v[30:31], v[126:127], v[246:247]
	v_pk_add_f32 v[254:255], v[254:255], v[160:161]
	s_nop 0
	v_pk_add_f32 v[246:247], v[246:247], v[254:255]
	s_nop 0
	v_add_f32_e32 v162, v246, v247
	s_waitcnt lgkmcnt(0)
	v_mad_u32_u24 v167, v77, s33, v195
	ds_read_b32 v76, v74 offset:400
	s_waitcnt vmcnt(14)
	v_cvt_scalef32_pk32_f32_fp6 v[0:31], v[44:49], 1.0
	global_load_dwordx2 v[48:49], v167, s[62:63] offset:16
	global_load_dwordx4 v[44:47], v167, s[62:63]
	v_pk_mul_f32 v[246:247], v[0:1], v[96:97]
	v_pk_mul_f32 v[254:255], v[2:3], v[98:99]
	v_pk_mul_f32 v[160:161], v[4:5], v[100:101]
	v_pk_fma_f32 v[246:247], v[6:7], v[102:103], v[246:247]
	v_pk_fma_f32 v[254:255], v[8:9], v[104:105], v[254:255]
	v_pk_fma_f32 v[160:161], v[10:11], v[106:107], v[160:161]
	v_pk_fma_f32 v[246:247], v[12:13], v[108:109], v[246:247]
	v_pk_fma_f32 v[254:255], v[14:15], v[110:111], v[254:255]
	v_pk_fma_f32 v[160:161], v[16:17], v[112:113], v[160:161]
	v_pk_fma_f32 v[246:247], v[18:19], v[114:115], v[246:247]
	v_pk_fma_f32 v[254:255], v[20:21], v[116:117], v[254:255]
	v_pk_fma_f32 v[160:161], v[22:23], v[118:119], v[160:161]
	v_pk_fma_f32 v[246:247], v[24:25], v[120:121], v[246:247]
	v_pk_fma_f32 v[254:255], v[26:27], v[122:123], v[254:255]
	v_pk_fma_f32 v[160:161], v[28:29], v[124:125], v[160:161]
	v_pk_fma_f32 v[246:247], v[30:31], v[126:127], v[246:247]
	v_pk_add_f32 v[254:255], v[254:255], v[160:161]
	s_nop 0
	v_pk_add_f32 v[246:247], v[246:247], v[254:255]
	s_nop 0
	v_add_f32_e32 v163, v246, v247
	s_waitcnt lgkmcnt(0)
; __device__ void peer_gather_phase(const Params& P, int l, bool do_store) {
;     ...
;         const int ea = __builtin_amdgcn_readlane(evs, kb + 2 * pr), eb = __builtin_amdgcn_readlane(evs, kb + 2 * pr + 1);
;         const uint2* up = (const uint2*)(U + (size_t)(uphi ? eb : ea) * 768);
;         u6[3 * pr] = up[0]; u6[3 * pr + 1] = up[1]; u6[3 * pr + 2] = up[2];
;     ...
;       for (int pr = 0; pr < 4; ++pr) {
;         v6u_t qv; qv[0] = u6[3 * pr].x; qv[1] = u6[3 * pr].y; qv[2] = u6[3 * pr + 1].x; qv[3] = u6[3 * pr + 1].y; qv[4] = u6[3 * pr + 2].x; qv[5] = u6[3 * pr + 2].y;
;         const v32f_t wv = __builtin_amdgcn_cvt_scalef32_pk32_f32_fp6(qv, 1.0f);
;         f32x2 a2 = f32x2{0.f, 0.f};
; #pragma unroll
;         for (int i = 0; i < 16; ++i) a2 += f32x2{wv[2 * i], wv[2 * i + 1]} * xu[i];
;         float hs = a2.x + a2.y;
;         hs += dpp_row_shr(hs, 1); hs += dpp_row_shr(hs, 2); hs += dpp_row_shr(hs, 4); hs += dpp_row_shr(hs, 8);
;         hs += __builtin_bit_cast(float, __builtin_amdgcn_update_dpp(0, __builtin_bit_cast(int, hs), 0x142, 0xa, 0xf, false));
;         const float da = __builtin_bit_cast(float, __builtin_amdgcn_readlane(__builtin_bit_cast(int, hs), 31));
;         const float db = __builtin_bit_cast(float, __builtin_amdgcn_readlane(__builtin_bit_cast(int, hs), 63));
;         dvec = (lane == kb + 2 * pr) ? da : dvec;
;         dvec = (lane == kb + 2 * pr + 1) ? db : dvec;
;       }
	v_mad_u32_u24 v167, v76, s33, v195
	ds_read_b32 v77, v74 offset:408
	s_waitcnt vmcnt(14)
	v_cvt_scalef32_pk32_f32_fp6 v[0:31], v[38:43], 1.0
	global_load_dwordx2 v[42:43], v167, s[62:63] offset:16
	global_load_dwordx4 v[38:41], v167, s[62:63]
	v_pk_mul_f32 v[246:247], v[0:1], v[96:97]
	v_pk_mul_f32 v[254:255], v[2:3], v[98:99]
	v_pk_mul_f32 v[160:161], v[4:5], v[100:101]
	v_pk_fma_f32 v[246:247], v[6:7], v[102:103], v[246:247]
	v_pk_fma_f32 v[254:255], v[8:9], v[104:105], v[254:255]
	v_pk_fma_f32 v[160:161], v[10:11], v[106:107], v[160:161]
	v_pk_fma_f32 v[246:247], v[12:13], v[108:109], v[246:247]
	v_pk_fma_f32 v[254:255], v[14:15], v[110:111], v[254:255]
	v_pk_fma_f32 v[160:161], v[16:17], v[112:113], v[160:161]
	v_pk_fma_f32 v[246:247], v[18:19], v[114:115], v[246:247]
	v_pk_fma_f32 v[254:255], v[20:21], v[116:117], v[254:255]
	v_pk_fma_f32 v[160:161], v[22:23], v[118:119], v[160:161]
	v_pk_fma_f32 v[246:247], v[24:25], v[120:121], v[246:247]
	v_pk_fma_f32 v[254:255], v[26:27], v[122:123], v[254:255]
	v_pk_fma_f32 v[160:161], v[28:29], v[124:125], v[160:161]
	v_pk_fma_f32 v[246:247], v[30:31], v[126:127], v[246:247]
	v_pk_add_f32 v[254:255], v[254:255], v[160:161]
	s_nop 0
	v_pk_add_f32 v[246:247], v[246:247], v[254:255]
	s_nop 0
	v_add_f32_e32 v164, v246, v247
	s_waitcnt lgkmcnt(0)
	v_mad_u32_u24 v167, v77, s33, v195
	ds_read_b32 v76, v74 offset:416
	s_waitcnt vmcnt(14)
	v_cvt_scalef32_pk32_f32_fp6 v[0:31], v[32:37], 1.0
	global_load_dwordx2 v[36:37], v167, s[62:63] offset:16
	global_load_dwordx4 v[32:35], v167, s[62:63]
	v_pk_mul_f32 v[246:247], v[0:1], v[96:97]
	v_pk_mul_f32 v[254:255], v[2:3], v[98:99]
	v_pk_mul_f32 v[160:161], v[4:5], v[100:101]
	v_pk_fma_f32 v[246:247], v[6:7], v[102:103], v[246:247]
	v_pk_fma_f32 v[254:255], v[8:9], v[104:105], v[254:255]
	v_pk_fma_f32 v[160:161], v[10:11], v[106:107], v[160:161]
	v_pk_fma_f32 v[246:247], v[12:13], v[108:109], v[246:247]
	v_pk_fma_f32 v[254:255], v[14:15], v[110:111], v[254:255]
	v_pk_fma_f32 v[160:161], v[16:17], v[112:113], v[160:161]
	v_pk_fma_f32 v[246:247], v[18:19], v[114:115], v[246:247]
	v_pk_fma_f32 v[254:255], v[20:21], v[116:117], v[254:255]
	v_pk_fma_f32 v[160:161], v[22:23], v[118:119], v[160:161]
	v_pk_fma_f32 v[246:247], v[24:25], v[120:121], v[246:247]
	v_pk_fma_f32 v[254:255], v[26:27], v[122:123], v[254:255]
	v_pk_fma_f32 v[160:161], v[28:29], v[124:125], v[160:161]
	v_pk_fma_f32 v[246:247], v[30:31], v[126:127], v[246:247]
	v_pk_add_f32 v[254:255], v[254:255], v[160:161]
	s_nop 0
	v_pk_add_f32 v[246:247], v[246:247], v[254:255]
	s_nop 0
	v_add_f32_e32 v165, v246, v247
	v_add_f32_dpp v162, v162, v162 row_shr:1 row_mask:0xf bank_mask:0xf bound_ctrl:1
	v_add_f32_dpp v163, v163, v163 row_shr:1 row_mask:0xf bank_mask:0xf bound_ctrl:1
	v_add_f32_dpp v164, v164, v164 row_shr:1 row_mask:0xf bank_mask:0xf bound_ctrl:1
	v_add_f32_dpp v165, v165, v165 row_shr:1 row_mask:0xf bank_mask:0xf bound_ctrl:1
	v_add_f32_dpp v162, v162, v162 row_shr:2 row_mask:0xf bank_mask:0xf bound_ctrl:1
	v_add_f32_dpp v163, v163, v163 row_shr:2 row_mask:0xf bank_mask:0xf bound_ctrl:1
	v_add_f32_dpp v164, v164, v164 row_shr:2 row_mask:0xf bank_mask:0xf bound_ctrl:1
	v_add_f32_dpp v165, v165, v165 row_shr:2 row_mask:0xf bank_mask:0xf bound_ctrl:1
	v_add_f32_dpp v162, v162, v162 row_shr:4 row_mask:0xf bank_mask:0xf bound_ctrl:1
	v_add_f32_dpp v163, v163, v163 row_shr:4 row_mask:0xf bank_mask:0xf bound_ctrl:1
	v_add_f32_dpp v164, v164, v164 row_shr:4 row_mask:0xf bank_mask:0xf bound_ctrl:1
	v_add_f32_dpp v165, v165, v165 row_shr:4 row_mask:0xf bank_mask:0xf bound_ctrl:1
	v_add_f32_dpp v162, v162, v162 row_shr:8 row_mask:0xf bank_mask:0xf bound_ctrl:1
	v_add_f32_dpp v163, v163, v163 row_shr:8 row_mask:0xf bank_mask:0xf bound_ctrl:1
	v_add_f32_dpp v164, v164, v164 row_shr:8 row_mask:0xf bank_mask:0xf bound_ctrl:1
	v_add_f32_dpp v165, v165, v165 row_shr:8 row_mask:0xf bank_mask:0xf bound_ctrl:1
	v_add_f32_dpp v162, v162, v162 row_bcast:15 row_mask:0xa bank_mask:0xf
	v_add_f32_dpp v163, v163, v163 row_bcast:15 row_mask:0xa bank_mask:0xf
	v_add_f32_dpp v164, v164, v164 row_bcast:15 row_mask:0xa bank_mask:0xf
	v_add_f32_dpp v165, v165, v165 row_bcast:15 row_mask:0xa bank_mask:0xf
	s_mov_b64 s[98:99], exec
	s_mov_b32 exec_lo, 0x80000000
	s_mov_b32 exec_hi, 0x80000000
	ds_write_b32 v74, v162 offset:64
	ds_write_b32 v74, v163 offset:72
	ds_write_b32 v74, v164 offset:80
	ds_write_b32 v74, v165 offset:88
	s_mov_b64 exec, s[98:99]
	s_waitcnt lgkmcnt(0)
	v_mad_u32_u24 v167, v76, s33, v195
	ds_read_b32 v77, v74 offset:424
	s_waitcnt vmcnt(14)
	v_cvt_scalef32_pk32_f32_fp6 v[0:31], v[196:201], 1.0
	global_load_dwordx2 v[200:201], v167, s[62:63] offset:16
	global_load_dwordx4 v[196:199], v167, s[62:63]
	v_pk_mul_f32 v[246:247], v[0:1], v[96:97]
	v_pk_mul_f32 v[254:255], v[2:3], v[98:99]
	v_pk_mul_f32 v[160:161], v[4:5], v[100:101]
	v_pk_fma_f32 v[246:247], v[6:7], v[102:103], v[246:247]
	v_pk_fma_f32 v[254:255], v[8:9], v[104:105], v[254:255]
	v_pk_fma_f32 v[160:161], v[10:11], v[106:107], v[160:161]
	v_pk_fma_f32 v[246:247], v[12:13], v[108:109], v[246:247]
	v_pk_fma_f32 v[254:255], v[14:15], v[110:111], v[254:255]
	v_pk_fma_f32 v[160:161], v[16:17], v[112:113], v[160:161]
	v_pk_fma_f32 v[246:247], v[18:19], v[114:115], v[246:247]
	v_pk_fma_f32 v[254:255], v[20:21], v[116:117], v[254:255]
	v_pk_fma_f32 v[160:161], v[22:23], v[118:119], v[160:161]
	v_pk_fma_f32 v[246:247], v[24:25], v[120:121], v[246:247]
	v_pk_fma_f32 v[254:255], v[26:27], v[122:123], v[254:255]
	v_pk_fma_f32 v[160:161], v[28:29], v[124:125], v[160:161]
	v_pk_fma_f32 v[246:247], v[30:31], v[126:127], v[246:247]
	v_pk_add_f32 v[254:255], v[254:255], v[160:161]
	s_nop 0
	v_pk_add_f32 v[246:247], v[246:247], v[254:255]
	s_nop 0
	v_add_f32_e32 v162, v246, v247
	s_waitcnt lgkmcnt(0)
; __device__ void peer_gather_phase(const Params& P, int l, bool do_store) {
;     ...
;         const int ea = __builtin_amdgcn_readlane(evs, kb + 2 * pr), eb = __builtin_amdgcn_readlane(evs, kb + 2 * pr + 1);
;         const uint2* up = (const uint2*)(U + (size_t)(uphi ? eb : ea) * 768);
;         u6[3 * pr] = up[0]; u6[3 * pr + 1] = up[1]; u6[3 * pr + 2] = up[2];
;     ...
;       for (int pr = 0; pr < 4; ++pr) {
;         v6u_t qv; qv[0] = u6[3 * pr].x; qv[1] = u6[3 * pr].y; qv[2] = u6[3 * pr + 1].x; qv[3] = u6[3 * pr + 1].y; qv[4] = u6[3 * pr + 2].x; qv[5] = u6[3 * pr + 2].y;
;         const v32f_t wv = __builtin_amdgcn_cvt_scalef32_pk32_f32_fp6(qv, 1.0f);
;         f32x2 a2 = f32x2{0.f, 0.f};
; #pragma unroll
;         for (int i = 0; i < 16; ++i) a2 += f32x2{wv[2 * i], wv[2 * i + 1]} * xu[i];
;         float hs = a2.x + a2.y;
;         hs += dpp_row_shr(hs, 1); hs += dpp_row_shr(hs, 2); hs += dpp_row_shr(hs, 4); hs += dpp_row_shr(hs, 8);
;         hs += __builtin_bit_cast(float, __builtin_amdgcn_update_dpp(0, __builtin_bit_cast(int, hs), 0x142, 0xa, 0xf, false));
;         const float da = __builtin_bit_cast(float, __builtin_amdgcn_readlane(__builtin_bit_cast(int, hs), 31));
;         const float db = __builtin_bit_cast(float, __builtin_amdgcn_readlane(__builtin_bit_cast(int, hs), 63));
;         dvec = (lane == kb + 2 * pr) ? da : dvec;
;         dvec = (lane == kb + 2 * pr + 1) ? db : dvec;
;       }
	v_mad_u32_u24 v167, v77, s33, v195
	ds_read_b32 v76, v74 offset:432
	s_waitcnt vmcnt(14)
	v_cvt_scalef32_pk32_f32_fp6 v[0:31], v[228:233], 1.0
	global_load_dwordx2 v[232:233], v167, s[62:63] offset:16
	global_load_dwordx4 v[228:231], v167, s[62:63]
	v_pk_mul_f32 v[246:247], v[0:1], v[96:97]
	v_pk_mul_f32 v[254:255], v[2:3], v[98:99]
	v_pk_mul_f32 v[160:161], v[4:5], v[100:101]
	v_pk_fma_f32 v[246:247], v[6:7], v[102:103], v[246:247]
	v_pk_fma_f32 v[254:255], v[8:9], v[104:105], v[254:255]
	v_pk_fma_f32 v[160:161], v[10:11], v[106:107], v[160:161]
	v_pk_fma_f32 v[246:247], v[12:13], v[108:109], v[246:247]
	v_pk_fma_f32 v[254:255], v[14:15], v[110:111], v[254:255]
	v_pk_fma_f32 v[160:161], v[16:17], v[112:113], v[160:161]
	v_pk_fma_f32 v[246:247], v[18:19], v[114:115], v[246:247]
	v_pk_fma_f32 v[254:255], v[20:21], v[116:117], v[254:255]
	v_pk_fma_f32 v[160:161], v[22:23], v[118:119], v[160:161]
	v_pk_fma_f32 v[246:247], v[24:25], v[120:121], v[246:247]
	v_pk_fma_f32 v[254:255], v[26:27], v[122:123], v[254:255]
	v_pk_fma_f32 v[160:161], v[28:29], v[124:125], v[160:161]
	v_pk_fma_f32 v[246:247], v[30:31], v[126:127], v[246:247]
	v_pk_add_f32 v[254:255], v[254:255], v[160:161]
	s_nop 0
	v_pk_add_f32 v[246:247], v[246:247], v[254:255]
	s_nop 0
	v_add_f32_e32 v163, v246, v247
	s_waitcnt lgkmcnt(0)
	v_mad_u32_u24 v167, v76, s33, v195
	ds_read_b32 v77, v74 offset:440
	s_waitcnt vmcnt(14)
	v_cvt_scalef32_pk32_f32_fp6 v[0:31], v[234:239], 1.0
	global_load_dwordx2 v[238:239], v167, s[62:63] offset:16
	global_load_dwordx4 v[234:237], v167, s[62:63]
	v_pk_mul_f32 v[246:247], v[0:1], v[96:97]
	v_pk_mul_f32 v[254:255], v[2:3], v[98:99]
	v_pk_mul_f32 v[160:161], v[4:5], v[100:101]
	v_pk_fma_f32 v[246:247], v[6:7], v[102:103], v[246:247]
	v_pk_fma_f32 v[254:255], v[8:9], v[104:105], v[254:255]
	v_pk_fma_f32 v[160:161], v[10:11], v[106:107], v[160:161]
	v_pk_fma_f32 v[246:247], v[12:13], v[108:109], v[246:247]
	v_pk_fma_f32 v[254:255], v[14:15], v[110:111], v[254:255]
	v_pk_fma_f32 v[160:161], v[16:17], v[112:113], v[160:161]
	v_pk_fma_f32 v[246:247], v[18:19], v[114:115], v[246:247]
	v_pk_fma_f32 v[254:255], v[20:21], v[116:117], v[254:255]
	v_pk_fma_f32 v[160:161], v[22:23], v[118:119], v[160:161]
	v_pk_fma_f32 v[246:247], v[24:25], v[120:121], v[246:247]
	v_pk_fma_f32 v[254:255], v[26:27], v[122:123], v[254:255]
	v_pk_fma_f32 v[160:161], v[28:29], v[124:125], v[160:161]
	v_pk_fma_f32 v[246:247], v[30:31], v[126:127], v[246:247]
	v_pk_add_f32 v[254:255], v[254:255], v[160:161]
	s_nop 0
	v_pk_add_f32 v[246:247], v[246:247], v[254:255]
	s_nop 0
	v_add_f32_e32 v164, v246, v247
	s_waitcnt lgkmcnt(0)
	v_mad_u32_u24 v167, v77, s33, v195
	ds_read_b32 v76, v74 offset:448
	s_waitcnt vmcnt(14)
	v_cvt_scalef32_pk32_f32_fp6 v[0:31], v[240:245], 1.0
	global_load_dwordx2 v[244:245], v167, s[62:63] offset:16
	global_load_dwordx4 v[240:243], v167, s[62:63]
	v_pk_mul_f32 v[246:247], v[0:1], v[96:97]
	v_pk_mul_f32 v[254:255], v[2:3], v[98:99]
	v_pk_mul_f32 v[160:161], v[4:5], v[100:101]
	v_pk_fma_f32 v[246:247], v[6:7], v[102:103], v[246:247]
	v_pk_fma_f32 v[254:255], v[8:9], v[104:105], v[254:255]
	v_pk_fma_f32 v[160:161], v[10:11], v[106:107], v[160:161]
	v_pk_fma_f32 v[246:247], v[12:13], v[108:109], v[246:247]
	v_pk_fma_f32 v[254:255], v[14:15], v[110:111], v[254:255]
	v_pk_fma_f32 v[160:161], v[16:17], v[112:113], v[160:161]
	v_pk_fma_f32 v[246:247], v[18:19], v[114:115], v[246:247]
	v_pk_fma_f32 v[254:255], v[20:21], v[116:117], v[254:255]
	v_pk_fma_f32 v[160:161], v[22:23], v[118:119], v[160:161]
	v_pk_fma_f32 v[246:247], v[24:25], v[120:121], v[246:247]
	v_pk_fma_f32 v[254:255], v[26:27], v[122:123], v[254:255]
	v_pk_fma_f32 v[160:161], v[28:29], v[124:125], v[160:161]
	v_pk_fma_f32 v[246:247], v[30:31], v[126:127], v[246:247]
	v_pk_add_f32 v[254:255], v[254:255], v[160:161]
	s_nop 0
	v_pk_add_f32 v[246:247], v[246:247], v[254:255]
	s_nop 0
	v_add_f32_e32 v165, v246, v247
	v_add_f32_dpp v162, v162, v162 row_shr:1 row_mask:0xf bank_mask:0xf bound_ctrl:1
	v_add_f32_dpp v163, v163, v163 row_shr:1 row_mask:0xf bank_mask:0xf bound_ctrl:1
	v_add_f32_dpp v164, v164, v164 row_shr:1 row_mask:0xf bank_mask:0xf bound_ctrl:1
	v_add_f32_dpp v165, v165, v165 row_shr:1 row_mask:0xf bank_mask:0xf bound_ctrl:1
	v_add_f32_dpp v162, v162, v162 row_shr:2 row_mask:0xf bank_mask:0xf bound_ctrl:1
	v_add_f32_dpp v163, v163, v163 row_shr:2 row_mask:0xf bank_mask:0xf bound_ctrl:1
	v_add_f32_dpp v164, v164, v164 row_shr:2 row_mask:0xf bank_mask:0xf bound_ctrl:1
	v_add_f32_dpp v165, v165, v165 row_shr:2 row_mask:0xf bank_mask:0xf bound_ctrl:1
	v_add_f32_dpp v162, v162, v162 row_shr:4 row_mask:0xf bank_mask:0xf bound_ctrl:1
	v_add_f32_dpp v163, v163, v163 row_shr:4 row_mask:0xf bank_mask:0xf bound_ctrl:1
	v_add_f32_dpp v164, v164, v164 row_shr:4 row_mask:0xf bank_mask:0xf bound_ctrl:1
	v_add_f32_dpp v165, v165, v165 row_shr:4 row_mask:0xf bank_mask:0xf bound_ctrl:1
	v_add_f32_dpp v162, v162, v162 row_shr:8 row_mask:0xf bank_mask:0xf bound_ctrl:1
	v_add_f32_dpp v163, v163, v163 row_shr:8 row_mask:0xf bank_mask:0xf bound_ctrl:1
	v_add_f32_dpp v164, v164, v164 row_shr:8 row_mask:0xf bank_mask:0xf bound_ctrl:1
	v_add_f32_dpp v165, v165, v165 row_shr:8 row_mask:0xf bank_mask:0xf bound_ctrl:1
	v_add_f32_dpp v162, v162, v162 row_bcast:15 row_mask:0xa bank_mask:0xf
	v_add_f32_dpp v163, v163, v163 row_bcast:15 row_mask:0xa bank_mask:0xf
	v_add_f32_dpp v164, v164, v164 row_bcast:15 row_mask:0xa bank_mask:0xf
	v_add_f32_dpp v165, v165, v165 row_bcast:15 row_mask:0xa bank_mask:0xf
	s_mov_b64 s[98:99], exec
	s_mov_b32 exec_lo, 0x80000000
	s_mov_b32 exec_hi, 0x80000000
	ds_write_b32 v74, v162 offset:96
	ds_write_b32 v74, v163 offset:104
	ds_write_b32 v74, v164 offset:112
	ds_write_b32 v74, v165 offset:120
	s_mov_b64 exec, s[98:99]
	s_waitcnt lgkmcnt(0)
; __device__ void peer_gather_phase(const Params& P, int l, bool do_store) {
;     ...
;         const int ea = __builtin_amdgcn_readlane(evs, kb + 2 * pr), eb = __builtin_amdgcn_readlane(evs, kb + 2 * pr + 1);
;         const uint2* up = (const uint2*)(U + (size_t)(uphi ? eb : ea) * 768);
;         u6[3 * pr] = up[0]; u6[3 * pr + 1] = up[1]; u6[3 * pr + 2] = up[2];
;     ...
;       for (int pr = 0; pr < 4; ++pr) {
;         v6u_t qv; qv[0] = u6[3 * pr].x; qv[1] = u6[3 * pr].y; qv[2] = u6[3 * pr + 1].x; qv[3] = u6[3 * pr + 1].y; qv[4] = u6[3 * pr + 2].x; qv[5] = u6[3 * pr + 2].y;
;         const v32f_t wv = __builtin_amdgcn_cvt_scalef32_pk32_f32_fp6(qv, 1.0f);
;         f32x2 a2 = f32x2{0.f, 0.f};
; #pragma unroll
;         for (int i = 0; i < 16; ++i) a2 += f32x2{wv[2 * i], wv[2 * i + 1]} * xu[i];
;         float hs = a2.x + a2.y;
;         hs += dpp_row_shr(hs, 1); hs += dpp_row_shr(hs, 2); hs += dpp_row_shr(hs, 4); hs += dpp_row_shr(hs, 8);
;         hs += __builtin_bit_cast(float, __builtin_amdgcn_update_dpp(0, __builtin_bit_cast(int, hs), 0x142, 0xa, 0xf, false));
;         const float da = __builtin_bit_cast(float, __builtin_amdgcn_readlane(__builtin_bit_cast(int, hs), 31));
;         const float db = __builtin_bit_cast(float, __builtin_amdgcn_readlane(__builtin_bit_cast(int, hs), 63));
;         dvec = (lane == kb + 2 * pr) ? da : dvec;
;         dvec = (lane == kb + 2 * pr + 1) ? db : dvec;
;       }
	v_mad_u32_u24 v167, v76, s33, v195
	ds_read_b32 v77, v74 offset:456
	s_waitcnt vmcnt(14)
	v_cvt_scalef32_pk32_f32_fp6 v[0:31], v[50:55], 1.0
	global_load_dwordx2 v[54:55], v167, s[62:63] offset:16
	global_load_dwordx4 v[50:53], v167, s[62:63]
	v_pk_mul_f32 v[246:247], v[0:1], v[96:97]
	v_pk_mul_f32 v[254:255], v[2:3], v[98:99]
	v_pk_mul_f32 v[160:161], v[4:5], v[100:101]
	v_pk_fma_f32 v[246:247], v[6:7], v[102:103], v[246:247]
	v_pk_fma_f32 v[254:255], v[8:9], v[104:105], v[254:255]
	v_pk_fma_f32 v[160:161], v[10:11], v[106:107], v[160:161]
	v_pk_fma_f32 v[246:247], v[12:13], v[108:109], v[246:247]
	v_pk_fma_f32 v[254:255], v[14:15], v[110:111], v[254:255]
	v_pk_fma_f32 v[160:161], v[16:17], v[112:113], v[160:161]
	v_pk_fma_f32 v[246:247], v[18:19], v[114:115], v[246:247]
	v_pk_fma_f32 v[254:255], v[20:21], v[116:117], v[254:255]
	v_pk_fma_f32 v[160:161], v[22:23], v[118:119], v[160:161]
	v_pk_fma_f32 v[246:247], v[24:25], v[120:121], v[246:247]
	v_pk_fma_f32 v[254:255], v[26:27], v[122:123], v[254:255]
	v_pk_fma_f32 v[160:161], v[28:29], v[124:125], v[160:161]
	v_pk_fma_f32 v[246:247], v[30:31], v[126:127], v[246:247]
	v_pk_add_f32 v[254:255], v[254:255], v[160:161]
	s_nop 0
	v_pk_add_f32 v[246:247], v[246:247], v[254:255]
	s_nop 0
	v_add_f32_e32 v162, v246, v247
	s_waitcnt lgkmcnt(0)
	v_mad_u32_u24 v167, v77, s33, v195
	ds_read_b32 v76, v74 offset:464
	s_waitcnt vmcnt(14)
	v_cvt_scalef32_pk32_f32_fp6 v[0:31], v[44:49], 1.0
	global_load_dwordx2 v[48:49], v167, s[62:63] offset:16
	global_load_dwordx4 v[44:47], v167, s[62:63]
	v_pk_mul_f32 v[246:247], v[0:1], v[96:97]
	v_pk_mul_f32 v[254:255], v[2:3], v[98:99]
	v_pk_mul_f32 v[160:161], v[4:5], v[100:101]
	v_pk_fma_f32 v[246:247], v[6:7], v[102:103], v[246:247]
	v_pk_fma_f32 v[254:255], v[8:9], v[104:105], v[254:255]
	v_pk_fma_f32 v[160:161], v[10:11], v[106:107], v[160:161]
	v_pk_fma_f32 v[246:247], v[12:13], v[108:109], v[246:247]
	v_pk_fma_f32 v[254:255], v[14:15], v[110:111], v[254:255]
	v_pk_fma_f32 v[160:161], v[16:17], v[112:113], v[160:161]
	v_pk_fma_f32 v[246:247], v[18:19], v[114:115], v[246:247]
	v_pk_fma_f32 v[254:255], v[20:21], v[116:117], v[254:255]
	v_pk_fma_f32 v[160:161], v[22:23], v[118:119], v[160:161]
	v_pk_fma_f32 v[246:247], v[24:25], v[120:121], v[246:247]
	v_pk_fma_f32 v[254:255], v[26:27], v[122:123], v[254:255]
	v_pk_fma_f32 v[160:161], v[28:29], v[124:125], v[160:161]
	v_pk_fma_f32 v[246:247], v[30:31], v[126:127], v[246:247]
	v_pk_add_f32 v[254:255], v[254:255], v[160:161]
	s_nop 0
	v_pk_add_f32 v[246:247], v[246:247], v[254:255]
	s_nop 0
	v_add_f32_e32 v163, v246, v247
	s_waitcnt lgkmcnt(0)
	v_mad_u32_u24 v167, v76, s33, v195
	ds_read_b32 v77, v74 offset:472
	s_waitcnt vmcnt(14)
	v_cvt_scalef32_pk32_f32_fp6 v[0:31], v[38:43], 1.0
	global_load_dwordx2 v[42:43], v167, s[62:63] offset:16
	global_load_dwordx4 v[38:41], v167, s[62:63]
	v_pk_mul_f32 v[246:247], v[0:1], v[96:97]
	v_pk_mul_f32 v[254:255], v[2:3], v[98:99]
	v_pk_mul_f32 v[160:161], v[4:5], v[100:101]
	v_pk_fma_f32 v[246:247], v[6:7], v[102:103], v[246:247]
	v_pk_fma_f32 v[254:255], v[8:9], v[104:105], v[254:255]
	v_pk_fma_f32 v[160:161], v[10:11], v[106:107], v[160:161]
	v_pk_fma_f32 v[246:247], v[12:13], v[108:109], v[246:247]
	v_pk_fma_f32 v[254:255], v[14:15], v[110:111], v[254:255]
	v_pk_fma_f32 v[160:161], v[16:17], v[112:113], v[160:161]
	v_pk_fma_f32 v[246:247], v[18:19], v[114:115], v[246:247]
	v_pk_fma_f32 v[254:255], v[20:21], v[116:117], v[254:255]
	v_pk_fma_f32 v[160:161], v[22:23], v[118:119], v[160:161]
	v_pk_fma_f32 v[246:247], v[24:25], v[120:121], v[246:247]
	v_pk_fma_f32 v[254:255], v[26:27], v[122:123], v[254:255]
	v_pk_fma_f32 v[160:161], v[28:29], v[124:125], v[160:161]
	v_pk_fma_f32 v[246:247], v[30:31], v[126:127], v[246:247]
	v_pk_add_f32 v[254:255], v[254:255], v[160:161]
	s_nop 0
	v_pk_add_f32 v[246:247], v[246:247], v[254:255]
	s_nop 0
	v_add_f32_e32 v164, v246, v247
	s_waitcnt lgkmcnt(0)
	v_mad_u32_u24 v167, v77, s33, v195
	ds_read_b32 v76, v74 offset:480
	s_waitcnt vmcnt(14)
	v_cvt_scalef32_pk32_f32_fp6 v[0:31], v[32:37], 1.0
	global_load_dwordx2 v[36:37], v167, s[62:63] offset:16
	global_load_dwordx4 v[32:35], v167, s[62:63]
	v_pk_mul_f32 v[246:247], v[0:1], v[96:97]
	v_pk_mul_f32 v[254:255], v[2:3], v[98:99]
	v_pk_mul_f32 v[160:161], v[4:5], v[100:101]
	v_pk_fma_f32 v[246:247], v[6:7], v[102:103], v[246:247]
	v_pk_fma_f32 v[254:255], v[8:9], v[104:105], v[254:255]
	v_pk_fma_f32 v[160:161], v[10:11], v[106:107], v[160:161]
	v_pk_fma_f32 v[246:247], v[12:13], v[108:109], v[246:247]
	v_pk_fma_f32 v[254:255], v[14:15], v[110:111], v[254:255]
	v_pk_fma_f32 v[160:161], v[16:17], v[112:113], v[160:161]
	v_pk_fma_f32 v[246:247], v[18:19], v[114:115], v[246:247]
	v_pk_fma_f32 v[254:255], v[20:21], v[116:117], v[254:255]
	v_pk_fma_f32 v[160:161], v[22:23], v[118:119], v[160:161]
	v_pk_fma_f32 v[246:247], v[24:25], v[120:121], v[246:247]
	v_pk_fma_f32 v[254:255], v[26:27], v[122:123], v[254:255]
	v_pk_fma_f32 v[160:161], v[28:29], v[124:125], v[160:161]
	v_pk_fma_f32 v[246:247], v[30:31], v[126:127], v[246:247]
	v_pk_add_f32 v[254:255], v[254:255], v[160:161]
	s_nop 0
	v_pk_add_f32 v[246:247], v[246:247], v[254:255]
	s_nop 0
	v_add_f32_e32 v165, v246, v247
	v_add_f32_dpp v162, v162, v162 row_shr:1 row_mask:0xf bank_mask:0xf bound_ctrl:1
	v_add_f32_dpp v163, v163, v163 row_shr:1 row_mask:0xf bank_mask:0xf bound_ctrl:1
	v_add_f32_dpp v164, v164, v164 row_shr:1 row_mask:0xf bank_mask:0xf bound_ctrl:1
	v_add_f32_dpp v165, v165, v165 row_shr:1 row_mask:0xf bank_mask:0xf bound_ctrl:1
	v_add_f32_dpp v162, v162, v162 row_shr:2 row_mask:0xf bank_mask:0xf bound_ctrl:1
; __device__ void peer_gather_phase(const Params& P, int l, bool do_store) {
;     ...
;         const int ea = __builtin_amdgcn_readlane(evs, kb + 2 * pr), eb = __builtin_amdgcn_readlane(evs, kb + 2 * pr + 1);
;         const uint2* up = (const uint2*)(U + (size_t)(uphi ? eb : ea) * 768);
;         u6[3 * pr] = up[0]; u6[3 * pr + 1] = up[1]; u6[3 * pr + 2] = up[2];
;     ...
;       for (int pr = 0; pr < 4; ++pr) {
;         v6u_t qv; qv[0] = u6[3 * pr].x; qv[1] = u6[3 * pr].y; qv[2] = u6[3 * pr + 1].x; qv[3] = u6[3 * pr + 1].y; qv[4] = u6[3 * pr + 2].x; qv[5] = u6[3 * pr + 2].y;
;         const v32f_t wv = __builtin_amdgcn_cvt_scalef32_pk32_f32_fp6(qv, 1.0f);
;         f32x2 a2 = f32x2{0.f, 0.f};
; #pragma unroll
;         for (int i = 0; i < 16; ++i) a2 += f32x2{wv[2 * i], wv[2 * i + 1]} * xu[i];
;         float hs = a2.x + a2.y;
;         hs += dpp_row_shr(hs, 1); hs += dpp_row_shr(hs, 2); hs += dpp_row_shr(hs, 4); hs += dpp_row_shr(hs, 8);
;         hs += __builtin_bit_cast(float, __builtin_amdgcn_update_dpp(0, __builtin_bit_cast(int, hs), 0x142, 0xa, 0xf, false));
;         const float da = __builtin_bit_cast(float, __builtin_amdgcn_readlane(__builtin_bit_cast(int, hs), 31));
;         const float db = __builtin_bit_cast(float, __builtin_amdgcn_readlane(__builtin_bit_cast(int, hs), 63));
;         dvec = (lane == kb + 2 * pr) ? da : dvec;
;         dvec = (lane == kb + 2 * pr + 1) ? db : dvec;
;       }
	v_add_f32_dpp v163, v163, v163 row_shr:2 row_mask:0xf bank_mask:0xf bound_ctrl:1
	v_add_f32_dpp v164, v164, v164 row_shr:2 row_mask:0xf bank_mask:0xf bound_ctrl:1
	v_add_f32_dpp v165, v165, v165 row_shr:2 row_mask:0xf bank_mask:0xf bound_ctrl:1
	v_add_f32_dpp v162, v162, v162 row_shr:4 row_mask:0xf bank_mask:0xf bound_ctrl:1
	v_add_f32_dpp v163, v163, v163 row_shr:4 row_mask:0xf bank_mask:0xf bound_ctrl:1
	v_add_f32_dpp v164, v164, v164 row_shr:4 row_mask:0xf bank_mask:0xf bound_ctrl:1
	v_add_f32_dpp v165, v165, v165 row_shr:4 row_mask:0xf bank_mask:0xf bound_ctrl:1
	v_add_f32_dpp v162, v162, v162 row_shr:8 row_mask:0xf bank_mask:0xf bound_ctrl:1
	v_add_f32_dpp v163, v163, v163 row_shr:8 row_mask:0xf bank_mask:0xf bound_ctrl:1
	v_add_f32_dpp v164, v164, v164 row_shr:8 row_mask:0xf bank_mask:0xf bound_ctrl:1
	v_add_f32_dpp v165, v165, v165 row_shr:8 row_mask:0xf bank_mask:0xf bound_ctrl:1
	v_add_f32_dpp v162, v162, v162 row_bcast:15 row_mask:0xa bank_mask:0xf
	v_add_f32_dpp v163, v163, v163 row_bcast:15 row_mask:0xa bank_mask:0xf
	v_add_f32_dpp v164, v164, v164 row_bcast:15 row_mask:0xa bank_mask:0xf
	v_add_f32_dpp v165, v165, v165 row_bcast:15 row_mask:0xa bank_mask:0xf
	s_mov_b64 s[98:99], exec
	s_mov_b32 exec_lo, 0x80000000
	s_mov_b32 exec_hi, 0x80000000
	ds_write_b32 v74, v162 offset:128
	ds_write_b32 v74, v163 offset:136
	ds_write_b32 v74, v164 offset:144
	ds_write_b32 v74, v165 offset:152
	s_mov_b64 exec, s[98:99]
	s_waitcnt lgkmcnt(0)
	v_mad_u32_u24 v167, v76, s33, v195
	ds_read_b32 v77, v74 offset:488
	s_waitcnt vmcnt(14)
	v_cvt_scalef32_pk32_f32_fp6 v[0:31], v[196:201], 1.0
	global_load_dwordx2 v[200:201], v167, s[62:63] offset:16
	global_load_dwordx4 v[196:199], v167, s[62:63]
	v_pk_mul_f32 v[246:247], v[0:1], v[96:97]
	v_pk_mul_f32 v[254:255], v[2:3], v[98:99]
	v_pk_mul_f32 v[160:161], v[4:5], v[100:101]
	v_pk_fma_f32 v[246:247], v[6:7], v[102:103], v[246:247]
	v_pk_fma_f32 v[254:255], v[8:9], v[104:105], v[254:255]
	v_pk_fma_f32 v[160:161], v[10:11], v[106:107], v[160:161]
	v_pk_fma_f32 v[246:247], v[12:13], v[108:109], v[246:247]
	v_pk_fma_f32 v[254:255], v[14:15], v[110:111], v[254:255]
	v_pk_fma_f32 v[160:161], v[16:17], v[112:113], v[160:161]
	v_pk_fma_f32 v[246:247], v[18:19], v[114:115], v[246:247]
	v_pk_fma_f32 v[254:255], v[20:21], v[116:117], v[254:255]
	v_pk_fma_f32 v[160:161], v[22:23], v[118:119], v[160:161]
	v_pk_fma_f32 v[246:247], v[24:25], v[120:121], v[246:247]
	v_pk_fma_f32 v[254:255], v[26:27], v[122:123], v[254:255]
	v_pk_fma_f32 v[160:161], v[28:29], v[124:125], v[160:161]
	v_pk_fma_f32 v[246:247], v[30:31], v[126:127], v[246:247]
	v_pk_add_f32 v[254:255], v[254:255], v[160:161]
	s_nop 0
	v_pk_add_f32 v[246:247], v[246:247], v[254:255]
	s_nop 0
	v_add_f32_e32 v162, v246, v247
	s_waitcnt lgkmcnt(0)
	v_mad_u32_u24 v167, v77, s33, v195
	ds_read_b32 v76, v74 offset:496
	s_waitcnt vmcnt(14)
	v_cvt_scalef32_pk32_f32_fp6 v[0:31], v[228:233], 1.0
	global_load_dwordx2 v[232:233], v167, s[62:63] offset:16
	global_load_dwordx4 v[228:231], v167, s[62:63]
	v_pk_mul_f32 v[246:247], v[0:1], v[96:97]
	v_pk_mul_f32 v[254:255], v[2:3], v[98:99]
	v_pk_mul_f32 v[160:161], v[4:5], v[100:101]
	v_pk_fma_f32 v[246:247], v[6:7], v[102:103], v[246:247]
	v_pk_fma_f32 v[254:255], v[8:9], v[104:105], v[254:255]
	v_pk_fma_f32 v[160:161], v[10:11], v[106:107], v[160:161]
	v_pk_fma_f32 v[246:247], v[12:13], v[108:109], v[246:247]
	v_pk_fma_f32 v[254:255], v[14:15], v[110:111], v[254:255]
	v_pk_fma_f32 v[160:161], v[16:17], v[112:113], v[160:161]
	v_pk_fma_f32 v[246:247], v[18:19], v[114:115], v[246:247]
	v_pk_fma_f32 v[254:255], v[20:21], v[116:117], v[254:255]
	v_pk_fma_f32 v[160:161], v[22:23], v[118:119], v[160:161]
	v_pk_fma_f32 v[246:247], v[24:25], v[120:121], v[246:247]
	v_pk_fma_f32 v[254:255], v[26:27], v[122:123], v[254:255]
	v_pk_fma_f32 v[160:161], v[28:29], v[124:125], v[160:161]
	v_pk_fma_f32 v[246:247], v[30:31], v[126:127], v[246:247]
	v_pk_add_f32 v[254:255], v[254:255], v[160:161]
	s_nop 0
	v_pk_add_f32 v[246:247], v[246:247], v[254:255]
	s_nop 0
	v_add_f32_e32 v163, v246, v247
	s_waitcnt lgkmcnt(0)
	v_mad_u32_u24 v167, v76, s33, v195
	ds_read_b32 v77, v74 offset:504
	s_waitcnt vmcnt(14)
	v_cvt_scalef32_pk32_f32_fp6 v[0:31], v[234:239], 1.0
	global_load_dwordx2 v[238:239], v167, s[62:63] offset:16
	global_load_dwordx4 v[234:237], v167, s[62:63]
	v_pk_mul_f32 v[246:247], v[0:1], v[96:97]
	v_pk_mul_f32 v[254:255], v[2:3], v[98:99]
	v_pk_mul_f32 v[160:161], v[4:5], v[100:101]
	v_pk_fma_f32 v[246:247], v[6:7], v[102:103], v[246:247]
	v_pk_fma_f32 v[254:255], v[8:9], v[104:105], v[254:255]
	v_pk_fma_f32 v[160:161], v[10:11], v[106:107], v[160:161]
	v_pk_fma_f32 v[246:247], v[12:13], v[108:109], v[246:247]
	v_pk_fma_f32 v[254:255], v[14:15], v[110:111], v[254:255]
	v_pk_fma_f32 v[160:161], v[16:17], v[112:113], v[160:161]
	v_pk_fma_f32 v[246:247], v[18:19], v[114:115], v[246:247]
	v_pk_fma_f32 v[254:255], v[20:21], v[116:117], v[254:255]
	v_pk_fma_f32 v[160:161], v[22:23], v[118:119], v[160:161]
	v_pk_fma_f32 v[246:247], v[24:25], v[120:121], v[246:247]
	v_pk_fma_f32 v[254:255], v[26:27], v[122:123], v[254:255]
	v_pk_fma_f32 v[160:161], v[28:29], v[124:125], v[160:161]
	v_pk_fma_f32 v[246:247], v[30:31], v[126:127], v[246:247]
	v_pk_add_f32 v[254:255], v[254:255], v[160:161]
	s_nop 0
	v_pk_add_f32 v[246:247], v[246:247], v[254:255]
	s_nop 0
	v_add_f32_e32 v164, v246, v247
	s_waitcnt lgkmcnt(0)
	v_mad_u32_u24 v167, v77, s33, v195
	s_waitcnt vmcnt(14)
; __device__ void peer_gather_phase(const Params& P, int l, bool do_store) {
;     ...
;         v6u_t qv; qv[0] = u6[3 * pr].x; qv[1] = u6[3 * pr].y; qv[2] = u6[3 * pr + 1].x; qv[3] = u6[3 * pr + 1].y; qv[4] = u6[3 * pr + 2].x; qv[5] = u6[3 * pr + 2].y;
;         const v32f_t wv = __builtin_amdgcn_cvt_scalef32_pk32_f32_fp6(qv, 1.0f);
;         f32x2 a2 = f32x2{0.f, 0.f};
; #pragma unroll
;         for (int i = 0; i < 16; ++i) a2 += f32x2{wv[2 * i], wv[2 * i + 1]} * xu[i];
;         float hs = a2.x + a2.y;
;         hs += dpp_row_shr(hs, 1); hs += dpp_row_shr(hs, 2); hs += dpp_row_shr(hs, 4); hs += dpp_row_shr(hs, 8);
;         hs += __builtin_bit_cast(float, __builtin_amdgcn_update_dpp(0, __builtin_bit_cast(int, hs), 0x142, 0xa, 0xf, false));
;         const float da = __builtin_bit_cast(float, __builtin_amdgcn_readlane(__builtin_bit_cast(int, hs), 31));
;         const float db = __builtin_bit_cast(float, __builtin_amdgcn_readlane(__builtin_bit_cast(int, hs), 63));
;         dvec = (lane == kb + 2 * pr) ? da : dvec;
;         dvec = (lane == kb + 2 * pr + 1) ? db : dvec;
;       }
	v_cvt_scalef32_pk32_f32_fp6 v[0:31], v[240:245], 1.0
	global_load_dwordx2 v[244:245], v167, s[62:63] offset:16
	global_load_dwordx4 v[240:243], v167, s[62:63]
	v_pk_mul_f32 v[246:247], v[0:1], v[96:97]
	v_pk_mul_f32 v[254:255], v[2:3], v[98:99]
	v_pk_mul_f32 v[160:161], v[4:5], v[100:101]
	v_pk_fma_f32 v[246:247], v[6:7], v[102:103], v[246:247]
	v_pk_fma_f32 v[254:255], v[8:9], v[104:105], v[254:255]
	v_pk_fma_f32 v[160:161], v[10:11], v[106:107], v[160:161]
	v_pk_fma_f32 v[246:247], v[12:13], v[108:109], v[246:247]
	v_pk_fma_f32 v[254:255], v[14:15], v[110:111], v[254:255]
	v_pk_fma_f32 v[160:161], v[16:17], v[112:113], v[160:161]
	v_pk_fma_f32 v[246:247], v[18:19], v[114:115], v[246:247]
	v_pk_fma_f32 v[254:255], v[20:21], v[116:117], v[254:255]
	v_pk_fma_f32 v[160:161], v[22:23], v[118:119], v[160:161]
	v_pk_fma_f32 v[246:247], v[24:25], v[120:121], v[246:247]
	v_pk_fma_f32 v[254:255], v[26:27], v[122:123], v[254:255]
	v_pk_fma_f32 v[160:161], v[28:29], v[124:125], v[160:161]
	v_pk_fma_f32 v[246:247], v[30:31], v[126:127], v[246:247]
	v_pk_add_f32 v[254:255], v[254:255], v[160:161]
	s_nop 0
	v_pk_add_f32 v[246:247], v[246:247], v[254:255]
	s_nop 0
	v_add_f32_e32 v165, v246, v247
	v_add_f32_dpp v162, v162, v162 row_shr:1 row_mask:0xf bank_mask:0xf bound_ctrl:1
	v_add_f32_dpp v163, v163, v163 row_shr:1 row_mask:0xf bank_mask:0xf bound_ctrl:1
	v_add_f32_dpp v164, v164, v164 row_shr:1 row_mask:0xf bank_mask:0xf bound_ctrl:1
	v_add_f32_dpp v165, v165, v165 row_shr:1 row_mask:0xf bank_mask:0xf bound_ctrl:1
	v_add_f32_dpp v162, v162, v162 row_shr:2 row_mask:0xf bank_mask:0xf bound_ctrl:1
	v_add_f32_dpp v163, v163, v163 row_shr:2 row_mask:0xf bank_mask:0xf bound_ctrl:1
	v_add_f32_dpp v164, v164, v164 row_shr:2 row_mask:0xf bank_mask:0xf bound_ctrl:1
	v_add_f32_dpp v165, v165, v165 row_shr:2 row_mask:0xf bank_mask:0xf bound_ctrl:1
	v_add_f32_dpp v162, v162, v162 row_shr:4 row_mask:0xf bank_mask:0xf bound_ctrl:1
	v_add_f32_dpp v163, v163, v163 row_shr:4 row_mask:0xf bank_mask:0xf bound_ctrl:1
	v_add_f32_dpp v164, v164, v164 row_shr:4 row_mask:0xf bank_mask:0xf bound_ctrl:1
	v_add_f32_dpp v165, v165, v165 row_shr:4 row_mask:0xf bank_mask:0xf bound_ctrl:1
	v_add_f32_dpp v162, v162, v162 row_shr:8 row_mask:0xf bank_mask:0xf bound_ctrl:1
	v_add_f32_dpp v163, v163, v163 row_shr:8 row_mask:0xf bank_mask:0xf bound_ctrl:1
	v_add_f32_dpp v164, v164, v164 row_shr:8 row_mask:0xf bank_mask:0xf bound_ctrl:1
	v_add_f32_dpp v165, v165, v165 row_shr:8 row_mask:0xf bank_mask:0xf bound_ctrl:1
	v_add_f32_dpp v162, v162, v162 row_bcast:15 row_mask:0xa bank_mask:0xf
	v_add_f32_dpp v163, v163, v163 row_bcast:15 row_mask:0xa bank_mask:0xf
	v_add_f32_dpp v164, v164, v164 row_bcast:15 row_mask:0xa bank_mask:0xf
	v_add_f32_dpp v165, v165, v165 row_bcast:15 row_mask:0xa bank_mask:0xf
	s_mov_b64 s[98:99], exec
	s_mov_b32 exec_lo, 0x80000000
	s_mov_b32 exec_hi, 0x80000000
	ds_write_b32 v74, v162 offset:160
	ds_write_b32 v74, v163 offset:168
	ds_write_b32 v74, v164 offset:176
	ds_write_b32 v74, v165 offset:184
	s_mov_b64 exec, s[98:99]
	s_waitcnt vmcnt(14)
	v_cvt_scalef32_pk32_f32_fp6 v[0:31], v[50:55], 1.0
	v_pk_mul_f32 v[246:247], v[0:1], v[96:97]
	v_pk_mul_f32 v[254:255], v[2:3], v[98:99]
	v_pk_mul_f32 v[160:161], v[4:5], v[100:101]
	v_pk_fma_f32 v[246:247], v[6:7], v[102:103], v[246:247]
	v_pk_fma_f32 v[254:255], v[8:9], v[104:105], v[254:255]
	v_pk_fma_f32 v[160:161], v[10:11], v[106:107], v[160:161]
	v_pk_fma_f32 v[246:247], v[12:13], v[108:109], v[246:247]
	v_pk_fma_f32 v[254:255], v[14:15], v[110:111], v[254:255]
	v_pk_fma_f32 v[160:161], v[16:17], v[112:113], v[160:161]
	v_pk_fma_f32 v[246:247], v[18:19], v[114:115], v[246:247]
	v_pk_fma_f32 v[254:255], v[20:21], v[116:117], v[254:255]
	v_pk_fma_f32 v[160:161], v[22:23], v[118:119], v[160:161]
	v_pk_fma_f32 v[246:247], v[24:25], v[120:121], v[246:247]
	v_pk_fma_f32 v[254:255], v[26:27], v[122:123], v[254:255]
	v_pk_fma_f32 v[160:161], v[28:29], v[124:125], v[160:161]
	v_pk_fma_f32 v[246:247], v[30:31], v[126:127], v[246:247]
	v_pk_add_f32 v[254:255], v[254:255], v[160:161]
	s_nop 0
	v_pk_add_f32 v[246:247], v[246:247], v[254:255]
	s_nop 0
	v_add_f32_e32 v162, v246, v247
	s_waitcnt vmcnt(12)
	v_cvt_scalef32_pk32_f32_fp6 v[0:31], v[44:49], 1.0
	v_pk_mul_f32 v[246:247], v[0:1], v[96:97]
	v_pk_mul_f32 v[254:255], v[2:3], v[98:99]
	v_pk_mul_f32 v[160:161], v[4:5], v[100:101]
	v_pk_fma_f32 v[246:247], v[6:7], v[102:103], v[246:247]
	v_pk_fma_f32 v[254:255], v[8:9], v[104:105], v[254:255]
	v_pk_fma_f32 v[160:161], v[10:11], v[106:107], v[160:161]
	v_pk_fma_f32 v[246:247], v[12:13], v[108:109], v[246:247]
	v_pk_fma_f32 v[254:255], v[14:15], v[110:111], v[254:255]
	v_pk_fma_f32 v[160:161], v[16:17], v[112:113], v[160:161]
	v_pk_fma_f32 v[246:247], v[18:19], v[114:115], v[246:247]
	v_pk_fma_f32 v[254:255], v[20:21], v[116:117], v[254:255]
	v_pk_fma_f32 v[160:161], v[22:23], v[118:119], v[160:161]
	v_pk_fma_f32 v[246:247], v[24:25], v[120:121], v[246:247]
	v_pk_fma_f32 v[254:255], v[26:27], v[122:123], v[254:255]
	v_pk_fma_f32 v[160:161], v[28:29], v[124:125], v[160:161]
	v_pk_fma_f32 v[246:247], v[30:31], v[126:127], v[246:247]
	v_pk_add_f32 v[254:255], v[254:255], v[160:161]
	s_nop 0
	v_pk_add_f32 v[246:247], v[246:247], v[254:255]
	s_nop 0
	v_add_f32_e32 v163, v246, v247
	s_waitcnt vmcnt(10)
; __device__ void peer_gather_phase(const Params& P, int l, bool do_store) {
;     ...
;         v6u_t qv; qv[0] = u6[3 * pr].x; qv[1] = u6[3 * pr].y; qv[2] = u6[3 * pr + 1].x; qv[3] = u6[3 * pr + 1].y; qv[4] = u6[3 * pr + 2].x; qv[5] = u6[3 * pr + 2].y;
;         const v32f_t wv = __builtin_amdgcn_cvt_scalef32_pk32_f32_fp6(qv, 1.0f);
;         f32x2 a2 = f32x2{0.f, 0.f};
; #pragma unroll
;         for (int i = 0; i < 16; ++i) a2 += f32x2{wv[2 * i], wv[2 * i + 1]} * xu[i];
;         float hs = a2.x + a2.y;
;         hs += dpp_row_shr(hs, 1); hs += dpp_row_shr(hs, 2); hs += dpp_row_shr(hs, 4); hs += dpp_row_shr(hs, 8);
;         hs += __builtin_bit_cast(float, __builtin_amdgcn_update_dpp(0, __builtin_bit_cast(int, hs), 0x142, 0xa, 0xf, false));
;         const float da = __builtin_bit_cast(float, __builtin_amdgcn_readlane(__builtin_bit_cast(int, hs), 31));
;         const float db = __builtin_bit_cast(float, __builtin_amdgcn_readlane(__builtin_bit_cast(int, hs), 63));
;         dvec = (lane == kb + 2 * pr) ? da : dvec;
;         dvec = (lane == kb + 2 * pr + 1) ? db : dvec;
;       }
	v_cvt_scalef32_pk32_f32_fp6 v[0:31], v[38:43], 1.0
	v_pk_mul_f32 v[246:247], v[0:1], v[96:97]
	v_pk_mul_f32 v[254:255], v[2:3], v[98:99]
	v_pk_mul_f32 v[160:161], v[4:5], v[100:101]
	v_pk_fma_f32 v[246:247], v[6:7], v[102:103], v[246:247]
	v_pk_fma_f32 v[254:255], v[8:9], v[104:105], v[254:255]
	v_pk_fma_f32 v[160:161], v[10:11], v[106:107], v[160:161]
	v_pk_fma_f32 v[246:247], v[12:13], v[108:109], v[246:247]
	v_pk_fma_f32 v[254:255], v[14:15], v[110:111], v[254:255]
	v_pk_fma_f32 v[160:161], v[16:17], v[112:113], v[160:161]
	v_pk_fma_f32 v[246:247], v[18:19], v[114:115], v[246:247]
	v_pk_fma_f32 v[254:255], v[20:21], v[116:117], v[254:255]
	v_pk_fma_f32 v[160:161], v[22:23], v[118:119], v[160:161]
	v_pk_fma_f32 v[246:247], v[24:25], v[120:121], v[246:247]
	v_pk_fma_f32 v[254:255], v[26:27], v[122:123], v[254:255]
	v_pk_fma_f32 v[160:161], v[28:29], v[124:125], v[160:161]
	v_pk_fma_f32 v[246:247], v[30:31], v[126:127], v[246:247]
	v_pk_add_f32 v[254:255], v[254:255], v[160:161]
	s_nop 0
	v_pk_add_f32 v[246:247], v[246:247], v[254:255]
	s_nop 0
	v_add_f32_e32 v164, v246, v247
	s_waitcnt vmcnt(8)
	v_cvt_scalef32_pk32_f32_fp6 v[0:31], v[32:37], 1.0
	v_pk_mul_f32 v[246:247], v[0:1], v[96:97]
	v_pk_mul_f32 v[254:255], v[2:3], v[98:99]
	v_pk_mul_f32 v[160:161], v[4:5], v[100:101]
	v_pk_fma_f32 v[246:247], v[6:7], v[102:103], v[246:247]
	v_pk_fma_f32 v[254:255], v[8:9], v[104:105], v[254:255]
	v_pk_fma_f32 v[160:161], v[10:11], v[106:107], v[160:161]
	v_pk_fma_f32 v[246:247], v[12:13], v[108:109], v[246:247]
	v_pk_fma_f32 v[254:255], v[14:15], v[110:111], v[254:255]
	v_pk_fma_f32 v[160:161], v[16:17], v[112:113], v[160:161]
	v_pk_fma_f32 v[246:247], v[18:19], v[114:115], v[246:247]
	v_pk_fma_f32 v[254:255], v[20:21], v[116:117], v[254:255]
	v_pk_fma_f32 v[160:161], v[22:23], v[118:119], v[160:161]
	v_pk_fma_f32 v[246:247], v[24:25], v[120:121], v[246:247]
	v_pk_fma_f32 v[254:255], v[26:27], v[122:123], v[254:255]
	v_pk_fma_f32 v[160:161], v[28:29], v[124:125], v[160:161]
	v_pk_fma_f32 v[246:247], v[30:31], v[126:127], v[246:247]
	v_pk_add_f32 v[254:255], v[254:255], v[160:161]
	s_nop 0
	v_pk_add_f32 v[246:247], v[246:247], v[254:255]
	s_nop 0
	v_add_f32_e32 v165, v246, v247
	v_add_f32_dpp v162, v162, v162 row_shr:1 row_mask:0xf bank_mask:0xf bound_ctrl:1
	v_add_f32_dpp v163, v163, v163 row_shr:1 row_mask:0xf bank_mask:0xf bound_ctrl:1
	v_add_f32_dpp v164, v164, v164 row_shr:1 row_mask:0xf bank_mask:0xf bound_ctrl:1
	v_add_f32_dpp v165, v165, v165 row_shr:1 row_mask:0xf bank_mask:0xf bound_ctrl:1
	v_add_f32_dpp v162, v162, v162 row_shr:2 row_mask:0xf bank_mask:0xf bound_ctrl:1
	v_add_f32_dpp v163, v163, v163 row_shr:2 row_mask:0xf bank_mask:0xf bound_ctrl:1
	v_add_f32_dpp v164, v164, v164 row_shr:2 row_mask:0xf bank_mask:0xf bound_ctrl:1
	v_add_f32_dpp v165, v165, v165 row_shr:2 row_mask:0xf bank_mask:0xf bound_ctrl:1
	v_add_f32_dpp v162, v162, v162 row_shr:4 row_mask:0xf bank_mask:0xf bound_ctrl:1
	v_add_f32_dpp v163, v163, v163 row_shr:4 row_mask:0xf bank_mask:0xf bound_ctrl:1
	v_add_f32_dpp v164, v164, v164 row_shr:4 row_mask:0xf bank_mask:0xf bound_ctrl:1
	v_add_f32_dpp v165, v165, v165 row_shr:4 row_mask:0xf bank_mask:0xf bound_ctrl:1
	v_add_f32_dpp v162, v162, v162 row_shr:8 row_mask:0xf bank_mask:0xf bound_ctrl:1
	v_add_f32_dpp v163, v163, v163 row_shr:8 row_mask:0xf bank_mask:0xf bound_ctrl:1
	v_add_f32_dpp v164, v164, v164 row_shr:8 row_mask:0xf bank_mask:0xf bound_ctrl:1
	v_add_f32_dpp v165, v165, v165 row_shr:8 row_mask:0xf bank_mask:0xf bound_ctrl:1
	v_add_f32_dpp v162, v162, v162 row_bcast:15 row_mask:0xa bank_mask:0xf
	v_add_f32_dpp v163, v163, v163 row_bcast:15 row_mask:0xa bank_mask:0xf
	v_add_f32_dpp v164, v164, v164 row_bcast:15 row_mask:0xa bank_mask:0xf
	v_add_f32_dpp v165, v165, v165 row_bcast:15 row_mask:0xa bank_mask:0xf
	s_mov_b64 s[98:99], exec
	s_mov_b32 exec_lo, 0x80000000
	s_mov_b32 exec_hi, 0x80000000
	ds_write_b32 v74, v162 offset:192
	ds_write_b32 v74, v163 offset:200
	ds_write_b32 v74, v164 offset:208
	ds_write_b32 v74, v165 offset:216
	s_mov_b64 exec, s[98:99]
	s_waitcnt vmcnt(6)
	v_cvt_scalef32_pk32_f32_fp6 v[0:31], v[196:201], 1.0
	v_pk_mul_f32 v[246:247], v[0:1], v[96:97]
	v_pk_mul_f32 v[254:255], v[2:3], v[98:99]
	v_pk_mul_f32 v[160:161], v[4:5], v[100:101]
	v_pk_fma_f32 v[246:247], v[6:7], v[102:103], v[246:247]
	v_pk_fma_f32 v[254:255], v[8:9], v[104:105], v[254:255]
	v_pk_fma_f32 v[160:161], v[10:11], v[106:107], v[160:161]
	v_pk_fma_f32 v[246:247], v[12:13], v[108:109], v[246:247]
	v_pk_fma_f32 v[254:255], v[14:15], v[110:111], v[254:255]
	v_pk_fma_f32 v[160:161], v[16:17], v[112:113], v[160:161]
	v_pk_fma_f32 v[246:247], v[18:19], v[114:115], v[246:247]
	v_pk_fma_f32 v[254:255], v[20:21], v[116:117], v[254:255]
	v_pk_fma_f32 v[160:161], v[22:23], v[118:119], v[160:161]
	v_pk_fma_f32 v[246:247], v[24:25], v[120:121], v[246:247]
	v_pk_fma_f32 v[254:255], v[26:27], v[122:123], v[254:255]
	v_pk_fma_f32 v[160:161], v[28:29], v[124:125], v[160:161]
	v_pk_fma_f32 v[246:247], v[30:31], v[126:127], v[246:247]
	v_pk_add_f32 v[254:255], v[254:255], v[160:161]
	s_nop 0
	v_pk_add_f32 v[246:247], v[246:247], v[254:255]
	s_nop 0
	v_add_f32_e32 v162, v246, v247
	s_waitcnt vmcnt(4)
; __device__ void peer_gather_phase(const Params& P, int l, bool do_store) {
;     ...
;         v6u_t qv; qv[0] = u6[3 * pr].x; qv[1] = u6[3 * pr].y; qv[2] = u6[3 * pr + 1].x; qv[3] = u6[3 * pr + 1].y; qv[4] = u6[3 * pr + 2].x; qv[5] = u6[3 * pr + 2].y;
;         const v32f_t wv = __builtin_amdgcn_cvt_scalef32_pk32_f32_fp6(qv, 1.0f);
;         f32x2 a2 = f32x2{0.f, 0.f};
; #pragma unroll
;         for (int i = 0; i < 16; ++i) a2 += f32x2{wv[2 * i], wv[2 * i + 1]} * xu[i];
;         float hs = a2.x + a2.y;
;         hs += dpp_row_shr(hs, 1); hs += dpp_row_shr(hs, 2); hs += dpp_row_shr(hs, 4); hs += dpp_row_shr(hs, 8);
;         hs += __builtin_bit_cast(float, __builtin_amdgcn_update_dpp(0, __builtin_bit_cast(int, hs), 0x142, 0xa, 0xf, false));
;         const float da = __builtin_bit_cast(float, __builtin_amdgcn_readlane(__builtin_bit_cast(int, hs), 31));
;         const float db = __builtin_bit_cast(float, __builtin_amdgcn_readlane(__builtin_bit_cast(int, hs), 63));
;         dvec = (lane == kb + 2 * pr) ? da : dvec;
;         dvec = (lane == kb + 2 * pr + 1) ? db : dvec;
;       }
;       const float sux = (bt < 8) ? sux0 : sux1;
;       const float gsx = (bt < 8) ? gsx0 : gsx1;
;       const float avec = gelu_t(dvec * sux) * gsx;
	v_cvt_scalef32_pk32_f32_fp6 v[0:31], v[228:233], 1.0
	v_pk_mul_f32 v[246:247], v[0:1], v[96:97]
	v_pk_mul_f32 v[254:255], v[2:3], v[98:99]
	v_pk_mul_f32 v[160:161], v[4:5], v[100:101]
	v_pk_fma_f32 v[246:247], v[6:7], v[102:103], v[246:247]
	v_pk_fma_f32 v[254:255], v[8:9], v[104:105], v[254:255]
	v_pk_fma_f32 v[160:161], v[10:11], v[106:107], v[160:161]
	v_pk_fma_f32 v[246:247], v[12:13], v[108:109], v[246:247]
	v_pk_fma_f32 v[254:255], v[14:15], v[110:111], v[254:255]
	v_pk_fma_f32 v[160:161], v[16:17], v[112:113], v[160:161]
	v_pk_fma_f32 v[246:247], v[18:19], v[114:115], v[246:247]
	v_pk_fma_f32 v[254:255], v[20:21], v[116:117], v[254:255]
	v_pk_fma_f32 v[160:161], v[22:23], v[118:119], v[160:161]
	v_pk_fma_f32 v[246:247], v[24:25], v[120:121], v[246:247]
	v_pk_fma_f32 v[254:255], v[26:27], v[122:123], v[254:255]
	v_pk_fma_f32 v[160:161], v[28:29], v[124:125], v[160:161]
	v_pk_fma_f32 v[246:247], v[30:31], v[126:127], v[246:247]
	v_pk_add_f32 v[254:255], v[254:255], v[160:161]
	s_nop 0
	v_pk_add_f32 v[246:247], v[246:247], v[254:255]
	s_nop 0
	v_add_f32_e32 v163, v246, v247
	s_waitcnt vmcnt(2)
	v_cvt_scalef32_pk32_f32_fp6 v[0:31], v[234:239], 1.0
	v_pk_mul_f32 v[246:247], v[0:1], v[96:97]
	v_pk_mul_f32 v[254:255], v[2:3], v[98:99]
	v_pk_mul_f32 v[160:161], v[4:5], v[100:101]
	v_pk_fma_f32 v[246:247], v[6:7], v[102:103], v[246:247]
	v_pk_fma_f32 v[254:255], v[8:9], v[104:105], v[254:255]
	v_pk_fma_f32 v[160:161], v[10:11], v[106:107], v[160:161]
	v_pk_fma_f32 v[246:247], v[12:13], v[108:109], v[246:247]
	v_pk_fma_f32 v[254:255], v[14:15], v[110:111], v[254:255]
	v_pk_fma_f32 v[160:161], v[16:17], v[112:113], v[160:161]
	v_pk_fma_f32 v[246:247], v[18:19], v[114:115], v[246:247]
	v_pk_fma_f32 v[254:255], v[20:21], v[116:117], v[254:255]
	v_pk_fma_f32 v[160:161], v[22:23], v[118:119], v[160:161]
	v_pk_fma_f32 v[246:247], v[24:25], v[120:121], v[246:247]
	v_pk_fma_f32 v[254:255], v[26:27], v[122:123], v[254:255]
	v_pk_fma_f32 v[160:161], v[28:29], v[124:125], v[160:161]
	v_pk_fma_f32 v[246:247], v[30:31], v[126:127], v[246:247]
	v_pk_add_f32 v[254:255], v[254:255], v[160:161]
	s_nop 0
	v_pk_add_f32 v[246:247], v[246:247], v[254:255]
	s_nop 0
	v_add_f32_e32 v164, v246, v247
	s_waitcnt vmcnt(0)
	v_cvt_scalef32_pk32_f32_fp6 v[0:31], v[240:245], 1.0
	v_pk_mul_f32 v[246:247], v[0:1], v[96:97]
	v_pk_mul_f32 v[254:255], v[2:3], v[98:99]
	v_pk_mul_f32 v[160:161], v[4:5], v[100:101]
	v_pk_fma_f32 v[246:247], v[6:7], v[102:103], v[246:247]
	v_pk_fma_f32 v[254:255], v[8:9], v[104:105], v[254:255]
	v_pk_fma_f32 v[160:161], v[10:11], v[106:107], v[160:161]
	v_pk_fma_f32 v[246:247], v[12:13], v[108:109], v[246:247]
	v_pk_fma_f32 v[254:255], v[14:15], v[110:111], v[254:255]
	v_pk_fma_f32 v[160:161], v[16:17], v[112:113], v[160:161]
	v_pk_fma_f32 v[246:247], v[18:19], v[114:115], v[246:247]
	v_pk_fma_f32 v[254:255], v[20:21], v[116:117], v[254:255]
	v_pk_fma_f32 v[160:161], v[22:23], v[118:119], v[160:161]
	v_pk_fma_f32 v[246:247], v[24:25], v[120:121], v[246:247]
	v_pk_fma_f32 v[254:255], v[26:27], v[122:123], v[254:255]
	v_pk_fma_f32 v[160:161], v[28:29], v[124:125], v[160:161]
	v_pk_fma_f32 v[246:247], v[30:31], v[126:127], v[246:247]
	v_pk_add_f32 v[254:255], v[254:255], v[160:161]
	s_nop 0
	v_pk_add_f32 v[246:247], v[246:247], v[254:255]
	s_nop 0
	v_add_f32_e32 v165, v246, v247
	v_add_f32_dpp v162, v162, v162 row_shr:1 row_mask:0xf bank_mask:0xf bound_ctrl:1
	v_add_f32_dpp v163, v163, v163 row_shr:1 row_mask:0xf bank_mask:0xf bound_ctrl:1
	v_add_f32_dpp v164, v164, v164 row_shr:1 row_mask:0xf bank_mask:0xf bound_ctrl:1
	v_add_f32_dpp v165, v165, v165 row_shr:1 row_mask:0xf bank_mask:0xf bound_ctrl:1
	v_add_f32_dpp v162, v162, v162 row_shr:2 row_mask:0xf bank_mask:0xf bound_ctrl:1
	v_add_f32_dpp v163, v163, v163 row_shr:2 row_mask:0xf bank_mask:0xf bound_ctrl:1
	v_add_f32_dpp v164, v164, v164 row_shr:2 row_mask:0xf bank_mask:0xf bound_ctrl:1
	v_add_f32_dpp v165, v165, v165 row_shr:2 row_mask:0xf bank_mask:0xf bound_ctrl:1
	v_add_f32_dpp v162, v162, v162 row_shr:4 row_mask:0xf bank_mask:0xf bound_ctrl:1
	v_add_f32_dpp v163, v163, v163 row_shr:4 row_mask:0xf bank_mask:0xf bound_ctrl:1
	v_add_f32_dpp v164, v164, v164 row_shr:4 row_mask:0xf bank_mask:0xf bound_ctrl:1
	v_add_f32_dpp v165, v165, v165 row_shr:4 row_mask:0xf bank_mask:0xf bound_ctrl:1
	v_add_f32_dpp v162, v162, v162 row_shr:8 row_mask:0xf bank_mask:0xf bound_ctrl:1
	v_add_f32_dpp v163, v163, v163 row_shr:8 row_mask:0xf bank_mask:0xf bound_ctrl:1
	v_add_f32_dpp v164, v164, v164 row_shr:8 row_mask:0xf bank_mask:0xf bound_ctrl:1
	v_add_f32_dpp v165, v165, v165 row_shr:8 row_mask:0xf bank_mask:0xf bound_ctrl:1
	v_add_f32_dpp v162, v162, v162 row_bcast:15 row_mask:0xa bank_mask:0xf
	v_add_f32_dpp v163, v163, v163 row_bcast:15 row_mask:0xa bank_mask:0xf
	v_add_f32_dpp v164, v164, v164 row_bcast:15 row_mask:0xa bank_mask:0xf
	v_add_f32_dpp v165, v165, v165 row_bcast:15 row_mask:0xa bank_mask:0xf
	s_mov_b64 s[98:99], exec
	s_mov_b32 exec_lo, 0x80000000
	s_mov_b32 exec_hi, 0x80000000
	ds_write_b32 v74, v162 offset:224
	ds_write_b32 v74, v163 offset:232
	ds_write_b32 v74, v164 offset:240
	ds_write_b32 v74, v165 offset:248
	s_mov_b64 exec, s[98:99]
	ds_read_b32 v166, v75
	s_waitcnt lgkmcnt(0)
	v_mul_f32_e32 v0, v190, v166
	v_mul_f32_e32 v1, 0x3d372713, v0
	v_mul_f32_e32 v1, v0, v1
	v_fma_f32 v1, v0, v1, v0
	v_mul_f32_e32 v1, 0x3f4c422a, v1
	v_add_f32_e32 v1, v1, v1
	v_mul_f32_e32 v1, 0x3fb8aa3b, v1
	v_exp_f32_e32 v1, v1
	v_mul_f32_e32 v0, 0.5, v0
	v_add_f32_e32 v1, 1.0, v1
	v_div_scale_f32 v2, s[0:1], v1, v1, 2.0
	v_rcp_f32_e32 v3, v2
	s_nop 0
	v_fma_f32 v4, -v2, v3, 1.0
	v_fmac_f32_e32 v3, v4, v3
	v_div_scale_f32 v4, vcc, 2.0, v1, 2.0
	v_mul_f32_e32 v5, v4, v3
	v_fma_f32 v6, -v2, v5, v4
	v_fmac_f32_e32 v5, v6, v3
	v_fma_f32 v2, -v2, v5, v4
	v_div_fmas_f32 v2, v2, v3, v5
	v_div_fixup_f32 v1, v2, v1, 2.0
	v_sub_f32_e32 v1, 1.0, v1
	v_add_f32_e32 v1, 1.0, v1
	v_mul_f32_e32 v0, v0, v1
	v_mul_f32_e32 v167, v192, v0
	s_nop 1
	v_readlane_b32 s0, v167, 0
	s_waitcnt vmcnt(48)
; __device__ void peer_gather_phase(const Params& P, int l, bool do_store) {
;     ...
;         v8[2 * pr] = *(const uint2*)(V + (size_t)ea * 512);
;         v8[2 * pr + 1] = *(const uint2*)(V + (size_t)eb * 512);
;     ...
; #pragma unroll
;       for (int j = 0; j < 8; ++j) {
;         const float a = __builtin_bit_cast(float, __builtin_amdgcn_readlane(__builtin_bit_cast(int, avec), kb + j));
;         const f32x2 aa = f32x2{a, a};
;         y[0] += aa * __builtin_amdgcn_cvt_scalef32_pk_f32_fp4(v8[j].x, 1.0f, 0); y[1] += aa * __builtin_amdgcn_cvt_scalef32_pk_f32_fp4(v8[j].x, 1.0f, 1);
;         y[2] += aa * __builtin_amdgcn_cvt_scalef32_pk_f32_fp4(v8[j].x, 1.0f, 2); y[3] += aa * __builtin_amdgcn_cvt_scalef32_pk_f32_fp4(v8[j].x, 1.0f, 3);
;         y[4] += aa * __builtin_amdgcn_cvt_scalef32_pk_f32_fp4(v8[j].y, 1.0f, 0); y[5] += aa * __builtin_amdgcn_cvt_scalef32_pk_f32_fp4(v8[j].y, 1.0f, 1);
;         y[6] += aa * __builtin_amdgcn_cvt_scalef32_pk_f32_fp4(v8[j].y, 1.0f, 2); y[7] += aa * __builtin_amdgcn_cvt_scalef32_pk_f32_fp4(v8[j].y, 1.0f, 3);
;       }
	v_cvt_scalef32_pk_f32_fp4 v[0:1], v144, 1.0
	v_cvt_scalef32_pk_f32_fp4 v[2:3], v144, 1.0 op_sel:[1,0,0]
	v_cvt_scalef32_pk_f32_fp4 v[4:5], v144, 1.0 op_sel:[0,1,0]
	v_cvt_scalef32_pk_f32_fp4 v[6:7], v144, 1.0 op_sel:[1,1,0]
	v_cvt_scalef32_pk_f32_fp4 v[8:9], v145, 1.0
	v_cvt_scalef32_pk_f32_fp4 v[10:11], v145, 1.0 op_sel:[1,0,0]
	v_cvt_scalef32_pk_f32_fp4 v[12:13], v145, 1.0 op_sel:[0,1,0]
	v_cvt_scalef32_pk_f32_fp4 v[14:15], v145, 1.0 op_sel:[1,1,0]
	v_readlane_b32 s54, v90, 16
	s_lshl_b32 s56, s54, 9
	s_add_u32 s56, s64, s56
	s_addc_u32 s57, s65, 0
	global_load_dwordx2 v[144:145], v227, s[56:57]
	v_pk_fma_f32 v[130:131], v[0:1], s[0:1], v[130:131] op_sel_hi:[1,0,1]
	v_pk_fma_f32 v[138:139], v[2:3], s[0:1], v[138:139] op_sel_hi:[1,0,1]
	v_pk_fma_f32 v[140:141], v[4:5], s[0:1], v[140:141] op_sel_hi:[1,0,1]
	v_pk_fma_f32 v[142:143], v[6:7], s[0:1], v[142:143] op_sel_hi:[1,0,1]
	v_pk_fma_f32 v[128:129], v[8:9], s[0:1], v[128:129] op_sel_hi:[1,0,1]
	v_pk_fma_f32 v[132:133], v[10:11], s[0:1], v[132:133] op_sel_hi:[1,0,1]
	v_pk_fma_f32 v[134:135], v[12:13], s[0:1], v[134:135] op_sel_hi:[1,0,1]
	v_pk_fma_f32 v[136:137], v[14:15], s[0:1], v[136:137] op_sel_hi:[1,0,1]
	v_readlane_b32 s0, v167, 1
	s_waitcnt vmcnt(48)
	v_cvt_scalef32_pk_f32_fp4 v[0:1], v146, 1.0
	v_cvt_scalef32_pk_f32_fp4 v[2:3], v146, 1.0 op_sel:[1,0,0]
	v_cvt_scalef32_pk_f32_fp4 v[4:5], v146, 1.0 op_sel:[0,1,0]
	v_cvt_scalef32_pk_f32_fp4 v[6:7], v146, 1.0 op_sel:[1,1,0]
	v_cvt_scalef32_pk_f32_fp4 v[8:9], v147, 1.0
	v_cvt_scalef32_pk_f32_fp4 v[10:11], v147, 1.0 op_sel:[1,0,0]
	v_cvt_scalef32_pk_f32_fp4 v[12:13], v147, 1.0 op_sel:[0,1,0]
	v_cvt_scalef32_pk_f32_fp4 v[14:15], v147, 1.0 op_sel:[1,1,0]
	v_readlane_b32 s54, v90, 17
	s_lshl_b32 s56, s54, 9
	s_add_u32 s56, s64, s56
	s_addc_u32 s57, s65, 0
	global_load_dwordx2 v[146:147], v227, s[56:57]
	v_pk_fma_f32 v[130:131], v[0:1], s[0:1], v[130:131] op_sel_hi:[1,0,1]
	v_pk_fma_f32 v[138:139], v[2:3], s[0:1], v[138:139] op_sel_hi:[1,0,1]
	v_pk_fma_f32 v[140:141], v[4:5], s[0:1], v[140:141] op_sel_hi:[1,0,1]
	v_pk_fma_f32 v[142:143], v[6:7], s[0:1], v[142:143] op_sel_hi:[1,0,1]
	v_pk_fma_f32 v[128:129], v[8:9], s[0:1], v[128:129] op_sel_hi:[1,0,1]
	v_pk_fma_f32 v[132:133], v[10:11], s[0:1], v[132:133] op_sel_hi:[1,0,1]
	v_pk_fma_f32 v[134:135], v[12:13], s[0:1], v[134:135] op_sel_hi:[1,0,1]
	v_pk_fma_f32 v[136:137], v[14:15], s[0:1], v[136:137] op_sel_hi:[1,0,1]
	v_readlane_b32 s0, v167, 2
	s_waitcnt vmcnt(48)
	v_cvt_scalef32_pk_f32_fp4 v[0:1], v148, 1.0
	v_cvt_scalef32_pk_f32_fp4 v[2:3], v148, 1.0 op_sel:[1,0,0]
	v_cvt_scalef32_pk_f32_fp4 v[4:5], v148, 1.0 op_sel:[0,1,0]
	v_cvt_scalef32_pk_f32_fp4 v[6:7], v148, 1.0 op_sel:[1,1,0]
	v_cvt_scalef32_pk_f32_fp4 v[8:9], v149, 1.0
	v_cvt_scalef32_pk_f32_fp4 v[10:11], v149, 1.0 op_sel:[1,0,0]
	v_cvt_scalef32_pk_f32_fp4 v[12:13], v149, 1.0 op_sel:[0,1,0]
	v_cvt_scalef32_pk_f32_fp4 v[14:15], v149, 1.0 op_sel:[1,1,0]
	v_readlane_b32 s54, v90, 18
	s_lshl_b32 s56, s54, 9
	s_add_u32 s56, s64, s56
	s_addc_u32 s57, s65, 0
	global_load_dwordx2 v[148:149], v227, s[56:57]
	v_pk_fma_f32 v[130:131], v[0:1], s[0:1], v[130:131] op_sel_hi:[1,0,1]
	v_pk_fma_f32 v[138:139], v[2:3], s[0:1], v[138:139] op_sel_hi:[1,0,1]
	v_pk_fma_f32 v[140:141], v[4:5], s[0:1], v[140:141] op_sel_hi:[1,0,1]
	v_pk_fma_f32 v[142:143], v[6:7], s[0:1], v[142:143] op_sel_hi:[1,0,1]
	v_pk_fma_f32 v[128:129], v[8:9], s[0:1], v[128:129] op_sel_hi:[1,0,1]
	v_pk_fma_f32 v[132:133], v[10:11], s[0:1], v[132:133] op_sel_hi:[1,0,1]
	v_pk_fma_f32 v[134:135], v[12:13], s[0:1], v[134:135] op_sel_hi:[1,0,1]
	v_pk_fma_f32 v[136:137], v[14:15], s[0:1], v[136:137] op_sel_hi:[1,0,1]
	v_readlane_b32 s0, v167, 3
	s_waitcnt vmcnt(48)
	v_cvt_scalef32_pk_f32_fp4 v[0:1], v150, 1.0
	v_cvt_scalef32_pk_f32_fp4 v[2:3], v150, 1.0 op_sel:[1,0,0]
	v_cvt_scalef32_pk_f32_fp4 v[4:5], v150, 1.0 op_sel:[0,1,0]
	v_cvt_scalef32_pk_f32_fp4 v[6:7], v150, 1.0 op_sel:[1,1,0]
	v_cvt_scalef32_pk_f32_fp4 v[8:9], v151, 1.0
	v_cvt_scalef32_pk_f32_fp4 v[10:11], v151, 1.0 op_sel:[1,0,0]
	v_cvt_scalef32_pk_f32_fp4 v[12:13], v151, 1.0 op_sel:[0,1,0]
	v_cvt_scalef32_pk_f32_fp4 v[14:15], v151, 1.0 op_sel:[1,1,0]
	v_readlane_b32 s54, v90, 19
	s_lshl_b32 s56, s54, 9
	s_add_u32 s56, s64, s56
	s_addc_u32 s57, s65, 0
	global_load_dwordx2 v[150:151], v227, s[56:57]
	v_pk_fma_f32 v[130:131], v[0:1], s[0:1], v[130:131] op_sel_hi:[1,0,1]
	v_pk_fma_f32 v[138:139], v[2:3], s[0:1], v[138:139] op_sel_hi:[1,0,1]
	v_pk_fma_f32 v[140:141], v[4:5], s[0:1], v[140:141] op_sel_hi:[1,0,1]
	v_pk_fma_f32 v[142:143], v[6:7], s[0:1], v[142:143] op_sel_hi:[1,0,1]
	v_pk_fma_f32 v[128:129], v[8:9], s[0:1], v[128:129] op_sel_hi:[1,0,1]
	v_pk_fma_f32 v[132:133], v[10:11], s[0:1], v[132:133] op_sel_hi:[1,0,1]
	v_pk_fma_f32 v[134:135], v[12:13], s[0:1], v[134:135] op_sel_hi:[1,0,1]
	v_pk_fma_f32 v[136:137], v[14:15], s[0:1], v[136:137] op_sel_hi:[1,0,1]
	v_readlane_b32 s0, v167, 4
	s_waitcnt vmcnt(48)
	v_cvt_scalef32_pk_f32_fp4 v[0:1], v152, 1.0
	v_cvt_scalef32_pk_f32_fp4 v[2:3], v152, 1.0 op_sel:[1,0,0]
	v_cvt_scalef32_pk_f32_fp4 v[4:5], v152, 1.0 op_sel:[0,1,0]
	v_cvt_scalef32_pk_f32_fp4 v[6:7], v152, 1.0 op_sel:[1,1,0]
	v_cvt_scalef32_pk_f32_fp4 v[8:9], v153, 1.0
	v_cvt_scalef32_pk_f32_fp4 v[10:11], v153, 1.0 op_sel:[1,0,0]
	v_cvt_scalef32_pk_f32_fp4 v[12:13], v153, 1.0 op_sel:[0,1,0]
	v_cvt_scalef32_pk_f32_fp4 v[14:15], v153, 1.0 op_sel:[1,1,0]
	v_readlane_b32 s54, v90, 20
	s_lshl_b32 s56, s54, 9
	s_add_u32 s56, s64, s56
	s_addc_u32 s57, s65, 0
	global_load_dwordx2 v[152:153], v227, s[56:57]
	v_pk_fma_f32 v[130:131], v[0:1], s[0:1], v[130:131] op_sel_hi:[1,0,1]
	v_pk_fma_f32 v[138:139], v[2:3], s[0:1], v[138:139] op_sel_hi:[1,0,1]
	v_pk_fma_f32 v[140:141], v[4:5], s[0:1], v[140:141] op_sel_hi:[1,0,1]
	v_pk_fma_f32 v[142:143], v[6:7], s[0:1], v[142:143] op_sel_hi:[1,0,1]
	v_pk_fma_f32 v[128:129], v[8:9], s[0:1], v[128:129] op_sel_hi:[1,0,1]
	v_pk_fma_f32 v[132:133], v[10:11], s[0:1], v[132:133] op_sel_hi:[1,0,1]
	v_pk_fma_f32 v[134:135], v[12:13], s[0:1], v[134:135] op_sel_hi:[1,0,1]
	v_pk_fma_f32 v[136:137], v[14:15], s[0:1], v[136:137] op_sel_hi:[1,0,1]
	v_readlane_b32 s0, v167, 5
	s_waitcnt vmcnt(48)
; __device__ void peer_gather_phase(const Params& P, int l, bool do_store) {
;     ...
;         const uint2* up = (const uint2*)(U + (size_t)(uphi ? eb : ea) * 768);
;         u6[3 * pr] = up[0]; u6[3 * pr + 1] = up[1]; u6[3 * pr + 2] = up[2];
;         v8[2 * pr] = *(const uint2*)(V + (size_t)ea * 512);
;         v8[2 * pr + 1] = *(const uint2*)(V + (size_t)eb * 512);
;     ...
; #pragma unroll
;       for (int j = 0; j < 8; ++j) {
;         const float a = __builtin_bit_cast(float, __builtin_amdgcn_readlane(__builtin_bit_cast(int, avec), kb + j));
;         const f32x2 aa = f32x2{a, a};
;         y[0] += aa * __builtin_amdgcn_cvt_scalef32_pk_f32_fp4(v8[j].x, 1.0f, 0); y[1] += aa * __builtin_amdgcn_cvt_scalef32_pk_f32_fp4(v8[j].x, 1.0f, 1);
;         y[2] += aa * __builtin_amdgcn_cvt_scalef32_pk_f32_fp4(v8[j].x, 1.0f, 2); y[3] += aa * __builtin_amdgcn_cvt_scalef32_pk_f32_fp4(v8[j].x, 1.0f, 3);
;         y[4] += aa * __builtin_amdgcn_cvt_scalef32_pk_f32_fp4(v8[j].y, 1.0f, 0); y[5] += aa * __builtin_amdgcn_cvt_scalef32_pk_f32_fp4(v8[j].y, 1.0f, 1);
;         y[6] += aa * __builtin_amdgcn_cvt_scalef32_pk_f32_fp4(v8[j].y, 1.0f, 2); y[7] += aa * __builtin_amdgcn_cvt_scalef32_pk_f32_fp4(v8[j].y, 1.0f, 3);
;       }
	v_cvt_scalef32_pk_f32_fp4 v[0:1], v154, 1.0
	v_cvt_scalef32_pk_f32_fp4 v[2:3], v154, 1.0 op_sel:[1,0,0]
	v_cvt_scalef32_pk_f32_fp4 v[4:5], v154, 1.0 op_sel:[0,1,0]
	v_cvt_scalef32_pk_f32_fp4 v[6:7], v154, 1.0 op_sel:[1,1,0]
	v_cvt_scalef32_pk_f32_fp4 v[8:9], v155, 1.0
	v_cvt_scalef32_pk_f32_fp4 v[10:11], v155, 1.0 op_sel:[1,0,0]
	v_cvt_scalef32_pk_f32_fp4 v[12:13], v155, 1.0 op_sel:[0,1,0]
	v_cvt_scalef32_pk_f32_fp4 v[14:15], v155, 1.0 op_sel:[1,1,0]
	v_readlane_b32 s54, v90, 21
	s_lshl_b32 s56, s54, 9
	s_add_u32 s56, s64, s56
	s_addc_u32 s57, s65, 0
	global_load_dwordx2 v[154:155], v227, s[56:57]
	v_pk_fma_f32 v[130:131], v[0:1], s[0:1], v[130:131] op_sel_hi:[1,0,1]
	v_pk_fma_f32 v[138:139], v[2:3], s[0:1], v[138:139] op_sel_hi:[1,0,1]
	v_pk_fma_f32 v[140:141], v[4:5], s[0:1], v[140:141] op_sel_hi:[1,0,1]
	v_pk_fma_f32 v[142:143], v[6:7], s[0:1], v[142:143] op_sel_hi:[1,0,1]
	v_pk_fma_f32 v[128:129], v[8:9], s[0:1], v[128:129] op_sel_hi:[1,0,1]
	v_pk_fma_f32 v[132:133], v[10:11], s[0:1], v[132:133] op_sel_hi:[1,0,1]
	v_pk_fma_f32 v[134:135], v[12:13], s[0:1], v[134:135] op_sel_hi:[1,0,1]
	v_pk_fma_f32 v[136:137], v[14:15], s[0:1], v[136:137] op_sel_hi:[1,0,1]
	v_readlane_b32 s0, v167, 6
	s_waitcnt vmcnt(48)
	v_cvt_scalef32_pk_f32_fp4 v[0:1], v156, 1.0
	v_cvt_scalef32_pk_f32_fp4 v[2:3], v156, 1.0 op_sel:[1,0,0]
	v_cvt_scalef32_pk_f32_fp4 v[4:5], v156, 1.0 op_sel:[0,1,0]
	v_cvt_scalef32_pk_f32_fp4 v[6:7], v156, 1.0 op_sel:[1,1,0]
	v_cvt_scalef32_pk_f32_fp4 v[8:9], v157, 1.0
	v_cvt_scalef32_pk_f32_fp4 v[10:11], v157, 1.0 op_sel:[1,0,0]
	v_cvt_scalef32_pk_f32_fp4 v[12:13], v157, 1.0 op_sel:[0,1,0]
	v_cvt_scalef32_pk_f32_fp4 v[14:15], v157, 1.0 op_sel:[1,1,0]
	v_readlane_b32 s54, v90, 22
	s_lshl_b32 s56, s54, 9
	s_add_u32 s56, s64, s56
	s_addc_u32 s57, s65, 0
	global_load_dwordx2 v[156:157], v227, s[56:57]
	v_pk_fma_f32 v[130:131], v[0:1], s[0:1], v[130:131] op_sel_hi:[1,0,1]
	v_pk_fma_f32 v[138:139], v[2:3], s[0:1], v[138:139] op_sel_hi:[1,0,1]
	v_pk_fma_f32 v[140:141], v[4:5], s[0:1], v[140:141] op_sel_hi:[1,0,1]
	v_pk_fma_f32 v[142:143], v[6:7], s[0:1], v[142:143] op_sel_hi:[1,0,1]
	v_pk_fma_f32 v[128:129], v[8:9], s[0:1], v[128:129] op_sel_hi:[1,0,1]
	v_pk_fma_f32 v[132:133], v[10:11], s[0:1], v[132:133] op_sel_hi:[1,0,1]
	v_pk_fma_f32 v[134:135], v[12:13], s[0:1], v[134:135] op_sel_hi:[1,0,1]
	v_pk_fma_f32 v[136:137], v[14:15], s[0:1], v[136:137] op_sel_hi:[1,0,1]
	v_readlane_b32 s0, v167, 7
	s_waitcnt vmcnt(48)
	v_cvt_scalef32_pk_f32_fp4 v[0:1], v158, 1.0
	v_cvt_scalef32_pk_f32_fp4 v[2:3], v158, 1.0 op_sel:[1,0,0]
	v_cvt_scalef32_pk_f32_fp4 v[4:5], v158, 1.0 op_sel:[0,1,0]
	v_cvt_scalef32_pk_f32_fp4 v[6:7], v158, 1.0 op_sel:[1,1,0]
	v_cvt_scalef32_pk_f32_fp4 v[8:9], v159, 1.0
	v_cvt_scalef32_pk_f32_fp4 v[10:11], v159, 1.0 op_sel:[1,0,0]
	v_cvt_scalef32_pk_f32_fp4 v[12:13], v159, 1.0 op_sel:[0,1,0]
	v_cvt_scalef32_pk_f32_fp4 v[14:15], v159, 1.0 op_sel:[1,1,0]
	v_readlane_b32 s54, v90, 23
	s_lshl_b32 s56, s54, 9
	s_add_u32 s56, s64, s56
	s_addc_u32 s57, s65, 0
	global_load_dwordx2 v[158:159], v227, s[56:57]
	v_pk_fma_f32 v[130:131], v[0:1], s[0:1], v[130:131] op_sel_hi:[1,0,1]
	v_pk_fma_f32 v[138:139], v[2:3], s[0:1], v[138:139] op_sel_hi:[1,0,1]
	v_pk_fma_f32 v[140:141], v[4:5], s[0:1], v[140:141] op_sel_hi:[1,0,1]
	v_pk_fma_f32 v[142:143], v[6:7], s[0:1], v[142:143] op_sel_hi:[1,0,1]
	v_pk_fma_f32 v[128:129], v[8:9], s[0:1], v[128:129] op_sel_hi:[1,0,1]
	v_pk_fma_f32 v[132:133], v[10:11], s[0:1], v[132:133] op_sel_hi:[1,0,1]
	v_pk_fma_f32 v[134:135], v[12:13], s[0:1], v[134:135] op_sel_hi:[1,0,1]
	v_pk_fma_f32 v[136:137], v[14:15], s[0:1], v[136:137] op_sel_hi:[1,0,1]
	v_readlane_b32 s0, v167, 8
	s_waitcnt vmcnt(48)
	v_cvt_scalef32_pk_f32_fp4 v[0:1], v168, 1.0
	v_cvt_scalef32_pk_f32_fp4 v[2:3], v168, 1.0 op_sel:[1,0,0]
	v_cvt_scalef32_pk_f32_fp4 v[4:5], v168, 1.0 op_sel:[0,1,0]
	v_cvt_scalef32_pk_f32_fp4 v[6:7], v168, 1.0 op_sel:[1,1,0]
	v_cvt_scalef32_pk_f32_fp4 v[8:9], v169, 1.0
	v_cvt_scalef32_pk_f32_fp4 v[10:11], v169, 1.0 op_sel:[1,0,0]
	v_cvt_scalef32_pk_f32_fp4 v[12:13], v169, 1.0 op_sel:[0,1,0]
	v_cvt_scalef32_pk_f32_fp4 v[14:15], v169, 1.0 op_sel:[1,1,0]
	v_readlane_b32 s54, v90, 24
	s_lshl_b32 s56, s54, 9
	s_add_u32 s56, s64, s56
	s_addc_u32 s57, s65, 0
	global_load_dwordx2 v[168:169], v227, s[56:57]
	v_pk_fma_f32 v[130:131], v[0:1], s[0:1], v[130:131] op_sel_hi:[1,0,1]
	v_pk_fma_f32 v[138:139], v[2:3], s[0:1], v[138:139] op_sel_hi:[1,0,1]
	v_pk_fma_f32 v[140:141], v[4:5], s[0:1], v[140:141] op_sel_hi:[1,0,1]
	v_pk_fma_f32 v[142:143], v[6:7], s[0:1], v[142:143] op_sel_hi:[1,0,1]
	v_pk_fma_f32 v[128:129], v[8:9], s[0:1], v[128:129] op_sel_hi:[1,0,1]
	v_pk_fma_f32 v[132:133], v[10:11], s[0:1], v[132:133] op_sel_hi:[1,0,1]
	v_pk_fma_f32 v[134:135], v[12:13], s[0:1], v[134:135] op_sel_hi:[1,0,1]
	v_pk_fma_f32 v[136:137], v[14:15], s[0:1], v[136:137] op_sel_hi:[1,0,1]
	v_readlane_b32 s0, v167, 9
	s_waitcnt vmcnt(48)
	v_cvt_scalef32_pk_f32_fp4 v[0:1], v170, 1.0
	v_cvt_scalef32_pk_f32_fp4 v[2:3], v170, 1.0 op_sel:[1,0,0]
	v_cvt_scalef32_pk_f32_fp4 v[4:5], v170, 1.0 op_sel:[0,1,0]
	v_cvt_scalef32_pk_f32_fp4 v[6:7], v170, 1.0 op_sel:[1,1,0]
	v_cvt_scalef32_pk_f32_fp4 v[8:9], v171, 1.0
	v_cvt_scalef32_pk_f32_fp4 v[10:11], v171, 1.0 op_sel:[1,0,0]
	v_cvt_scalef32_pk_f32_fp4 v[12:13], v171, 1.0 op_sel:[0,1,0]
	v_cvt_scalef32_pk_f32_fp4 v[14:15], v171, 1.0 op_sel:[1,1,0]
	v_readlane_b32 s54, v90, 25
	s_lshl_b32 s56, s54, 9
	s_add_u32 s56, s64, s56
	s_addc_u32 s57, s65, 0
	global_load_dwordx2 v[170:171], v227, s[56:57]
	v_pk_fma_f32 v[130:131], v[0:1], s[0:1], v[130:131] op_sel_hi:[1,0,1]
	v_pk_fma_f32 v[138:139], v[2:3], s[0:1], v[138:139] op_sel_hi:[1,0,1]
	v_pk_fma_f32 v[140:141], v[4:5], s[0:1], v[140:141] op_sel_hi:[1,0,1]
	v_pk_fma_f32 v[142:143], v[6:7], s[0:1], v[142:143] op_sel_hi:[1,0,1]
	v_pk_fma_f32 v[128:129], v[8:9], s[0:1], v[128:129] op_sel_hi:[1,0,1]
	v_pk_fma_f32 v[132:133], v[10:11], s[0:1], v[132:133] op_sel_hi:[1,0,1]
	v_pk_fma_f32 v[134:135], v[12:13], s[0:1], v[134:135] op_sel_hi:[1,0,1]
	v_pk_fma_f32 v[136:137], v[14:15], s[0:1], v[136:137] op_sel_hi:[1,0,1]
	v_readlane_b32 s0, v167, 10
	s_waitcnt vmcnt(48)
; __device__ void peer_gather_phase(const Params& P, int l, bool do_store) {
;     ...
;         const uint2* up = (const uint2*)(U + (size_t)(uphi ? eb : ea) * 768);
;         u6[3 * pr] = up[0]; u6[3 * pr + 1] = up[1]; u6[3 * pr + 2] = up[2];
;         v8[2 * pr] = *(const uint2*)(V + (size_t)ea * 512);
;         v8[2 * pr + 1] = *(const uint2*)(V + (size_t)eb * 512);
;     ...
; #pragma unroll
;       for (int j = 0; j < 8; ++j) {
;         const float a = __builtin_bit_cast(float, __builtin_amdgcn_readlane(__builtin_bit_cast(int, avec), kb + j));
;         const f32x2 aa = f32x2{a, a};
;         y[0] += aa * __builtin_amdgcn_cvt_scalef32_pk_f32_fp4(v8[j].x, 1.0f, 0); y[1] += aa * __builtin_amdgcn_cvt_scalef32_pk_f32_fp4(v8[j].x, 1.0f, 1);
;         y[2] += aa * __builtin_amdgcn_cvt_scalef32_pk_f32_fp4(v8[j].x, 1.0f, 2); y[3] += aa * __builtin_amdgcn_cvt_scalef32_pk_f32_fp4(v8[j].x, 1.0f, 3);
;         y[4] += aa * __builtin_amdgcn_cvt_scalef32_pk_f32_fp4(v8[j].y, 1.0f, 0); y[5] += aa * __builtin_amdgcn_cvt_scalef32_pk_f32_fp4(v8[j].y, 1.0f, 1);
;         y[6] += aa * __builtin_amdgcn_cvt_scalef32_pk_f32_fp4(v8[j].y, 1.0f, 2); y[7] += aa * __builtin_amdgcn_cvt_scalef32_pk_f32_fp4(v8[j].y, 1.0f, 3);
;       }
	v_cvt_scalef32_pk_f32_fp4 v[0:1], v172, 1.0
	v_cvt_scalef32_pk_f32_fp4 v[2:3], v172, 1.0 op_sel:[1,0,0]
	v_cvt_scalef32_pk_f32_fp4 v[4:5], v172, 1.0 op_sel:[0,1,0]
	v_cvt_scalef32_pk_f32_fp4 v[6:7], v172, 1.0 op_sel:[1,1,0]
	v_cvt_scalef32_pk_f32_fp4 v[8:9], v173, 1.0
	v_cvt_scalef32_pk_f32_fp4 v[10:11], v173, 1.0 op_sel:[1,0,0]
	v_cvt_scalef32_pk_f32_fp4 v[12:13], v173, 1.0 op_sel:[0,1,0]
	v_cvt_scalef32_pk_f32_fp4 v[14:15], v173, 1.0 op_sel:[1,1,0]
	v_readlane_b32 s54, v90, 26
	s_lshl_b32 s56, s54, 9
	s_add_u32 s56, s64, s56
	s_addc_u32 s57, s65, 0
	global_load_dwordx2 v[172:173], v227, s[56:57]
	v_pk_fma_f32 v[130:131], v[0:1], s[0:1], v[130:131] op_sel_hi:[1,0,1]
	v_pk_fma_f32 v[138:139], v[2:3], s[0:1], v[138:139] op_sel_hi:[1,0,1]
	v_pk_fma_f32 v[140:141], v[4:5], s[0:1], v[140:141] op_sel_hi:[1,0,1]
	v_pk_fma_f32 v[142:143], v[6:7], s[0:1], v[142:143] op_sel_hi:[1,0,1]
	v_pk_fma_f32 v[128:129], v[8:9], s[0:1], v[128:129] op_sel_hi:[1,0,1]
	v_pk_fma_f32 v[132:133], v[10:11], s[0:1], v[132:133] op_sel_hi:[1,0,1]
	v_pk_fma_f32 v[134:135], v[12:13], s[0:1], v[134:135] op_sel_hi:[1,0,1]
	v_pk_fma_f32 v[136:137], v[14:15], s[0:1], v[136:137] op_sel_hi:[1,0,1]
	v_readlane_b32 s0, v167, 11
	s_waitcnt vmcnt(48)
	v_cvt_scalef32_pk_f32_fp4 v[0:1], v174, 1.0
	v_cvt_scalef32_pk_f32_fp4 v[2:3], v174, 1.0 op_sel:[1,0,0]
	v_cvt_scalef32_pk_f32_fp4 v[4:5], v174, 1.0 op_sel:[0,1,0]
	v_cvt_scalef32_pk_f32_fp4 v[6:7], v174, 1.0 op_sel:[1,1,0]
	v_cvt_scalef32_pk_f32_fp4 v[8:9], v175, 1.0
	v_cvt_scalef32_pk_f32_fp4 v[10:11], v175, 1.0 op_sel:[1,0,0]
	v_cvt_scalef32_pk_f32_fp4 v[12:13], v175, 1.0 op_sel:[0,1,0]
	v_cvt_scalef32_pk_f32_fp4 v[14:15], v175, 1.0 op_sel:[1,1,0]
	v_readlane_b32 s54, v90, 27
	s_lshl_b32 s56, s54, 9
	s_add_u32 s56, s64, s56
	s_addc_u32 s57, s65, 0
	global_load_dwordx2 v[174:175], v227, s[56:57]
	v_pk_fma_f32 v[130:131], v[0:1], s[0:1], v[130:131] op_sel_hi:[1,0,1]
	v_pk_fma_f32 v[138:139], v[2:3], s[0:1], v[138:139] op_sel_hi:[1,0,1]
	v_pk_fma_f32 v[140:141], v[4:5], s[0:1], v[140:141] op_sel_hi:[1,0,1]
	v_pk_fma_f32 v[142:143], v[6:7], s[0:1], v[142:143] op_sel_hi:[1,0,1]
	v_pk_fma_f32 v[128:129], v[8:9], s[0:1], v[128:129] op_sel_hi:[1,0,1]
	v_pk_fma_f32 v[132:133], v[10:11], s[0:1], v[132:133] op_sel_hi:[1,0,1]
	v_pk_fma_f32 v[134:135], v[12:13], s[0:1], v[134:135] op_sel_hi:[1,0,1]
	v_pk_fma_f32 v[136:137], v[14:15], s[0:1], v[136:137] op_sel_hi:[1,0,1]
	v_readlane_b32 s0, v167, 12
	s_waitcnt vmcnt(48)
	v_cvt_scalef32_pk_f32_fp4 v[0:1], v180, 1.0
	v_cvt_scalef32_pk_f32_fp4 v[2:3], v180, 1.0 op_sel:[1,0,0]
	v_cvt_scalef32_pk_f32_fp4 v[4:5], v180, 1.0 op_sel:[0,1,0]
	v_cvt_scalef32_pk_f32_fp4 v[6:7], v180, 1.0 op_sel:[1,1,0]
	v_cvt_scalef32_pk_f32_fp4 v[8:9], v181, 1.0
	v_cvt_scalef32_pk_f32_fp4 v[10:11], v181, 1.0 op_sel:[1,0,0]
	v_cvt_scalef32_pk_f32_fp4 v[12:13], v181, 1.0 op_sel:[0,1,0]
	v_cvt_scalef32_pk_f32_fp4 v[14:15], v181, 1.0 op_sel:[1,1,0]
	v_readlane_b32 s54, v90, 28
	s_lshl_b32 s56, s54, 9
	s_add_u32 s56, s64, s56
	s_addc_u32 s57, s65, 0
	global_load_dwordx2 v[180:181], v227, s[56:57]
	v_pk_fma_f32 v[130:131], v[0:1], s[0:1], v[130:131] op_sel_hi:[1,0,1]
	v_pk_fma_f32 v[138:139], v[2:3], s[0:1], v[138:139] op_sel_hi:[1,0,1]
	v_pk_fma_f32 v[140:141], v[4:5], s[0:1], v[140:141] op_sel_hi:[1,0,1]
	v_pk_fma_f32 v[142:143], v[6:7], s[0:1], v[142:143] op_sel_hi:[1,0,1]
	v_pk_fma_f32 v[128:129], v[8:9], s[0:1], v[128:129] op_sel_hi:[1,0,1]
	v_pk_fma_f32 v[132:133], v[10:11], s[0:1], v[132:133] op_sel_hi:[1,0,1]
	v_pk_fma_f32 v[134:135], v[12:13], s[0:1], v[134:135] op_sel_hi:[1,0,1]
	v_pk_fma_f32 v[136:137], v[14:15], s[0:1], v[136:137] op_sel_hi:[1,0,1]
	v_readlane_b32 s0, v167, 13
	s_waitcnt vmcnt(48)
	v_cvt_scalef32_pk_f32_fp4 v[0:1], v182, 1.0
	v_cvt_scalef32_pk_f32_fp4 v[2:3], v182, 1.0 op_sel:[1,0,0]
	v_cvt_scalef32_pk_f32_fp4 v[4:5], v182, 1.0 op_sel:[0,1,0]
	v_cvt_scalef32_pk_f32_fp4 v[6:7], v182, 1.0 op_sel:[1,1,0]
	v_cvt_scalef32_pk_f32_fp4 v[8:9], v183, 1.0
	v_cvt_scalef32_pk_f32_fp4 v[10:11], v183, 1.0 op_sel:[1,0,0]
	v_cvt_scalef32_pk_f32_fp4 v[12:13], v183, 1.0 op_sel:[0,1,0]
	v_cvt_scalef32_pk_f32_fp4 v[14:15], v183, 1.0 op_sel:[1,1,0]
	v_readlane_b32 s54, v90, 29
	s_lshl_b32 s56, s54, 9
	s_add_u32 s56, s64, s56
	s_addc_u32 s57, s65, 0
	global_load_dwordx2 v[182:183], v227, s[56:57]
	v_pk_fma_f32 v[130:131], v[0:1], s[0:1], v[130:131] op_sel_hi:[1,0,1]
	v_pk_fma_f32 v[138:139], v[2:3], s[0:1], v[138:139] op_sel_hi:[1,0,1]
	v_pk_fma_f32 v[140:141], v[4:5], s[0:1], v[140:141] op_sel_hi:[1,0,1]
	v_pk_fma_f32 v[142:143], v[6:7], s[0:1], v[142:143] op_sel_hi:[1,0,1]
	v_pk_fma_f32 v[128:129], v[8:9], s[0:1], v[128:129] op_sel_hi:[1,0,1]
	v_pk_fma_f32 v[132:133], v[10:11], s[0:1], v[132:133] op_sel_hi:[1,0,1]
	v_pk_fma_f32 v[134:135], v[12:13], s[0:1], v[134:135] op_sel_hi:[1,0,1]
	v_pk_fma_f32 v[136:137], v[14:15], s[0:1], v[136:137] op_sel_hi:[1,0,1]
	v_readlane_b32 s0, v167, 14
	s_waitcnt vmcnt(48)
	v_cvt_scalef32_pk_f32_fp4 v[0:1], v184, 1.0
	v_cvt_scalef32_pk_f32_fp4 v[2:3], v184, 1.0 op_sel:[1,0,0]
	v_cvt_scalef32_pk_f32_fp4 v[4:5], v184, 1.0 op_sel:[0,1,0]
	v_cvt_scalef32_pk_f32_fp4 v[6:7], v184, 1.0 op_sel:[1,1,0]
	v_cvt_scalef32_pk_f32_fp4 v[8:9], v185, 1.0
	v_cvt_scalef32_pk_f32_fp4 v[10:11], v185, 1.0 op_sel:[1,0,0]
	v_cvt_scalef32_pk_f32_fp4 v[12:13], v185, 1.0 op_sel:[0,1,0]
	v_cvt_scalef32_pk_f32_fp4 v[14:15], v185, 1.0 op_sel:[1,1,0]
	v_readlane_b32 s54, v90, 30
	s_lshl_b32 s56, s54, 9
	s_add_u32 s56, s64, s56
	s_addc_u32 s57, s65, 0
	global_load_dwordx2 v[184:185], v227, s[56:57]
	v_pk_fma_f32 v[130:131], v[0:1], s[0:1], v[130:131] op_sel_hi:[1,0,1]
	v_pk_fma_f32 v[138:139], v[2:3], s[0:1], v[138:139] op_sel_hi:[1,0,1]
	v_pk_fma_f32 v[140:141], v[4:5], s[0:1], v[140:141] op_sel_hi:[1,0,1]
	v_pk_fma_f32 v[142:143], v[6:7], s[0:1], v[142:143] op_sel_hi:[1,0,1]
	v_pk_fma_f32 v[128:129], v[8:9], s[0:1], v[128:129] op_sel_hi:[1,0,1]
	v_pk_fma_f32 v[132:133], v[10:11], s[0:1], v[132:133] op_sel_hi:[1,0,1]
	v_pk_fma_f32 v[134:135], v[12:13], s[0:1], v[134:135] op_sel_hi:[1,0,1]
	v_pk_fma_f32 v[136:137], v[14:15], s[0:1], v[136:137] op_sel_hi:[1,0,1]
	v_readlane_b32 s0, v167, 15
	s_waitcnt vmcnt(48)
; __device__ void peer_gather_phase(const Params& P, int l, bool do_store) {
;     ...
;         const uint2* up = (const uint2*)(U + (size_t)(uphi ? eb : ea) * 768);
;         u6[3 * pr] = up[0]; u6[3 * pr + 1] = up[1]; u6[3 * pr + 2] = up[2];
;         v8[2 * pr] = *(const uint2*)(V + (size_t)ea * 512);
;         v8[2 * pr + 1] = *(const uint2*)(V + (size_t)eb * 512);
;     ...
; #pragma unroll
;       for (int j = 0; j < 8; ++j) {
;         const float a = __builtin_bit_cast(float, __builtin_amdgcn_readlane(__builtin_bit_cast(int, avec), kb + j));
;         const f32x2 aa = f32x2{a, a};
;         y[0] += aa * __builtin_amdgcn_cvt_scalef32_pk_f32_fp4(v8[j].x, 1.0f, 0); y[1] += aa * __builtin_amdgcn_cvt_scalef32_pk_f32_fp4(v8[j].x, 1.0f, 1);
;         y[2] += aa * __builtin_amdgcn_cvt_scalef32_pk_f32_fp4(v8[j].x, 1.0f, 2); y[3] += aa * __builtin_amdgcn_cvt_scalef32_pk_f32_fp4(v8[j].x, 1.0f, 3);
;         y[4] += aa * __builtin_amdgcn_cvt_scalef32_pk_f32_fp4(v8[j].y, 1.0f, 0); y[5] += aa * __builtin_amdgcn_cvt_scalef32_pk_f32_fp4(v8[j].y, 1.0f, 1);
;         y[6] += aa * __builtin_amdgcn_cvt_scalef32_pk_f32_fp4(v8[j].y, 1.0f, 2); y[7] += aa * __builtin_amdgcn_cvt_scalef32_pk_f32_fp4(v8[j].y, 1.0f, 3);
;       }
	v_cvt_scalef32_pk_f32_fp4 v[0:1], v186, 1.0
	v_cvt_scalef32_pk_f32_fp4 v[2:3], v186, 1.0 op_sel:[1,0,0]
	v_cvt_scalef32_pk_f32_fp4 v[4:5], v186, 1.0 op_sel:[0,1,0]
	v_cvt_scalef32_pk_f32_fp4 v[6:7], v186, 1.0 op_sel:[1,1,0]
	v_cvt_scalef32_pk_f32_fp4 v[8:9], v187, 1.0
	v_cvt_scalef32_pk_f32_fp4 v[10:11], v187, 1.0 op_sel:[1,0,0]
	v_cvt_scalef32_pk_f32_fp4 v[12:13], v187, 1.0 op_sel:[0,1,0]
	v_cvt_scalef32_pk_f32_fp4 v[14:15], v187, 1.0 op_sel:[1,1,0]
	v_readlane_b32 s54, v90, 31
	s_lshl_b32 s56, s54, 9
	s_add_u32 s56, s64, s56
	s_addc_u32 s57, s65, 0
	global_load_dwordx2 v[186:187], v227, s[56:57]
	v_pk_fma_f32 v[130:131], v[0:1], s[0:1], v[130:131] op_sel_hi:[1,0,1]
	v_pk_fma_f32 v[138:139], v[2:3], s[0:1], v[138:139] op_sel_hi:[1,0,1]
	v_pk_fma_f32 v[140:141], v[4:5], s[0:1], v[140:141] op_sel_hi:[1,0,1]
	v_pk_fma_f32 v[142:143], v[6:7], s[0:1], v[142:143] op_sel_hi:[1,0,1]
	v_pk_fma_f32 v[128:129], v[8:9], s[0:1], v[128:129] op_sel_hi:[1,0,1]
	v_pk_fma_f32 v[132:133], v[10:11], s[0:1], v[132:133] op_sel_hi:[1,0,1]
	v_pk_fma_f32 v[134:135], v[12:13], s[0:1], v[134:135] op_sel_hi:[1,0,1]
	v_pk_fma_f32 v[136:137], v[14:15], s[0:1], v[136:137] op_sel_hi:[1,0,1]
	v_readlane_b32 s0, v167, 16
	s_waitcnt vmcnt(15)
	v_cvt_scalef32_pk_f32_fp4 v[0:1], v144, 1.0
	v_cvt_scalef32_pk_f32_fp4 v[2:3], v144, 1.0 op_sel:[1,0,0]
	v_cvt_scalef32_pk_f32_fp4 v[4:5], v144, 1.0 op_sel:[0,1,0]
	v_cvt_scalef32_pk_f32_fp4 v[6:7], v144, 1.0 op_sel:[1,1,0]
	v_cvt_scalef32_pk_f32_fp4 v[8:9], v145, 1.0
	v_cvt_scalef32_pk_f32_fp4 v[10:11], v145, 1.0 op_sel:[1,0,0]
	v_cvt_scalef32_pk_f32_fp4 v[12:13], v145, 1.0 op_sel:[0,1,0]
	v_cvt_scalef32_pk_f32_fp4 v[14:15], v145, 1.0 op_sel:[1,1,0]
	v_readlane_b32 s54, v90, 32
	s_lshl_b32 s56, s54, 9
	s_add_u32 s56, s64, s56
	s_addc_u32 s57, s65, 0
	global_load_dwordx2 v[144:145], v227, s[56:57]
	v_pk_fma_f32 v[130:131], v[0:1], s[0:1], v[130:131] op_sel_hi:[1,0,1]
	v_pk_fma_f32 v[138:139], v[2:3], s[0:1], v[138:139] op_sel_hi:[1,0,1]
	v_pk_fma_f32 v[140:141], v[4:5], s[0:1], v[140:141] op_sel_hi:[1,0,1]
	v_pk_fma_f32 v[142:143], v[6:7], s[0:1], v[142:143] op_sel_hi:[1,0,1]
	v_pk_fma_f32 v[128:129], v[8:9], s[0:1], v[128:129] op_sel_hi:[1,0,1]
	v_pk_fma_f32 v[132:133], v[10:11], s[0:1], v[132:133] op_sel_hi:[1,0,1]
	v_pk_fma_f32 v[134:135], v[12:13], s[0:1], v[134:135] op_sel_hi:[1,0,1]
	v_pk_fma_f32 v[136:137], v[14:15], s[0:1], v[136:137] op_sel_hi:[1,0,1]
	v_readlane_b32 s0, v167, 17
	s_waitcnt vmcnt(15)
	v_cvt_scalef32_pk_f32_fp4 v[0:1], v146, 1.0
	v_cvt_scalef32_pk_f32_fp4 v[2:3], v146, 1.0 op_sel:[1,0,0]
	v_cvt_scalef32_pk_f32_fp4 v[4:5], v146, 1.0 op_sel:[0,1,0]
	v_cvt_scalef32_pk_f32_fp4 v[6:7], v146, 1.0 op_sel:[1,1,0]
	v_cvt_scalef32_pk_f32_fp4 v[8:9], v147, 1.0
	v_cvt_scalef32_pk_f32_fp4 v[10:11], v147, 1.0 op_sel:[1,0,0]
	v_cvt_scalef32_pk_f32_fp4 v[12:13], v147, 1.0 op_sel:[0,1,0]
	v_cvt_scalef32_pk_f32_fp4 v[14:15], v147, 1.0 op_sel:[1,1,0]
	v_readlane_b32 s54, v90, 33
	s_lshl_b32 s56, s54, 9
	s_add_u32 s56, s64, s56
	s_addc_u32 s57, s65, 0
	global_load_dwordx2 v[146:147], v227, s[56:57]
	v_pk_fma_f32 v[130:131], v[0:1], s[0:1], v[130:131] op_sel_hi:[1,0,1]
	v_pk_fma_f32 v[138:139], v[2:3], s[0:1], v[138:139] op_sel_hi:[1,0,1]
	v_pk_fma_f32 v[140:141], v[4:5], s[0:1], v[140:141] op_sel_hi:[1,0,1]
	v_pk_fma_f32 v[142:143], v[6:7], s[0:1], v[142:143] op_sel_hi:[1,0,1]
	v_pk_fma_f32 v[128:129], v[8:9], s[0:1], v[128:129] op_sel_hi:[1,0,1]
	v_pk_fma_f32 v[132:133], v[10:11], s[0:1], v[132:133] op_sel_hi:[1,0,1]
	v_pk_fma_f32 v[134:135], v[12:13], s[0:1], v[134:135] op_sel_hi:[1,0,1]
	v_pk_fma_f32 v[136:137], v[14:15], s[0:1], v[136:137] op_sel_hi:[1,0,1]
	v_readlane_b32 s0, v167, 18
	s_waitcnt vmcnt(15)
	v_cvt_scalef32_pk_f32_fp4 v[0:1], v148, 1.0
	v_cvt_scalef32_pk_f32_fp4 v[2:3], v148, 1.0 op_sel:[1,0,0]
	v_cvt_scalef32_pk_f32_fp4 v[4:5], v148, 1.0 op_sel:[0,1,0]
	v_cvt_scalef32_pk_f32_fp4 v[6:7], v148, 1.0 op_sel:[1,1,0]
	v_cvt_scalef32_pk_f32_fp4 v[8:9], v149, 1.0
	v_cvt_scalef32_pk_f32_fp4 v[10:11], v149, 1.0 op_sel:[1,0,0]
	v_cvt_scalef32_pk_f32_fp4 v[12:13], v149, 1.0 op_sel:[0,1,0]
	v_cvt_scalef32_pk_f32_fp4 v[14:15], v149, 1.0 op_sel:[1,1,0]
	v_readlane_b32 s54, v90, 34
	s_lshl_b32 s56, s54, 9
	s_add_u32 s56, s64, s56
	s_addc_u32 s57, s65, 0
	global_load_dwordx2 v[148:149], v227, s[56:57]
	v_pk_fma_f32 v[130:131], v[0:1], s[0:1], v[130:131] op_sel_hi:[1,0,1]
	v_pk_fma_f32 v[138:139], v[2:3], s[0:1], v[138:139] op_sel_hi:[1,0,1]
	v_pk_fma_f32 v[140:141], v[4:5], s[0:1], v[140:141] op_sel_hi:[1,0,1]
	v_pk_fma_f32 v[142:143], v[6:7], s[0:1], v[142:143] op_sel_hi:[1,0,1]
	v_pk_fma_f32 v[128:129], v[8:9], s[0:1], v[128:129] op_sel_hi:[1,0,1]
	v_pk_fma_f32 v[132:133], v[10:11], s[0:1], v[132:133] op_sel_hi:[1,0,1]
	v_pk_fma_f32 v[134:135], v[12:13], s[0:1], v[134:135] op_sel_hi:[1,0,1]
	v_pk_fma_f32 v[136:137], v[14:15], s[0:1], v[136:137] op_sel_hi:[1,0,1]
	v_readlane_b32 s0, v167, 19
	s_waitcnt vmcnt(15)
	v_cvt_scalef32_pk_f32_fp4 v[0:1], v150, 1.0
	v_cvt_scalef32_pk_f32_fp4 v[2:3], v150, 1.0 op_sel:[1,0,0]
	v_cvt_scalef32_pk_f32_fp4 v[4:5], v150, 1.0 op_sel:[0,1,0]
	v_cvt_scalef32_pk_f32_fp4 v[6:7], v150, 1.0 op_sel:[1,1,0]
	v_cvt_scalef32_pk_f32_fp4 v[8:9], v151, 1.0
	v_cvt_scalef32_pk_f32_fp4 v[10:11], v151, 1.0 op_sel:[1,0,0]
	v_cvt_scalef32_pk_f32_fp4 v[12:13], v151, 1.0 op_sel:[0,1,0]
	v_cvt_scalef32_pk_f32_fp4 v[14:15], v151, 1.0 op_sel:[1,1,0]
	v_readlane_b32 s54, v90, 35
	s_lshl_b32 s56, s54, 9
	s_add_u32 s56, s64, s56
	s_addc_u32 s57, s65, 0
	global_load_dwordx2 v[150:151], v227, s[56:57]
	v_pk_fma_f32 v[130:131], v[0:1], s[0:1], v[130:131] op_sel_hi:[1,0,1]
	v_pk_fma_f32 v[138:139], v[2:3], s[0:1], v[138:139] op_sel_hi:[1,0,1]
	v_pk_fma_f32 v[140:141], v[4:5], s[0:1], v[140:141] op_sel_hi:[1,0,1]
	v_pk_fma_f32 v[142:143], v[6:7], s[0:1], v[142:143] op_sel_hi:[1,0,1]
	v_pk_fma_f32 v[128:129], v[8:9], s[0:1], v[128:129] op_sel_hi:[1,0,1]
	v_pk_fma_f32 v[132:133], v[10:11], s[0:1], v[132:133] op_sel_hi:[1,0,1]
	v_pk_fma_f32 v[134:135], v[12:13], s[0:1], v[134:135] op_sel_hi:[1,0,1]
	v_pk_fma_f32 v[136:137], v[14:15], s[0:1], v[136:137] op_sel_hi:[1,0,1]
	v_readlane_b32 s0, v167, 20
	s_waitcnt vmcnt(15)
; __device__ void peer_gather_phase(const Params& P, int l, bool do_store) {
;     ...
;         const uint2* up = (const uint2*)(U + (size_t)(uphi ? eb : ea) * 768);
;         u6[3 * pr] = up[0]; u6[3 * pr + 1] = up[1]; u6[3 * pr + 2] = up[2];
;         v8[2 * pr] = *(const uint2*)(V + (size_t)ea * 512);
;         v8[2 * pr + 1] = *(const uint2*)(V + (size_t)eb * 512);
;     ...
; #pragma unroll
;       for (int j = 0; j < 8; ++j) {
;         const float a = __builtin_bit_cast(float, __builtin_amdgcn_readlane(__builtin_bit_cast(int, avec), kb + j));
;         const f32x2 aa = f32x2{a, a};
;         y[0] += aa * __builtin_amdgcn_cvt_scalef32_pk_f32_fp4(v8[j].x, 1.0f, 0); y[1] += aa * __builtin_amdgcn_cvt_scalef32_pk_f32_fp4(v8[j].x, 1.0f, 1);
;         y[2] += aa * __builtin_amdgcn_cvt_scalef32_pk_f32_fp4(v8[j].x, 1.0f, 2); y[3] += aa * __builtin_amdgcn_cvt_scalef32_pk_f32_fp4(v8[j].x, 1.0f, 3);
;         y[4] += aa * __builtin_amdgcn_cvt_scalef32_pk_f32_fp4(v8[j].y, 1.0f, 0); y[5] += aa * __builtin_amdgcn_cvt_scalef32_pk_f32_fp4(v8[j].y, 1.0f, 1);
;         y[6] += aa * __builtin_amdgcn_cvt_scalef32_pk_f32_fp4(v8[j].y, 1.0f, 2); y[7] += aa * __builtin_amdgcn_cvt_scalef32_pk_f32_fp4(v8[j].y, 1.0f, 3);
;       }
	v_cvt_scalef32_pk_f32_fp4 v[0:1], v152, 1.0
	v_cvt_scalef32_pk_f32_fp4 v[2:3], v152, 1.0 op_sel:[1,0,0]
	v_cvt_scalef32_pk_f32_fp4 v[4:5], v152, 1.0 op_sel:[0,1,0]
	v_cvt_scalef32_pk_f32_fp4 v[6:7], v152, 1.0 op_sel:[1,1,0]
	v_cvt_scalef32_pk_f32_fp4 v[8:9], v153, 1.0
	v_cvt_scalef32_pk_f32_fp4 v[10:11], v153, 1.0 op_sel:[1,0,0]
	v_cvt_scalef32_pk_f32_fp4 v[12:13], v153, 1.0 op_sel:[0,1,0]
	v_cvt_scalef32_pk_f32_fp4 v[14:15], v153, 1.0 op_sel:[1,1,0]
	v_readlane_b32 s54, v90, 36
	s_lshl_b32 s56, s54, 9
	s_add_u32 s56, s64, s56
	s_addc_u32 s57, s65, 0
	global_load_dwordx2 v[152:153], v227, s[56:57]
	v_pk_fma_f32 v[130:131], v[0:1], s[0:1], v[130:131] op_sel_hi:[1,0,1]
	v_pk_fma_f32 v[138:139], v[2:3], s[0:1], v[138:139] op_sel_hi:[1,0,1]
	v_pk_fma_f32 v[140:141], v[4:5], s[0:1], v[140:141] op_sel_hi:[1,0,1]
	v_pk_fma_f32 v[142:143], v[6:7], s[0:1], v[142:143] op_sel_hi:[1,0,1]
	v_pk_fma_f32 v[128:129], v[8:9], s[0:1], v[128:129] op_sel_hi:[1,0,1]
	v_pk_fma_f32 v[132:133], v[10:11], s[0:1], v[132:133] op_sel_hi:[1,0,1]
	v_pk_fma_f32 v[134:135], v[12:13], s[0:1], v[134:135] op_sel_hi:[1,0,1]
	v_pk_fma_f32 v[136:137], v[14:15], s[0:1], v[136:137] op_sel_hi:[1,0,1]
	v_readlane_b32 s0, v167, 21
	s_waitcnt vmcnt(15)
	v_cvt_scalef32_pk_f32_fp4 v[0:1], v154, 1.0
	v_cvt_scalef32_pk_f32_fp4 v[2:3], v154, 1.0 op_sel:[1,0,0]
	v_cvt_scalef32_pk_f32_fp4 v[4:5], v154, 1.0 op_sel:[0,1,0]
	v_cvt_scalef32_pk_f32_fp4 v[6:7], v154, 1.0 op_sel:[1,1,0]
	v_cvt_scalef32_pk_f32_fp4 v[8:9], v155, 1.0
	v_cvt_scalef32_pk_f32_fp4 v[10:11], v155, 1.0 op_sel:[1,0,0]
	v_cvt_scalef32_pk_f32_fp4 v[12:13], v155, 1.0 op_sel:[0,1,0]
	v_cvt_scalef32_pk_f32_fp4 v[14:15], v155, 1.0 op_sel:[1,1,0]
	v_readlane_b32 s54, v90, 37
	s_lshl_b32 s56, s54, 9
	s_add_u32 s56, s64, s56
	s_addc_u32 s57, s65, 0
	global_load_dwordx2 v[154:155], v227, s[56:57]
	v_pk_fma_f32 v[130:131], v[0:1], s[0:1], v[130:131] op_sel_hi:[1,0,1]
	v_pk_fma_f32 v[138:139], v[2:3], s[0:1], v[138:139] op_sel_hi:[1,0,1]
	v_pk_fma_f32 v[140:141], v[4:5], s[0:1], v[140:141] op_sel_hi:[1,0,1]
	v_pk_fma_f32 v[142:143], v[6:7], s[0:1], v[142:143] op_sel_hi:[1,0,1]
	v_pk_fma_f32 v[128:129], v[8:9], s[0:1], v[128:129] op_sel_hi:[1,0,1]
	v_pk_fma_f32 v[132:133], v[10:11], s[0:1], v[132:133] op_sel_hi:[1,0,1]
	v_pk_fma_f32 v[134:135], v[12:13], s[0:1], v[134:135] op_sel_hi:[1,0,1]
	v_pk_fma_f32 v[136:137], v[14:15], s[0:1], v[136:137] op_sel_hi:[1,0,1]
	v_readlane_b32 s0, v167, 22
	s_waitcnt vmcnt(15)
	v_cvt_scalef32_pk_f32_fp4 v[0:1], v156, 1.0
	v_cvt_scalef32_pk_f32_fp4 v[2:3], v156, 1.0 op_sel:[1,0,0]
	v_cvt_scalef32_pk_f32_fp4 v[4:5], v156, 1.0 op_sel:[0,1,0]
	v_cvt_scalef32_pk_f32_fp4 v[6:7], v156, 1.0 op_sel:[1,1,0]
	v_cvt_scalef32_pk_f32_fp4 v[8:9], v157, 1.0
	v_cvt_scalef32_pk_f32_fp4 v[10:11], v157, 1.0 op_sel:[1,0,0]
	v_cvt_scalef32_pk_f32_fp4 v[12:13], v157, 1.0 op_sel:[0,1,0]
	v_cvt_scalef32_pk_f32_fp4 v[14:15], v157, 1.0 op_sel:[1,1,0]
	v_readlane_b32 s54, v90, 38
	s_lshl_b32 s56, s54, 9
	s_add_u32 s56, s64, s56
	s_addc_u32 s57, s65, 0
	global_load_dwordx2 v[156:157], v227, s[56:57]
	v_pk_fma_f32 v[130:131], v[0:1], s[0:1], v[130:131] op_sel_hi:[1,0,1]
	v_pk_fma_f32 v[138:139], v[2:3], s[0:1], v[138:139] op_sel_hi:[1,0,1]
	v_pk_fma_f32 v[140:141], v[4:5], s[0:1], v[140:141] op_sel_hi:[1,0,1]
	v_pk_fma_f32 v[142:143], v[6:7], s[0:1], v[142:143] op_sel_hi:[1,0,1]
	v_pk_fma_f32 v[128:129], v[8:9], s[0:1], v[128:129] op_sel_hi:[1,0,1]
	v_pk_fma_f32 v[132:133], v[10:11], s[0:1], v[132:133] op_sel_hi:[1,0,1]
	v_pk_fma_f32 v[134:135], v[12:13], s[0:1], v[134:135] op_sel_hi:[1,0,1]
	v_pk_fma_f32 v[136:137], v[14:15], s[0:1], v[136:137] op_sel_hi:[1,0,1]
	v_readlane_b32 s0, v167, 23
	s_waitcnt vmcnt(15)
	v_cvt_scalef32_pk_f32_fp4 v[0:1], v158, 1.0
	v_cvt_scalef32_pk_f32_fp4 v[2:3], v158, 1.0 op_sel:[1,0,0]
	v_cvt_scalef32_pk_f32_fp4 v[4:5], v158, 1.0 op_sel:[0,1,0]
	v_cvt_scalef32_pk_f32_fp4 v[6:7], v158, 1.0 op_sel:[1,1,0]
	v_cvt_scalef32_pk_f32_fp4 v[8:9], v159, 1.0
	v_cvt_scalef32_pk_f32_fp4 v[10:11], v159, 1.0 op_sel:[1,0,0]
	v_cvt_scalef32_pk_f32_fp4 v[12:13], v159, 1.0 op_sel:[0,1,0]
	v_cvt_scalef32_pk_f32_fp4 v[14:15], v159, 1.0 op_sel:[1,1,0]
	v_readlane_b32 s54, v90, 39
	s_lshl_b32 s56, s54, 9
	s_add_u32 s56, s64, s56
	s_addc_u32 s57, s65, 0
	global_load_dwordx2 v[158:159], v227, s[56:57]
	v_pk_fma_f32 v[130:131], v[0:1], s[0:1], v[130:131] op_sel_hi:[1,0,1]
	v_pk_fma_f32 v[138:139], v[2:3], s[0:1], v[138:139] op_sel_hi:[1,0,1]
	v_pk_fma_f32 v[140:141], v[4:5], s[0:1], v[140:141] op_sel_hi:[1,0,1]
	v_pk_fma_f32 v[142:143], v[6:7], s[0:1], v[142:143] op_sel_hi:[1,0,1]
	v_pk_fma_f32 v[128:129], v[8:9], s[0:1], v[128:129] op_sel_hi:[1,0,1]
	v_pk_fma_f32 v[132:133], v[10:11], s[0:1], v[132:133] op_sel_hi:[1,0,1]
	v_pk_fma_f32 v[134:135], v[12:13], s[0:1], v[134:135] op_sel_hi:[1,0,1]
	v_pk_fma_f32 v[136:137], v[14:15], s[0:1], v[136:137] op_sel_hi:[1,0,1]
	v_readlane_b32 s0, v167, 24
	s_waitcnt vmcnt(15)
	v_cvt_scalef32_pk_f32_fp4 v[0:1], v168, 1.0
	v_cvt_scalef32_pk_f32_fp4 v[2:3], v168, 1.0 op_sel:[1,0,0]
	v_cvt_scalef32_pk_f32_fp4 v[4:5], v168, 1.0 op_sel:[0,1,0]
	v_cvt_scalef32_pk_f32_fp4 v[6:7], v168, 1.0 op_sel:[1,1,0]
	v_cvt_scalef32_pk_f32_fp4 v[8:9], v169, 1.0
	v_cvt_scalef32_pk_f32_fp4 v[10:11], v169, 1.0 op_sel:[1,0,0]
	v_cvt_scalef32_pk_f32_fp4 v[12:13], v169, 1.0 op_sel:[0,1,0]
	v_cvt_scalef32_pk_f32_fp4 v[14:15], v169, 1.0 op_sel:[1,1,0]
	v_readlane_b32 s54, v90, 40
	s_lshl_b32 s56, s54, 9
	s_add_u32 s56, s64, s56
	s_addc_u32 s57, s65, 0
	global_load_dwordx2 v[168:169], v227, s[56:57]
	v_pk_fma_f32 v[130:131], v[0:1], s[0:1], v[130:131] op_sel_hi:[1,0,1]
	v_pk_fma_f32 v[138:139], v[2:3], s[0:1], v[138:139] op_sel_hi:[1,0,1]
	v_pk_fma_f32 v[140:141], v[4:5], s[0:1], v[140:141] op_sel_hi:[1,0,1]
	v_pk_fma_f32 v[142:143], v[6:7], s[0:1], v[142:143] op_sel_hi:[1,0,1]
	v_pk_fma_f32 v[128:129], v[8:9], s[0:1], v[128:129] op_sel_hi:[1,0,1]
	v_pk_fma_f32 v[132:133], v[10:11], s[0:1], v[132:133] op_sel_hi:[1,0,1]
	v_pk_fma_f32 v[134:135], v[12:13], s[0:1], v[134:135] op_sel_hi:[1,0,1]
	v_pk_fma_f32 v[136:137], v[14:15], s[0:1], v[136:137] op_sel_hi:[1,0,1]
	v_readlane_b32 s0, v167, 25
	s_waitcnt vmcnt(15)
; __device__ void peer_gather_phase(const Params& P, int l, bool do_store) {
;     ...
;         const uint2* up = (const uint2*)(U + (size_t)(uphi ? eb : ea) * 768);
;         u6[3 * pr] = up[0]; u6[3 * pr + 1] = up[1]; u6[3 * pr + 2] = up[2];
;         v8[2 * pr] = *(const uint2*)(V + (size_t)ea * 512);
;         v8[2 * pr + 1] = *(const uint2*)(V + (size_t)eb * 512);
;     ...
; #pragma unroll
;       for (int j = 0; j < 8; ++j) {
;         const float a = __builtin_bit_cast(float, __builtin_amdgcn_readlane(__builtin_bit_cast(int, avec), kb + j));
;         const f32x2 aa = f32x2{a, a};
;         y[0] += aa * __builtin_amdgcn_cvt_scalef32_pk_f32_fp4(v8[j].x, 1.0f, 0); y[1] += aa * __builtin_amdgcn_cvt_scalef32_pk_f32_fp4(v8[j].x, 1.0f, 1);
;         y[2] += aa * __builtin_amdgcn_cvt_scalef32_pk_f32_fp4(v8[j].x, 1.0f, 2); y[3] += aa * __builtin_amdgcn_cvt_scalef32_pk_f32_fp4(v8[j].x, 1.0f, 3);
;         y[4] += aa * __builtin_amdgcn_cvt_scalef32_pk_f32_fp4(v8[j].y, 1.0f, 0); y[5] += aa * __builtin_amdgcn_cvt_scalef32_pk_f32_fp4(v8[j].y, 1.0f, 1);
;         y[6] += aa * __builtin_amdgcn_cvt_scalef32_pk_f32_fp4(v8[j].y, 1.0f, 2); y[7] += aa * __builtin_amdgcn_cvt_scalef32_pk_f32_fp4(v8[j].y, 1.0f, 3);
;       }
	v_cvt_scalef32_pk_f32_fp4 v[0:1], v170, 1.0
	v_cvt_scalef32_pk_f32_fp4 v[2:3], v170, 1.0 op_sel:[1,0,0]
	v_cvt_scalef32_pk_f32_fp4 v[4:5], v170, 1.0 op_sel:[0,1,0]
	v_cvt_scalef32_pk_f32_fp4 v[6:7], v170, 1.0 op_sel:[1,1,0]
	v_cvt_scalef32_pk_f32_fp4 v[8:9], v171, 1.0
	v_cvt_scalef32_pk_f32_fp4 v[10:11], v171, 1.0 op_sel:[1,0,0]
	v_cvt_scalef32_pk_f32_fp4 v[12:13], v171, 1.0 op_sel:[0,1,0]
	v_cvt_scalef32_pk_f32_fp4 v[14:15], v171, 1.0 op_sel:[1,1,0]
	v_readlane_b32 s54, v90, 41
	s_lshl_b32 s56, s54, 9
	s_add_u32 s56, s64, s56
	s_addc_u32 s57, s65, 0
	global_load_dwordx2 v[170:171], v227, s[56:57]
	v_pk_fma_f32 v[130:131], v[0:1], s[0:1], v[130:131] op_sel_hi:[1,0,1]
	v_pk_fma_f32 v[138:139], v[2:3], s[0:1], v[138:139] op_sel_hi:[1,0,1]
	v_pk_fma_f32 v[140:141], v[4:5], s[0:1], v[140:141] op_sel_hi:[1,0,1]
	v_pk_fma_f32 v[142:143], v[6:7], s[0:1], v[142:143] op_sel_hi:[1,0,1]
	v_pk_fma_f32 v[128:129], v[8:9], s[0:1], v[128:129] op_sel_hi:[1,0,1]
	v_pk_fma_f32 v[132:133], v[10:11], s[0:1], v[132:133] op_sel_hi:[1,0,1]
	v_pk_fma_f32 v[134:135], v[12:13], s[0:1], v[134:135] op_sel_hi:[1,0,1]
	v_pk_fma_f32 v[136:137], v[14:15], s[0:1], v[136:137] op_sel_hi:[1,0,1]
	v_readlane_b32 s0, v167, 26
	s_waitcnt vmcnt(15)
	v_cvt_scalef32_pk_f32_fp4 v[0:1], v172, 1.0
	v_cvt_scalef32_pk_f32_fp4 v[2:3], v172, 1.0 op_sel:[1,0,0]
	v_cvt_scalef32_pk_f32_fp4 v[4:5], v172, 1.0 op_sel:[0,1,0]
	v_cvt_scalef32_pk_f32_fp4 v[6:7], v172, 1.0 op_sel:[1,1,0]
	v_cvt_scalef32_pk_f32_fp4 v[8:9], v173, 1.0
	v_cvt_scalef32_pk_f32_fp4 v[10:11], v173, 1.0 op_sel:[1,0,0]
	v_cvt_scalef32_pk_f32_fp4 v[12:13], v173, 1.0 op_sel:[0,1,0]
	v_cvt_scalef32_pk_f32_fp4 v[14:15], v173, 1.0 op_sel:[1,1,0]
	v_readlane_b32 s54, v90, 42
	s_lshl_b32 s56, s54, 9
	s_add_u32 s56, s64, s56
	s_addc_u32 s57, s65, 0
	global_load_dwordx2 v[172:173], v227, s[56:57]
	v_pk_fma_f32 v[130:131], v[0:1], s[0:1], v[130:131] op_sel_hi:[1,0,1]
	v_pk_fma_f32 v[138:139], v[2:3], s[0:1], v[138:139] op_sel_hi:[1,0,1]
	v_pk_fma_f32 v[140:141], v[4:5], s[0:1], v[140:141] op_sel_hi:[1,0,1]
	v_pk_fma_f32 v[142:143], v[6:7], s[0:1], v[142:143] op_sel_hi:[1,0,1]
	v_pk_fma_f32 v[128:129], v[8:9], s[0:1], v[128:129] op_sel_hi:[1,0,1]
	v_pk_fma_f32 v[132:133], v[10:11], s[0:1], v[132:133] op_sel_hi:[1,0,1]
	v_pk_fma_f32 v[134:135], v[12:13], s[0:1], v[134:135] op_sel_hi:[1,0,1]
	v_pk_fma_f32 v[136:137], v[14:15], s[0:1], v[136:137] op_sel_hi:[1,0,1]
	v_readlane_b32 s0, v167, 27
	s_waitcnt vmcnt(15)
	v_cvt_scalef32_pk_f32_fp4 v[0:1], v174, 1.0
	v_cvt_scalef32_pk_f32_fp4 v[2:3], v174, 1.0 op_sel:[1,0,0]
	v_cvt_scalef32_pk_f32_fp4 v[4:5], v174, 1.0 op_sel:[0,1,0]
	v_cvt_scalef32_pk_f32_fp4 v[6:7], v174, 1.0 op_sel:[1,1,0]
	v_cvt_scalef32_pk_f32_fp4 v[8:9], v175, 1.0
	v_cvt_scalef32_pk_f32_fp4 v[10:11], v175, 1.0 op_sel:[1,0,0]
	v_cvt_scalef32_pk_f32_fp4 v[12:13], v175, 1.0 op_sel:[0,1,0]
	v_cvt_scalef32_pk_f32_fp4 v[14:15], v175, 1.0 op_sel:[1,1,0]
	v_readlane_b32 s54, v90, 43
	s_lshl_b32 s56, s54, 9
	s_add_u32 s56, s64, s56
	s_addc_u32 s57, s65, 0
	global_load_dwordx2 v[174:175], v227, s[56:57]
	v_pk_fma_f32 v[130:131], v[0:1], s[0:1], v[130:131] op_sel_hi:[1,0,1]
	v_pk_fma_f32 v[138:139], v[2:3], s[0:1], v[138:139] op_sel_hi:[1,0,1]
	v_pk_fma_f32 v[140:141], v[4:5], s[0:1], v[140:141] op_sel_hi:[1,0,1]
	v_pk_fma_f32 v[142:143], v[6:7], s[0:1], v[142:143] op_sel_hi:[1,0,1]
	v_pk_fma_f32 v[128:129], v[8:9], s[0:1], v[128:129] op_sel_hi:[1,0,1]
	v_pk_fma_f32 v[132:133], v[10:11], s[0:1], v[132:133] op_sel_hi:[1,0,1]
	v_pk_fma_f32 v[134:135], v[12:13], s[0:1], v[134:135] op_sel_hi:[1,0,1]
	v_pk_fma_f32 v[136:137], v[14:15], s[0:1], v[136:137] op_sel_hi:[1,0,1]
	v_readlane_b32 s0, v167, 28
	s_waitcnt vmcnt(15)
	v_cvt_scalef32_pk_f32_fp4 v[0:1], v180, 1.0
	v_cvt_scalef32_pk_f32_fp4 v[2:3], v180, 1.0 op_sel:[1,0,0]
	v_cvt_scalef32_pk_f32_fp4 v[4:5], v180, 1.0 op_sel:[0,1,0]
	v_cvt_scalef32_pk_f32_fp4 v[6:7], v180, 1.0 op_sel:[1,1,0]
	v_cvt_scalef32_pk_f32_fp4 v[8:9], v181, 1.0
	v_cvt_scalef32_pk_f32_fp4 v[10:11], v181, 1.0 op_sel:[1,0,0]
	v_cvt_scalef32_pk_f32_fp4 v[12:13], v181, 1.0 op_sel:[0,1,0]
	v_cvt_scalef32_pk_f32_fp4 v[14:15], v181, 1.0 op_sel:[1,1,0]
	v_readlane_b32 s54, v90, 44
	s_lshl_b32 s56, s54, 9
	s_add_u32 s56, s64, s56
	s_addc_u32 s57, s65, 0
	global_load_dwordx2 v[180:181], v227, s[56:57]
	v_pk_fma_f32 v[130:131], v[0:1], s[0:1], v[130:131] op_sel_hi:[1,0,1]
	v_pk_fma_f32 v[138:139], v[2:3], s[0:1], v[138:139] op_sel_hi:[1,0,1]
	v_pk_fma_f32 v[140:141], v[4:5], s[0:1], v[140:141] op_sel_hi:[1,0,1]
	v_pk_fma_f32 v[142:143], v[6:7], s[0:1], v[142:143] op_sel_hi:[1,0,1]
	v_pk_fma_f32 v[128:129], v[8:9], s[0:1], v[128:129] op_sel_hi:[1,0,1]
	v_pk_fma_f32 v[132:133], v[10:11], s[0:1], v[132:133] op_sel_hi:[1,0,1]
	v_pk_fma_f32 v[134:135], v[12:13], s[0:1], v[134:135] op_sel_hi:[1,0,1]
	v_pk_fma_f32 v[136:137], v[14:15], s[0:1], v[136:137] op_sel_hi:[1,0,1]
	v_readlane_b32 s0, v167, 29
	s_waitcnt vmcnt(15)
	v_cvt_scalef32_pk_f32_fp4 v[0:1], v182, 1.0
	v_cvt_scalef32_pk_f32_fp4 v[2:3], v182, 1.0 op_sel:[1,0,0]
	v_cvt_scalef32_pk_f32_fp4 v[4:5], v182, 1.0 op_sel:[0,1,0]
	v_cvt_scalef32_pk_f32_fp4 v[6:7], v182, 1.0 op_sel:[1,1,0]
	v_cvt_scalef32_pk_f32_fp4 v[8:9], v183, 1.0
	v_cvt_scalef32_pk_f32_fp4 v[10:11], v183, 1.0 op_sel:[1,0,0]
	v_cvt_scalef32_pk_f32_fp4 v[12:13], v183, 1.0 op_sel:[0,1,0]
	v_cvt_scalef32_pk_f32_fp4 v[14:15], v183, 1.0 op_sel:[1,1,0]
	v_readlane_b32 s54, v90, 45
	s_lshl_b32 s56, s54, 9
	s_add_u32 s56, s64, s56
	s_addc_u32 s57, s65, 0
	global_load_dwordx2 v[182:183], v227, s[56:57]
	v_pk_fma_f32 v[130:131], v[0:1], s[0:1], v[130:131] op_sel_hi:[1,0,1]
	v_pk_fma_f32 v[138:139], v[2:3], s[0:1], v[138:139] op_sel_hi:[1,0,1]
	v_pk_fma_f32 v[140:141], v[4:5], s[0:1], v[140:141] op_sel_hi:[1,0,1]
	v_pk_fma_f32 v[142:143], v[6:7], s[0:1], v[142:143] op_sel_hi:[1,0,1]
	v_pk_fma_f32 v[128:129], v[8:9], s[0:1], v[128:129] op_sel_hi:[1,0,1]
	v_pk_fma_f32 v[132:133], v[10:11], s[0:1], v[132:133] op_sel_hi:[1,0,1]
	v_pk_fma_f32 v[134:135], v[12:13], s[0:1], v[134:135] op_sel_hi:[1,0,1]
	v_pk_fma_f32 v[136:137], v[14:15], s[0:1], v[136:137] op_sel_hi:[1,0,1]
	v_readlane_b32 s0, v167, 30
	s_waitcnt vmcnt(15)
; __device__ void peer_gather_phase(const Params& P, int l, bool do_store) {
;     ...
;         const uint2* up = (const uint2*)(U + (size_t)(uphi ? eb : ea) * 768);
;         u6[3 * pr] = up[0]; u6[3 * pr + 1] = up[1]; u6[3 * pr + 2] = up[2];
;         v8[2 * pr] = *(const uint2*)(V + (size_t)ea * 512);
;         v8[2 * pr + 1] = *(const uint2*)(V + (size_t)eb * 512);
;     ...
; #pragma unroll
;       for (int j = 0; j < 8; ++j) {
;         const float a = __builtin_bit_cast(float, __builtin_amdgcn_readlane(__builtin_bit_cast(int, avec), kb + j));
;         const f32x2 aa = f32x2{a, a};
;         y[0] += aa * __builtin_amdgcn_cvt_scalef32_pk_f32_fp4(v8[j].x, 1.0f, 0); y[1] += aa * __builtin_amdgcn_cvt_scalef32_pk_f32_fp4(v8[j].x, 1.0f, 1);
;         y[2] += aa * __builtin_amdgcn_cvt_scalef32_pk_f32_fp4(v8[j].x, 1.0f, 2); y[3] += aa * __builtin_amdgcn_cvt_scalef32_pk_f32_fp4(v8[j].x, 1.0f, 3);
;         y[4] += aa * __builtin_amdgcn_cvt_scalef32_pk_f32_fp4(v8[j].y, 1.0f, 0); y[5] += aa * __builtin_amdgcn_cvt_scalef32_pk_f32_fp4(v8[j].y, 1.0f, 1);
;         y[6] += aa * __builtin_amdgcn_cvt_scalef32_pk_f32_fp4(v8[j].y, 1.0f, 2); y[7] += aa * __builtin_amdgcn_cvt_scalef32_pk_f32_fp4(v8[j].y, 1.0f, 3);
;       }
	v_cvt_scalef32_pk_f32_fp4 v[0:1], v184, 1.0
	v_cvt_scalef32_pk_f32_fp4 v[2:3], v184, 1.0 op_sel:[1,0,0]
	v_cvt_scalef32_pk_f32_fp4 v[4:5], v184, 1.0 op_sel:[0,1,0]
	v_cvt_scalef32_pk_f32_fp4 v[6:7], v184, 1.0 op_sel:[1,1,0]
	v_cvt_scalef32_pk_f32_fp4 v[8:9], v185, 1.0
	v_cvt_scalef32_pk_f32_fp4 v[10:11], v185, 1.0 op_sel:[1,0,0]
	v_cvt_scalef32_pk_f32_fp4 v[12:13], v185, 1.0 op_sel:[0,1,0]
	v_cvt_scalef32_pk_f32_fp4 v[14:15], v185, 1.0 op_sel:[1,1,0]
	v_readlane_b32 s54, v90, 46
	s_lshl_b32 s56, s54, 9
	s_add_u32 s56, s64, s56
	s_addc_u32 s57, s65, 0
	global_load_dwordx2 v[184:185], v227, s[56:57]
	v_pk_fma_f32 v[130:131], v[0:1], s[0:1], v[130:131] op_sel_hi:[1,0,1]
	v_pk_fma_f32 v[138:139], v[2:3], s[0:1], v[138:139] op_sel_hi:[1,0,1]
	v_pk_fma_f32 v[140:141], v[4:5], s[0:1], v[140:141] op_sel_hi:[1,0,1]
	v_pk_fma_f32 v[142:143], v[6:7], s[0:1], v[142:143] op_sel_hi:[1,0,1]
	v_pk_fma_f32 v[128:129], v[8:9], s[0:1], v[128:129] op_sel_hi:[1,0,1]
	v_pk_fma_f32 v[132:133], v[10:11], s[0:1], v[132:133] op_sel_hi:[1,0,1]
	v_pk_fma_f32 v[134:135], v[12:13], s[0:1], v[134:135] op_sel_hi:[1,0,1]
	v_pk_fma_f32 v[136:137], v[14:15], s[0:1], v[136:137] op_sel_hi:[1,0,1]
	v_readlane_b32 s0, v167, 31
	s_waitcnt vmcnt(15)
	v_cvt_scalef32_pk_f32_fp4 v[0:1], v186, 1.0
	v_cvt_scalef32_pk_f32_fp4 v[2:3], v186, 1.0 op_sel:[1,0,0]
	v_cvt_scalef32_pk_f32_fp4 v[4:5], v186, 1.0 op_sel:[0,1,0]
	v_cvt_scalef32_pk_f32_fp4 v[6:7], v186, 1.0 op_sel:[1,1,0]
	v_cvt_scalef32_pk_f32_fp4 v[8:9], v187, 1.0
	v_cvt_scalef32_pk_f32_fp4 v[10:11], v187, 1.0 op_sel:[1,0,0]
	v_cvt_scalef32_pk_f32_fp4 v[12:13], v187, 1.0 op_sel:[0,1,0]
	v_cvt_scalef32_pk_f32_fp4 v[14:15], v187, 1.0 op_sel:[1,1,0]
	v_readlane_b32 s54, v90, 47
	s_lshl_b32 s56, s54, 9
	s_add_u32 s56, s64, s56
	s_addc_u32 s57, s65, 0
	global_load_dwordx2 v[186:187], v227, s[56:57]
	v_pk_fma_f32 v[130:131], v[0:1], s[0:1], v[130:131] op_sel_hi:[1,0,1]
	v_pk_fma_f32 v[138:139], v[2:3], s[0:1], v[138:139] op_sel_hi:[1,0,1]
	v_pk_fma_f32 v[140:141], v[4:5], s[0:1], v[140:141] op_sel_hi:[1,0,1]
	v_pk_fma_f32 v[142:143], v[6:7], s[0:1], v[142:143] op_sel_hi:[1,0,1]
	v_pk_fma_f32 v[128:129], v[8:9], s[0:1], v[128:129] op_sel_hi:[1,0,1]
	v_pk_fma_f32 v[132:133], v[10:11], s[0:1], v[132:133] op_sel_hi:[1,0,1]
	v_pk_fma_f32 v[134:135], v[12:13], s[0:1], v[134:135] op_sel_hi:[1,0,1]
	v_pk_fma_f32 v[136:137], v[14:15], s[0:1], v[136:137] op_sel_hi:[1,0,1]
	v_readlane_b32 s0, v167, 32
	s_waitcnt vmcnt(15)
	v_cvt_scalef32_pk_f32_fp4 v[0:1], v144, 1.0
	v_cvt_scalef32_pk_f32_fp4 v[2:3], v144, 1.0 op_sel:[1,0,0]
	v_cvt_scalef32_pk_f32_fp4 v[4:5], v144, 1.0 op_sel:[0,1,0]
	v_cvt_scalef32_pk_f32_fp4 v[6:7], v144, 1.0 op_sel:[1,1,0]
	v_cvt_scalef32_pk_f32_fp4 v[8:9], v145, 1.0
	v_cvt_scalef32_pk_f32_fp4 v[10:11], v145, 1.0 op_sel:[1,0,0]
	v_cvt_scalef32_pk_f32_fp4 v[12:13], v145, 1.0 op_sel:[0,1,0]
	v_cvt_scalef32_pk_f32_fp4 v[14:15], v145, 1.0 op_sel:[1,1,0]
	v_readlane_b32 s54, v90, 48
	s_lshl_b32 s56, s54, 9
	s_add_u32 s56, s64, s56
	s_addc_u32 s57, s65, 0
	global_load_dwordx2 v[144:145], v227, s[56:57]
	v_pk_fma_f32 v[130:131], v[0:1], s[0:1], v[130:131] op_sel_hi:[1,0,1]
	v_pk_fma_f32 v[138:139], v[2:3], s[0:1], v[138:139] op_sel_hi:[1,0,1]
	v_pk_fma_f32 v[140:141], v[4:5], s[0:1], v[140:141] op_sel_hi:[1,0,1]
	v_pk_fma_f32 v[142:143], v[6:7], s[0:1], v[142:143] op_sel_hi:[1,0,1]
	v_pk_fma_f32 v[128:129], v[8:9], s[0:1], v[128:129] op_sel_hi:[1,0,1]
	v_pk_fma_f32 v[132:133], v[10:11], s[0:1], v[132:133] op_sel_hi:[1,0,1]
	v_pk_fma_f32 v[134:135], v[12:13], s[0:1], v[134:135] op_sel_hi:[1,0,1]
	v_pk_fma_f32 v[136:137], v[14:15], s[0:1], v[136:137] op_sel_hi:[1,0,1]
	v_readlane_b32 s0, v167, 33
	s_waitcnt vmcnt(15)
	v_cvt_scalef32_pk_f32_fp4 v[0:1], v146, 1.0
	v_cvt_scalef32_pk_f32_fp4 v[2:3], v146, 1.0 op_sel:[1,0,0]
	v_cvt_scalef32_pk_f32_fp4 v[4:5], v146, 1.0 op_sel:[0,1,0]
	v_cvt_scalef32_pk_f32_fp4 v[6:7], v146, 1.0 op_sel:[1,1,0]
	v_cvt_scalef32_pk_f32_fp4 v[8:9], v147, 1.0
	v_cvt_scalef32_pk_f32_fp4 v[10:11], v147, 1.0 op_sel:[1,0,0]
	v_cvt_scalef32_pk_f32_fp4 v[12:13], v147, 1.0 op_sel:[0,1,0]
	v_cvt_scalef32_pk_f32_fp4 v[14:15], v147, 1.0 op_sel:[1,1,0]
	v_readlane_b32 s54, v90, 49
	s_lshl_b32 s56, s54, 9
	s_add_u32 s56, s64, s56
	s_addc_u32 s57, s65, 0
	global_load_dwordx2 v[146:147], v227, s[56:57]
	v_pk_fma_f32 v[130:131], v[0:1], s[0:1], v[130:131] op_sel_hi:[1,0,1]
	v_pk_fma_f32 v[138:139], v[2:3], s[0:1], v[138:139] op_sel_hi:[1,0,1]
	v_pk_fma_f32 v[140:141], v[4:5], s[0:1], v[140:141] op_sel_hi:[1,0,1]
	v_pk_fma_f32 v[142:143], v[6:7], s[0:1], v[142:143] op_sel_hi:[1,0,1]
	v_pk_fma_f32 v[128:129], v[8:9], s[0:1], v[128:129] op_sel_hi:[1,0,1]
	v_pk_fma_f32 v[132:133], v[10:11], s[0:1], v[132:133] op_sel_hi:[1,0,1]
	v_pk_fma_f32 v[134:135], v[12:13], s[0:1], v[134:135] op_sel_hi:[1,0,1]
	v_pk_fma_f32 v[136:137], v[14:15], s[0:1], v[136:137] op_sel_hi:[1,0,1]
	v_readlane_b32 s0, v167, 34
	s_waitcnt vmcnt(15)
	v_cvt_scalef32_pk_f32_fp4 v[0:1], v148, 1.0
	v_cvt_scalef32_pk_f32_fp4 v[2:3], v148, 1.0 op_sel:[1,0,0]
	v_cvt_scalef32_pk_f32_fp4 v[4:5], v148, 1.0 op_sel:[0,1,0]
	v_cvt_scalef32_pk_f32_fp4 v[6:7], v148, 1.0 op_sel:[1,1,0]
	v_cvt_scalef32_pk_f32_fp4 v[8:9], v149, 1.0
	v_cvt_scalef32_pk_f32_fp4 v[10:11], v149, 1.0 op_sel:[1,0,0]
	v_cvt_scalef32_pk_f32_fp4 v[12:13], v149, 1.0 op_sel:[0,1,0]
	v_cvt_scalef32_pk_f32_fp4 v[14:15], v149, 1.0 op_sel:[1,1,0]
	v_readlane_b32 s54, v90, 50
	s_lshl_b32 s56, s54, 9
	s_add_u32 s56, s64, s56
	s_addc_u32 s57, s65, 0
	global_load_dwordx2 v[148:149], v227, s[56:57]
	v_pk_fma_f32 v[130:131], v[0:1], s[0:1], v[130:131] op_sel_hi:[1,0,1]
	v_pk_fma_f32 v[138:139], v[2:3], s[0:1], v[138:139] op_sel_hi:[1,0,1]
	v_pk_fma_f32 v[140:141], v[4:5], s[0:1], v[140:141] op_sel_hi:[1,0,1]
	v_pk_fma_f32 v[142:143], v[6:7], s[0:1], v[142:143] op_sel_hi:[1,0,1]
	v_pk_fma_f32 v[128:129], v[8:9], s[0:1], v[128:129] op_sel_hi:[1,0,1]
	v_pk_fma_f32 v[132:133], v[10:11], s[0:1], v[132:133] op_sel_hi:[1,0,1]
	v_pk_fma_f32 v[134:135], v[12:13], s[0:1], v[134:135] op_sel_hi:[1,0,1]
	v_pk_fma_f32 v[136:137], v[14:15], s[0:1], v[136:137] op_sel_hi:[1,0,1]
	v_readlane_b32 s0, v167, 35
	s_waitcnt vmcnt(15)
; __device__ void peer_gather_phase(const Params& P, int l, bool do_store) {
;     ...
;         const uint2* up = (const uint2*)(U + (size_t)(uphi ? eb : ea) * 768);
;         u6[3 * pr] = up[0]; u6[3 * pr + 1] = up[1]; u6[3 * pr + 2] = up[2];
;         v8[2 * pr] = *(const uint2*)(V + (size_t)ea * 512);
;         v8[2 * pr + 1] = *(const uint2*)(V + (size_t)eb * 512);
;     ...
; #pragma unroll
;       for (int j = 0; j < 8; ++j) {
;         const float a = __builtin_bit_cast(float, __builtin_amdgcn_readlane(__builtin_bit_cast(int, avec), kb + j));
;         const f32x2 aa = f32x2{a, a};
;         y[0] += aa * __builtin_amdgcn_cvt_scalef32_pk_f32_fp4(v8[j].x, 1.0f, 0); y[1] += aa * __builtin_amdgcn_cvt_scalef32_pk_f32_fp4(v8[j].x, 1.0f, 1);
;         y[2] += aa * __builtin_amdgcn_cvt_scalef32_pk_f32_fp4(v8[j].x, 1.0f, 2); y[3] += aa * __builtin_amdgcn_cvt_scalef32_pk_f32_fp4(v8[j].x, 1.0f, 3);
;         y[4] += aa * __builtin_amdgcn_cvt_scalef32_pk_f32_fp4(v8[j].y, 1.0f, 0); y[5] += aa * __builtin_amdgcn_cvt_scalef32_pk_f32_fp4(v8[j].y, 1.0f, 1);
;         y[6] += aa * __builtin_amdgcn_cvt_scalef32_pk_f32_fp4(v8[j].y, 1.0f, 2); y[7] += aa * __builtin_amdgcn_cvt_scalef32_pk_f32_fp4(v8[j].y, 1.0f, 3);
;       }
	v_cvt_scalef32_pk_f32_fp4 v[0:1], v150, 1.0
	v_cvt_scalef32_pk_f32_fp4 v[2:3], v150, 1.0 op_sel:[1,0,0]
	v_cvt_scalef32_pk_f32_fp4 v[4:5], v150, 1.0 op_sel:[0,1,0]
	v_cvt_scalef32_pk_f32_fp4 v[6:7], v150, 1.0 op_sel:[1,1,0]
	v_cvt_scalef32_pk_f32_fp4 v[8:9], v151, 1.0
	v_cvt_scalef32_pk_f32_fp4 v[10:11], v151, 1.0 op_sel:[1,0,0]
	v_cvt_scalef32_pk_f32_fp4 v[12:13], v151, 1.0 op_sel:[0,1,0]
	v_cvt_scalef32_pk_f32_fp4 v[14:15], v151, 1.0 op_sel:[1,1,0]
	v_readlane_b32 s54, v90, 51
	s_lshl_b32 s56, s54, 9
	s_add_u32 s56, s64, s56
	s_addc_u32 s57, s65, 0
	global_load_dwordx2 v[150:151], v227, s[56:57]
	v_pk_fma_f32 v[130:131], v[0:1], s[0:1], v[130:131] op_sel_hi:[1,0,1]
	v_pk_fma_f32 v[138:139], v[2:3], s[0:1], v[138:139] op_sel_hi:[1,0,1]
	v_pk_fma_f32 v[140:141], v[4:5], s[0:1], v[140:141] op_sel_hi:[1,0,1]
	v_pk_fma_f32 v[142:143], v[6:7], s[0:1], v[142:143] op_sel_hi:[1,0,1]
	v_pk_fma_f32 v[128:129], v[8:9], s[0:1], v[128:129] op_sel_hi:[1,0,1]
	v_pk_fma_f32 v[132:133], v[10:11], s[0:1], v[132:133] op_sel_hi:[1,0,1]
	v_pk_fma_f32 v[134:135], v[12:13], s[0:1], v[134:135] op_sel_hi:[1,0,1]
	v_pk_fma_f32 v[136:137], v[14:15], s[0:1], v[136:137] op_sel_hi:[1,0,1]
	v_readlane_b32 s0, v167, 36
	s_waitcnt vmcnt(15)
	v_cvt_scalef32_pk_f32_fp4 v[0:1], v152, 1.0
	v_cvt_scalef32_pk_f32_fp4 v[2:3], v152, 1.0 op_sel:[1,0,0]
	v_cvt_scalef32_pk_f32_fp4 v[4:5], v152, 1.0 op_sel:[0,1,0]
	v_cvt_scalef32_pk_f32_fp4 v[6:7], v152, 1.0 op_sel:[1,1,0]
	v_cvt_scalef32_pk_f32_fp4 v[8:9], v153, 1.0
	v_cvt_scalef32_pk_f32_fp4 v[10:11], v153, 1.0 op_sel:[1,0,0]
	v_cvt_scalef32_pk_f32_fp4 v[12:13], v153, 1.0 op_sel:[0,1,0]
	v_cvt_scalef32_pk_f32_fp4 v[14:15], v153, 1.0 op_sel:[1,1,0]
	v_readlane_b32 s54, v90, 52
	s_lshl_b32 s56, s54, 9
	s_add_u32 s56, s64, s56
	s_addc_u32 s57, s65, 0
	global_load_dwordx2 v[152:153], v227, s[56:57]
	v_pk_fma_f32 v[130:131], v[0:1], s[0:1], v[130:131] op_sel_hi:[1,0,1]
	v_pk_fma_f32 v[138:139], v[2:3], s[0:1], v[138:139] op_sel_hi:[1,0,1]
	v_pk_fma_f32 v[140:141], v[4:5], s[0:1], v[140:141] op_sel_hi:[1,0,1]
	v_pk_fma_f32 v[142:143], v[6:7], s[0:1], v[142:143] op_sel_hi:[1,0,1]
	v_pk_fma_f32 v[128:129], v[8:9], s[0:1], v[128:129] op_sel_hi:[1,0,1]
	v_pk_fma_f32 v[132:133], v[10:11], s[0:1], v[132:133] op_sel_hi:[1,0,1]
	v_pk_fma_f32 v[134:135], v[12:13], s[0:1], v[134:135] op_sel_hi:[1,0,1]
	v_pk_fma_f32 v[136:137], v[14:15], s[0:1], v[136:137] op_sel_hi:[1,0,1]
	v_readlane_b32 s0, v167, 37
	s_waitcnt vmcnt(15)
	v_cvt_scalef32_pk_f32_fp4 v[0:1], v154, 1.0
	v_cvt_scalef32_pk_f32_fp4 v[2:3], v154, 1.0 op_sel:[1,0,0]
	v_cvt_scalef32_pk_f32_fp4 v[4:5], v154, 1.0 op_sel:[0,1,0]
	v_cvt_scalef32_pk_f32_fp4 v[6:7], v154, 1.0 op_sel:[1,1,0]
	v_cvt_scalef32_pk_f32_fp4 v[8:9], v155, 1.0
	v_cvt_scalef32_pk_f32_fp4 v[10:11], v155, 1.0 op_sel:[1,0,0]
	v_cvt_scalef32_pk_f32_fp4 v[12:13], v155, 1.0 op_sel:[0,1,0]
	v_cvt_scalef32_pk_f32_fp4 v[14:15], v155, 1.0 op_sel:[1,1,0]
	v_readlane_b32 s54, v90, 53
	s_lshl_b32 s56, s54, 9
	s_add_u32 s56, s64, s56
	s_addc_u32 s57, s65, 0
	global_load_dwordx2 v[154:155], v227, s[56:57]
	v_pk_fma_f32 v[130:131], v[0:1], s[0:1], v[130:131] op_sel_hi:[1,0,1]
	v_pk_fma_f32 v[138:139], v[2:3], s[0:1], v[138:139] op_sel_hi:[1,0,1]
	v_pk_fma_f32 v[140:141], v[4:5], s[0:1], v[140:141] op_sel_hi:[1,0,1]
	v_pk_fma_f32 v[142:143], v[6:7], s[0:1], v[142:143] op_sel_hi:[1,0,1]
	v_pk_fma_f32 v[128:129], v[8:9], s[0:1], v[128:129] op_sel_hi:[1,0,1]
	v_pk_fma_f32 v[132:133], v[10:11], s[0:1], v[132:133] op_sel_hi:[1,0,1]
	v_pk_fma_f32 v[134:135], v[12:13], s[0:1], v[134:135] op_sel_hi:[1,0,1]
	v_pk_fma_f32 v[136:137], v[14:15], s[0:1], v[136:137] op_sel_hi:[1,0,1]
	v_readlane_b32 s0, v167, 38
	s_waitcnt vmcnt(15)
	v_cvt_scalef32_pk_f32_fp4 v[0:1], v156, 1.0
	v_cvt_scalef32_pk_f32_fp4 v[2:3], v156, 1.0 op_sel:[1,0,0]
	v_cvt_scalef32_pk_f32_fp4 v[4:5], v156, 1.0 op_sel:[0,1,0]
	v_cvt_scalef32_pk_f32_fp4 v[6:7], v156, 1.0 op_sel:[1,1,0]
	v_cvt_scalef32_pk_f32_fp4 v[8:9], v157, 1.0
	v_cvt_scalef32_pk_f32_fp4 v[10:11], v157, 1.0 op_sel:[1,0,0]
	v_cvt_scalef32_pk_f32_fp4 v[12:13], v157, 1.0 op_sel:[0,1,0]
	v_cvt_scalef32_pk_f32_fp4 v[14:15], v157, 1.0 op_sel:[1,1,0]
	v_readlane_b32 s54, v90, 54
	s_lshl_b32 s56, s54, 9
	s_add_u32 s56, s64, s56
	s_addc_u32 s57, s65, 0
	global_load_dwordx2 v[156:157], v227, s[56:57]
	v_pk_fma_f32 v[130:131], v[0:1], s[0:1], v[130:131] op_sel_hi:[1,0,1]
	v_pk_fma_f32 v[138:139], v[2:3], s[0:1], v[138:139] op_sel_hi:[1,0,1]
	v_pk_fma_f32 v[140:141], v[4:5], s[0:1], v[140:141] op_sel_hi:[1,0,1]
	v_pk_fma_f32 v[142:143], v[6:7], s[0:1], v[142:143] op_sel_hi:[1,0,1]
	v_pk_fma_f32 v[128:129], v[8:9], s[0:1], v[128:129] op_sel_hi:[1,0,1]
	v_pk_fma_f32 v[132:133], v[10:11], s[0:1], v[132:133] op_sel_hi:[1,0,1]
	v_pk_fma_f32 v[134:135], v[12:13], s[0:1], v[134:135] op_sel_hi:[1,0,1]
	v_pk_fma_f32 v[136:137], v[14:15], s[0:1], v[136:137] op_sel_hi:[1,0,1]
	v_readlane_b32 s0, v167, 39
	s_waitcnt vmcnt(15)
	v_cvt_scalef32_pk_f32_fp4 v[0:1], v158, 1.0
	v_cvt_scalef32_pk_f32_fp4 v[2:3], v158, 1.0 op_sel:[1,0,0]
	v_cvt_scalef32_pk_f32_fp4 v[4:5], v158, 1.0 op_sel:[0,1,0]
	v_cvt_scalef32_pk_f32_fp4 v[6:7], v158, 1.0 op_sel:[1,1,0]
	v_cvt_scalef32_pk_f32_fp4 v[8:9], v159, 1.0
	v_cvt_scalef32_pk_f32_fp4 v[10:11], v159, 1.0 op_sel:[1,0,0]
	v_cvt_scalef32_pk_f32_fp4 v[12:13], v159, 1.0 op_sel:[0,1,0]
	v_cvt_scalef32_pk_f32_fp4 v[14:15], v159, 1.0 op_sel:[1,1,0]
	v_readlane_b32 s54, v90, 55
	s_lshl_b32 s56, s54, 9
	s_add_u32 s56, s64, s56
	s_addc_u32 s57, s65, 0
	global_load_dwordx2 v[158:159], v227, s[56:57]
	v_pk_fma_f32 v[130:131], v[0:1], s[0:1], v[130:131] op_sel_hi:[1,0,1]
	v_pk_fma_f32 v[138:139], v[2:3], s[0:1], v[138:139] op_sel_hi:[1,0,1]
	v_pk_fma_f32 v[140:141], v[4:5], s[0:1], v[140:141] op_sel_hi:[1,0,1]
	v_pk_fma_f32 v[142:143], v[6:7], s[0:1], v[142:143] op_sel_hi:[1,0,1]
	v_pk_fma_f32 v[128:129], v[8:9], s[0:1], v[128:129] op_sel_hi:[1,0,1]
	v_pk_fma_f32 v[132:133], v[10:11], s[0:1], v[132:133] op_sel_hi:[1,0,1]
	v_pk_fma_f32 v[134:135], v[12:13], s[0:1], v[134:135] op_sel_hi:[1,0,1]
	v_pk_fma_f32 v[136:137], v[14:15], s[0:1], v[136:137] op_sel_hi:[1,0,1]
	v_readlane_b32 s0, v167, 40
	s_waitcnt vmcnt(15)
; __device__ void peer_gather_phase(const Params& P, int l, bool do_store) {
;     ...
;         const uint2* up = (const uint2*)(U + (size_t)(uphi ? eb : ea) * 768);
;         u6[3 * pr] = up[0]; u6[3 * pr + 1] = up[1]; u6[3 * pr + 2] = up[2];
;         v8[2 * pr] = *(const uint2*)(V + (size_t)ea * 512);
;         v8[2 * pr + 1] = *(const uint2*)(V + (size_t)eb * 512);
;     ...
; #pragma unroll
;       for (int j = 0; j < 8; ++j) {
;         const float a = __builtin_bit_cast(float, __builtin_amdgcn_readlane(__builtin_bit_cast(int, avec), kb + j));
;         const f32x2 aa = f32x2{a, a};
;         y[0] += aa * __builtin_amdgcn_cvt_scalef32_pk_f32_fp4(v8[j].x, 1.0f, 0); y[1] += aa * __builtin_amdgcn_cvt_scalef32_pk_f32_fp4(v8[j].x, 1.0f, 1);
;         y[2] += aa * __builtin_amdgcn_cvt_scalef32_pk_f32_fp4(v8[j].x, 1.0f, 2); y[3] += aa * __builtin_amdgcn_cvt_scalef32_pk_f32_fp4(v8[j].x, 1.0f, 3);
;         y[4] += aa * __builtin_amdgcn_cvt_scalef32_pk_f32_fp4(v8[j].y, 1.0f, 0); y[5] += aa * __builtin_amdgcn_cvt_scalef32_pk_f32_fp4(v8[j].y, 1.0f, 1);
;         y[6] += aa * __builtin_amdgcn_cvt_scalef32_pk_f32_fp4(v8[j].y, 1.0f, 2); y[7] += aa * __builtin_amdgcn_cvt_scalef32_pk_f32_fp4(v8[j].y, 1.0f, 3);
;       }
	v_cvt_scalef32_pk_f32_fp4 v[0:1], v168, 1.0
	v_cvt_scalef32_pk_f32_fp4 v[2:3], v168, 1.0 op_sel:[1,0,0]
	v_cvt_scalef32_pk_f32_fp4 v[4:5], v168, 1.0 op_sel:[0,1,0]
	v_cvt_scalef32_pk_f32_fp4 v[6:7], v168, 1.0 op_sel:[1,1,0]
	v_cvt_scalef32_pk_f32_fp4 v[8:9], v169, 1.0
	v_cvt_scalef32_pk_f32_fp4 v[10:11], v169, 1.0 op_sel:[1,0,0]
	v_cvt_scalef32_pk_f32_fp4 v[12:13], v169, 1.0 op_sel:[0,1,0]
	v_cvt_scalef32_pk_f32_fp4 v[14:15], v169, 1.0 op_sel:[1,1,0]
	v_readlane_b32 s54, v90, 56
	s_lshl_b32 s56, s54, 9
	s_add_u32 s56, s64, s56
	s_addc_u32 s57, s65, 0
	global_load_dwordx2 v[168:169], v227, s[56:57]
	v_pk_fma_f32 v[130:131], v[0:1], s[0:1], v[130:131] op_sel_hi:[1,0,1]
	v_pk_fma_f32 v[138:139], v[2:3], s[0:1], v[138:139] op_sel_hi:[1,0,1]
	v_pk_fma_f32 v[140:141], v[4:5], s[0:1], v[140:141] op_sel_hi:[1,0,1]
	v_pk_fma_f32 v[142:143], v[6:7], s[0:1], v[142:143] op_sel_hi:[1,0,1]
	v_pk_fma_f32 v[128:129], v[8:9], s[0:1], v[128:129] op_sel_hi:[1,0,1]
	v_pk_fma_f32 v[132:133], v[10:11], s[0:1], v[132:133] op_sel_hi:[1,0,1]
	v_pk_fma_f32 v[134:135], v[12:13], s[0:1], v[134:135] op_sel_hi:[1,0,1]
	v_pk_fma_f32 v[136:137], v[14:15], s[0:1], v[136:137] op_sel_hi:[1,0,1]
	v_readlane_b32 s0, v167, 41
	s_waitcnt vmcnt(15)
	v_cvt_scalef32_pk_f32_fp4 v[0:1], v170, 1.0
	v_cvt_scalef32_pk_f32_fp4 v[2:3], v170, 1.0 op_sel:[1,0,0]
	v_cvt_scalef32_pk_f32_fp4 v[4:5], v170, 1.0 op_sel:[0,1,0]
	v_cvt_scalef32_pk_f32_fp4 v[6:7], v170, 1.0 op_sel:[1,1,0]
	v_cvt_scalef32_pk_f32_fp4 v[8:9], v171, 1.0
	v_cvt_scalef32_pk_f32_fp4 v[10:11], v171, 1.0 op_sel:[1,0,0]
	v_cvt_scalef32_pk_f32_fp4 v[12:13], v171, 1.0 op_sel:[0,1,0]
	v_cvt_scalef32_pk_f32_fp4 v[14:15], v171, 1.0 op_sel:[1,1,0]
	v_readlane_b32 s54, v90, 57
	s_lshl_b32 s56, s54, 9
	s_add_u32 s56, s64, s56
	s_addc_u32 s57, s65, 0
	global_load_dwordx2 v[170:171], v227, s[56:57]
	v_pk_fma_f32 v[130:131], v[0:1], s[0:1], v[130:131] op_sel_hi:[1,0,1]
	v_pk_fma_f32 v[138:139], v[2:3], s[0:1], v[138:139] op_sel_hi:[1,0,1]
	v_pk_fma_f32 v[140:141], v[4:5], s[0:1], v[140:141] op_sel_hi:[1,0,1]
	v_pk_fma_f32 v[142:143], v[6:7], s[0:1], v[142:143] op_sel_hi:[1,0,1]
	v_pk_fma_f32 v[128:129], v[8:9], s[0:1], v[128:129] op_sel_hi:[1,0,1]
	v_pk_fma_f32 v[132:133], v[10:11], s[0:1], v[132:133] op_sel_hi:[1,0,1]
	v_pk_fma_f32 v[134:135], v[12:13], s[0:1], v[134:135] op_sel_hi:[1,0,1]
	v_pk_fma_f32 v[136:137], v[14:15], s[0:1], v[136:137] op_sel_hi:[1,0,1]
	v_readlane_b32 s0, v167, 42
	s_waitcnt vmcnt(15)
	v_cvt_scalef32_pk_f32_fp4 v[0:1], v172, 1.0
	v_cvt_scalef32_pk_f32_fp4 v[2:3], v172, 1.0 op_sel:[1,0,0]
	v_cvt_scalef32_pk_f32_fp4 v[4:5], v172, 1.0 op_sel:[0,1,0]
	v_cvt_scalef32_pk_f32_fp4 v[6:7], v172, 1.0 op_sel:[1,1,0]
	v_cvt_scalef32_pk_f32_fp4 v[8:9], v173, 1.0
	v_cvt_scalef32_pk_f32_fp4 v[10:11], v173, 1.0 op_sel:[1,0,0]
	v_cvt_scalef32_pk_f32_fp4 v[12:13], v173, 1.0 op_sel:[0,1,0]
	v_cvt_scalef32_pk_f32_fp4 v[14:15], v173, 1.0 op_sel:[1,1,0]
	v_readlane_b32 s54, v90, 58
	s_lshl_b32 s56, s54, 9
	s_add_u32 s56, s64, s56
	s_addc_u32 s57, s65, 0
	global_load_dwordx2 v[172:173], v227, s[56:57]
	v_pk_fma_f32 v[130:131], v[0:1], s[0:1], v[130:131] op_sel_hi:[1,0,1]
	v_pk_fma_f32 v[138:139], v[2:3], s[0:1], v[138:139] op_sel_hi:[1,0,1]
	v_pk_fma_f32 v[140:141], v[4:5], s[0:1], v[140:141] op_sel_hi:[1,0,1]
	v_pk_fma_f32 v[142:143], v[6:7], s[0:1], v[142:143] op_sel_hi:[1,0,1]
	v_pk_fma_f32 v[128:129], v[8:9], s[0:1], v[128:129] op_sel_hi:[1,0,1]
	v_pk_fma_f32 v[132:133], v[10:11], s[0:1], v[132:133] op_sel_hi:[1,0,1]
	v_pk_fma_f32 v[134:135], v[12:13], s[0:1], v[134:135] op_sel_hi:[1,0,1]
	v_pk_fma_f32 v[136:137], v[14:15], s[0:1], v[136:137] op_sel_hi:[1,0,1]
	v_readlane_b32 s0, v167, 43
	s_waitcnt vmcnt(15)
	v_cvt_scalef32_pk_f32_fp4 v[0:1], v174, 1.0
	v_cvt_scalef32_pk_f32_fp4 v[2:3], v174, 1.0 op_sel:[1,0,0]
	v_cvt_scalef32_pk_f32_fp4 v[4:5], v174, 1.0 op_sel:[0,1,0]
	v_cvt_scalef32_pk_f32_fp4 v[6:7], v174, 1.0 op_sel:[1,1,0]
	v_cvt_scalef32_pk_f32_fp4 v[8:9], v175, 1.0
	v_cvt_scalef32_pk_f32_fp4 v[10:11], v175, 1.0 op_sel:[1,0,0]
	v_cvt_scalef32_pk_f32_fp4 v[12:13], v175, 1.0 op_sel:[0,1,0]
	v_cvt_scalef32_pk_f32_fp4 v[14:15], v175, 1.0 op_sel:[1,1,0]
	v_readlane_b32 s54, v90, 59
	s_lshl_b32 s56, s54, 9
	s_add_u32 s56, s64, s56
	s_addc_u32 s57, s65, 0
	global_load_dwordx2 v[174:175], v227, s[56:57]
	v_pk_fma_f32 v[130:131], v[0:1], s[0:1], v[130:131] op_sel_hi:[1,0,1]
	v_pk_fma_f32 v[138:139], v[2:3], s[0:1], v[138:139] op_sel_hi:[1,0,1]
	v_pk_fma_f32 v[140:141], v[4:5], s[0:1], v[140:141] op_sel_hi:[1,0,1]
	v_pk_fma_f32 v[142:143], v[6:7], s[0:1], v[142:143] op_sel_hi:[1,0,1]
	v_pk_fma_f32 v[128:129], v[8:9], s[0:1], v[128:129] op_sel_hi:[1,0,1]
	v_pk_fma_f32 v[132:133], v[10:11], s[0:1], v[132:133] op_sel_hi:[1,0,1]
	v_pk_fma_f32 v[134:135], v[12:13], s[0:1], v[134:135] op_sel_hi:[1,0,1]
	v_pk_fma_f32 v[136:137], v[14:15], s[0:1], v[136:137] op_sel_hi:[1,0,1]
	v_readlane_b32 s0, v167, 44
	s_waitcnt vmcnt(15)
	v_cvt_scalef32_pk_f32_fp4 v[0:1], v180, 1.0
	v_cvt_scalef32_pk_f32_fp4 v[2:3], v180, 1.0 op_sel:[1,0,0]
	v_cvt_scalef32_pk_f32_fp4 v[4:5], v180, 1.0 op_sel:[0,1,0]
	v_cvt_scalef32_pk_f32_fp4 v[6:7], v180, 1.0 op_sel:[1,1,0]
	v_cvt_scalef32_pk_f32_fp4 v[8:9], v181, 1.0
	v_cvt_scalef32_pk_f32_fp4 v[10:11], v181, 1.0 op_sel:[1,0,0]
	v_cvt_scalef32_pk_f32_fp4 v[12:13], v181, 1.0 op_sel:[0,1,0]
	v_cvt_scalef32_pk_f32_fp4 v[14:15], v181, 1.0 op_sel:[1,1,0]
	v_readlane_b32 s54, v90, 60
	s_lshl_b32 s56, s54, 9
	s_add_u32 s56, s64, s56
	s_addc_u32 s57, s65, 0
	global_load_dwordx2 v[180:181], v227, s[56:57]
	v_pk_fma_f32 v[130:131], v[0:1], s[0:1], v[130:131] op_sel_hi:[1,0,1]
	v_pk_fma_f32 v[138:139], v[2:3], s[0:1], v[138:139] op_sel_hi:[1,0,1]
	v_pk_fma_f32 v[140:141], v[4:5], s[0:1], v[140:141] op_sel_hi:[1,0,1]
	v_pk_fma_f32 v[142:143], v[6:7], s[0:1], v[142:143] op_sel_hi:[1,0,1]
	v_pk_fma_f32 v[128:129], v[8:9], s[0:1], v[128:129] op_sel_hi:[1,0,1]
	v_pk_fma_f32 v[132:133], v[10:11], s[0:1], v[132:133] op_sel_hi:[1,0,1]
	v_pk_fma_f32 v[134:135], v[12:13], s[0:1], v[134:135] op_sel_hi:[1,0,1]
	v_pk_fma_f32 v[136:137], v[14:15], s[0:1], v[136:137] op_sel_hi:[1,0,1]
	v_readlane_b32 s0, v167, 45
	s_waitcnt vmcnt(15)
; __device__ void peer_gather_phase(const Params& P, int l, bool do_store) {
;     ...
;         const uint2* up = (const uint2*)(U + (size_t)(uphi ? eb : ea) * 768);
;         u6[3 * pr] = up[0]; u6[3 * pr + 1] = up[1]; u6[3 * pr + 2] = up[2];
;         v8[2 * pr] = *(const uint2*)(V + (size_t)ea * 512);
;         v8[2 * pr + 1] = *(const uint2*)(V + (size_t)eb * 512);
;     ...
; #pragma unroll
;       for (int j = 0; j < 8; ++j) {
;         const float a = __builtin_bit_cast(float, __builtin_amdgcn_readlane(__builtin_bit_cast(int, avec), kb + j));
;         const f32x2 aa = f32x2{a, a};
;         y[0] += aa * __builtin_amdgcn_cvt_scalef32_pk_f32_fp4(v8[j].x, 1.0f, 0); y[1] += aa * __builtin_amdgcn_cvt_scalef32_pk_f32_fp4(v8[j].x, 1.0f, 1);
;         y[2] += aa * __builtin_amdgcn_cvt_scalef32_pk_f32_fp4(v8[j].x, 1.0f, 2); y[3] += aa * __builtin_amdgcn_cvt_scalef32_pk_f32_fp4(v8[j].x, 1.0f, 3);
;         y[4] += aa * __builtin_amdgcn_cvt_scalef32_pk_f32_fp4(v8[j].y, 1.0f, 0); y[5] += aa * __builtin_amdgcn_cvt_scalef32_pk_f32_fp4(v8[j].y, 1.0f, 1);
;         y[6] += aa * __builtin_amdgcn_cvt_scalef32_pk_f32_fp4(v8[j].y, 1.0f, 2); y[7] += aa * __builtin_amdgcn_cvt_scalef32_pk_f32_fp4(v8[j].y, 1.0f, 3);
;       }
	v_cvt_scalef32_pk_f32_fp4 v[0:1], v182, 1.0
	v_cvt_scalef32_pk_f32_fp4 v[2:3], v182, 1.0 op_sel:[1,0,0]
	v_cvt_scalef32_pk_f32_fp4 v[4:5], v182, 1.0 op_sel:[0,1,0]
	v_cvt_scalef32_pk_f32_fp4 v[6:7], v182, 1.0 op_sel:[1,1,0]
	v_cvt_scalef32_pk_f32_fp4 v[8:9], v183, 1.0
	v_cvt_scalef32_pk_f32_fp4 v[10:11], v183, 1.0 op_sel:[1,0,0]
	v_cvt_scalef32_pk_f32_fp4 v[12:13], v183, 1.0 op_sel:[0,1,0]
	v_cvt_scalef32_pk_f32_fp4 v[14:15], v183, 1.0 op_sel:[1,1,0]
	v_readlane_b32 s54, v90, 61
	s_lshl_b32 s56, s54, 9
	s_add_u32 s56, s64, s56
	s_addc_u32 s57, s65, 0
	global_load_dwordx2 v[182:183], v227, s[56:57]
	v_pk_fma_f32 v[130:131], v[0:1], s[0:1], v[130:131] op_sel_hi:[1,0,1]
	v_pk_fma_f32 v[138:139], v[2:3], s[0:1], v[138:139] op_sel_hi:[1,0,1]
	v_pk_fma_f32 v[140:141], v[4:5], s[0:1], v[140:141] op_sel_hi:[1,0,1]
	v_pk_fma_f32 v[142:143], v[6:7], s[0:1], v[142:143] op_sel_hi:[1,0,1]
	v_pk_fma_f32 v[128:129], v[8:9], s[0:1], v[128:129] op_sel_hi:[1,0,1]
	v_pk_fma_f32 v[132:133], v[10:11], s[0:1], v[132:133] op_sel_hi:[1,0,1]
	v_pk_fma_f32 v[134:135], v[12:13], s[0:1], v[134:135] op_sel_hi:[1,0,1]
	v_pk_fma_f32 v[136:137], v[14:15], s[0:1], v[136:137] op_sel_hi:[1,0,1]
	v_readlane_b32 s0, v167, 46
	s_waitcnt vmcnt(15)
	v_cvt_scalef32_pk_f32_fp4 v[0:1], v184, 1.0
	v_cvt_scalef32_pk_f32_fp4 v[2:3], v184, 1.0 op_sel:[1,0,0]
	v_cvt_scalef32_pk_f32_fp4 v[4:5], v184, 1.0 op_sel:[0,1,0]
	v_cvt_scalef32_pk_f32_fp4 v[6:7], v184, 1.0 op_sel:[1,1,0]
	v_cvt_scalef32_pk_f32_fp4 v[8:9], v185, 1.0
	v_cvt_scalef32_pk_f32_fp4 v[10:11], v185, 1.0 op_sel:[1,0,0]
	v_cvt_scalef32_pk_f32_fp4 v[12:13], v185, 1.0 op_sel:[0,1,0]
	v_cvt_scalef32_pk_f32_fp4 v[14:15], v185, 1.0 op_sel:[1,1,0]
	v_readlane_b32 s54, v90, 62
	s_lshl_b32 s56, s54, 9
	s_add_u32 s56, s64, s56
	s_addc_u32 s57, s65, 0
	global_load_dwordx2 v[184:185], v227, s[56:57]
	v_pk_fma_f32 v[130:131], v[0:1], s[0:1], v[130:131] op_sel_hi:[1,0,1]
	v_pk_fma_f32 v[138:139], v[2:3], s[0:1], v[138:139] op_sel_hi:[1,0,1]
	v_pk_fma_f32 v[140:141], v[4:5], s[0:1], v[140:141] op_sel_hi:[1,0,1]
	v_pk_fma_f32 v[142:143], v[6:7], s[0:1], v[142:143] op_sel_hi:[1,0,1]
	v_pk_fma_f32 v[128:129], v[8:9], s[0:1], v[128:129] op_sel_hi:[1,0,1]
	v_pk_fma_f32 v[132:133], v[10:11], s[0:1], v[132:133] op_sel_hi:[1,0,1]
	v_pk_fma_f32 v[134:135], v[12:13], s[0:1], v[134:135] op_sel_hi:[1,0,1]
	v_pk_fma_f32 v[136:137], v[14:15], s[0:1], v[136:137] op_sel_hi:[1,0,1]
	v_readlane_b32 s0, v167, 47
	s_waitcnt vmcnt(15)
	v_cvt_scalef32_pk_f32_fp4 v[0:1], v186, 1.0
	v_cvt_scalef32_pk_f32_fp4 v[2:3], v186, 1.0 op_sel:[1,0,0]
	v_cvt_scalef32_pk_f32_fp4 v[4:5], v186, 1.0 op_sel:[0,1,0]
	v_cvt_scalef32_pk_f32_fp4 v[6:7], v186, 1.0 op_sel:[1,1,0]
	v_cvt_scalef32_pk_f32_fp4 v[8:9], v187, 1.0
	v_cvt_scalef32_pk_f32_fp4 v[10:11], v187, 1.0 op_sel:[1,0,0]
	v_cvt_scalef32_pk_f32_fp4 v[12:13], v187, 1.0 op_sel:[0,1,0]
	v_cvt_scalef32_pk_f32_fp4 v[14:15], v187, 1.0 op_sel:[1,1,0]
	v_readlane_b32 s54, v90, 63
	s_lshl_b32 s56, s54, 9
	s_add_u32 s56, s64, s56
	s_addc_u32 s57, s65, 0
	global_load_dwordx2 v[186:187], v227, s[56:57]
	v_pk_fma_f32 v[130:131], v[0:1], s[0:1], v[130:131] op_sel_hi:[1,0,1]
	v_pk_fma_f32 v[138:139], v[2:3], s[0:1], v[138:139] op_sel_hi:[1,0,1]
	v_pk_fma_f32 v[140:141], v[4:5], s[0:1], v[140:141] op_sel_hi:[1,0,1]
	v_pk_fma_f32 v[142:143], v[6:7], s[0:1], v[142:143] op_sel_hi:[1,0,1]
	v_pk_fma_f32 v[128:129], v[8:9], s[0:1], v[128:129] op_sel_hi:[1,0,1]
	v_pk_fma_f32 v[132:133], v[10:11], s[0:1], v[132:133] op_sel_hi:[1,0,1]
	v_pk_fma_f32 v[134:135], v[12:13], s[0:1], v[134:135] op_sel_hi:[1,0,1]
	v_pk_fma_f32 v[136:137], v[14:15], s[0:1], v[136:137] op_sel_hi:[1,0,1]
	v_readlane_b32 s0, v167, 48
	s_waitcnt vmcnt(15)
	v_cvt_scalef32_pk_f32_fp4 v[0:1], v144, 1.0
	v_cvt_scalef32_pk_f32_fp4 v[2:3], v144, 1.0 op_sel:[1,0,0]
	v_cvt_scalef32_pk_f32_fp4 v[4:5], v144, 1.0 op_sel:[0,1,0]
	v_cvt_scalef32_pk_f32_fp4 v[6:7], v144, 1.0 op_sel:[1,1,0]
	v_cvt_scalef32_pk_f32_fp4 v[8:9], v145, 1.0
	v_cvt_scalef32_pk_f32_fp4 v[10:11], v145, 1.0 op_sel:[1,0,0]
	v_cvt_scalef32_pk_f32_fp4 v[12:13], v145, 1.0 op_sel:[0,1,0]
	v_cvt_scalef32_pk_f32_fp4 v[14:15], v145, 1.0 op_sel:[1,1,0]
	v_pk_fma_f32 v[130:131], v[0:1], s[0:1], v[130:131] op_sel_hi:[1,0,1]
	v_pk_fma_f32 v[138:139], v[2:3], s[0:1], v[138:139] op_sel_hi:[1,0,1]
	v_pk_fma_f32 v[140:141], v[4:5], s[0:1], v[140:141] op_sel_hi:[1,0,1]
	v_pk_fma_f32 v[142:143], v[6:7], s[0:1], v[142:143] op_sel_hi:[1,0,1]
	v_pk_fma_f32 v[128:129], v[8:9], s[0:1], v[128:129] op_sel_hi:[1,0,1]
	v_pk_fma_f32 v[132:133], v[10:11], s[0:1], v[132:133] op_sel_hi:[1,0,1]
	v_pk_fma_f32 v[134:135], v[12:13], s[0:1], v[134:135] op_sel_hi:[1,0,1]
	v_pk_fma_f32 v[136:137], v[14:15], s[0:1], v[136:137] op_sel_hi:[1,0,1]
	v_readlane_b32 s0, v167, 49
	s_waitcnt vmcnt(14)
	v_cvt_scalef32_pk_f32_fp4 v[0:1], v146, 1.0
	v_cvt_scalef32_pk_f32_fp4 v[2:3], v146, 1.0 op_sel:[1,0,0]
	v_cvt_scalef32_pk_f32_fp4 v[4:5], v146, 1.0 op_sel:[0,1,0]
	v_cvt_scalef32_pk_f32_fp4 v[6:7], v146, 1.0 op_sel:[1,1,0]
	v_cvt_scalef32_pk_f32_fp4 v[8:9], v147, 1.0
	v_cvt_scalef32_pk_f32_fp4 v[10:11], v147, 1.0 op_sel:[1,0,0]
	v_cvt_scalef32_pk_f32_fp4 v[12:13], v147, 1.0 op_sel:[0,1,0]
	v_cvt_scalef32_pk_f32_fp4 v[14:15], v147, 1.0 op_sel:[1,1,0]
	v_pk_fma_f32 v[130:131], v[0:1], s[0:1], v[130:131] op_sel_hi:[1,0,1]
	v_pk_fma_f32 v[138:139], v[2:3], s[0:1], v[138:139] op_sel_hi:[1,0,1]
	v_pk_fma_f32 v[140:141], v[4:5], s[0:1], v[140:141] op_sel_hi:[1,0,1]
	v_pk_fma_f32 v[142:143], v[6:7], s[0:1], v[142:143] op_sel_hi:[1,0,1]
	v_pk_fma_f32 v[128:129], v[8:9], s[0:1], v[128:129] op_sel_hi:[1,0,1]
	v_pk_fma_f32 v[132:133], v[10:11], s[0:1], v[132:133] op_sel_hi:[1,0,1]
	v_pk_fma_f32 v[134:135], v[12:13], s[0:1], v[134:135] op_sel_hi:[1,0,1]
	v_pk_fma_f32 v[136:137], v[14:15], s[0:1], v[136:137] op_sel_hi:[1,0,1]
	v_readlane_b32 s0, v167, 50
	s_waitcnt vmcnt(13)
; __device__ void peer_gather_phase(const Params& P, int l, bool do_store) {
;     ...
; #pragma unroll
;       for (int j = 0; j < 8; ++j) {
;         const float a = __builtin_bit_cast(float, __builtin_amdgcn_readlane(__builtin_bit_cast(int, avec), kb + j));
;         const f32x2 aa = f32x2{a, a};
;         y[0] += aa * __builtin_amdgcn_cvt_scalef32_pk_f32_fp4(v8[j].x, 1.0f, 0); y[1] += aa * __builtin_amdgcn_cvt_scalef32_pk_f32_fp4(v8[j].x, 1.0f, 1);
;         y[2] += aa * __builtin_amdgcn_cvt_scalef32_pk_f32_fp4(v8[j].x, 1.0f, 2); y[3] += aa * __builtin_amdgcn_cvt_scalef32_pk_f32_fp4(v8[j].x, 1.0f, 3);
;         y[4] += aa * __builtin_amdgcn_cvt_scalef32_pk_f32_fp4(v8[j].y, 1.0f, 0); y[5] += aa * __builtin_amdgcn_cvt_scalef32_pk_f32_fp4(v8[j].y, 1.0f, 1);
;         y[6] += aa * __builtin_amdgcn_cvt_scalef32_pk_f32_fp4(v8[j].y, 1.0f, 2); y[7] += aa * __builtin_amdgcn_cvt_scalef32_pk_f32_fp4(v8[j].y, 1.0f, 3);
;       }
	v_cvt_scalef32_pk_f32_fp4 v[0:1], v148, 1.0
	v_cvt_scalef32_pk_f32_fp4 v[2:3], v148, 1.0 op_sel:[1,0,0]
	v_cvt_scalef32_pk_f32_fp4 v[4:5], v148, 1.0 op_sel:[0,1,0]
	v_cvt_scalef32_pk_f32_fp4 v[6:7], v148, 1.0 op_sel:[1,1,0]
	v_cvt_scalef32_pk_f32_fp4 v[8:9], v149, 1.0
	v_cvt_scalef32_pk_f32_fp4 v[10:11], v149, 1.0 op_sel:[1,0,0]
	v_cvt_scalef32_pk_f32_fp4 v[12:13], v149, 1.0 op_sel:[0,1,0]
	v_cvt_scalef32_pk_f32_fp4 v[14:15], v149, 1.0 op_sel:[1,1,0]
	v_pk_fma_f32 v[130:131], v[0:1], s[0:1], v[130:131] op_sel_hi:[1,0,1]
	v_pk_fma_f32 v[138:139], v[2:3], s[0:1], v[138:139] op_sel_hi:[1,0,1]
	v_pk_fma_f32 v[140:141], v[4:5], s[0:1], v[140:141] op_sel_hi:[1,0,1]
	v_pk_fma_f32 v[142:143], v[6:7], s[0:1], v[142:143] op_sel_hi:[1,0,1]
	v_pk_fma_f32 v[128:129], v[8:9], s[0:1], v[128:129] op_sel_hi:[1,0,1]
	v_pk_fma_f32 v[132:133], v[10:11], s[0:1], v[132:133] op_sel_hi:[1,0,1]
	v_pk_fma_f32 v[134:135], v[12:13], s[0:1], v[134:135] op_sel_hi:[1,0,1]
	v_pk_fma_f32 v[136:137], v[14:15], s[0:1], v[136:137] op_sel_hi:[1,0,1]
	v_readlane_b32 s0, v167, 51
	s_waitcnt vmcnt(12)
	v_cvt_scalef32_pk_f32_fp4 v[0:1], v150, 1.0
	v_cvt_scalef32_pk_f32_fp4 v[2:3], v150, 1.0 op_sel:[1,0,0]
	v_cvt_scalef32_pk_f32_fp4 v[4:5], v150, 1.0 op_sel:[0,1,0]
	v_cvt_scalef32_pk_f32_fp4 v[6:7], v150, 1.0 op_sel:[1,1,0]
	v_cvt_scalef32_pk_f32_fp4 v[8:9], v151, 1.0
	v_cvt_scalef32_pk_f32_fp4 v[10:11], v151, 1.0 op_sel:[1,0,0]
	v_cvt_scalef32_pk_f32_fp4 v[12:13], v151, 1.0 op_sel:[0,1,0]
	v_cvt_scalef32_pk_f32_fp4 v[14:15], v151, 1.0 op_sel:[1,1,0]
	v_pk_fma_f32 v[130:131], v[0:1], s[0:1], v[130:131] op_sel_hi:[1,0,1]
	v_pk_fma_f32 v[138:139], v[2:3], s[0:1], v[138:139] op_sel_hi:[1,0,1]
	v_pk_fma_f32 v[140:141], v[4:5], s[0:1], v[140:141] op_sel_hi:[1,0,1]
	v_pk_fma_f32 v[142:143], v[6:7], s[0:1], v[142:143] op_sel_hi:[1,0,1]
	v_pk_fma_f32 v[128:129], v[8:9], s[0:1], v[128:129] op_sel_hi:[1,0,1]
	v_pk_fma_f32 v[132:133], v[10:11], s[0:1], v[132:133] op_sel_hi:[1,0,1]
	v_pk_fma_f32 v[134:135], v[12:13], s[0:1], v[134:135] op_sel_hi:[1,0,1]
	v_pk_fma_f32 v[136:137], v[14:15], s[0:1], v[136:137] op_sel_hi:[1,0,1]
	v_readlane_b32 s0, v167, 52
	s_waitcnt vmcnt(11)
	v_cvt_scalef32_pk_f32_fp4 v[0:1], v152, 1.0
	v_cvt_scalef32_pk_f32_fp4 v[2:3], v152, 1.0 op_sel:[1,0,0]
	v_cvt_scalef32_pk_f32_fp4 v[4:5], v152, 1.0 op_sel:[0,1,0]
	v_cvt_scalef32_pk_f32_fp4 v[6:7], v152, 1.0 op_sel:[1,1,0]
	v_cvt_scalef32_pk_f32_fp4 v[8:9], v153, 1.0
	v_cvt_scalef32_pk_f32_fp4 v[10:11], v153, 1.0 op_sel:[1,0,0]
	v_cvt_scalef32_pk_f32_fp4 v[12:13], v153, 1.0 op_sel:[0,1,0]
	v_cvt_scalef32_pk_f32_fp4 v[14:15], v153, 1.0 op_sel:[1,1,0]
	v_pk_fma_f32 v[130:131], v[0:1], s[0:1], v[130:131] op_sel_hi:[1,0,1]
	v_pk_fma_f32 v[138:139], v[2:3], s[0:1], v[138:139] op_sel_hi:[1,0,1]
	v_pk_fma_f32 v[140:141], v[4:5], s[0:1], v[140:141] op_sel_hi:[1,0,1]
	v_pk_fma_f32 v[142:143], v[6:7], s[0:1], v[142:143] op_sel_hi:[1,0,1]
	v_pk_fma_f32 v[128:129], v[8:9], s[0:1], v[128:129] op_sel_hi:[1,0,1]
	v_pk_fma_f32 v[132:133], v[10:11], s[0:1], v[132:133] op_sel_hi:[1,0,1]
	v_pk_fma_f32 v[134:135], v[12:13], s[0:1], v[134:135] op_sel_hi:[1,0,1]
	v_pk_fma_f32 v[136:137], v[14:15], s[0:1], v[136:137] op_sel_hi:[1,0,1]
	v_readlane_b32 s0, v167, 53
	s_waitcnt vmcnt(10)
	v_cvt_scalef32_pk_f32_fp4 v[0:1], v154, 1.0
	v_cvt_scalef32_pk_f32_fp4 v[2:3], v154, 1.0 op_sel:[1,0,0]
	v_cvt_scalef32_pk_f32_fp4 v[4:5], v154, 1.0 op_sel:[0,1,0]
	v_cvt_scalef32_pk_f32_fp4 v[6:7], v154, 1.0 op_sel:[1,1,0]
	v_cvt_scalef32_pk_f32_fp4 v[8:9], v155, 1.0
	v_cvt_scalef32_pk_f32_fp4 v[10:11], v155, 1.0 op_sel:[1,0,0]
	v_cvt_scalef32_pk_f32_fp4 v[12:13], v155, 1.0 op_sel:[0,1,0]
	v_cvt_scalef32_pk_f32_fp4 v[14:15], v155, 1.0 op_sel:[1,1,0]
	v_pk_fma_f32 v[130:131], v[0:1], s[0:1], v[130:131] op_sel_hi:[1,0,1]
	v_pk_fma_f32 v[138:139], v[2:3], s[0:1], v[138:139] op_sel_hi:[1,0,1]
	v_pk_fma_f32 v[140:141], v[4:5], s[0:1], v[140:141] op_sel_hi:[1,0,1]
	v_pk_fma_f32 v[142:143], v[6:7], s[0:1], v[142:143] op_sel_hi:[1,0,1]
	v_pk_fma_f32 v[128:129], v[8:9], s[0:1], v[128:129] op_sel_hi:[1,0,1]
	v_pk_fma_f32 v[132:133], v[10:11], s[0:1], v[132:133] op_sel_hi:[1,0,1]
	v_pk_fma_f32 v[134:135], v[12:13], s[0:1], v[134:135] op_sel_hi:[1,0,1]
	v_pk_fma_f32 v[136:137], v[14:15], s[0:1], v[136:137] op_sel_hi:[1,0,1]
	v_readlane_b32 s0, v167, 54
	s_waitcnt vmcnt(9)
	v_cvt_scalef32_pk_f32_fp4 v[0:1], v156, 1.0
	v_cvt_scalef32_pk_f32_fp4 v[2:3], v156, 1.0 op_sel:[1,0,0]
	v_cvt_scalef32_pk_f32_fp4 v[4:5], v156, 1.0 op_sel:[0,1,0]
	v_cvt_scalef32_pk_f32_fp4 v[6:7], v156, 1.0 op_sel:[1,1,0]
	v_cvt_scalef32_pk_f32_fp4 v[8:9], v157, 1.0
	v_cvt_scalef32_pk_f32_fp4 v[10:11], v157, 1.0 op_sel:[1,0,0]
	v_cvt_scalef32_pk_f32_fp4 v[12:13], v157, 1.0 op_sel:[0,1,0]
	v_cvt_scalef32_pk_f32_fp4 v[14:15], v157, 1.0 op_sel:[1,1,0]
	v_pk_fma_f32 v[130:131], v[0:1], s[0:1], v[130:131] op_sel_hi:[1,0,1]
	v_pk_fma_f32 v[138:139], v[2:3], s[0:1], v[138:139] op_sel_hi:[1,0,1]
	v_pk_fma_f32 v[140:141], v[4:5], s[0:1], v[140:141] op_sel_hi:[1,0,1]
	v_pk_fma_f32 v[142:143], v[6:7], s[0:1], v[142:143] op_sel_hi:[1,0,1]
	v_pk_fma_f32 v[128:129], v[8:9], s[0:1], v[128:129] op_sel_hi:[1,0,1]
	v_pk_fma_f32 v[132:133], v[10:11], s[0:1], v[132:133] op_sel_hi:[1,0,1]
	v_pk_fma_f32 v[134:135], v[12:13], s[0:1], v[134:135] op_sel_hi:[1,0,1]
	v_pk_fma_f32 v[136:137], v[14:15], s[0:1], v[136:137] op_sel_hi:[1,0,1]
	v_readlane_b32 s0, v167, 55
	s_waitcnt vmcnt(8)
; __device__ void peer_gather_phase(const Params& P, int l, bool do_store) {
;     ...
; #pragma unroll
;       for (int j = 0; j < 8; ++j) {
;         const float a = __builtin_bit_cast(float, __builtin_amdgcn_readlane(__builtin_bit_cast(int, avec), kb + j));
;         const f32x2 aa = f32x2{a, a};
;         y[0] += aa * __builtin_amdgcn_cvt_scalef32_pk_f32_fp4(v8[j].x, 1.0f, 0); y[1] += aa * __builtin_amdgcn_cvt_scalef32_pk_f32_fp4(v8[j].x, 1.0f, 1);
;         y[2] += aa * __builtin_amdgcn_cvt_scalef32_pk_f32_fp4(v8[j].x, 1.0f, 2); y[3] += aa * __builtin_amdgcn_cvt_scalef32_pk_f32_fp4(v8[j].x, 1.0f, 3);
;         y[4] += aa * __builtin_amdgcn_cvt_scalef32_pk_f32_fp4(v8[j].y, 1.0f, 0); y[5] += aa * __builtin_amdgcn_cvt_scalef32_pk_f32_fp4(v8[j].y, 1.0f, 1);
;         y[6] += aa * __builtin_amdgcn_cvt_scalef32_pk_f32_fp4(v8[j].y, 1.0f, 2); y[7] += aa * __builtin_amdgcn_cvt_scalef32_pk_f32_fp4(v8[j].y, 1.0f, 3);
;       }
	v_cvt_scalef32_pk_f32_fp4 v[0:1], v158, 1.0
	v_cvt_scalef32_pk_f32_fp4 v[2:3], v158, 1.0 op_sel:[1,0,0]
	v_cvt_scalef32_pk_f32_fp4 v[4:5], v158, 1.0 op_sel:[0,1,0]
	v_cvt_scalef32_pk_f32_fp4 v[6:7], v158, 1.0 op_sel:[1,1,0]
	v_cvt_scalef32_pk_f32_fp4 v[8:9], v159, 1.0
	v_cvt_scalef32_pk_f32_fp4 v[10:11], v159, 1.0 op_sel:[1,0,0]
	v_cvt_scalef32_pk_f32_fp4 v[12:13], v159, 1.0 op_sel:[0,1,0]
	v_cvt_scalef32_pk_f32_fp4 v[14:15], v159, 1.0 op_sel:[1,1,0]
	v_pk_fma_f32 v[130:131], v[0:1], s[0:1], v[130:131] op_sel_hi:[1,0,1]
	v_pk_fma_f32 v[138:139], v[2:3], s[0:1], v[138:139] op_sel_hi:[1,0,1]
	v_pk_fma_f32 v[140:141], v[4:5], s[0:1], v[140:141] op_sel_hi:[1,0,1]
	v_pk_fma_f32 v[142:143], v[6:7], s[0:1], v[142:143] op_sel_hi:[1,0,1]
	v_pk_fma_f32 v[128:129], v[8:9], s[0:1], v[128:129] op_sel_hi:[1,0,1]
	v_pk_fma_f32 v[132:133], v[10:11], s[0:1], v[132:133] op_sel_hi:[1,0,1]
	v_pk_fma_f32 v[134:135], v[12:13], s[0:1], v[134:135] op_sel_hi:[1,0,1]
	v_pk_fma_f32 v[136:137], v[14:15], s[0:1], v[136:137] op_sel_hi:[1,0,1]
	v_readlane_b32 s0, v167, 56
	s_waitcnt vmcnt(7)
	v_cvt_scalef32_pk_f32_fp4 v[0:1], v168, 1.0
	v_cvt_scalef32_pk_f32_fp4 v[2:3], v168, 1.0 op_sel:[1,0,0]
	v_cvt_scalef32_pk_f32_fp4 v[4:5], v168, 1.0 op_sel:[0,1,0]
	v_cvt_scalef32_pk_f32_fp4 v[6:7], v168, 1.0 op_sel:[1,1,0]
	v_cvt_scalef32_pk_f32_fp4 v[8:9], v169, 1.0
	v_cvt_scalef32_pk_f32_fp4 v[10:11], v169, 1.0 op_sel:[1,0,0]
	v_cvt_scalef32_pk_f32_fp4 v[12:13], v169, 1.0 op_sel:[0,1,0]
	v_cvt_scalef32_pk_f32_fp4 v[14:15], v169, 1.0 op_sel:[1,1,0]
	v_pk_fma_f32 v[130:131], v[0:1], s[0:1], v[130:131] op_sel_hi:[1,0,1]
	v_pk_fma_f32 v[138:139], v[2:3], s[0:1], v[138:139] op_sel_hi:[1,0,1]
	v_pk_fma_f32 v[140:141], v[4:5], s[0:1], v[140:141] op_sel_hi:[1,0,1]
	v_pk_fma_f32 v[142:143], v[6:7], s[0:1], v[142:143] op_sel_hi:[1,0,1]
	v_pk_fma_f32 v[128:129], v[8:9], s[0:1], v[128:129] op_sel_hi:[1,0,1]
	v_pk_fma_f32 v[132:133], v[10:11], s[0:1], v[132:133] op_sel_hi:[1,0,1]
	v_pk_fma_f32 v[134:135], v[12:13], s[0:1], v[134:135] op_sel_hi:[1,0,1]
	v_pk_fma_f32 v[136:137], v[14:15], s[0:1], v[136:137] op_sel_hi:[1,0,1]
	v_readlane_b32 s0, v167, 57
	s_waitcnt vmcnt(6)
	v_cvt_scalef32_pk_f32_fp4 v[0:1], v170, 1.0
	v_cvt_scalef32_pk_f32_fp4 v[2:3], v170, 1.0 op_sel:[1,0,0]
	v_cvt_scalef32_pk_f32_fp4 v[4:5], v170, 1.0 op_sel:[0,1,0]
	v_cvt_scalef32_pk_f32_fp4 v[6:7], v170, 1.0 op_sel:[1,1,0]
	v_cvt_scalef32_pk_f32_fp4 v[8:9], v171, 1.0
	v_cvt_scalef32_pk_f32_fp4 v[10:11], v171, 1.0 op_sel:[1,0,0]
	v_cvt_scalef32_pk_f32_fp4 v[12:13], v171, 1.0 op_sel:[0,1,0]
	v_cvt_scalef32_pk_f32_fp4 v[14:15], v171, 1.0 op_sel:[1,1,0]
	v_pk_fma_f32 v[130:131], v[0:1], s[0:1], v[130:131] op_sel_hi:[1,0,1]
	v_pk_fma_f32 v[138:139], v[2:3], s[0:1], v[138:139] op_sel_hi:[1,0,1]
	v_pk_fma_f32 v[140:141], v[4:5], s[0:1], v[140:141] op_sel_hi:[1,0,1]
	v_pk_fma_f32 v[142:143], v[6:7], s[0:1], v[142:143] op_sel_hi:[1,0,1]
	v_pk_fma_f32 v[128:129], v[8:9], s[0:1], v[128:129] op_sel_hi:[1,0,1]
	v_pk_fma_f32 v[132:133], v[10:11], s[0:1], v[132:133] op_sel_hi:[1,0,1]
	v_pk_fma_f32 v[134:135], v[12:13], s[0:1], v[134:135] op_sel_hi:[1,0,1]
	v_pk_fma_f32 v[136:137], v[14:15], s[0:1], v[136:137] op_sel_hi:[1,0,1]
	v_readlane_b32 s0, v167, 58
	s_waitcnt vmcnt(5)
	v_cvt_scalef32_pk_f32_fp4 v[0:1], v172, 1.0
	v_cvt_scalef32_pk_f32_fp4 v[2:3], v172, 1.0 op_sel:[1,0,0]
	v_cvt_scalef32_pk_f32_fp4 v[4:5], v172, 1.0 op_sel:[0,1,0]
	v_cvt_scalef32_pk_f32_fp4 v[6:7], v172, 1.0 op_sel:[1,1,0]
	v_cvt_scalef32_pk_f32_fp4 v[8:9], v173, 1.0
	v_cvt_scalef32_pk_f32_fp4 v[10:11], v173, 1.0 op_sel:[1,0,0]
	v_cvt_scalef32_pk_f32_fp4 v[12:13], v173, 1.0 op_sel:[0,1,0]
	v_cvt_scalef32_pk_f32_fp4 v[14:15], v173, 1.0 op_sel:[1,1,0]
	v_pk_fma_f32 v[130:131], v[0:1], s[0:1], v[130:131] op_sel_hi:[1,0,1]
	v_pk_fma_f32 v[138:139], v[2:3], s[0:1], v[138:139] op_sel_hi:[1,0,1]
	v_pk_fma_f32 v[140:141], v[4:5], s[0:1], v[140:141] op_sel_hi:[1,0,1]
	v_pk_fma_f32 v[142:143], v[6:7], s[0:1], v[142:143] op_sel_hi:[1,0,1]
	v_pk_fma_f32 v[128:129], v[8:9], s[0:1], v[128:129] op_sel_hi:[1,0,1]
	v_pk_fma_f32 v[132:133], v[10:11], s[0:1], v[132:133] op_sel_hi:[1,0,1]
	v_pk_fma_f32 v[134:135], v[12:13], s[0:1], v[134:135] op_sel_hi:[1,0,1]
	v_pk_fma_f32 v[136:137], v[14:15], s[0:1], v[136:137] op_sel_hi:[1,0,1]
	v_readlane_b32 s0, v167, 59
	s_waitcnt vmcnt(4)
	v_cvt_scalef32_pk_f32_fp4 v[0:1], v174, 1.0
	v_cvt_scalef32_pk_f32_fp4 v[2:3], v174, 1.0 op_sel:[1,0,0]
	v_cvt_scalef32_pk_f32_fp4 v[4:5], v174, 1.0 op_sel:[0,1,0]
	v_cvt_scalef32_pk_f32_fp4 v[6:7], v174, 1.0 op_sel:[1,1,0]
	v_cvt_scalef32_pk_f32_fp4 v[8:9], v175, 1.0
	v_cvt_scalef32_pk_f32_fp4 v[10:11], v175, 1.0 op_sel:[1,0,0]
	v_cvt_scalef32_pk_f32_fp4 v[12:13], v175, 1.0 op_sel:[0,1,0]
	v_cvt_scalef32_pk_f32_fp4 v[14:15], v175, 1.0 op_sel:[1,1,0]
	v_pk_fma_f32 v[130:131], v[0:1], s[0:1], v[130:131] op_sel_hi:[1,0,1]
	v_pk_fma_f32 v[138:139], v[2:3], s[0:1], v[138:139] op_sel_hi:[1,0,1]
	v_pk_fma_f32 v[140:141], v[4:5], s[0:1], v[140:141] op_sel_hi:[1,0,1]
	v_pk_fma_f32 v[142:143], v[6:7], s[0:1], v[142:143] op_sel_hi:[1,0,1]
	v_pk_fma_f32 v[128:129], v[8:9], s[0:1], v[128:129] op_sel_hi:[1,0,1]
	v_pk_fma_f32 v[132:133], v[10:11], s[0:1], v[132:133] op_sel_hi:[1,0,1]
	v_pk_fma_f32 v[134:135], v[12:13], s[0:1], v[134:135] op_sel_hi:[1,0,1]
	v_pk_fma_f32 v[136:137], v[14:15], s[0:1], v[136:137] op_sel_hi:[1,0,1]
	v_readlane_b32 s0, v167, 60
	s_waitcnt vmcnt(3)
; __device__ void peer_gather_phase(const Params& P, int l, bool do_store) {
;     ...
; #pragma unroll
;       for (int j = 0; j < 8; ++j) {
;         const float a = __builtin_bit_cast(float, __builtin_amdgcn_readlane(__builtin_bit_cast(int, avec), kb + j));
;         const f32x2 aa = f32x2{a, a};
;         y[0] += aa * __builtin_amdgcn_cvt_scalef32_pk_f32_fp4(v8[j].x, 1.0f, 0); y[1] += aa * __builtin_amdgcn_cvt_scalef32_pk_f32_fp4(v8[j].x, 1.0f, 1);
;         y[2] += aa * __builtin_amdgcn_cvt_scalef32_pk_f32_fp4(v8[j].x, 1.0f, 2); y[3] += aa * __builtin_amdgcn_cvt_scalef32_pk_f32_fp4(v8[j].x, 1.0f, 3);
;         y[4] += aa * __builtin_amdgcn_cvt_scalef32_pk_f32_fp4(v8[j].y, 1.0f, 0); y[5] += aa * __builtin_amdgcn_cvt_scalef32_pk_f32_fp4(v8[j].y, 1.0f, 1);
;         y[6] += aa * __builtin_amdgcn_cvt_scalef32_pk_f32_fp4(v8[j].y, 1.0f, 2); y[7] += aa * __builtin_amdgcn_cvt_scalef32_pk_f32_fp4(v8[j].y, 1.0f, 3);
;       }
	v_cvt_scalef32_pk_f32_fp4 v[0:1], v180, 1.0
	v_cvt_scalef32_pk_f32_fp4 v[2:3], v180, 1.0 op_sel:[1,0,0]
	v_cvt_scalef32_pk_f32_fp4 v[4:5], v180, 1.0 op_sel:[0,1,0]
	v_cvt_scalef32_pk_f32_fp4 v[6:7], v180, 1.0 op_sel:[1,1,0]
	v_cvt_scalef32_pk_f32_fp4 v[8:9], v181, 1.0
	v_cvt_scalef32_pk_f32_fp4 v[10:11], v181, 1.0 op_sel:[1,0,0]
	v_cvt_scalef32_pk_f32_fp4 v[12:13], v181, 1.0 op_sel:[0,1,0]
	v_cvt_scalef32_pk_f32_fp4 v[14:15], v181, 1.0 op_sel:[1,1,0]
	v_pk_fma_f32 v[130:131], v[0:1], s[0:1], v[130:131] op_sel_hi:[1,0,1]
	v_pk_fma_f32 v[138:139], v[2:3], s[0:1], v[138:139] op_sel_hi:[1,0,1]
	v_pk_fma_f32 v[140:141], v[4:5], s[0:1], v[140:141] op_sel_hi:[1,0,1]
	v_pk_fma_f32 v[142:143], v[6:7], s[0:1], v[142:143] op_sel_hi:[1,0,1]
	v_pk_fma_f32 v[128:129], v[8:9], s[0:1], v[128:129] op_sel_hi:[1,0,1]
	v_pk_fma_f32 v[132:133], v[10:11], s[0:1], v[132:133] op_sel_hi:[1,0,1]
	v_pk_fma_f32 v[134:135], v[12:13], s[0:1], v[134:135] op_sel_hi:[1,0,1]
	v_pk_fma_f32 v[136:137], v[14:15], s[0:1], v[136:137] op_sel_hi:[1,0,1]
	v_readlane_b32 s0, v167, 61
	s_waitcnt vmcnt(2)
	v_cvt_scalef32_pk_f32_fp4 v[0:1], v182, 1.0
	v_cvt_scalef32_pk_f32_fp4 v[2:3], v182, 1.0 op_sel:[1,0,0]
	v_cvt_scalef32_pk_f32_fp4 v[4:5], v182, 1.0 op_sel:[0,1,0]
	v_cvt_scalef32_pk_f32_fp4 v[6:7], v182, 1.0 op_sel:[1,1,0]
	v_cvt_scalef32_pk_f32_fp4 v[8:9], v183, 1.0
	v_cvt_scalef32_pk_f32_fp4 v[10:11], v183, 1.0 op_sel:[1,0,0]
	v_cvt_scalef32_pk_f32_fp4 v[12:13], v183, 1.0 op_sel:[0,1,0]
	v_cvt_scalef32_pk_f32_fp4 v[14:15], v183, 1.0 op_sel:[1,1,0]
	v_pk_fma_f32 v[130:131], v[0:1], s[0:1], v[130:131] op_sel_hi:[1,0,1]
	v_pk_fma_f32 v[138:139], v[2:3], s[0:1], v[138:139] op_sel_hi:[1,0,1]
	v_pk_fma_f32 v[140:141], v[4:5], s[0:1], v[140:141] op_sel_hi:[1,0,1]
	v_pk_fma_f32 v[142:143], v[6:7], s[0:1], v[142:143] op_sel_hi:[1,0,1]
	v_pk_fma_f32 v[128:129], v[8:9], s[0:1], v[128:129] op_sel_hi:[1,0,1]
	v_pk_fma_f32 v[132:133], v[10:11], s[0:1], v[132:133] op_sel_hi:[1,0,1]
	v_pk_fma_f32 v[134:135], v[12:13], s[0:1], v[134:135] op_sel_hi:[1,0,1]
	v_pk_fma_f32 v[136:137], v[14:15], s[0:1], v[136:137] op_sel_hi:[1,0,1]
	v_readlane_b32 s0, v167, 62
	s_waitcnt vmcnt(1)
	v_cvt_scalef32_pk_f32_fp4 v[0:1], v184, 1.0
	v_cvt_scalef32_pk_f32_fp4 v[2:3], v184, 1.0 op_sel:[1,0,0]
	v_cvt_scalef32_pk_f32_fp4 v[4:5], v184, 1.0 op_sel:[0,1,0]
	v_cvt_scalef32_pk_f32_fp4 v[6:7], v184, 1.0 op_sel:[1,1,0]
	v_cvt_scalef32_pk_f32_fp4 v[8:9], v185, 1.0
	v_cvt_scalef32_pk_f32_fp4 v[10:11], v185, 1.0 op_sel:[1,0,0]
	v_cvt_scalef32_pk_f32_fp4 v[12:13], v185, 1.0 op_sel:[0,1,0]
	v_cvt_scalef32_pk_f32_fp4 v[14:15], v185, 1.0 op_sel:[1,1,0]
	v_pk_fma_f32 v[130:131], v[0:1], s[0:1], v[130:131] op_sel_hi:[1,0,1]
	v_pk_fma_f32 v[138:139], v[2:3], s[0:1], v[138:139] op_sel_hi:[1,0,1]
	v_pk_fma_f32 v[140:141], v[4:5], s[0:1], v[140:141] op_sel_hi:[1,0,1]
	v_pk_fma_f32 v[142:143], v[6:7], s[0:1], v[142:143] op_sel_hi:[1,0,1]
	v_pk_fma_f32 v[128:129], v[8:9], s[0:1], v[128:129] op_sel_hi:[1,0,1]
	v_pk_fma_f32 v[132:133], v[10:11], s[0:1], v[132:133] op_sel_hi:[1,0,1]
	v_pk_fma_f32 v[134:135], v[12:13], s[0:1], v[134:135] op_sel_hi:[1,0,1]
	v_pk_fma_f32 v[136:137], v[14:15], s[0:1], v[136:137] op_sel_hi:[1,0,1]
	v_readlane_b32 s0, v167, 63
	s_waitcnt vmcnt(0)
; __device__ void peer_gather_phase(const Params& P, int l, bool do_store) {
;     ...
;       for (int j = 0; j < 8; ++j) {
;         const float a = __builtin_bit_cast(float, __builtin_amdgcn_readlane(__builtin_bit_cast(int, avec), kb + j));
;         const f32x2 aa = f32x2{a, a};
;         y[0] += aa * __builtin_amdgcn_cvt_scalef32_pk_f32_fp4(v8[j].x, 1.0f, 0); y[1] += aa * __builtin_amdgcn_cvt_scalef32_pk_f32_fp4(v8[j].x, 1.0f, 1);
;         y[2] += aa * __builtin_amdgcn_cvt_scalef32_pk_f32_fp4(v8[j].x, 1.0f, 2); y[3] += aa * __builtin_amdgcn_cvt_scalef32_pk_f32_fp4(v8[j].x, 1.0f, 3);
;         y[4] += aa * __builtin_amdgcn_cvt_scalef32_pk_f32_fp4(v8[j].y, 1.0f, 0); y[5] += aa * __builtin_amdgcn_cvt_scalef32_pk_f32_fp4(v8[j].y, 1.0f, 1);
;         y[6] += aa * __builtin_amdgcn_cvt_scalef32_pk_f32_fp4(v8[j].y, 1.0f, 2); y[7] += aa * __builtin_amdgcn_cvt_scalef32_pk_f32_fp4(v8[j].y, 1.0f, 3);
;     ...
;     float* xfp = P.out + (size_t)t * 1024 + lane * 16;
;     float pre[16];
; #pragma unroll
;     for (int k2 = 0; k2 < 8; ++k2) {
;       pre[2 * k2 + 0] = ALPHA_C * xf[k2].x + y[k2].x;
;       pre[2 * k2 + 1] = ALPHA_C * xf[k2].y + y[k2].y;
;     }
;     float sm = 0.f;
; #pragma unroll
;     for (int k = 0; k < 16; ++k) sm += pre[k];
;     const float mean = wave_sum(sm) * (1.f / 1024.f);
;     float vs = 0.f;
; #pragma unroll
;     for (int k = 0; k < 16; ++k) { const float dd = pre[k] - mean; vs += dd * dd; }
;     const float rstd = rsqrtf(wave_sum(vs) * (1.f / 1024.f) + EPS_C);
;     const float* g2 = P.ln2_g + l * 1024 + lane * 16;
;     const float* b2 = P.ln2_b + l * 1024 + lane * 16;
;     float o[16];
; #pragma unroll
;     for (int k4 = 0; k4 < 4; ++k4) {
;       const float4 gg = *(const float4*)(g2 + 4 * k4), bb = *(const float4*)(b2 + 4 * k4);
;       o[4 * k4 + 0] = (pre[4 * k4 + 0] - mean) * rstd * gg.x + bb.x; o[4 * k4 + 1] = (pre[4 * k4 + 1] - mean) * rstd * gg.y + bb.y;
;       o[4 * k4 + 2] = (pre[4 * k4 + 2] - mean) * rstd * gg.z + bb.z; o[4 * k4 + 3] = (pre[4 * k4 + 3] - mean) * rstd * gg.w + bb.w;
;       float4 ov; ov.x = o[4 * k4]; ov.y = o[4 * k4 + 1]; ov.z = o[4 * k4 + 2]; ov.w = o[4 * k4 + 3];
;       if (do_store && l == 1) *(float4*)(xfp + 4 * k4) = ov;
;     }
	v_cvt_scalef32_pk_f32_fp4 v[0:1], v186, 1.0
	v_cvt_scalef32_pk_f32_fp4 v[2:3], v186, 1.0 op_sel:[1,0,0]
	v_cvt_scalef32_pk_f32_fp4 v[4:5], v186, 1.0 op_sel:[0,1,0]
	v_cvt_scalef32_pk_f32_fp4 v[6:7], v186, 1.0 op_sel:[1,1,0]
	v_cvt_scalef32_pk_f32_fp4 v[8:9], v187, 1.0
	v_cvt_scalef32_pk_f32_fp4 v[10:11], v187, 1.0 op_sel:[1,0,0]
	v_cvt_scalef32_pk_f32_fp4 v[12:13], v187, 1.0 op_sel:[0,1,0]
	v_cvt_scalef32_pk_f32_fp4 v[14:15], v187, 1.0 op_sel:[1,1,0]
	v_pk_fma_f32 v[130:131], v[0:1], s[0:1], v[130:131] op_sel_hi:[1,0,1]
	v_pk_fma_f32 v[138:139], v[2:3], s[0:1], v[138:139] op_sel_hi:[1,0,1]
	v_pk_fma_f32 v[140:141], v[4:5], s[0:1], v[140:141] op_sel_hi:[1,0,1]
	v_pk_fma_f32 v[142:143], v[6:7], s[0:1], v[142:143] op_sel_hi:[1,0,1]
	v_pk_fma_f32 v[128:129], v[8:9], s[0:1], v[128:129] op_sel_hi:[1,0,1]
	v_pk_fma_f32 v[132:133], v[10:11], s[0:1], v[132:133] op_sel_hi:[1,0,1]
	v_pk_fma_f32 v[134:135], v[12:13], s[0:1], v[134:135] op_sel_hi:[1,0,1]
	v_pk_fma_f32 v[136:137], v[14:15], s[0:1], v[136:137] op_sel_hi:[1,0,1]
	v_lshlrev_b32_e32 v0, 16, v70
	v_lshlrev_b32_e32 v2, 16, v69
	v_and_b32_e32 v3, 0xffff0000, v69
	v_and_b32_e32 v1, 0xffff0000, v70
	s_mov_b32 s0, 0x3fb504f3
	v_pk_fma_f32 v[16:17], v[0:1], s[0:1], v[140:141] op_sel_hi:[1,0,1]
	v_pk_fma_f32 v[18:19], v[2:3], s[0:1], v[138:139] op_sel_hi:[1,0,1]
	global_load_dwordx4 v[0:3], v[82:83], off
	global_load_dwordx4 v[20:23], v[84:85], off
	global_load_dwordx4 v[44:47], v[82:83], off offset:16
	global_load_dwordx4 v[48:51], v[84:85], off offset:16
	global_load_dwordx4 v[52:55], v[82:83], off offset:32
	global_load_dwordx4 v[228:231], v[84:85], off offset:32
	global_load_dwordx4 v[232:235], v[82:83], off offset:48
	global_load_dwordx4 v[236:239], v[84:85], off offset:48
	v_lshlrev_b32_e32 v4, 16, v68
	v_and_b32_e32 v5, 0xffff0000, v68
	v_pk_fma_f32 v[4:5], v[4:5], s[0:1], v[130:131] op_sel_hi:[1,0,1]
	v_lshlrev_b32_e32 v10, 16, v71
	v_add_f32_e32 v24, 0, v4
	v_add_f32_e32 v24, v5, v24
	v_add_f32_e32 v24, v18, v24
	v_add_f32_e32 v24, v19, v24
	v_and_b32_e32 v11, 0xffff0000, v71
	v_add_f32_e32 v24, v16, v24
	v_pk_fma_f32 v[10:11], v[10:11], s[0:1], v[142:143] op_sel_hi:[1,0,1]
	v_add_f32_e32 v24, v17, v24
	v_lshlrev_b32_e32 v6, 16, v64
	v_lshlrev_b32_e32 v8, 16, v66
	v_lshlrev_b32_e32 v12, 16, v65
	v_lshlrev_b32_e32 v14, 16, v67
	v_and_b32_e32 v7, 0xffff0000, v64
	v_and_b32_e32 v13, 0xffff0000, v65
	v_and_b32_e32 v9, 0xffff0000, v66
	v_and_b32_e32 v15, 0xffff0000, v67
	v_add_f32_e32 v24, v10, v24
	v_add_f32_e32 v26, v11, v24
	v_pk_fma_f32 v[24:25], v[14:15], s[0:1], v[136:137] op_sel_hi:[1,0,1]
	v_pk_fma_f32 v[14:15], v[8:9], s[0:1], v[134:135] op_sel_hi:[1,0,1]
	v_pk_fma_f32 v[8:9], v[12:13], s[0:1], v[132:133] op_sel_hi:[1,0,1]
	v_pk_fma_f32 v[12:13], v[6:7], s[0:1], v[128:129] op_sel_hi:[1,0,1]
	v_mov_b32_e32 v7, v177
	v_add_f32_e32 v6, v12, v26
	v_add_f32_e32 v6, v13, v6
	v_add_f32_e32 v6, v8, v6
	v_add_f32_e32 v6, v9, v6
	v_add_f32_e32 v6, v14, v6
	v_add_f32_e32 v6, v15, v6
	v_add_f32_e32 v6, v24, v6
	v_add_f32_e32 v6, v25, v6
	s_nop 1
	v_add_f32_dpp v6, v6, v6 row_shr:1 row_mask:0xf bank_mask:0xf bound_ctrl:1
	s_nop 1
	v_add_f32_dpp v6, v6, v6 row_shr:2 row_mask:0xf bank_mask:0xf bound_ctrl:1
	s_nop 1
	v_add_f32_dpp v6, v6, v6 row_shr:4 row_mask:0xf bank_mask:0xf bound_ctrl:1
	s_nop 1
	v_add_f32_dpp v6, v6, v6 row_shr:8 row_mask:0xf bank_mask:0xf bound_ctrl:1
	s_nop 1
	v_mov_b32_dpp v7, v6 row_bcast:15 row_mask:0xa bank_mask:0xf
	v_add_f32_e32 v6, v6, v7
	v_mov_b32_e32 v7, v177
	s_nop 1
	v_mov_b32_dpp v7, v6 row_bcast:31 row_mask:0xc bank_mask:0xf
	v_add_f32_e32 v6, v6, v7
	s_nop 0
	v_readlane_b32 s0, v6, 63
	s_nop 1
	v_mul_f32_e32 v26, s0, v210
	v_pk_add_f32 v[28:29], v[4:5], v[26:27] op_sel_hi:[1,0] neg_lo:[0,1] neg_hi:[0,1]
	v_pk_add_f32 v[32:33], v[18:19], v[26:27] op_sel_hi:[1,0] neg_lo:[0,1] neg_hi:[0,1]
	v_pk_mul_f32 v[30:31], v[28:29], v[28:29]
	v_pk_mul_f32 v[18:19], v[32:33], v[32:33]
	v_pk_add_f32 v[4:5], v[16:17], v[26:27] op_sel_hi:[1,0] neg_lo:[0,1] neg_hi:[0,1]
	v_pk_add_f32 v[6:7], v[10:11], v[26:27] op_sel_hi:[1,0] neg_lo:[0,1] neg_hi:[0,1]
	v_pk_add_f32 v[10:11], v[12:13], v[26:27] op_sel_hi:[1,0] neg_lo:[0,1] neg_hi:[0,1]
	v_pk_add_f32 v[8:9], v[8:9], v[26:27] op_sel_hi:[1,0] neg_lo:[0,1] neg_hi:[0,1]
	v_pk_add_f32 v[14:15], v[14:15], v[26:27] op_sel_hi:[1,0] neg_lo:[0,1] neg_hi:[0,1]
	v_pk_add_f32 v[12:13], v[24:25], v[26:27] op_sel_hi:[1,0] neg_lo:[0,1] neg_hi:[0,1]
	v_add_f32_e32 v26, v30, v31
	v_add_f32_e32 v18, v18, v26
	v_pk_mul_f32 v[16:17], v[4:5], v[4:5]
	v_add_f32_e32 v18, v19, v18
	v_add_f32_e32 v16, v16, v18
	v_pk_mul_f32 v[34:35], v[6:7], v[6:7]
	v_add_f32_e32 v16, v17, v16
	v_add_f32_e32 v16, v34, v16
	v_pk_mul_f32 v[36:37], v[10:11], v[10:11]
	v_add_f32_e32 v16, v35, v16
	v_add_f32_e32 v16, v36, v16
	v_pk_mul_f32 v[38:39], v[8:9], v[8:9]
	v_add_f32_e32 v16, v37, v16
	v_add_f32_e32 v16, v38, v16
	v_pk_mul_f32 v[40:41], v[14:15], v[14:15]
	v_add_f32_e32 v16, v39, v16
	v_add_f32_e32 v16, v40, v16
	v_pk_mul_f32 v[24:25], v[12:13], v[12:13]
	v_add_f32_e32 v16, v41, v16
	v_add_f32_e32 v16, v24, v16
	v_add_f32_e32 v16, v25, v16
	v_mov_b32_e32 v17, v177
	s_nop 0
	v_add_f32_dpp v16, v16, v16 row_shr:1 row_mask:0xf bank_mask:0xf bound_ctrl:1
	s_nop 1
	v_add_f32_dpp v16, v16, v16 row_shr:2 row_mask:0xf bank_mask:0xf bound_ctrl:1
	s_nop 1
	v_add_f32_dpp v16, v16, v16 row_shr:4 row_mask:0xf bank_mask:0xf bound_ctrl:1
	s_nop 1
	v_add_f32_dpp v16, v16, v16 row_shr:8 row_mask:0xf bank_mask:0xf bound_ctrl:1
	s_nop 1
	v_mov_b32_dpp v17, v16 row_bcast:15 row_mask:0xa bank_mask:0xf
	v_add_f32_e32 v16, v16, v17
	v_mov_b32_e32 v17, v177
	s_nop 1
	v_mov_b32_dpp v17, v16 row_bcast:31 row_mask:0xc bank_mask:0xf
	v_add_f32_e32 v16, v16, v17
	s_nop 0
	v_readlane_b32 s0, v16, 63
	s_nop 1
	v_fma_f32 v16, s0, v210, v203
	s_mov_b32 s0, 0x800000
	v_mul_f32_e32 v17, 0x4b800000, v16
	v_cmp_gt_f32_e32 vcc, s0, v16
	s_nop 1
	v_cndmask_b32_e32 v16, v16, v17, vcc
	v_rsq_f32_e32 v18, v16
	v_lshl_add_u64 v[16:17], v[94:95], 2, v[80:81]
	v_mul_f32_e32 v19, 0x45800000, v18
	v_cndmask_b32_e32 v18, v18, v19, vcc
	v_pk_mul_f32 v[24:25], v[28:29], v[18:19] op_sel_hi:[1,0]
	s_and_b64 vcc, exec, s[38:39]
	s_waitcnt vmcnt(0)
	v_pk_fma_f32 v[0:1], v[0:1], v[24:25], v[20:21]
	v_pk_mul_f32 v[20:21], v[32:33], v[18:19] op_sel_hi:[1,0]
	s_nop 0
	v_pk_fma_f32 v[2:3], v[2:3], v[20:21], v[22:23]
	s_cbranch_vccz .LBB0_25
	global_store_dwordx4 v[16:17], v[0:3], off
